# SALU spacing variant (guide 7.5): one SALU per MFMA gap starting after the 2nd MFMA instead of two per gap after the 4th
# speedup vs baseline: 1.0086x; 1.0086x over previous
.LBB0_86:
	v_mov_b64_e32 v[0:1], 0x800
	s_ashr_i32 s7, s6, 31
	v_cmp_lt_i64_e32 vcc, s[8:9], v[0:1]
	s_lshl_b64 s[8:9], s[6:7], 20
	s_add_u32 s8, s23, s8
	s_addc_u32 s9, s24, s9
	s_and_b64 s[10:11], vcc, exec
	s_cselect_b32 s7, s9, s15
	s_cselect_b32 s38, s8, s14
	s_ashr_i32 s5, s4, 31
	s_lshl_b64 s[10:11], s[4:5], 20
	s_add_u32 s10, s25, s10
	s_addc_u32 s11, s26, s11
	s_and_b64 s[18:19], vcc, exec
	s_cselect_b32 s5, s11, s17
	s_cselect_b32 s39, s10, s16
	s_add_u32 s14, s14, 0x80080
	s_addc_u32 s15, s15, 0
	s_add_u32 s40, s16, 0x100
	s_addc_u32 s41, s17, 0
	s_mov_b32 s42, -2
	s_mov_b64 s[48:49], 0x80
	v_add_u32_e32 v220, 0x10000, v183
	s_add_u32 s16, s14, 0xfff80080
	s_addc_u32 s17, s15, -1
	s_add_i32 s43, 0, 0x10000
	ds_read_b128 v[128:131], v220 offset:0
	ds_read_b128 v[132:135], v220 offset:1024
	ds_read_b128 v[136:139], v220 offset:2048
	ds_read_b128 v[140:143], v220 offset:3072
	s_cmp_eq_u32 s42, 28
	s_cselect_b32 s19, s7, s17
	s_cselect_b32 s18, s38, s16
	s_cselect_b32 s17, s5, s41
	s_cselect_b32 s16, s39, s40
	s_add_i32 m0, s28, 0xc000
	ds_read_b128 v[144:147], v185
	ds_read_b128 v[148:151], v185 offset:1024
	ds_read_b128 v[152:155], v185 offset:2048
	ds_read_b128 v[156:159], v185 offset:3072
	ds_read_b128 v[170:173], v185 offset:4096
	ds_read_b128 v[174:177], v185 offset:5120
	ds_read_b128 v[178:181], v185 offset:6144
	ds_read_b128 v[186:189], v185 offset:7168
	global_load_lds_dwordx4 v166, s[14:15]
	s_add_i32 m0, s28, 0xe000
	s_nop 0
	global_load_lds_dwordx4 v168, s[14:15]
	s_waitcnt lgkmcnt(8)
	s_barrier
	s_waitcnt lgkmcnt(0)
	v_mfma_f32_16x16x32_bf16 v[124:127], v[128:131], v[144:147], 0
	v_mfma_f32_16x16x32_bf16 v[120:123], v[136:139], v[144:147], 0
	s_add_i32 s46, 0, 0x14000
	v_mfma_f32_16x16x32_bf16 v[108:111], v[128:131], v[152:155], 0
	s_add_i32 s43, s43, s27
	v_mfma_f32_16x16x32_bf16 v[104:107], v[136:139], v[152:155], 0
	s_mov_b32 m0, s43
	v_mfma_f32_16x16x32_bf16 v[92:95], v[128:131], v[170:173], 0
	v_mfma_f32_16x16x32_bf16 v[88:91], v[136:139], v[170:173], 0
	v_mfma_f32_16x16x32_bf16 v[76:79], v[128:131], v[178:181], 0
	v_mfma_f32_16x16x32_bf16 v[72:75], v[136:139], v[178:181], 0
	v_mfma_f32_16x16x32_bf16 v[124:127], v[132:135], v[148:151], v[124:127]
	v_mfma_f32_16x16x32_bf16 v[120:123], v[140:143], v[148:151], v[120:123]
	v_mfma_f32_16x16x32_bf16 v[108:111], v[132:135], v[156:159], v[108:111]
	v_mfma_f32_16x16x32_bf16 v[104:107], v[140:143], v[156:159], v[104:107]
	v_mfma_f32_16x16x32_bf16 v[92:95], v[132:135], v[174:177], v[92:95]
	v_mfma_f32_16x16x32_bf16 v[88:91], v[140:143], v[174:177], v[88:91]
	v_mfma_f32_16x16x32_bf16 v[76:79], v[132:135], v[186:189], v[76:79]
	v_mfma_f32_16x16x32_bf16 v[72:75], v[140:143], v[186:189], v[72:75]
	s_barrier
	ds_read_b128 v[196:199], v220 offset:16384
	ds_read_b128 v[204:207], v220 offset:17408
	ds_read_b128 v[208:211], v220 offset:18432
	ds_read_b128 v[214:217], v220 offset:19456
	global_load_lds_dwordx4 v192, s[16:17]
	s_add_i32 m0, s43, 0x2000
	s_nop 0
	global_load_lds_dwordx4 v164, s[16:17]
	s_barrier
	s_waitcnt lgkmcnt(0)
	v_mfma_f32_16x16x32_bf16 v[116:119], v[196:199], v[144:147], 0
	v_mfma_f32_16x16x32_bf16 v[112:115], v[208:211], v[144:147], 0
	s_mov_b32 m0, s28
	v_mfma_f32_16x16x32_bf16 v[100:103], v[196:199], v[152:155], 0
	s_add_u32 s48, s18, 0x80
	v_mfma_f32_16x16x32_bf16 v[96:99], v[208:211], v[152:155], 0
	s_addc_u32 s49, s19, 0
	v_mfma_f32_16x16x32_bf16 v[84:87], v[196:199], v[170:173], 0
	v_mfma_f32_16x16x32_bf16 v[80:83], v[208:211], v[170:173], 0
	v_mfma_f32_16x16x32_bf16 v[68:71], v[196:199], v[178:181], 0
	v_mfma_f32_16x16x32_bf16 v[64:67], v[208:211], v[178:181], 0
	v_mfma_f32_16x16x32_bf16 v[116:119], v[204:207], v[148:151], v[116:119]
	v_mfma_f32_16x16x32_bf16 v[112:115], v[214:217], v[148:151], v[112:115]
	v_mfma_f32_16x16x32_bf16 v[100:103], v[204:207], v[156:159], v[100:103]
	v_mfma_f32_16x16x32_bf16 v[96:99], v[214:217], v[156:159], v[96:99]
	v_mfma_f32_16x16x32_bf16 v[84:87], v[204:207], v[174:177], v[84:87]
	v_mfma_f32_16x16x32_bf16 v[80:83], v[214:217], v[174:177], v[80:83]
	v_mfma_f32_16x16x32_bf16 v[68:71], v[204:207], v[186:189], v[68:71]
	v_mfma_f32_16x16x32_bf16 v[64:67], v[214:217], v[186:189], v[64:67]
	s_barrier
	ds_read_b128 v[144:147], v185 offset:16384
	ds_read_b128 v[148:151], v185 offset:17408
	ds_read_b128 v[152:155], v185 offset:18432
	ds_read_b128 v[156:159], v185 offset:19456
	ds_read_b128 v[170:173], v185 offset:20480
	ds_read_b128 v[174:177], v185 offset:21504
	ds_read_b128 v[178:181], v185 offset:22528
	ds_read_b128 v[186:189], v185 offset:23552
	global_load_lds_dwordx4 v160, s[18:19]
	s_mov_b32 m0, s29
	s_nop 0
	global_load_lds_dwordx4 v162, s[18:19]
	s_barrier
	s_waitcnt lgkmcnt(0)
	v_mfma_f32_16x16x32_bf16 v[60:63], v[128:131], v[144:147], 0
	v_mfma_f32_16x16x32_bf16 v[56:59], v[136:139], v[144:147], 0
	s_add_u32 s44, s16, 0x80000
	v_mfma_f32_16x16x32_bf16 v[44:47], v[128:131], v[152:155], 0
	s_addc_u32 s45, s17, 0
	v_mfma_f32_16x16x32_bf16 v[40:43], v[136:139], v[152:155], 0
	s_add_i32 s43, s46, s27
	v_mfma_f32_16x16x32_bf16 v[28:31], v[128:131], v[170:173], 0
	s_mov_b32 m0, s43
	v_mfma_f32_16x16x32_bf16 v[24:27], v[136:139], v[170:173], 0
	v_mfma_f32_16x16x32_bf16 v[12:15], v[128:131], v[178:181], 0
	v_mfma_f32_16x16x32_bf16 v[8:11], v[136:139], v[178:181], 0
	v_mfma_f32_16x16x32_bf16 v[60:63], v[132:135], v[148:151], v[60:63]
	v_mfma_f32_16x16x32_bf16 v[56:59], v[140:143], v[148:151], v[56:59]
	v_mfma_f32_16x16x32_bf16 v[44:47], v[132:135], v[156:159], v[44:47]
	v_mfma_f32_16x16x32_bf16 v[40:43], v[140:143], v[156:159], v[40:43]
	v_mfma_f32_16x16x32_bf16 v[28:31], v[132:135], v[174:177], v[28:31]
	v_mfma_f32_16x16x32_bf16 v[24:27], v[140:143], v[174:177], v[24:27]
	v_mfma_f32_16x16x32_bf16 v[12:15], v[132:135], v[186:189], v[12:15]
	v_mfma_f32_16x16x32_bf16 v[8:11], v[140:143], v[186:189], v[8:11]
	s_barrier
	global_load_lds_dwordx4 v192, s[44:45]
	s_add_i32 m0, s43, 0x2000
	s_nop 0
	global_load_lds_dwordx4 v164, s[44:45]
	s_waitcnt vmcnt(6)
	s_barrier
	v_mfma_f32_16x16x32_bf16 v[52:55], v[196:199], v[144:147], 0
	v_mfma_f32_16x16x32_bf16 v[48:51], v[208:211], v[144:147], 0
	s_add_i32 s43, 0, 0x18000
	v_mfma_f32_16x16x32_bf16 v[36:39], v[196:199], v[152:155], 0
	s_add_u32 s18, s18, 0x80000
	v_mfma_f32_16x16x32_bf16 v[32:35], v[208:211], v[152:155], 0
	s_addc_u32 s19, s19, 0
	v_mfma_f32_16x16x32_bf16 v[20:23], v[196:199], v[170:173], 0
	s_mov_b32 m0, s30
	v_mfma_f32_16x16x32_bf16 v[16:19], v[208:211], v[170:173], 0
	v_mfma_f32_16x16x32_bf16 v[4:7], v[196:199], v[178:181], 0
	v_mfma_f32_16x16x32_bf16 v[0:3], v[208:211], v[178:181], 0
	v_mfma_f32_16x16x32_bf16 v[52:55], v[204:207], v[148:151], v[52:55]
	v_mfma_f32_16x16x32_bf16 v[48:51], v[214:217], v[148:151], v[48:51]
	v_mfma_f32_16x16x32_bf16 v[36:39], v[204:207], v[156:159], v[36:39]
	v_mfma_f32_16x16x32_bf16 v[32:35], v[214:217], v[156:159], v[32:35]
	v_mfma_f32_16x16x32_bf16 v[20:23], v[204:207], v[174:177], v[20:23]
	v_mfma_f32_16x16x32_bf16 v[16:19], v[214:217], v[174:177], v[16:19]
	v_mfma_f32_16x16x32_bf16 v[4:7], v[204:207], v[186:189], v[4:7]
	v_mfma_f32_16x16x32_bf16 v[0:3], v[214:217], v[186:189], v[0:3]
	s_barrier
	ds_read_b128 v[128:131], v220 offset:32768
	ds_read_b128 v[132:135], v220 offset:33792
	ds_read_b128 v[136:139], v220 offset:34816
	ds_read_b128 v[140:143], v220 offset:35840
	ds_read_b128 v[144:147], v185 offset:32768
	ds_read_b128 v[148:151], v185 offset:33792
	ds_read_b128 v[152:155], v185 offset:34816
	ds_read_b128 v[156:159], v185 offset:35840
	ds_read_b128 v[170:173], v185 offset:36864
	ds_read_b128 v[174:177], v185 offset:37888
	ds_read_b128 v[178:181], v185 offset:38912
	ds_read_b128 v[186:189], v185 offset:39936
	global_load_lds_dwordx4 v160, s[18:19]
	s_mov_b32 m0, s31
	s_nop 0
	global_load_lds_dwordx4 v162, s[18:19]
	s_waitcnt lgkmcnt(8)
	s_barrier
	s_waitcnt lgkmcnt(0)
	v_mfma_f32_16x16x32_bf16 v[124:127], v[128:131], v[144:147], v[124:127]
	v_mfma_f32_16x16x32_bf16 v[120:123], v[136:139], v[144:147], v[120:123]
	s_add_i32 s18, 0, 0x1c000
	v_mfma_f32_16x16x32_bf16 v[108:111], v[128:131], v[152:155], v[108:111]
	s_add_i32 s19, s43, s27
	v_mfma_f32_16x16x32_bf16 v[104:107], v[136:139], v[152:155], v[104:107]
	s_add_i32 m0, s19, 0xffffff80
	v_mfma_f32_16x16x32_bf16 v[92:95], v[128:131], v[170:173], v[92:95]
	v_mfma_f32_16x16x32_bf16 v[88:91], v[136:139], v[170:173], v[88:91]
	v_mfma_f32_16x16x32_bf16 v[76:79], v[128:131], v[178:181], v[76:79]
	v_mfma_f32_16x16x32_bf16 v[72:75], v[136:139], v[178:181], v[72:75]
	v_mfma_f32_16x16x32_bf16 v[124:127], v[132:135], v[148:151], v[124:127]
	v_mfma_f32_16x16x32_bf16 v[120:123], v[140:143], v[148:151], v[120:123]
	v_mfma_f32_16x16x32_bf16 v[108:111], v[132:135], v[156:159], v[108:111]
	v_mfma_f32_16x16x32_bf16 v[104:107], v[140:143], v[156:159], v[104:107]
	v_mfma_f32_16x16x32_bf16 v[92:95], v[132:135], v[174:177], v[92:95]
	v_mfma_f32_16x16x32_bf16 v[88:91], v[140:143], v[174:177], v[88:91]
	v_mfma_f32_16x16x32_bf16 v[76:79], v[132:135], v[186:189], v[76:79]
	v_mfma_f32_16x16x32_bf16 v[72:75], v[140:143], v[186:189], v[72:75]
	s_barrier
	ds_read_b128 v[196:199], v220 offset:49152
	ds_read_b128 v[204:207], v220 offset:50176
	ds_read_b128 v[208:211], v220 offset:51200
	ds_read_b128 v[214:217], v220 offset:52224
	global_load_lds_dwordx4 v192, s[16:17] offset:128
	s_add_i32 m0, s19, 0x1f80
	s_nop 0
	global_load_lds_dwordx4 v164, s[16:17] offset:128
	s_barrier
	s_waitcnt lgkmcnt(0)
	v_mfma_f32_16x16x32_bf16 v[116:119], v[196:199], v[144:147], v[116:119]
	v_mfma_f32_16x16x32_bf16 v[112:115], v[208:211], v[144:147], v[112:115]
	s_mov_b32 m0, s35
	v_mfma_f32_16x16x32_bf16 v[100:103], v[196:199], v[152:155], v[100:103]
	v_mfma_f32_16x16x32_bf16 v[96:99], v[208:211], v[152:155], v[96:99]
	v_mfma_f32_16x16x32_bf16 v[84:87], v[196:199], v[170:173], v[84:87]
	v_mfma_f32_16x16x32_bf16 v[80:83], v[208:211], v[170:173], v[80:83]
	v_mfma_f32_16x16x32_bf16 v[68:71], v[196:199], v[178:181], v[68:71]
	v_mfma_f32_16x16x32_bf16 v[64:67], v[208:211], v[178:181], v[64:67]
	v_mfma_f32_16x16x32_bf16 v[116:119], v[204:207], v[148:151], v[116:119]
	v_mfma_f32_16x16x32_bf16 v[112:115], v[214:217], v[148:151], v[112:115]
	v_mfma_f32_16x16x32_bf16 v[100:103], v[204:207], v[156:159], v[100:103]
	v_mfma_f32_16x16x32_bf16 v[96:99], v[214:217], v[156:159], v[96:99]
	v_mfma_f32_16x16x32_bf16 v[84:87], v[204:207], v[174:177], v[84:87]
	v_mfma_f32_16x16x32_bf16 v[80:83], v[214:217], v[174:177], v[80:83]
	v_mfma_f32_16x16x32_bf16 v[68:71], v[204:207], v[186:189], v[68:71]
	v_mfma_f32_16x16x32_bf16 v[64:67], v[214:217], v[186:189], v[64:67]
	s_barrier
	ds_read_b128 v[144:147], v185 offset:49152
	ds_read_b128 v[148:151], v185 offset:50176
	ds_read_b128 v[152:155], v185 offset:51200
	ds_read_b128 v[156:159], v185 offset:52224
	ds_read_b128 v[170:173], v185 offset:53248
	ds_read_b128 v[174:177], v185 offset:54272
	ds_read_b128 v[178:181], v185 offset:55296
	ds_read_b128 v[186:189], v185 offset:56320
	global_load_lds_dwordx4 v160, s[48:49]
	s_mov_b32 m0, s36
	s_nop 0
	global_load_lds_dwordx4 v162, s[48:49]
	s_barrier
	s_waitcnt lgkmcnt(0)
	v_mfma_f32_16x16x32_bf16 v[60:63], v[128:131], v[144:147], v[60:63]
	v_mfma_f32_16x16x32_bf16 v[56:59], v[136:139], v[144:147], v[56:59]
	s_add_u32 s16, s16, 0x80080
	v_mfma_f32_16x16x32_bf16 v[44:47], v[128:131], v[152:155], v[44:47]
	s_addc_u32 s17, s17, 0
	v_mfma_f32_16x16x32_bf16 v[40:43], v[136:139], v[152:155], v[40:43]
	s_add_i32 s18, s18, s27
	v_mfma_f32_16x16x32_bf16 v[28:31], v[128:131], v[170:173], v[28:31]
	s_mov_b32 m0, s18
	v_mfma_f32_16x16x32_bf16 v[24:27], v[136:139], v[170:173], v[24:27]
	v_mfma_f32_16x16x32_bf16 v[12:15], v[128:131], v[178:181], v[12:15]
	v_mfma_f32_16x16x32_bf16 v[8:11], v[136:139], v[178:181], v[8:11]
	v_mfma_f32_16x16x32_bf16 v[60:63], v[132:135], v[148:151], v[60:63]
	v_mfma_f32_16x16x32_bf16 v[56:59], v[140:143], v[148:151], v[56:59]
	v_mfma_f32_16x16x32_bf16 v[44:47], v[132:135], v[156:159], v[44:47]
	v_mfma_f32_16x16x32_bf16 v[40:43], v[140:143], v[156:159], v[40:43]
	v_mfma_f32_16x16x32_bf16 v[28:31], v[132:135], v[174:177], v[28:31]
	v_mfma_f32_16x16x32_bf16 v[24:27], v[140:143], v[174:177], v[24:27]
	v_mfma_f32_16x16x32_bf16 v[12:15], v[132:135], v[186:189], v[12:15]
	v_mfma_f32_16x16x32_bf16 v[8:11], v[140:143], v[186:189], v[8:11]
	s_barrier
	global_load_lds_dwordx4 v192, s[16:17]
	s_add_i32 m0, s18, 0x2000
	s_nop 0
	global_load_lds_dwordx4 v164, s[16:17]
	s_waitcnt vmcnt(6)
	s_barrier
	v_mfma_f32_16x16x32_bf16 v[52:55], v[196:199], v[144:147], v[52:55]
	v_mfma_f32_16x16x32_bf16 v[48:51], v[208:211], v[144:147], v[48:51]
	s_add_i32 s42, s42, 2
	v_mfma_f32_16x16x32_bf16 v[36:39], v[196:199], v[152:155], v[36:39]
	s_add_u32 s14, s14, 0x100
	v_mfma_f32_16x16x32_bf16 v[32:35], v[208:211], v[152:155], v[32:35]
	s_addc_u32 s15, s15, 0
	v_mfma_f32_16x16x32_bf16 v[20:23], v[196:199], v[170:173], v[20:23]
	s_add_u32 s40, s40, 0x100
	v_mfma_f32_16x16x32_bf16 v[16:19], v[208:211], v[170:173], v[16:19]
	s_addc_u32 s41, s41, 0
	v_mfma_f32_16x16x32_bf16 v[4:7], v[196:199], v[178:181], v[4:7]
	s_add_u32 s16, s14, 0xfff80080
	s_addc_u32 s17, s15, -1
	v_mfma_f32_16x16x32_bf16 v[0:3], v[208:211], v[178:181], v[0:3]
	s_add_i32 s43, 0, 0x10000
	s_cmp_eq_u32 s42, 28
	v_mfma_f32_16x16x32_bf16 v[52:55], v[204:207], v[148:151], v[52:55]
	s_cselect_b32 s19, s7, s17
	s_cselect_b32 s18, s38, s16
	v_mfma_f32_16x16x32_bf16 v[48:51], v[214:217], v[148:151], v[48:51]
	s_cselect_b32 s17, s5, s41
	s_cselect_b32 s16, s39, s40
	v_mfma_f32_16x16x32_bf16 v[36:39], v[204:207], v[156:159], v[36:39]
	s_add_i32 m0, s28, 0xc000
	v_mfma_f32_16x16x32_bf16 v[32:35], v[214:217], v[156:159], v[32:35]
	v_mfma_f32_16x16x32_bf16 v[20:23], v[204:207], v[174:177], v[20:23]
	v_mfma_f32_16x16x32_bf16 v[16:19], v[214:217], v[174:177], v[16:19]
	v_mfma_f32_16x16x32_bf16 v[4:7], v[204:207], v[186:189], v[4:7]
	v_mfma_f32_16x16x32_bf16 v[0:3], v[214:217], v[186:189], v[0:3]
	s_cmp_gt_u32 s42, 29
	s_barrier
.LBB0_87:
	ds_read_b128 v[128:131], v220 offset:0
	ds_read_b128 v[132:135], v220 offset:1024
	ds_read_b128 v[136:139], v220 offset:2048
	ds_read_b128 v[140:143], v220 offset:3072
	ds_read_b128 v[144:147], v185
	ds_read_b128 v[148:151], v185 offset:1024
	ds_read_b128 v[152:155], v185 offset:2048
	ds_read_b128 v[156:159], v185 offset:3072
	ds_read_b128 v[170:173], v185 offset:4096
	ds_read_b128 v[174:177], v185 offset:5120
	ds_read_b128 v[178:181], v185 offset:6144
	ds_read_b128 v[186:189], v185 offset:7168
	global_load_lds_dwordx4 v166, s[14:15]
	s_add_i32 m0, s28, 0xe000
	s_nop 0
	global_load_lds_dwordx4 v168, s[14:15]
	s_waitcnt lgkmcnt(8)
	s_barrier
	s_waitcnt lgkmcnt(0)
	v_mfma_f32_16x16x32_bf16 v[124:127], v[128:131], v[144:147], v[124:127]
	v_mfma_f32_16x16x32_bf16 v[120:123], v[136:139], v[144:147], v[120:123]
	s_add_i32 s46, 0, 0x14000
	v_mfma_f32_16x16x32_bf16 v[108:111], v[128:131], v[152:155], v[108:111]
	s_add_i32 s43, s43, s27
	v_mfma_f32_16x16x32_bf16 v[104:107], v[136:139], v[152:155], v[104:107]
	s_mov_b32 m0, s43
	v_mfma_f32_16x16x32_bf16 v[92:95], v[128:131], v[170:173], v[92:95]
	v_mfma_f32_16x16x32_bf16 v[88:91], v[136:139], v[170:173], v[88:91]
	v_mfma_f32_16x16x32_bf16 v[76:79], v[128:131], v[178:181], v[76:79]
	v_mfma_f32_16x16x32_bf16 v[72:75], v[136:139], v[178:181], v[72:75]
	v_mfma_f32_16x16x32_bf16 v[124:127], v[132:135], v[148:151], v[124:127]
	v_mfma_f32_16x16x32_bf16 v[120:123], v[140:143], v[148:151], v[120:123]
	v_mfma_f32_16x16x32_bf16 v[108:111], v[132:135], v[156:159], v[108:111]
	v_mfma_f32_16x16x32_bf16 v[104:107], v[140:143], v[156:159], v[104:107]
	v_mfma_f32_16x16x32_bf16 v[92:95], v[132:135], v[174:177], v[92:95]
	v_mfma_f32_16x16x32_bf16 v[88:91], v[140:143], v[174:177], v[88:91]
	v_mfma_f32_16x16x32_bf16 v[76:79], v[132:135], v[186:189], v[76:79]
	v_mfma_f32_16x16x32_bf16 v[72:75], v[140:143], v[186:189], v[72:75]
	s_barrier
	ds_read_b128 v[196:199], v220 offset:16384
	ds_read_b128 v[204:207], v220 offset:17408
	ds_read_b128 v[208:211], v220 offset:18432
	ds_read_b128 v[214:217], v220 offset:19456
	global_load_lds_dwordx4 v192, s[16:17]
	s_add_i32 m0, s43, 0x2000
	s_nop 0
	global_load_lds_dwordx4 v164, s[16:17]
	s_barrier
	s_waitcnt lgkmcnt(0)
	v_mfma_f32_16x16x32_bf16 v[116:119], v[196:199], v[144:147], v[116:119]
	v_mfma_f32_16x16x32_bf16 v[112:115], v[208:211], v[144:147], v[112:115]
	s_mov_b32 m0, s28
	v_mfma_f32_16x16x32_bf16 v[100:103], v[196:199], v[152:155], v[100:103]
	s_add_u32 s48, s18, 0x80
	v_mfma_f32_16x16x32_bf16 v[96:99], v[208:211], v[152:155], v[96:99]
	s_addc_u32 s49, s19, 0
	v_mfma_f32_16x16x32_bf16 v[84:87], v[196:199], v[170:173], v[84:87]
	v_mfma_f32_16x16x32_bf16 v[80:83], v[208:211], v[170:173], v[80:83]
	v_mfma_f32_16x16x32_bf16 v[68:71], v[196:199], v[178:181], v[68:71]
	v_mfma_f32_16x16x32_bf16 v[64:67], v[208:211], v[178:181], v[64:67]
	v_mfma_f32_16x16x32_bf16 v[116:119], v[204:207], v[148:151], v[116:119]
	v_mfma_f32_16x16x32_bf16 v[112:115], v[214:217], v[148:151], v[112:115]
	v_mfma_f32_16x16x32_bf16 v[100:103], v[204:207], v[156:159], v[100:103]
	v_mfma_f32_16x16x32_bf16 v[96:99], v[214:217], v[156:159], v[96:99]
	v_mfma_f32_16x16x32_bf16 v[84:87], v[204:207], v[174:177], v[84:87]
	v_mfma_f32_16x16x32_bf16 v[80:83], v[214:217], v[174:177], v[80:83]
	v_mfma_f32_16x16x32_bf16 v[68:71], v[204:207], v[186:189], v[68:71]
	v_mfma_f32_16x16x32_bf16 v[64:67], v[214:217], v[186:189], v[64:67]
	s_barrier
	ds_read_b128 v[144:147], v185 offset:16384
	ds_read_b128 v[148:151], v185 offset:17408
	ds_read_b128 v[152:155], v185 offset:18432
	ds_read_b128 v[156:159], v185 offset:19456
	ds_read_b128 v[170:173], v185 offset:20480
	ds_read_b128 v[174:177], v185 offset:21504
	ds_read_b128 v[178:181], v185 offset:22528
	ds_read_b128 v[186:189], v185 offset:23552
	global_load_lds_dwordx4 v160, s[18:19]
	s_mov_b32 m0, s29
	s_nop 0
	global_load_lds_dwordx4 v162, s[18:19]
	s_barrier
	s_waitcnt lgkmcnt(0)
	v_mfma_f32_16x16x32_bf16 v[60:63], v[128:131], v[144:147], v[60:63]
	v_mfma_f32_16x16x32_bf16 v[56:59], v[136:139], v[144:147], v[56:59]
	s_add_u32 s44, s16, 0x80000
	v_mfma_f32_16x16x32_bf16 v[44:47], v[128:131], v[152:155], v[44:47]
	s_addc_u32 s45, s17, 0
	v_mfma_f32_16x16x32_bf16 v[40:43], v[136:139], v[152:155], v[40:43]
	s_add_i32 s43, s46, s27
	v_mfma_f32_16x16x32_bf16 v[28:31], v[128:131], v[170:173], v[28:31]
	s_mov_b32 m0, s43
	v_mfma_f32_16x16x32_bf16 v[24:27], v[136:139], v[170:173], v[24:27]
	v_mfma_f32_16x16x32_bf16 v[12:15], v[128:131], v[178:181], v[12:15]
	v_mfma_f32_16x16x32_bf16 v[8:11], v[136:139], v[178:181], v[8:11]
	v_mfma_f32_16x16x32_bf16 v[60:63], v[132:135], v[148:151], v[60:63]
	v_mfma_f32_16x16x32_bf16 v[56:59], v[140:143], v[148:151], v[56:59]
	v_mfma_f32_16x16x32_bf16 v[44:47], v[132:135], v[156:159], v[44:47]
	v_mfma_f32_16x16x32_bf16 v[40:43], v[140:143], v[156:159], v[40:43]
	v_mfma_f32_16x16x32_bf16 v[28:31], v[132:135], v[174:177], v[28:31]
	v_mfma_f32_16x16x32_bf16 v[24:27], v[140:143], v[174:177], v[24:27]
	v_mfma_f32_16x16x32_bf16 v[12:15], v[132:135], v[186:189], v[12:15]
	v_mfma_f32_16x16x32_bf16 v[8:11], v[140:143], v[186:189], v[8:11]
	s_barrier
	global_load_lds_dwordx4 v192, s[44:45]
	s_add_i32 m0, s43, 0x2000
	s_nop 0
	global_load_lds_dwordx4 v164, s[44:45]
	s_waitcnt vmcnt(6)
	s_barrier
	v_mfma_f32_16x16x32_bf16 v[52:55], v[196:199], v[144:147], v[52:55]
	v_mfma_f32_16x16x32_bf16 v[48:51], v[208:211], v[144:147], v[48:51]
	s_add_i32 s43, 0, 0x18000
	v_mfma_f32_16x16x32_bf16 v[36:39], v[196:199], v[152:155], v[36:39]
	s_add_u32 s18, s18, 0x80000
	v_mfma_f32_16x16x32_bf16 v[32:35], v[208:211], v[152:155], v[32:35]
	s_addc_u32 s19, s19, 0
	v_mfma_f32_16x16x32_bf16 v[20:23], v[196:199], v[170:173], v[20:23]
	s_mov_b32 m0, s30
	v_mfma_f32_16x16x32_bf16 v[16:19], v[208:211], v[170:173], v[16:19]
	v_mfma_f32_16x16x32_bf16 v[4:7], v[196:199], v[178:181], v[4:7]
	v_mfma_f32_16x16x32_bf16 v[0:3], v[208:211], v[178:181], v[0:3]
	v_mfma_f32_16x16x32_bf16 v[52:55], v[204:207], v[148:151], v[52:55]
	v_mfma_f32_16x16x32_bf16 v[48:51], v[214:217], v[148:151], v[48:51]
	v_mfma_f32_16x16x32_bf16 v[36:39], v[204:207], v[156:159], v[36:39]
	v_mfma_f32_16x16x32_bf16 v[32:35], v[214:217], v[156:159], v[32:35]
	v_mfma_f32_16x16x32_bf16 v[20:23], v[204:207], v[174:177], v[20:23]
	v_mfma_f32_16x16x32_bf16 v[16:19], v[214:217], v[174:177], v[16:19]
	v_mfma_f32_16x16x32_bf16 v[4:7], v[204:207], v[186:189], v[4:7]
	v_mfma_f32_16x16x32_bf16 v[0:3], v[214:217], v[186:189], v[0:3]
	s_barrier
	ds_read_b128 v[128:131], v220 offset:32768
	ds_read_b128 v[132:135], v220 offset:33792
	ds_read_b128 v[136:139], v220 offset:34816
	ds_read_b128 v[140:143], v220 offset:35840
	ds_read_b128 v[144:147], v185 offset:32768
	ds_read_b128 v[148:151], v185 offset:33792
	ds_read_b128 v[152:155], v185 offset:34816
	ds_read_b128 v[156:159], v185 offset:35840
	ds_read_b128 v[170:173], v185 offset:36864
	ds_read_b128 v[174:177], v185 offset:37888
	ds_read_b128 v[178:181], v185 offset:38912
	ds_read_b128 v[186:189], v185 offset:39936
	global_load_lds_dwordx4 v160, s[18:19]
	s_mov_b32 m0, s31
	s_nop 0
	global_load_lds_dwordx4 v162, s[18:19]
	s_waitcnt lgkmcnt(8)
	s_barrier
	s_waitcnt lgkmcnt(0)
	v_mfma_f32_16x16x32_bf16 v[124:127], v[128:131], v[144:147], v[124:127]
	v_mfma_f32_16x16x32_bf16 v[120:123], v[136:139], v[144:147], v[120:123]
	s_add_i32 s18, 0, 0x1c000
	v_mfma_f32_16x16x32_bf16 v[108:111], v[128:131], v[152:155], v[108:111]
	s_add_i32 s19, s43, s27
	v_mfma_f32_16x16x32_bf16 v[104:107], v[136:139], v[152:155], v[104:107]
	s_add_i32 m0, s19, 0xffffff80
	v_mfma_f32_16x16x32_bf16 v[92:95], v[128:131], v[170:173], v[92:95]
	v_mfma_f32_16x16x32_bf16 v[88:91], v[136:139], v[170:173], v[88:91]
	v_mfma_f32_16x16x32_bf16 v[76:79], v[128:131], v[178:181], v[76:79]
	v_mfma_f32_16x16x32_bf16 v[72:75], v[136:139], v[178:181], v[72:75]
	v_mfma_f32_16x16x32_bf16 v[124:127], v[132:135], v[148:151], v[124:127]
	v_mfma_f32_16x16x32_bf16 v[120:123], v[140:143], v[148:151], v[120:123]
	v_mfma_f32_16x16x32_bf16 v[108:111], v[132:135], v[156:159], v[108:111]
	v_mfma_f32_16x16x32_bf16 v[104:107], v[140:143], v[156:159], v[104:107]
	v_mfma_f32_16x16x32_bf16 v[92:95], v[132:135], v[174:177], v[92:95]
	v_mfma_f32_16x16x32_bf16 v[88:91], v[140:143], v[174:177], v[88:91]
	v_mfma_f32_16x16x32_bf16 v[76:79], v[132:135], v[186:189], v[76:79]
	v_mfma_f32_16x16x32_bf16 v[72:75], v[140:143], v[186:189], v[72:75]
	s_barrier
	ds_read_b128 v[196:199], v220 offset:49152
	ds_read_b128 v[204:207], v220 offset:50176
	ds_read_b128 v[208:211], v220 offset:51200
	ds_read_b128 v[214:217], v220 offset:52224
	global_load_lds_dwordx4 v192, s[16:17] offset:128
	s_add_i32 m0, s19, 0x1f80
	s_nop 0
	global_load_lds_dwordx4 v164, s[16:17] offset:128
	s_barrier
	s_waitcnt lgkmcnt(0)
	v_mfma_f32_16x16x32_bf16 v[116:119], v[196:199], v[144:147], v[116:119]
	v_mfma_f32_16x16x32_bf16 v[112:115], v[208:211], v[144:147], v[112:115]
	s_mov_b32 m0, s35
	v_mfma_f32_16x16x32_bf16 v[100:103], v[196:199], v[152:155], v[100:103]
	v_mfma_f32_16x16x32_bf16 v[96:99], v[208:211], v[152:155], v[96:99]
	v_mfma_f32_16x16x32_bf16 v[84:87], v[196:199], v[170:173], v[84:87]
	v_mfma_f32_16x16x32_bf16 v[80:83], v[208:211], v[170:173], v[80:83]
	v_mfma_f32_16x16x32_bf16 v[68:71], v[196:199], v[178:181], v[68:71]
	v_mfma_f32_16x16x32_bf16 v[64:67], v[208:211], v[178:181], v[64:67]
	v_mfma_f32_16x16x32_bf16 v[116:119], v[204:207], v[148:151], v[116:119]
	v_mfma_f32_16x16x32_bf16 v[112:115], v[214:217], v[148:151], v[112:115]
	v_mfma_f32_16x16x32_bf16 v[100:103], v[204:207], v[156:159], v[100:103]
	v_mfma_f32_16x16x32_bf16 v[96:99], v[214:217], v[156:159], v[96:99]
	v_mfma_f32_16x16x32_bf16 v[84:87], v[204:207], v[174:177], v[84:87]
	v_mfma_f32_16x16x32_bf16 v[80:83], v[214:217], v[174:177], v[80:83]
	v_mfma_f32_16x16x32_bf16 v[68:71], v[204:207], v[186:189], v[68:71]
	v_mfma_f32_16x16x32_bf16 v[64:67], v[214:217], v[186:189], v[64:67]
	s_barrier
	ds_read_b128 v[144:147], v185 offset:49152
	ds_read_b128 v[148:151], v185 offset:50176
	ds_read_b128 v[152:155], v185 offset:51200
	ds_read_b128 v[156:159], v185 offset:52224
	ds_read_b128 v[170:173], v185 offset:53248
	ds_read_b128 v[174:177], v185 offset:54272
	ds_read_b128 v[178:181], v185 offset:55296
	ds_read_b128 v[186:189], v185 offset:56320
	global_load_lds_dwordx4 v160, s[48:49]
	s_mov_b32 m0, s36
	s_nop 0
	global_load_lds_dwordx4 v162, s[48:49]
	s_barrier
	s_waitcnt lgkmcnt(0)
	v_mfma_f32_16x16x32_bf16 v[60:63], v[128:131], v[144:147], v[60:63]
	v_mfma_f32_16x16x32_bf16 v[56:59], v[136:139], v[144:147], v[56:59]
	s_add_u32 s16, s16, 0x80080
	v_mfma_f32_16x16x32_bf16 v[44:47], v[128:131], v[152:155], v[44:47]
	s_addc_u32 s17, s17, 0
	v_mfma_f32_16x16x32_bf16 v[40:43], v[136:139], v[152:155], v[40:43]
	s_add_i32 s18, s18, s27
	v_mfma_f32_16x16x32_bf16 v[28:31], v[128:131], v[170:173], v[28:31]
	s_mov_b32 m0, s18
	v_mfma_f32_16x16x32_bf16 v[24:27], v[136:139], v[170:173], v[24:27]
	v_mfma_f32_16x16x32_bf16 v[12:15], v[128:131], v[178:181], v[12:15]
	v_mfma_f32_16x16x32_bf16 v[8:11], v[136:139], v[178:181], v[8:11]
	v_mfma_f32_16x16x32_bf16 v[60:63], v[132:135], v[148:151], v[60:63]
	v_mfma_f32_16x16x32_bf16 v[56:59], v[140:143], v[148:151], v[56:59]
	v_mfma_f32_16x16x32_bf16 v[44:47], v[132:135], v[156:159], v[44:47]
	v_mfma_f32_16x16x32_bf16 v[40:43], v[140:143], v[156:159], v[40:43]
	v_mfma_f32_16x16x32_bf16 v[28:31], v[132:135], v[174:177], v[28:31]
	v_mfma_f32_16x16x32_bf16 v[24:27], v[140:143], v[174:177], v[24:27]
	v_mfma_f32_16x16x32_bf16 v[12:15], v[132:135], v[186:189], v[12:15]
	v_mfma_f32_16x16x32_bf16 v[8:11], v[140:143], v[186:189], v[8:11]
	s_barrier
	global_load_lds_dwordx4 v192, s[16:17]
	s_add_i32 m0, s18, 0x2000
	s_nop 0
	global_load_lds_dwordx4 v164, s[16:17]
	s_waitcnt vmcnt(6)
	s_barrier
	v_mfma_f32_16x16x32_bf16 v[52:55], v[196:199], v[144:147], v[52:55]
	v_mfma_f32_16x16x32_bf16 v[48:51], v[208:211], v[144:147], v[48:51]
	s_add_i32 s42, s42, 2
	v_mfma_f32_16x16x32_bf16 v[36:39], v[196:199], v[152:155], v[36:39]
	s_add_u32 s14, s14, 0x100
	v_mfma_f32_16x16x32_bf16 v[32:35], v[208:211], v[152:155], v[32:35]
	s_addc_u32 s15, s15, 0
	v_mfma_f32_16x16x32_bf16 v[20:23], v[196:199], v[170:173], v[20:23]
	s_add_u32 s40, s40, 0x100
	v_mfma_f32_16x16x32_bf16 v[16:19], v[208:211], v[170:173], v[16:19]
	s_addc_u32 s41, s41, 0
	v_mfma_f32_16x16x32_bf16 v[4:7], v[196:199], v[178:181], v[4:7]
	s_add_u32 s16, s14, 0xfff80080
	s_addc_u32 s17, s15, -1
	v_mfma_f32_16x16x32_bf16 v[0:3], v[208:211], v[178:181], v[0:3]
	s_add_i32 s43, 0, 0x10000
	s_cmp_eq_u32 s42, 28
	v_mfma_f32_16x16x32_bf16 v[52:55], v[204:207], v[148:151], v[52:55]
	s_cselect_b32 s19, s7, s17
	s_cselect_b32 s18, s38, s16
	v_mfma_f32_16x16x32_bf16 v[48:51], v[214:217], v[148:151], v[48:51]
	s_cselect_b32 s17, s5, s41
	s_cselect_b32 s16, s39, s40
	v_mfma_f32_16x16x32_bf16 v[36:39], v[204:207], v[156:159], v[36:39]
	s_add_i32 m0, s28, 0xc000
	v_mfma_f32_16x16x32_bf16 v[32:35], v[214:217], v[156:159], v[32:35]
	v_mfma_f32_16x16x32_bf16 v[20:23], v[204:207], v[174:177], v[20:23]
	v_mfma_f32_16x16x32_bf16 v[16:19], v[214:217], v[174:177], v[16:19]
	v_mfma_f32_16x16x32_bf16 v[4:7], v[204:207], v[186:189], v[4:7]
	v_mfma_f32_16x16x32_bf16 v[0:3], v[214:217], v[186:189], v[0:3]
	s_cmp_gt_u32 s42, 29
	s_barrier
	s_cbranch_scc0 .LBB0_87
	v_lshl_or_b32 v128, s13, 8, v184
	v_lshl_add_u32 v172, s12, 8, v182
	v_ashrrev_i32_e32 v129, 31, v128
	v_lshlrev_b64 v[170:171], 1, v[128:129]
	v_ashrrev_i32_e32 v173, 31, v172
	v_lshl_add_u64 v[174:175], s[2:3], 0, v[170:171]
	v_lshlrev_b64 v[128:129], 13, v[172:173]
	v_lshl_add_u64 v[130:131], v[174:175], 0, v[128:129]
	global_load_dwordx4 v[186:189], v[130:131], off
	global_load_dwordx4 v[196:199], v[130:131], off offset:256
	s_lshl_b32 s5, s13, 1
	v_mul_f32_e32 v133, 0xbfb8aa3b, v124
	v_mul_f32_e32 v135, 0xbfb8aa3b, v125
	v_mul_f32_e32 v137, 0xbfb8aa3b, v126
	v_mul_f32_e32 v138, 0xbfb8aa3b, v127
	v_mul_f32_e32 v139, 0xbfb8aa3b, v120
	v_mul_f32_e32 v140, 0xbfb8aa3b, v121
	s_and_b32 s12, s5, -4
	v_or_b32_e32 v132, 16, v172
	v_or_b32_e32 v136, 48, v172
	v_exp_f32_e32 v148, v133
	v_exp_f32_e32 v149, v135
	v_exp_f32_e32 v150, v137
	v_exp_f32_e32 v151, v138
	v_exp_f32_e32 v204, v139
	v_exp_f32_e32 v205, v140
	s_ashr_i32 s13, s12, 31
	v_or_b32_e32 v134, 32, v172
	v_ashrrev_i32_e32 v133, 31, v132
	v_ashrrev_i32_e32 v137, 31, v136
	s_lshl_b64 s[12:13], s[12:13], 2
	v_mul_f32_e32 v141, 0xbfb8aa3b, v122
	v_ashrrev_i32_e32 v135, 31, v134
	v_lshlrev_b64 v[180:181], 13, v[132:133]
	v_lshlrev_b64 v[176:177], 13, v[136:137]
	s_add_u32 s12, s33, s12
	v_exp_f32_e32 v212, v141
	v_lshlrev_b64 v[138:139], 7, v[172:173]
	v_lshlrev_b64 v[140:141], 7, v[132:133]
	v_lshlrev_b64 v[142:143], 7, v[134:135]
	v_lshlrev_b64 v[178:179], 13, v[134:135]
	v_lshlrev_b64 v[144:145], 7, v[136:137]
	v_lshl_add_u64 v[128:129], s[2:3], 0, v[128:129]
	v_lshl_add_u64 v[130:131], v[174:175], 0, v[180:181]
	v_lshl_add_u64 v[136:137], v[174:175], 0, v[176:177]
	s_addc_u32 s13, s34, s13
	v_lshl_add_u64 v[146:147], v[174:175], 0, v[178:179]
	v_lshl_add_u64 v[190:191], v[128:129], 0, v[170:171]
	global_load_dwordx4 v[156:159], v[130:131], off
	global_load_dwordx4 v[152:155], v[130:131], off offset:256
	global_load_dwordx4 v[132:135], v[136:137], off
	s_nop 0
	global_load_dwordx4 v[128:131], v[136:137], off offset:256
	v_add_f32_e32 v148, 1.0, v148
	v_add_f32_e32 v149, 1.0, v149
	v_add_f32_e32 v150, 1.0, v150
	v_add_f32_e32 v151, 1.0, v151
	v_add_f32_e32 v173, 1.0, v204
	v_add_f32_e32 v204, 1.0, v205
	v_lshl_add_u64 v[136:137], s[12:13], 0, v[138:139]
	v_lshl_add_u64 v[138:139], s[12:13], 0, v[140:141]
	v_lshl_add_u64 v[140:141], s[12:13], 0, v[142:143]
	v_lshl_add_u64 v[144:145], s[12:13], 0, v[144:145]
	v_rcp_f32_e32 v214, v148
	v_rcp_f32_e32 v215, v149
	v_rcp_f32_e32 v216, v150
	v_rcp_f32_e32 v217, v151
	v_rcp_f32_e32 v218, v204
	global_load_dwordx4 v[204:207], v[136:137], off
	global_load_dwordx4 v[208:211], v[138:139], off
	s_nop 0
	global_load_dwordx4 v[136:139], v[140:141], off
	global_load_dwordx4 v[148:151], v[146:147], off
	s_nop 0
	global_load_dwordx4 v[140:143], v[146:147], off offset:256
	s_nop 0
	global_load_dwordx4 v[144:147], v[144:145], off
	v_rcp_f32_e32 v173, v173
	v_mul_f32_e32 v124, v124, v214
	v_mul_f32_e32 v125, v125, v215
	v_mul_f32_e32 v127, v127, v217
	v_mul_f32_e32 v120, v120, v173
	v_mul_f32_e32 v121, v121, v218
	s_mov_b32 s14, 0x358637bd
	s_mov_b32 s5, 0x800000
	v_mul_f32_e32 v126, v126, v216
	s_mov_b64 s[16:17], s[10:11]
	s_mov_b32 s11, 0xc000
	s_waitcnt vmcnt(0)
	v_lshlrev_b32_e32 v173, 16, v186
	v_and_b32_e32 v186, 0xffff0000, v186
	v_lshlrev_b32_e32 v214, 16, v187
	v_and_b32_e32 v187, 0xffff0000, v187
	v_mul_f32_e32 v125, v125, v186
	v_mul_f32_e32 v127, v127, v187
	v_add_f32_e32 v186, 1.0, v212
	v_mul_f32_e32 v187, 0xbfb8aa3b, v123
	v_rcp_f32_e32 v186, v186
	v_exp_f32_e32 v187, v187
	v_mul_f32_e32 v124, v124, v173
	v_and_b32_e32 v173, 0xffff0000, v188
	v_mul_f32_e32 v122, v122, v186
	v_add_f32_e32 v186, 1.0, v187
	v_mul_f32_e32 v187, 0xbfb8aa3b, v116
	v_rcp_f32_e32 v186, v186
	v_exp_f32_e32 v187, v187
	v_mul_f32_e32 v121, v121, v173
	v_lshlrev_b32_e32 v173, 16, v189
	v_mul_f32_e32 v123, v123, v186
	v_add_f32_e32 v186, 1.0, v187
	v_mul_f32_e32 v187, 0xbfb8aa3b, v117
	v_rcp_f32_e32 v186, v186
	v_exp_f32_e32 v187, v187
	v_mul_f32_e32 v122, v122, v173
	v_and_b32_e32 v173, 0xffff0000, v189
	v_mul_f32_e32 v116, v116, v186
	v_add_f32_e32 v186, 1.0, v187
	v_mul_f32_e32 v187, 0xbfb8aa3b, v118
	v_rcp_f32_e32 v186, v186
	v_exp_f32_e32 v187, v187
	v_mul_f32_e32 v123, v123, v173
	v_lshlrev_b32_e32 v173, 16, v196
	v_mul_f32_e32 v173, v116, v173
	v_mul_f32_e32 v116, v117, v186
	v_add_f32_e32 v186, 1.0, v187
	v_mul_f32_e32 v187, 0xbfb8aa3b, v119
	v_rcp_f32_e32 v186, v186
	v_exp_f32_e32 v187, v187
	v_and_b32_e32 v117, 0xffff0000, v196
	v_lshlrev_b32_e32 v215, 16, v188
	v_mul_f32_e32 v188, v116, v117
	v_mul_f32_e32 v116, v118, v186
	v_add_f32_e32 v118, 1.0, v187
	v_rcp_f32_e32 v118, v118
	v_mul_f32_e32 v186, 0xbfb8aa3b, v112
	v_exp_f32_e32 v186, v186
	v_lshlrev_b32_e32 v117, 16, v197
	v_mul_f32_e32 v187, v116, v117
	v_mul_f32_e32 v116, v119, v118
	v_mul_f32_e32 v119, 0xbfb8aa3b, v113
	v_add_f32_e32 v118, 1.0, v186
	v_exp_f32_e32 v119, v119
	v_rcp_f32_e32 v118, v118
	v_and_b32_e32 v117, 0xffff0000, v197
	v_mul_f32_e32 v186, v116, v117
	v_add_f32_e32 v117, 1.0, v119
	v_mul_f32_e32 v112, v112, v118
	v_rcp_f32_e32 v117, v117
	v_mul_f32_e32 v118, 0xbfb8aa3b, v114
	v_exp_f32_e32 v118, v118
	v_lshlrev_b32_e32 v116, 16, v198
	v_mul_f32_e32 v189, v112, v116
	v_mul_f32_e32 v112, v113, v117
	v_and_b32_e32 v113, 0xffff0000, v198
	v_add_f32_e32 v116, 1.0, v118
	v_mul_f32_e32 v196, v112, v113
	v_mul_f32_e32 v112, 0xbfb8aa3b, v115
	v_rcp_f32_e32 v116, v116
	v_exp_f32_e32 v112, v112
	v_mov_b32_e32 v117, v206
	v_mov_b32_e32 v206, v211
	v_mul_f32_e32 v113, v114, v116
	v_lshlrev_b32_e32 v114, 16, v199
	v_add_f32_e32 v112, 1.0, v112
	v_mul_f32_e32 v197, v113, v114
	v_rcp_f32_e32 v114, v112
	v_mov_b32_e32 v112, v208
	v_mov_b32_e32 v113, v204
	v_mov_b32_e32 v204, v209
	v_pk_add_f32 v[112:113], v[112:113], v[204:205]
	v_mov_b32_e32 v116, v210
	v_pk_add_f32 v[112:113], v[116:117], v[112:113]
	v_mul_f32_e32 v114, v115, v114
	v_pk_add_f32 v[116:117], v[206:207], v[112:113]
	v_mov_b64_e32 v[112:113], s[14:15]
	s_mov_b32 s14, 0x3b000000
	v_pk_fma_f32 v[118:119], v[116:117], s[14:15], v[112:113] op_sel_hi:[1,0,0]
	v_and_b32_e32 v115, 0xffff0000, v199
	v_mul_f32_e32 v116, 0x4b800000, v119
	v_cmp_gt_f32_e32 vcc, s5, v119
	v_mul_f32_e32 v126, v126, v214
	v_mul_f32_e32 v120, v120, v215
	v_cndmask_b32_e32 v116, v119, v116, vcc
	v_rsq_f32_e32 v116, v116
	v_mul_f32_e32 v119, v114, v115
	v_mul_f32_e32 v114, 0x45800000, v116
	v_cndmask_b32_e32 v198, v116, v114, vcc
	v_mul_f32_e32 v114, v124, v198
	v_mul_f32_e32 v115, v125, v198
	v_cvt_pk_bf16_f32 v114, v114, v115
	v_mul_f32_e32 v115, v126, v198
	v_mul_f32_e32 v116, v127, v198
	v_cvt_pk_bf16_f32 v115, v115, v116
	v_mul_f32_e32 v116, v120, v198
	v_mul_f32_e32 v117, v121, v198
	v_cvt_pk_bf16_f32 v116, v116, v117
	v_mul_f32_e32 v117, v122, v198
	v_mul_f32_e32 v120, v123, v198
	v_cvt_pk_bf16_f32 v117, v117, v120
	global_store_dwordx4 v[190:191], v[114:117], off
	v_mul_f32_e32 v119, v119, v198
	v_cmp_gt_f32_e32 vcc, s5, v118
	v_mul_f32_e32 v114, v173, v198
	v_mul_f32_e32 v115, v188, v198
	v_cvt_pk_bf16_f32 v114, v114, v115
	v_mul_f32_e32 v115, v187, v198
	v_mul_f32_e32 v116, v186, v198
	v_cvt_pk_bf16_f32 v115, v115, v116
	v_mul_f32_e32 v116, v189, v198
	v_mul_f32_e32 v117, v196, v198
	v_cvt_pk_bf16_f32 v116, v116, v117
	v_mul_f32_e32 v117, v197, v198
	v_cvt_pk_bf16_f32 v117, v117, v119
	v_mul_f32_e32 v119, 0x4b800000, v118
	v_cndmask_b32_e32 v118, v118, v119, vcc
	global_store_dwordx4 v[190:191], v[114:117], off offset:256
	v_rsq_f32_e32 v118, v118
	v_mul_f32_e32 v123, 0xbfb8aa3b, v61
	v_mul_f32_e32 v114, 0xbfb8aa3b, v108
	v_exp_f32_e32 v116, v114
	v_mul_f32_e32 v114, 0x45800000, v118
	v_cndmask_b32_e32 v117, v118, v114, vcc
	v_mul_f32_e32 v118, 0xbfb8aa3b, v109
	v_add_f32_e32 v116, 1.0, v116
	v_rcp_f32_e32 v116, v116
	v_exp_f32_e32 v118, v118
	v_lshl_add_u64 v[114:115], s[2:3], 0, v[180:181]
	v_lshl_add_u64 v[114:115], v[114:115], 0, v[170:171]
	v_mul_f32_e32 v108, v108, v116
	v_lshlrev_b32_e32 v116, 16, v156
	v_mul_f32_e32 v108, v108, v116
	v_add_f32_e32 v116, 1.0, v118
	v_rcp_f32_e32 v116, v116
	v_mul_f32_e32 v118, 0xbfb8aa3b, v110
	v_exp_f32_e32 v118, v118
	v_mul_f32_e32 v108, v108, v117
	v_mul_f32_e32 v109, v109, v116
	v_and_b32_e32 v116, 0xffff0000, v156
	v_mul_f32_e32 v109, v109, v116
	v_add_f32_e32 v116, 1.0, v118
	v_mul_f32_e32 v118, 0xbfb8aa3b, v111
	v_rcp_f32_e32 v116, v116
	v_exp_f32_e32 v118, v118
	v_mul_f32_e32 v109, v109, v117
	v_cvt_pk_bf16_f32 v108, v108, v109
	v_mul_f32_e32 v109, v110, v116
	v_add_f32_e32 v110, 1.0, v118
	v_rcp_f32_e32 v110, v110
	v_lshlrev_b32_e32 v116, 16, v157
	v_mul_f32_e32 v109, v109, v116
	v_and_b32_e32 v116, 0xffff0000, v157
	v_mul_f32_e32 v110, v111, v110
	v_mul_f32_e32 v111, 0xbfb8aa3b, v104
	v_exp_f32_e32 v111, v111
	v_mul_f32_e32 v110, v110, v116
	v_mul_f32_e32 v109, v109, v117
	v_mul_f32_e32 v110, v110, v117
	v_add_f32_e32 v111, 1.0, v111
	v_cvt_pk_bf16_f32 v109, v109, v110
	v_mul_f32_e32 v110, 0xbfb8aa3b, v105
	v_rcp_f32_e32 v111, v111
	v_exp_f32_e32 v110, v110
	v_exp_f32_e32 v123, v123
	v_mul_f32_e32 v124, 0xbfb8aa3b, v62
	v_mul_f32_e32 v104, v104, v111
	v_lshlrev_b32_e32 v111, 16, v158
	v_add_f32_e32 v110, 1.0, v110
	v_mul_f32_e32 v104, v104, v111
	v_rcp_f32_e32 v110, v110
	v_mul_f32_e32 v111, 0xbfb8aa3b, v106
	v_exp_f32_e32 v111, v111
	v_mul_f32_e32 v104, v104, v117
	v_mul_f32_e32 v105, v105, v110
	v_and_b32_e32 v110, 0xffff0000, v158
	v_mul_f32_e32 v105, v105, v110
	v_add_f32_e32 v110, 1.0, v111
	v_rcp_f32_e32 v111, v110
	v_mul_f32_e32 v110, 0xbfb8aa3b, v107
	v_exp_f32_e32 v116, v110
	v_mul_f32_e32 v105, v105, v117
	v_cvt_pk_bf16_f32 v110, v104, v105
	v_mul_f32_e32 v104, v106, v111
	v_add_f32_e32 v105, 1.0, v116
	v_rcp_f32_e32 v105, v105
	v_lshlrev_b32_e32 v106, 16, v159
	v_mul_f32_e32 v104, v104, v106
	v_and_b32_e32 v106, 0xffff0000, v159
	v_mul_f32_e32 v105, v107, v105
	v_mul_f32_e32 v107, 0xbfb8aa3b, v100
	v_exp_f32_e32 v107, v107
	v_mul_f32_e32 v104, v104, v117
	v_mul_f32_e32 v105, v105, v106
	v_mul_f32_e32 v105, v105, v117
	v_cvt_pk_bf16_f32 v111, v104, v105
	v_add_f32_e32 v104, 1.0, v107
	v_rcp_f32_e32 v104, v104
	v_mul_f32_e32 v105, 0xbfb8aa3b, v101
	v_exp_f32_e32 v105, v105
	global_store_dwordx4 v[114:115], v[108:111], off
	v_mul_f32_e32 v100, v100, v104
	v_lshlrev_b32_e32 v104, 16, v152
	v_mul_f32_e32 v100, v100, v104
	v_add_f32_e32 v104, 1.0, v105
	v_rcp_f32_e32 v104, v104
	v_mul_f32_e32 v105, 0xbfb8aa3b, v102
	v_exp_f32_e32 v105, v105
	v_mul_f32_e32 v100, v100, v117
	v_mul_f32_e32 v101, v101, v104
	v_and_b32_e32 v104, 0xffff0000, v152
	v_mul_f32_e32 v101, v101, v104
	v_add_f32_e32 v104, 1.0, v105
	v_mul_f32_e32 v105, 0xbfb8aa3b, v103
	v_rcp_f32_e32 v104, v104
	v_exp_f32_e32 v105, v105
	v_mul_f32_e32 v101, v101, v117
	v_cvt_pk_bf16_f32 v100, v100, v101
	v_mul_f32_e32 v101, v102, v104
	v_add_f32_e32 v102, 1.0, v105
	v_rcp_f32_e32 v102, v102
	v_lshlrev_b32_e32 v104, 16, v153
	v_mul_f32_e32 v101, v101, v104
	v_and_b32_e32 v104, 0xffff0000, v153
	v_mul_f32_e32 v102, v103, v102
	v_mul_f32_e32 v103, 0xbfb8aa3b, v96
	v_exp_f32_e32 v103, v103
	v_mul_f32_e32 v102, v102, v104
	v_mul_f32_e32 v101, v101, v117
	v_mul_f32_e32 v102, v102, v117
	v_add_f32_e32 v103, 1.0, v103
	v_cvt_pk_bf16_f32 v101, v101, v102
	v_mul_f32_e32 v102, 0xbfb8aa3b, v97
	v_rcp_f32_e32 v103, v103
	v_exp_f32_e32 v102, v102
	v_add_f32_e32 v123, 1.0, v123
	v_rcp_f32_e32 v123, v123
	v_mul_f32_e32 v96, v96, v103
	v_lshlrev_b32_e32 v103, 16, v154
	v_add_f32_e32 v102, 1.0, v102
	v_mul_f32_e32 v96, v96, v103
	v_rcp_f32_e32 v102, v102
	v_mul_f32_e32 v103, 0xbfb8aa3b, v98
	v_exp_f32_e32 v103, v103
	v_mul_f32_e32 v96, v96, v117
	v_mul_f32_e32 v97, v97, v102
	v_and_b32_e32 v102, 0xffff0000, v154
	v_mul_f32_e32 v97, v97, v102
	v_add_f32_e32 v102, 1.0, v103
	v_rcp_f32_e32 v103, v102
	v_mul_f32_e32 v102, 0xbfb8aa3b, v99
	v_exp_f32_e32 v104, v102
	v_mul_f32_e32 v97, v97, v117
	v_cvt_pk_bf16_f32 v102, v96, v97
	v_mul_f32_e32 v96, v98, v103
	v_add_f32_e32 v97, 1.0, v104
	v_rcp_f32_e32 v97, v97
	v_lshlrev_b32_e32 v98, 16, v155
	v_mul_f32_e32 v96, v96, v98
	v_and_b32_e32 v98, 0xffff0000, v155
	v_mul_f32_e32 v97, v99, v97
	v_mul_f32_e32 v99, 0xbfb8aa3b, v93
	v_exp_f32_e32 v99, v99
	v_mul_f32_e32 v97, v97, v98
	v_mul_f32_e32 v96, v96, v117
	v_mul_f32_e32 v97, v97, v117
	v_cvt_pk_bf16_f32 v103, v96, v97
	global_store_dwordx4 v[114:115], v[100:103], off offset:256
	v_add_f32_e32 v99, 1.0, v99
	v_rcp_f32_e32 v99, v99
	v_mul_f32_e32 v100, 0xbfb8aa3b, v94
	v_exp_f32_e32 v100, v100
	v_mul_f32_e32 v98, 0xbfb8aa3b, v92
	v_mul_f32_e32 v93, v93, v99
	v_exp_f32_e32 v98, v98
	v_add_f32_e32 v99, 1.0, v100
	v_mul_f32_e32 v100, 0xbfb8aa3b, v95
	v_rcp_f32_e32 v99, v99
	v_exp_f32_e32 v100, v100
	v_add_f32_e32 v98, 1.0, v98
	v_rcp_f32_e32 v98, v98
	v_mul_f32_e32 v94, v94, v99
	v_add_f32_e32 v99, 1.0, v100
	v_mul_f32_e32 v100, 0xbfb8aa3b, v88
	v_rcp_f32_e32 v99, v99
	v_exp_f32_e32 v100, v100
	v_mul_f32_e32 v92, v92, v98
	v_lshlrev_b32_e32 v98, 16, v148
	v_mul_f32_e32 v95, v95, v99
	v_add_f32_e32 v99, 1.0, v100
	v_mul_f32_e32 v100, 0xbfb8aa3b, v89
	v_rcp_f32_e32 v99, v99
	v_exp_f32_e32 v100, v100
	v_mul_f32_e32 v92, v92, v98
	v_and_b32_e32 v98, 0xffff0000, v148
	v_mul_f32_e32 v88, v88, v99
	v_add_f32_e32 v99, 1.0, v100
	v_mul_f32_e32 v100, 0xbfb8aa3b, v90
	v_rcp_f32_e32 v99, v99
	v_exp_f32_e32 v100, v100
	v_mul_f32_e32 v93, v93, v98
	v_lshlrev_b32_e32 v98, 16, v149
	v_mul_f32_e32 v89, v89, v99
	v_add_f32_e32 v99, 1.0, v100
	v_mul_f32_e32 v100, 0xbfb8aa3b, v91
	v_rcp_f32_e32 v99, v99
	v_exp_f32_e32 v100, v100
	v_mul_f32_e32 v94, v94, v98
	v_and_b32_e32 v98, 0xffff0000, v149
	v_mul_f32_e32 v90, v90, v99
	v_add_f32_e32 v99, 1.0, v100
	v_mul_f32_e32 v100, 0xbfb8aa3b, v84
	v_rcp_f32_e32 v99, v99
	v_exp_f32_e32 v100, v100
	v_mul_f32_e32 v95, v95, v98
	v_lshlrev_b32_e32 v98, 16, v150
	v_mul_f32_e32 v91, v91, v99
	v_add_f32_e32 v99, 1.0, v100
	v_mul_f32_e32 v100, 0xbfb8aa3b, v85
	v_rcp_f32_e32 v99, v99
	v_exp_f32_e32 v100, v100
	v_mul_f32_e32 v88, v88, v98
	v_and_b32_e32 v98, 0xffff0000, v150
	v_mul_f32_e32 v84, v84, v99
	v_add_f32_e32 v99, 1.0, v100
	v_mul_f32_e32 v100, 0xbfb8aa3b, v86
	v_rcp_f32_e32 v99, v99
	v_exp_f32_e32 v100, v100
	v_mul_f32_e32 v89, v89, v98
	v_lshlrev_b32_e32 v98, 16, v151
	v_mul_f32_e32 v90, v90, v98
	v_and_b32_e32 v98, 0xffff0000, v151
	v_mul_f32_e32 v91, v91, v98
	v_lshlrev_b32_e32 v98, 16, v140
	v_mul_f32_e32 v98, v84, v98
	v_mul_f32_e32 v84, v85, v99
	v_add_f32_e32 v99, 1.0, v100
	v_mul_f32_e32 v100, 0xbfb8aa3b, v87
	v_rcp_f32_e32 v99, v99
	v_exp_f32_e32 v100, v100
	v_and_b32_e32 v85, 0xffff0000, v140
	v_mul_f32_e32 v101, v84, v85
	v_mul_f32_e32 v84, v86, v99
	v_add_f32_e32 v86, 1.0, v100
	v_rcp_f32_e32 v86, v86
	v_mul_f32_e32 v99, 0xbfb8aa3b, v80
	v_exp_f32_e32 v99, v99
	v_lshlrev_b32_e32 v85, 16, v141
	v_mul_f32_e32 v100, v84, v85
	v_mul_f32_e32 v84, v87, v86
	v_mul_f32_e32 v87, 0xbfb8aa3b, v81
	v_add_f32_e32 v86, 1.0, v99
	v_exp_f32_e32 v87, v87
	v_rcp_f32_e32 v86, v86
	v_and_b32_e32 v85, 0xffff0000, v141
	v_mul_f32_e32 v99, v84, v85
	v_add_f32_e32 v85, 1.0, v87
	v_mul_f32_e32 v80, v80, v86
	v_rcp_f32_e32 v85, v85
	v_mul_f32_e32 v86, 0xbfb8aa3b, v82
	v_exp_f32_e32 v86, v86
	v_lshlrev_b32_e32 v84, 16, v142
	v_mul_f32_e32 v87, v80, v84
	v_mul_f32_e32 v80, v81, v85
	v_and_b32_e32 v81, 0xffff0000, v142
	v_add_f32_e32 v84, 1.0, v86
	v_mul_f32_e32 v86, v80, v81
	v_mul_f32_e32 v80, 0xbfb8aa3b, v83
	v_rcp_f32_e32 v84, v84
	v_exp_f32_e32 v80, v80
	v_mov_b32_e32 v85, v138
	v_mov_b32_e32 v138, v147
	v_mul_f32_e32 v81, v82, v84
	v_lshlrev_b32_e32 v82, 16, v143
	v_add_f32_e32 v80, 1.0, v80
	v_mul_f32_e32 v102, v81, v82
	v_rcp_f32_e32 v82, v80
	v_mov_b32_e32 v80, v144
	v_mov_b32_e32 v81, v136
	v_mov_b32_e32 v136, v145
	v_pk_add_f32 v[80:81], v[80:81], v[136:137]
	v_mov_b32_e32 v84, v146
	v_pk_add_f32 v[80:81], v[84:85], v[80:81]
	v_lshl_add_u64 v[96:97], s[2:3], 0, v[178:179]
	v_pk_add_f32 v[80:81], v[138:139], v[80:81]
	v_lshl_add_u64 v[96:97], v[96:97], 0, v[170:171]
	v_pk_fma_f32 v[84:85], v[80:81], s[14:15], v[112:113] op_sel_hi:[1,0,0]
	v_mul_f32_e32 v81, v83, v82
	v_mul_f32_e32 v80, 0x4b800000, v85
	v_cmp_gt_f32_e32 vcc, s5, v85
	v_and_b32_e32 v82, 0xffff0000, v143
	v_exp_f32_e32 v124, v124
	v_cndmask_b32_e32 v80, v85, v80, vcc
	v_rsq_f32_e32 v80, v80
	v_mul_f32_e32 v85, v81, v82
	v_mul_f32_e32 v61, v61, v123
	v_mul_f32_e32 v123, 0xbfb8aa3b, v63
	v_mul_f32_e32 v81, 0x45800000, v80
	v_cndmask_b32_e32 v103, v80, v81, vcc
	v_mul_f32_e32 v80, v92, v103
	v_mul_f32_e32 v81, v93, v103
	v_cvt_pk_bf16_f32 v80, v80, v81
	v_mul_f32_e32 v81, v94, v103
	v_mul_f32_e32 v82, v95, v103
	v_cvt_pk_bf16_f32 v81, v81, v82
	v_mul_f32_e32 v82, v88, v103
	v_mul_f32_e32 v83, v89, v103
	v_cvt_pk_bf16_f32 v82, v82, v83
	v_mul_f32_e32 v83, v90, v103
	v_mul_f32_e32 v88, v91, v103
	v_cvt_pk_bf16_f32 v83, v83, v88
	global_store_dwordx4 v[96:97], v[80:83], off
	v_mul_f32_e32 v85, v85, v103
	v_cmp_gt_f32_e32 vcc, s5, v84
	v_mul_f32_e32 v80, v98, v103
	v_mul_f32_e32 v81, v101, v103
	v_cvt_pk_bf16_f32 v80, v80, v81
	v_mul_f32_e32 v81, v100, v103
	v_mul_f32_e32 v82, v99, v103
	v_cvt_pk_bf16_f32 v81, v81, v82
	v_mul_f32_e32 v82, v87, v103
	v_mul_f32_e32 v83, v86, v103
	v_cvt_pk_bf16_f32 v82, v82, v83
	v_mul_f32_e32 v83, v102, v103
	v_cvt_pk_bf16_f32 v83, v83, v85
	v_mul_f32_e32 v85, 0x4b800000, v84
	v_cndmask_b32_e32 v84, v84, v85, vcc
	global_store_dwordx4 v[96:97], v[80:83], off offset:256
	v_rsq_f32_e32 v84, v84
	v_exp_f32_e32 v123, v123
	v_mul_f32_e32 v80, 0xbfb8aa3b, v76
	v_exp_f32_e32 v82, v80
	v_mul_f32_e32 v80, 0x45800000, v84
	v_cndmask_b32_e32 v83, v84, v80, vcc
	v_mul_f32_e32 v84, 0xbfb8aa3b, v77
	v_add_f32_e32 v82, 1.0, v82
	v_rcp_f32_e32 v82, v82
	v_exp_f32_e32 v84, v84
	v_lshl_add_u64 v[80:81], s[2:3], 0, v[176:177]
	v_lshl_add_u64 v[80:81], v[80:81], 0, v[170:171]
	v_mul_f32_e32 v76, v76, v82
	v_lshlrev_b32_e32 v82, 16, v132
	v_mul_f32_e32 v76, v76, v82
	v_add_f32_e32 v82, 1.0, v84
	v_rcp_f32_e32 v82, v82
	v_mul_f32_e32 v84, 0xbfb8aa3b, v78
	v_exp_f32_e32 v84, v84
	v_mul_f32_e32 v76, v76, v83
	v_mul_f32_e32 v77, v77, v82
	v_and_b32_e32 v82, 0xffff0000, v132
	v_mul_f32_e32 v77, v77, v82
	v_add_f32_e32 v82, 1.0, v84
	v_mul_f32_e32 v84, 0xbfb8aa3b, v79
	v_rcp_f32_e32 v82, v82
	v_exp_f32_e32 v84, v84
	v_mul_f32_e32 v77, v77, v83
	v_cvt_pk_bf16_f32 v76, v76, v77
	v_mul_f32_e32 v77, v78, v82
	v_add_f32_e32 v78, 1.0, v84
	v_rcp_f32_e32 v78, v78
	v_lshlrev_b32_e32 v82, 16, v133
	v_mul_f32_e32 v77, v77, v82
	v_and_b32_e32 v82, 0xffff0000, v133
	v_mul_f32_e32 v78, v79, v78
	v_mul_f32_e32 v79, 0xbfb8aa3b, v72
	v_exp_f32_e32 v79, v79
	v_mul_f32_e32 v78, v78, v82
	v_mul_f32_e32 v77, v77, v83
	v_mul_f32_e32 v78, v78, v83
	v_add_f32_e32 v79, 1.0, v79
	v_cvt_pk_bf16_f32 v77, v77, v78
	v_mul_f32_e32 v78, 0xbfb8aa3b, v73
	v_rcp_f32_e32 v79, v79
	v_exp_f32_e32 v78, v78
	v_mul_f32_e32 v72, v72, v79
	v_lshlrev_b32_e32 v79, 16, v134
	v_add_f32_e32 v78, 1.0, v78
	v_mul_f32_e32 v72, v72, v79
	v_rcp_f32_e32 v78, v78
	v_mul_f32_e32 v79, 0xbfb8aa3b, v74
	v_exp_f32_e32 v79, v79
	v_mul_f32_e32 v72, v72, v83
	v_mul_f32_e32 v73, v73, v78
	v_and_b32_e32 v78, 0xffff0000, v134
	v_mul_f32_e32 v73, v73, v78
	v_add_f32_e32 v78, 1.0, v79
	v_rcp_f32_e32 v79, v78
	v_mul_f32_e32 v78, 0xbfb8aa3b, v75
	v_exp_f32_e32 v82, v78
	v_mul_f32_e32 v73, v73, v83
	v_cvt_pk_bf16_f32 v78, v72, v73
	v_mul_f32_e32 v72, v74, v79
	v_add_f32_e32 v73, 1.0, v82
	v_rcp_f32_e32 v73, v73
	v_lshlrev_b32_e32 v74, 16, v135
	v_mul_f32_e32 v72, v72, v74
	v_and_b32_e32 v74, 0xffff0000, v135
	v_mul_f32_e32 v73, v75, v73
	v_mul_f32_e32 v75, 0xbfb8aa3b, v68
	v_exp_f32_e32 v75, v75
	v_mul_f32_e32 v72, v72, v83
	v_mul_f32_e32 v73, v73, v74
	v_mul_f32_e32 v73, v73, v83
	v_cvt_pk_bf16_f32 v79, v72, v73
	v_add_f32_e32 v72, 1.0, v75
	v_rcp_f32_e32 v72, v72
	v_mul_f32_e32 v73, 0xbfb8aa3b, v69
	v_exp_f32_e32 v73, v73
	global_store_dwordx4 v[80:81], v[76:79], off
	v_mul_f32_e32 v68, v68, v72
	v_lshlrev_b32_e32 v72, 16, v128
	v_mul_f32_e32 v68, v68, v72
	v_add_f32_e32 v72, 1.0, v73
	v_rcp_f32_e32 v72, v72
	v_mul_f32_e32 v73, 0xbfb8aa3b, v70
	v_exp_f32_e32 v73, v73
	v_mul_f32_e32 v68, v68, v83
	v_mul_f32_e32 v69, v69, v72
	v_and_b32_e32 v72, 0xffff0000, v128
	v_mul_f32_e32 v69, v69, v72
	v_add_f32_e32 v72, 1.0, v73
	v_mul_f32_e32 v73, 0xbfb8aa3b, v71
	v_rcp_f32_e32 v72, v72
	v_exp_f32_e32 v73, v73
	v_mul_f32_e32 v69, v69, v83
	v_cvt_pk_bf16_f32 v68, v68, v69
	v_mul_f32_e32 v69, v70, v72
	v_add_f32_e32 v70, 1.0, v73
	v_rcp_f32_e32 v70, v70
	v_lshlrev_b32_e32 v72, 16, v129
	v_mul_f32_e32 v69, v69, v72
	v_and_b32_e32 v72, 0xffff0000, v129
	v_mul_f32_e32 v70, v71, v70
	v_mul_f32_e32 v71, 0xbfb8aa3b, v64
	v_exp_f32_e32 v71, v71
	v_mul_f32_e32 v70, v70, v72
	v_mul_f32_e32 v69, v69, v83
	v_mul_f32_e32 v70, v70, v83
	v_add_f32_e32 v71, 1.0, v71
	v_cvt_pk_bf16_f32 v69, v69, v70
	v_mul_f32_e32 v70, 0xbfb8aa3b, v65
	v_rcp_f32_e32 v71, v71
	v_exp_f32_e32 v70, v70
	v_mul_f32_e32 v64, v64, v71
	v_lshlrev_b32_e32 v71, 16, v130
	v_add_f32_e32 v70, 1.0, v70
	v_mul_f32_e32 v64, v64, v71
	v_rcp_f32_e32 v70, v70
	v_mul_f32_e32 v71, 0xbfb8aa3b, v66
	v_exp_f32_e32 v71, v71
	v_mul_f32_e32 v64, v64, v83
	v_mul_f32_e32 v65, v65, v70
	v_and_b32_e32 v70, 0xffff0000, v130
	v_mul_f32_e32 v65, v65, v70
	v_add_f32_e32 v70, 1.0, v71
	v_rcp_f32_e32 v71, v70
	v_mul_f32_e32 v70, 0xbfb8aa3b, v67
	v_exp_f32_e32 v72, v70
	v_mul_f32_e32 v65, v65, v83
	v_cvt_pk_bf16_f32 v70, v64, v65
	v_mul_f32_e32 v64, v66, v71
	v_add_f32_e32 v65, 1.0, v72
	v_rcp_f32_e32 v65, v65
	v_lshlrev_b32_e32 v66, 16, v131
	v_mul_f32_e32 v64, v64, v66
	v_and_b32_e32 v66, 0xffff0000, v131
	v_mul_f32_e32 v65, v67, v65
	v_mul_f32_e32 v64, v64, v83
	v_mul_f32_e32 v65, v65, v66
	v_mul_f32_e32 v65, v65, v83
	v_cvt_pk_bf16_f32 v71, v64, v65
	v_add_u32_e32 v64, 0x80, v172
	v_ashrrev_i32_e32 v65, 31, v64
	v_lshlrev_b64 v[110:111], 13, v[64:65]
	v_lshl_add_u64 v[66:67], v[174:175], 0, v[110:111]
	global_load_dwordx4 v[102:105], v[66:67], off
	v_lshlrev_b64 v[64:65], 7, v[64:65]
	global_store_dwordx4 v[80:81], v[68:71], off offset:256
	v_lshl_add_u64 v[64:65], s[12:13], 0, v[64:65]
	global_load_dwordx4 v[106:109], v[64:65], off
	v_add_u32_e32 v64, 0x90, v172
	v_ashrrev_i32_e32 v65, 31, v64
	v_lshlrev_b64 v[68:69], 7, v[64:65]
	v_lshl_add_u64 v[68:69], s[12:13], 0, v[68:69]
	global_load_dwordx4 v[114:117], v[66:67], off offset:256
	global_load_dwordx4 v[118:121], v[68:69], off
	v_lshlrev_b64 v[100:101], 13, v[64:65]
	v_lshl_add_u64 v[64:65], v[174:175], 0, v[100:101]
	global_load_dwordx4 v[92:95], v[64:65], off
	global_load_dwordx4 v[88:91], v[64:65], off offset:256
	v_add_u32_e32 v64, 0xa0, v172
	v_ashrrev_i32_e32 v65, 31, v64
	v_lshlrev_b64 v[66:67], 7, v[64:65]
	v_lshl_add_u64 v[66:67], s[12:13], 0, v[66:67]
	v_lshlrev_b64 v[98:99], 13, v[64:65]
	v_lshl_add_u64 v[64:65], v[174:175], 0, v[98:99]
	global_load_dwordx4 v[72:75], v[66:67], off
	global_load_dwordx4 v[84:87], v[64:65], off
	v_add_u32_e32 v66, 0xb0, v172
	v_ashrrev_i32_e32 v67, 31, v66
	v_lshlrev_b64 v[68:69], 7, v[66:67]
	v_lshlrev_b64 v[96:97], 13, v[66:67]
	v_mul_f32_e32 v66, 0xbfb8aa3b, v60
	v_exp_f32_e32 v122, v66
	v_lshl_add_u64 v[68:69], s[12:13], 0, v[68:69]
	global_load_dwordx4 v[76:79], v[64:65], off offset:256
	global_load_dwordx4 v[80:83], v[68:69], off
	v_lshl_add_u64 v[64:65], v[174:175], 0, v[96:97]
	v_add_f32_e32 v122, 1.0, v122
	v_rcp_f32_e32 v122, v122
	global_load_dwordx4 v[68:71], v[64:65], off
	s_nop 0
	global_load_dwordx4 v[64:67], v[64:65], off offset:256
	v_lshl_add_u64 v[110:111], s[2:3], 0, v[110:111]
	v_lshl_add_u64 v[110:111], v[110:111], 0, v[170:171]
	v_mul_f32_e32 v60, v60, v122
	s_mov_b32 s13, s4
	s_mov_b32 s12, s6
	s_waitcnt vmcnt(0)
	v_lshlrev_b32_e32 v122, 16, v102
	v_mul_f32_e32 v60, v60, v122
	v_add_f32_e32 v122, 1.0, v124
	v_rcp_f32_e32 v122, v122
	v_and_b32_e32 v102, 0xffff0000, v102
	v_mul_f32_e32 v61, v61, v102
	v_lshlrev_b32_e32 v102, 16, v103
	v_mul_f32_e32 v62, v62, v122
	v_add_f32_e32 v122, 1.0, v123
	v_mul_f32_e32 v123, 0xbfb8aa3b, v56
	v_rcp_f32_e32 v122, v122
	v_exp_f32_e32 v123, v123
	v_mul_f32_e32 v62, v62, v102
	v_and_b32_e32 v102, 0xffff0000, v103
	v_mul_f32_e32 v63, v63, v122
	v_add_f32_e32 v103, 1.0, v123
	v_mul_f32_e32 v122, 0xbfb8aa3b, v57
	v_rcp_f32_e32 v103, v103
	v_exp_f32_e32 v122, v122
	v_mul_f32_e32 v63, v63, v102
	v_lshlrev_b32_e32 v102, 16, v104
	v_mul_f32_e32 v56, v56, v103
	v_add_f32_e32 v103, 1.0, v122
	v_mul_f32_e32 v122, 0xbfb8aa3b, v58
	v_rcp_f32_e32 v103, v103
	v_exp_f32_e32 v122, v122
	v_mul_f32_e32 v56, v56, v102
	v_and_b32_e32 v102, 0xffff0000, v104
	v_mul_f32_e32 v57, v57, v103
	v_add_f32_e32 v103, 1.0, v122
	v_mul_f32_e32 v104, 0xbfb8aa3b, v59
	v_rcp_f32_e32 v103, v103
	v_exp_f32_e32 v104, v104
	v_mul_f32_e32 v57, v57, v102
	v_lshlrev_b32_e32 v102, 16, v105
	v_mul_f32_e32 v58, v58, v103
	v_add_f32_e32 v103, 1.0, v104
	v_mul_f32_e32 v104, 0xbfb8aa3b, v52
	v_rcp_f32_e32 v103, v103
	v_exp_f32_e32 v104, v104
	v_mul_f32_e32 v58, v58, v102
	v_and_b32_e32 v102, 0xffff0000, v105
	v_mul_f32_e32 v59, v59, v103
	v_add_f32_e32 v103, 1.0, v104
	v_mul_f32_e32 v104, 0xbfb8aa3b, v53
	v_rcp_f32_e32 v103, v103
	v_exp_f32_e32 v104, v104
	v_mul_f32_e32 v59, v59, v102
	v_lshlrev_b32_e32 v102, 16, v114
	v_mul_f32_e32 v52, v52, v103
	v_add_f32_e32 v103, 1.0, v104
	v_mul_f32_e32 v104, 0xbfb8aa3b, v54
	v_rcp_f32_e32 v103, v103
	v_exp_f32_e32 v104, v104
	v_mul_f32_e32 v102, v52, v102
	v_mul_f32_e32 v52, v53, v103
	v_add_f32_e32 v103, 1.0, v104
	v_mul_f32_e32 v104, 0xbfb8aa3b, v55
	v_rcp_f32_e32 v103, v103
	v_exp_f32_e32 v104, v104
	v_and_b32_e32 v53, 0xffff0000, v114
	v_mul_f32_e32 v105, v52, v53
	v_mul_f32_e32 v52, v54, v103
	v_add_f32_e32 v54, 1.0, v104
	v_rcp_f32_e32 v54, v54
	v_mul_f32_e32 v103, 0xbfb8aa3b, v48
	v_exp_f32_e32 v103, v103
	v_lshlrev_b32_e32 v53, 16, v115
	v_mul_f32_e32 v104, v52, v53
	v_mul_f32_e32 v52, v55, v54
	v_mul_f32_e32 v55, 0xbfb8aa3b, v49
	v_add_f32_e32 v54, 1.0, v103
	v_exp_f32_e32 v55, v55
	v_rcp_f32_e32 v54, v54
	v_and_b32_e32 v53, 0xffff0000, v115
	v_mul_f32_e32 v103, v52, v53
	v_add_f32_e32 v53, 1.0, v55
	v_mul_f32_e32 v48, v48, v54
	v_rcp_f32_e32 v53, v53
	v_mul_f32_e32 v54, 0xbfb8aa3b, v50
	v_exp_f32_e32 v54, v54
	v_lshlrev_b32_e32 v52, 16, v116
	v_mul_f32_e32 v55, v48, v52
	v_mul_f32_e32 v48, v49, v53
	v_and_b32_e32 v49, 0xffff0000, v116
	v_add_f32_e32 v52, 1.0, v54
	v_mul_f32_e32 v54, v48, v49
	v_mul_f32_e32 v48, 0xbfb8aa3b, v51
	v_rcp_f32_e32 v52, v52
	v_exp_f32_e32 v48, v48
	v_mov_b32_e32 v53, v108
	v_mov_b32_e32 v108, v121
	v_mul_f32_e32 v49, v50, v52
	v_lshlrev_b32_e32 v50, 16, v117
	v_add_f32_e32 v48, 1.0, v48
	v_mul_f32_e32 v114, v49, v50
	v_rcp_f32_e32 v50, v48
	v_mov_b32_e32 v48, v118
	v_mov_b32_e32 v49, v106
	v_mov_b32_e32 v106, v119
	v_pk_add_f32 v[48:49], v[48:49], v[106:107]
	v_mov_b32_e32 v52, v120
	v_pk_add_f32 v[48:49], v[52:53], v[48:49]
	s_nop 0
	v_pk_add_f32 v[48:49], v[108:109], v[48:49]
	s_nop 0
	v_pk_fma_f32 v[52:53], v[48:49], s[14:15], v[112:113] op_sel_hi:[1,0,0]
	v_mul_f32_e32 v49, v51, v50
	v_mul_f32_e32 v48, 0x4b800000, v53
	v_cmp_gt_f32_e32 vcc, s5, v53
	v_and_b32_e32 v50, 0xffff0000, v117
	s_nop 0
	v_cndmask_b32_e32 v48, v53, v48, vcc
	v_rsq_f32_e32 v48, v48
	v_mul_f32_e32 v53, v49, v50
	v_mul_f32_e32 v49, 0x45800000, v48
	v_cndmask_b32_e32 v106, v48, v49, vcc
	v_mul_f32_e32 v48, v60, v106
	v_mul_f32_e32 v49, v61, v106
	v_cvt_pk_bf16_f32 v48, v48, v49
	v_mul_f32_e32 v49, v62, v106
	v_mul_f32_e32 v50, v63, v106
	v_cvt_pk_bf16_f32 v49, v49, v50
	v_mul_f32_e32 v50, v56, v106
	v_mul_f32_e32 v51, v57, v106
	v_cvt_pk_bf16_f32 v50, v50, v51
	v_mul_f32_e32 v51, v58, v106
	v_mul_f32_e32 v56, v59, v106
	v_cvt_pk_bf16_f32 v51, v51, v56
	global_store_dwordx4 v[110:111], v[48:51], off
	v_mul_f32_e32 v53, v53, v106
	v_cmp_gt_f32_e32 vcc, s5, v52
	v_mul_f32_e32 v48, v102, v106
	v_mul_f32_e32 v49, v105, v106
	v_cvt_pk_bf16_f32 v48, v48, v49
	v_mul_f32_e32 v49, v104, v106
	v_mul_f32_e32 v50, v103, v106
	v_cvt_pk_bf16_f32 v49, v49, v50
	v_mul_f32_e32 v50, v55, v106
	v_mul_f32_e32 v51, v54, v106
	v_cvt_pk_bf16_f32 v50, v50, v51
	v_mul_f32_e32 v51, v114, v106
	v_cvt_pk_bf16_f32 v51, v51, v53
	v_mul_f32_e32 v53, 0x4b800000, v52
	v_cndmask_b32_e32 v52, v52, v53, vcc
	global_store_dwordx4 v[110:111], v[48:51], off offset:256
	v_rsq_f32_e32 v52, v52
	s_nop 0
	v_mul_f32_e32 v48, 0xbfb8aa3b, v44
	v_exp_f32_e32 v50, v48
	v_mul_f32_e32 v48, 0x45800000, v52
	v_cndmask_b32_e32 v51, v52, v48, vcc
	v_mul_f32_e32 v52, 0xbfb8aa3b, v45
	v_add_f32_e32 v50, 1.0, v50
	v_rcp_f32_e32 v50, v50
	v_exp_f32_e32 v52, v52
	v_lshl_add_u64 v[48:49], s[2:3], 0, v[100:101]
	v_lshl_add_u64 v[48:49], v[48:49], 0, v[170:171]
	v_mul_f32_e32 v44, v44, v50
	v_lshlrev_b32_e32 v50, 16, v92
	v_mul_f32_e32 v44, v44, v50
	v_add_f32_e32 v50, 1.0, v52
	v_rcp_f32_e32 v50, v50
	v_mul_f32_e32 v52, 0xbfb8aa3b, v46
	v_exp_f32_e32 v52, v52
	v_mul_f32_e32 v44, v44, v51
	v_mul_f32_e32 v45, v45, v50
	v_and_b32_e32 v50, 0xffff0000, v92
	v_mul_f32_e32 v45, v45, v50
	v_add_f32_e32 v50, 1.0, v52
	v_mul_f32_e32 v52, 0xbfb8aa3b, v47
	v_rcp_f32_e32 v50, v50
	v_exp_f32_e32 v52, v52
	v_mul_f32_e32 v45, v45, v51
	v_cvt_pk_bf16_f32 v44, v44, v45
	v_mul_f32_e32 v45, v46, v50
	v_add_f32_e32 v46, 1.0, v52
	v_rcp_f32_e32 v46, v46
	v_lshlrev_b32_e32 v50, 16, v93
	v_mul_f32_e32 v45, v45, v50
	v_and_b32_e32 v50, 0xffff0000, v93
	v_mul_f32_e32 v46, v47, v46
	v_mul_f32_e32 v47, 0xbfb8aa3b, v40
	v_exp_f32_e32 v47, v47
	v_mul_f32_e32 v46, v46, v50
	v_mul_f32_e32 v45, v45, v51
	v_mul_f32_e32 v46, v46, v51
	v_add_f32_e32 v47, 1.0, v47
	v_cvt_pk_bf16_f32 v45, v45, v46
	v_mul_f32_e32 v46, 0xbfb8aa3b, v41
	v_rcp_f32_e32 v47, v47
	v_exp_f32_e32 v46, v46
	v_mul_f32_e32 v40, v40, v47
	v_lshlrev_b32_e32 v47, 16, v94
	v_add_f32_e32 v46, 1.0, v46
	v_mul_f32_e32 v40, v40, v47
	v_rcp_f32_e32 v46, v46
	v_mul_f32_e32 v47, 0xbfb8aa3b, v42
	v_exp_f32_e32 v47, v47
	v_mul_f32_e32 v40, v40, v51
	v_mul_f32_e32 v41, v41, v46
	v_and_b32_e32 v46, 0xffff0000, v94
	v_mul_f32_e32 v41, v41, v46
	v_add_f32_e32 v46, 1.0, v47
	v_rcp_f32_e32 v47, v46
	v_mul_f32_e32 v46, 0xbfb8aa3b, v43
	v_exp_f32_e32 v50, v46
	v_mul_f32_e32 v41, v41, v51
	v_cvt_pk_bf16_f32 v46, v40, v41
	v_mul_f32_e32 v40, v42, v47
	v_add_f32_e32 v41, 1.0, v50
	v_rcp_f32_e32 v41, v41
	v_lshlrev_b32_e32 v42, 16, v95
	v_mul_f32_e32 v40, v40, v42
	v_and_b32_e32 v42, 0xffff0000, v95
	v_mul_f32_e32 v41, v43, v41
	v_mul_f32_e32 v43, 0xbfb8aa3b, v36
	v_exp_f32_e32 v43, v43
	v_mul_f32_e32 v40, v40, v51
	v_mul_f32_e32 v41, v41, v42
	v_mul_f32_e32 v41, v41, v51
	v_cvt_pk_bf16_f32 v47, v40, v41
	v_add_f32_e32 v40, 1.0, v43
	v_rcp_f32_e32 v40, v40
	v_mul_f32_e32 v41, 0xbfb8aa3b, v37
	v_exp_f32_e32 v41, v41
	global_store_dwordx4 v[48:49], v[44:47], off
	v_mul_f32_e32 v36, v36, v40
	v_lshlrev_b32_e32 v40, 16, v88
	v_mul_f32_e32 v36, v36, v40
	v_add_f32_e32 v40, 1.0, v41
	v_rcp_f32_e32 v40, v40
	v_mul_f32_e32 v41, 0xbfb8aa3b, v38
	v_exp_f32_e32 v41, v41
	v_mul_f32_e32 v36, v36, v51
	v_mul_f32_e32 v37, v37, v40
	v_and_b32_e32 v40, 0xffff0000, v88
	v_mul_f32_e32 v37, v37, v40
	v_add_f32_e32 v40, 1.0, v41
	v_mul_f32_e32 v41, 0xbfb8aa3b, v39
	v_rcp_f32_e32 v40, v40
	v_exp_f32_e32 v41, v41
	v_mul_f32_e32 v37, v37, v51
	v_cvt_pk_bf16_f32 v36, v36, v37
	v_mul_f32_e32 v37, v38, v40
	v_add_f32_e32 v38, 1.0, v41
	v_rcp_f32_e32 v38, v38
	v_lshlrev_b32_e32 v40, 16, v89
	v_mul_f32_e32 v37, v37, v40
	v_and_b32_e32 v40, 0xffff0000, v89
	v_mul_f32_e32 v38, v39, v38
	v_mul_f32_e32 v39, 0xbfb8aa3b, v32
	v_exp_f32_e32 v39, v39
	v_mul_f32_e32 v38, v38, v40
	v_mul_f32_e32 v37, v37, v51
	v_mul_f32_e32 v38, v38, v51
	v_add_f32_e32 v39, 1.0, v39
	v_cvt_pk_bf16_f32 v37, v37, v38
	v_mul_f32_e32 v38, 0xbfb8aa3b, v33
	v_rcp_f32_e32 v39, v39
	v_exp_f32_e32 v38, v38
	v_mul_f32_e32 v32, v32, v39
	v_lshlrev_b32_e32 v39, 16, v90
	v_add_f32_e32 v38, 1.0, v38
	v_mul_f32_e32 v32, v32, v39
	v_rcp_f32_e32 v38, v38
	v_mul_f32_e32 v39, 0xbfb8aa3b, v34
	v_exp_f32_e32 v39, v39
	v_mul_f32_e32 v32, v32, v51
	v_mul_f32_e32 v33, v33, v38
	v_and_b32_e32 v38, 0xffff0000, v90
	v_mul_f32_e32 v33, v33, v38
	v_add_f32_e32 v38, 1.0, v39
	v_rcp_f32_e32 v39, v38
	v_mul_f32_e32 v38, 0xbfb8aa3b, v35
	v_exp_f32_e32 v40, v38
	v_mul_f32_e32 v33, v33, v51
	v_cvt_pk_bf16_f32 v38, v32, v33
	v_mul_f32_e32 v32, v34, v39
	v_add_f32_e32 v33, 1.0, v40
	v_rcp_f32_e32 v33, v33
	v_lshlrev_b32_e32 v34, 16, v91
	v_mul_f32_e32 v32, v32, v34
	v_and_b32_e32 v34, 0xffff0000, v91
	v_mul_f32_e32 v33, v35, v33
	v_mul_f32_e32 v35, 0xbfb8aa3b, v29
	v_exp_f32_e32 v35, v35
	v_mul_f32_e32 v33, v33, v34
	v_mul_f32_e32 v32, v32, v51
	v_mul_f32_e32 v33, v33, v51
	v_cvt_pk_bf16_f32 v39, v32, v33
	global_store_dwordx4 v[48:49], v[36:39], off offset:256
	v_add_f32_e32 v35, 1.0, v35
	v_rcp_f32_e32 v35, v35
	v_mul_f32_e32 v36, 0xbfb8aa3b, v30
	v_exp_f32_e32 v36, v36
	v_mul_f32_e32 v34, 0xbfb8aa3b, v28
	v_mul_f32_e32 v29, v29, v35
	v_exp_f32_e32 v34, v34
	v_add_f32_e32 v35, 1.0, v36
	v_mul_f32_e32 v36, 0xbfb8aa3b, v31
	v_rcp_f32_e32 v35, v35
	v_exp_f32_e32 v36, v36
	v_add_f32_e32 v34, 1.0, v34
	v_rcp_f32_e32 v34, v34
	v_mul_f32_e32 v30, v30, v35
	v_add_f32_e32 v35, 1.0, v36
	v_mul_f32_e32 v36, 0xbfb8aa3b, v24
	v_rcp_f32_e32 v35, v35
	v_exp_f32_e32 v36, v36
	v_mul_f32_e32 v28, v28, v34
	v_lshlrev_b32_e32 v34, 16, v84
	v_mul_f32_e32 v31, v31, v35
	v_add_f32_e32 v35, 1.0, v36
	v_mul_f32_e32 v36, 0xbfb8aa3b, v25
	v_rcp_f32_e32 v35, v35
	v_exp_f32_e32 v36, v36
	v_mul_f32_e32 v28, v28, v34
	v_and_b32_e32 v34, 0xffff0000, v84
	v_mul_f32_e32 v24, v24, v35
	v_add_f32_e32 v35, 1.0, v36
	v_mul_f32_e32 v36, 0xbfb8aa3b, v26
	v_rcp_f32_e32 v35, v35
	v_exp_f32_e32 v36, v36
	v_mul_f32_e32 v29, v29, v34
	v_lshlrev_b32_e32 v34, 16, v85
	v_mul_f32_e32 v25, v25, v35
	v_add_f32_e32 v35, 1.0, v36
	v_mul_f32_e32 v36, 0xbfb8aa3b, v27
	v_rcp_f32_e32 v35, v35
	v_exp_f32_e32 v36, v36
	v_mul_f32_e32 v30, v30, v34
	v_and_b32_e32 v34, 0xffff0000, v85
	v_mul_f32_e32 v26, v26, v35
	v_add_f32_e32 v35, 1.0, v36
	v_mul_f32_e32 v36, 0xbfb8aa3b, v20
	v_rcp_f32_e32 v35, v35
	v_exp_f32_e32 v36, v36
	v_mul_f32_e32 v31, v31, v34
	v_lshlrev_b32_e32 v34, 16, v86
	v_mul_f32_e32 v27, v27, v35
	v_add_f32_e32 v35, 1.0, v36
	v_mul_f32_e32 v36, 0xbfb8aa3b, v21
	v_rcp_f32_e32 v35, v35
	v_exp_f32_e32 v36, v36
	v_mul_f32_e32 v24, v24, v34
	v_and_b32_e32 v34, 0xffff0000, v86
	v_mul_f32_e32 v20, v20, v35
	v_add_f32_e32 v35, 1.0, v36
	v_mul_f32_e32 v36, 0xbfb8aa3b, v22
	v_rcp_f32_e32 v35, v35
	v_exp_f32_e32 v36, v36
	v_mul_f32_e32 v25, v25, v34
	v_lshlrev_b32_e32 v34, 16, v87
	v_mul_f32_e32 v26, v26, v34
	v_and_b32_e32 v34, 0xffff0000, v87
	v_mul_f32_e32 v27, v27, v34
	v_lshlrev_b32_e32 v34, 16, v76
	v_mul_f32_e32 v34, v20, v34
	v_mul_f32_e32 v20, v21, v35
	v_add_f32_e32 v35, 1.0, v36
	v_mul_f32_e32 v36, 0xbfb8aa3b, v23
	v_rcp_f32_e32 v35, v35
	v_exp_f32_e32 v36, v36
	v_and_b32_e32 v21, 0xffff0000, v76
	v_mul_f32_e32 v37, v20, v21
	v_mul_f32_e32 v20, v22, v35
	v_add_f32_e32 v22, 1.0, v36
	v_rcp_f32_e32 v22, v22
	v_mul_f32_e32 v35, 0xbfb8aa3b, v16
	v_exp_f32_e32 v35, v35
	v_lshlrev_b32_e32 v21, 16, v77
	v_mul_f32_e32 v36, v20, v21
	v_mul_f32_e32 v20, v23, v22
	v_mul_f32_e32 v23, 0xbfb8aa3b, v17
	v_add_f32_e32 v22, 1.0, v35
	v_exp_f32_e32 v23, v23
	v_rcp_f32_e32 v22, v22
	v_and_b32_e32 v21, 0xffff0000, v77
	v_mul_f32_e32 v35, v20, v21
	v_add_f32_e32 v21, 1.0, v23
	v_mul_f32_e32 v16, v16, v22
	v_rcp_f32_e32 v21, v21
	v_mul_f32_e32 v22, 0xbfb8aa3b, v18
	v_exp_f32_e32 v22, v22
	v_lshlrev_b32_e32 v20, 16, v78
	v_mul_f32_e32 v23, v16, v20
	v_mul_f32_e32 v16, v17, v21
	v_and_b32_e32 v17, 0xffff0000, v78
	v_add_f32_e32 v20, 1.0, v22
	v_mul_f32_e32 v22, v16, v17
	v_mul_f32_e32 v16, 0xbfb8aa3b, v19
	v_rcp_f32_e32 v20, v20
	v_exp_f32_e32 v16, v16
	v_mov_b32_e32 v21, v74
	v_mov_b32_e32 v74, v83
	v_mul_f32_e32 v17, v18, v20
	v_lshlrev_b32_e32 v18, 16, v79
	v_add_f32_e32 v16, 1.0, v16
	v_mul_f32_e32 v38, v17, v18
	v_rcp_f32_e32 v18, v16
	v_mov_b32_e32 v16, v80
	v_mov_b32_e32 v17, v72
	v_mov_b32_e32 v72, v81
	v_pk_add_f32 v[16:17], v[16:17], v[72:73]
	v_mov_b32_e32 v20, v82
	v_pk_add_f32 v[16:17], v[20:21], v[16:17]
	v_lshl_add_u64 v[32:33], s[2:3], 0, v[98:99]
	v_pk_add_f32 v[16:17], v[74:75], v[16:17]
	v_lshl_add_u64 v[32:33], v[32:33], 0, v[170:171]
	v_pk_fma_f32 v[20:21], v[16:17], s[14:15], v[112:113] op_sel_hi:[1,0,0]
	v_mul_f32_e32 v17, v19, v18
	v_mul_f32_e32 v16, 0x4b800000, v21
	v_cmp_gt_f32_e32 vcc, s5, v21
	v_and_b32_e32 v18, 0xffff0000, v79
	s_mov_b64 s[14:15], s[8:9]
	v_cndmask_b32_e32 v16, v21, v16, vcc
	v_rsq_f32_e32 v16, v16
	v_mul_f32_e32 v21, v17, v18
	v_mul_f32_e32 v17, 0x45800000, v16
	v_cndmask_b32_e32 v39, v16, v17, vcc
	v_mul_f32_e32 v16, v28, v39
	v_mul_f32_e32 v17, v29, v39
	v_cvt_pk_bf16_f32 v16, v16, v17
	v_mul_f32_e32 v17, v30, v39
	v_mul_f32_e32 v18, v31, v39
	v_cvt_pk_bf16_f32 v17, v17, v18
	v_mul_f32_e32 v18, v24, v39
	v_mul_f32_e32 v19, v25, v39
	v_cvt_pk_bf16_f32 v18, v18, v19
	v_mul_f32_e32 v19, v26, v39
	v_mul_f32_e32 v24, v27, v39
	v_cvt_pk_bf16_f32 v19, v19, v24
	global_store_dwordx4 v[32:33], v[16:19], off
	v_mul_f32_e32 v21, v21, v39
	v_cmp_gt_f32_e32 vcc, s5, v20
	v_mul_f32_e32 v16, v34, v39
	v_mul_f32_e32 v17, v37, v39
	v_cvt_pk_bf16_f32 v16, v16, v17
	v_mul_f32_e32 v17, v36, v39
	v_mul_f32_e32 v18, v35, v39
	v_cvt_pk_bf16_f32 v17, v17, v18
	v_mul_f32_e32 v18, v23, v39
	v_mul_f32_e32 v19, v22, v39
	v_cvt_pk_bf16_f32 v18, v18, v19
	v_mul_f32_e32 v19, v38, v39
	v_cvt_pk_bf16_f32 v19, v19, v21
	v_mul_f32_e32 v21, 0x4b800000, v20
	v_cndmask_b32_e32 v20, v20, v21, vcc
	global_store_dwordx4 v[32:33], v[16:19], off offset:256
	v_rsq_f32_e32 v20, v20
	s_nop 0
	v_mul_f32_e32 v16, 0xbfb8aa3b, v12
	v_exp_f32_e32 v18, v16
	v_mul_f32_e32 v16, 0x45800000, v20
	v_cndmask_b32_e32 v19, v20, v16, vcc
	v_mul_f32_e32 v20, 0xbfb8aa3b, v13
	v_add_f32_e32 v18, 1.0, v18
	v_rcp_f32_e32 v18, v18
	v_exp_f32_e32 v20, v20
	v_lshl_add_u64 v[16:17], s[2:3], 0, v[96:97]
	v_lshl_add_u64 v[16:17], v[16:17], 0, v[170:171]
	v_mul_f32_e32 v12, v12, v18
	v_lshlrev_b32_e32 v18, 16, v68
	v_mul_f32_e32 v12, v12, v18
	v_add_f32_e32 v18, 1.0, v20
	v_rcp_f32_e32 v18, v18
	v_mul_f32_e32 v20, 0xbfb8aa3b, v14
	v_exp_f32_e32 v20, v20
	v_mul_f32_e32 v12, v12, v19
	v_mul_f32_e32 v13, v13, v18
	v_and_b32_e32 v18, 0xffff0000, v68
	v_mul_f32_e32 v13, v13, v18
	v_add_f32_e32 v18, 1.0, v20
	v_mul_f32_e32 v20, 0xbfb8aa3b, v15
	v_rcp_f32_e32 v18, v18
	v_exp_f32_e32 v20, v20
	v_mul_f32_e32 v13, v13, v19
	v_cvt_pk_bf16_f32 v12, v12, v13
	v_mul_f32_e32 v13, v14, v18
	v_add_f32_e32 v14, 1.0, v20
	v_rcp_f32_e32 v14, v14
	v_lshlrev_b32_e32 v18, 16, v69
	v_mul_f32_e32 v13, v13, v18
	v_and_b32_e32 v18, 0xffff0000, v69
	v_mul_f32_e32 v14, v15, v14
	v_mul_f32_e32 v15, 0xbfb8aa3b, v8
	v_exp_f32_e32 v15, v15
	v_mul_f32_e32 v14, v14, v18
	v_mul_f32_e32 v13, v13, v19
	v_mul_f32_e32 v14, v14, v19
	v_add_f32_e32 v15, 1.0, v15
	v_cvt_pk_bf16_f32 v13, v13, v14
	v_mul_f32_e32 v14, 0xbfb8aa3b, v9
	v_rcp_f32_e32 v15, v15
	v_exp_f32_e32 v14, v14
	s_and_b64 vcc, exec, s[0:1]
	v_mul_f32_e32 v8, v8, v15
	v_lshlrev_b32_e32 v15, 16, v70
	v_add_f32_e32 v14, 1.0, v14
	v_mul_f32_e32 v8, v8, v15
	v_rcp_f32_e32 v14, v14
	v_mul_f32_e32 v15, 0xbfb8aa3b, v10
	v_exp_f32_e32 v15, v15
	v_mul_f32_e32 v8, v8, v19
	v_mul_f32_e32 v9, v9, v14
	v_and_b32_e32 v14, 0xffff0000, v70
	v_mul_f32_e32 v9, v9, v14
	v_add_f32_e32 v14, 1.0, v15
	v_rcp_f32_e32 v15, v14
	v_mul_f32_e32 v14, 0xbfb8aa3b, v11
	v_exp_f32_e32 v18, v14
	v_mul_f32_e32 v9, v9, v19
	v_cvt_pk_bf16_f32 v14, v8, v9
	v_mul_f32_e32 v8, v10, v15
	v_add_f32_e32 v9, 1.0, v18
	v_rcp_f32_e32 v9, v9
	v_lshlrev_b32_e32 v10, 16, v71
	v_mul_f32_e32 v8, v8, v10
	v_and_b32_e32 v10, 0xffff0000, v71
	v_mul_f32_e32 v9, v11, v9
	v_mul_f32_e32 v11, 0xbfb8aa3b, v4
	v_exp_f32_e32 v11, v11
	v_mul_f32_e32 v8, v8, v19
	v_mul_f32_e32 v9, v9, v10
	v_mul_f32_e32 v9, v9, v19
	v_cvt_pk_bf16_f32 v15, v8, v9
	v_add_f32_e32 v8, 1.0, v11
	v_rcp_f32_e32 v8, v8
	v_mul_f32_e32 v9, 0xbfb8aa3b, v5
	v_exp_f32_e32 v9, v9
	global_store_dwordx4 v[16:17], v[12:15], off
	v_mul_f32_e32 v4, v4, v8
	v_lshlrev_b32_e32 v8, 16, v64
	v_mul_f32_e32 v4, v4, v8
	v_add_f32_e32 v8, 1.0, v9
	v_rcp_f32_e32 v8, v8
	v_mul_f32_e32 v9, 0xbfb8aa3b, v6
	v_exp_f32_e32 v9, v9
	v_mul_f32_e32 v4, v4, v19
	v_mul_f32_e32 v5, v5, v8
	v_and_b32_e32 v8, 0xffff0000, v64
	v_mul_f32_e32 v5, v5, v8
	v_add_f32_e32 v8, 1.0, v9
	v_mul_f32_e32 v9, 0xbfb8aa3b, v7
	v_rcp_f32_e32 v8, v8
	v_exp_f32_e32 v9, v9
	v_mul_f32_e32 v5, v5, v19
	v_cvt_pk_bf16_f32 v4, v4, v5
	v_mul_f32_e32 v5, v6, v8
	v_add_f32_e32 v6, 1.0, v9
	v_rcp_f32_e32 v6, v6
	v_lshlrev_b32_e32 v8, 16, v65
	v_mul_f32_e32 v5, v5, v8
	v_and_b32_e32 v8, 0xffff0000, v65
	v_mul_f32_e32 v6, v7, v6
	v_mul_f32_e32 v7, 0xbfb8aa3b, v0
	v_exp_f32_e32 v7, v7
	v_mul_f32_e32 v6, v6, v8
	v_mul_f32_e32 v5, v5, v19
	v_mul_f32_e32 v6, v6, v19
	v_add_f32_e32 v7, 1.0, v7
	v_cvt_pk_bf16_f32 v5, v5, v6
	v_mul_f32_e32 v6, 0xbfb8aa3b, v1
	v_rcp_f32_e32 v7, v7
	v_exp_f32_e32 v6, v6
	v_mul_f32_e32 v0, v0, v7
	v_lshlrev_b32_e32 v7, 16, v66
	v_add_f32_e32 v6, 1.0, v6
	v_mul_f32_e32 v0, v0, v7
	v_rcp_f32_e32 v6, v6
	v_mul_f32_e32 v7, 0xbfb8aa3b, v2
	v_exp_f32_e32 v7, v7
	v_mul_f32_e32 v0, v0, v19
	v_mul_f32_e32 v1, v1, v6
	v_and_b32_e32 v6, 0xffff0000, v66
	v_mul_f32_e32 v1, v1, v6
	v_add_f32_e32 v6, 1.0, v7
	v_rcp_f32_e32 v7, v6
	v_mul_f32_e32 v6, 0xbfb8aa3b, v3
	v_exp_f32_e32 v8, v6
	v_mul_f32_e32 v1, v1, v19
	v_cvt_pk_bf16_f32 v6, v0, v1
	v_mul_f32_e32 v0, v2, v7
	v_add_f32_e32 v1, 1.0, v8
	v_rcp_f32_e32 v1, v1
	v_lshlrev_b32_e32 v2, 16, v67
	v_mul_f32_e32 v0, v0, v2
	v_and_b32_e32 v2, 0xffff0000, v67
	v_mul_f32_e32 v1, v3, v1
	v_mul_f32_e32 v1, v1, v2
	v_mul_f32_e32 v0, v0, v19
	v_mul_f32_e32 v1, v1, v19
	v_cvt_pk_bf16_f32 v7, v0, v1
	global_store_dwordx4 v[16:17], v[4:7], off offset:256
	s_cbranch_vccz .LBB0_80
	s_waitcnt vmcnt(0)
	s_cmpk_gt_u32 s21, 0xff
	s_cbranch_scc1 .LBB0_91
	s_barrier

.LBB0_199:
	v_mov_b64_e32 v[0:1], 0x1000
	s_ashr_i32 s9, s8, 31
	v_cmp_lt_i64_e32 vcc, s[10:11], v[0:1]
	s_lshl_b64 s[10:11], s[8:9], 20
	s_add_u32 s10, s23, s10
	s_addc_u32 s11, s24, s11
	s_and_b64 s[12:13], vcc, exec
	s_cselect_b32 s5, s11, s15
	s_cselect_b32 s9, s10, s14
	s_ashr_i32 s7, s6, 31
	s_lshl_b64 s[12:13], s[6:7], 20
	s_add_u32 s12, s25, s12
	s_addc_u32 s13, s26, s13
	s_and_b64 s[18:19], vcc, exec
	s_cselect_b32 s7, s13, s17
	s_cselect_b32 s37, s12, s16
	s_add_u32 s14, s14, 0x80080
	s_addc_u32 s15, s15, 0
	s_add_u32 s38, s16, 0x100
	s_addc_u32 s39, s17, 0
	s_mov_b32 s40, -2
	s_mov_b64 s[48:49], 0x80
	v_add_u32_e32 v222, 0x10000, v238
	s_add_u32 s16, s14, 0xfff80080
	s_addc_u32 s17, s15, -1
	s_add_i32 s41, 0, 0x10000
	ds_read_b128 v[128:131], v222 offset:0
	ds_read_b128 v[132:135], v222 offset:1024
	ds_read_b128 v[136:139], v222 offset:2048
	ds_read_b128 v[140:143], v222 offset:3072
	s_cmp_eq_u32 s40, 28
	s_cselect_b32 s19, s5, s17
	s_cselect_b32 s18, s9, s16
	s_cselect_b32 s17, s7, s39
	s_cselect_b32 s16, s37, s38
	s_add_i32 m0, s28, 0xc000
	ds_read_b128 v[144:147], v240
	ds_read_b128 v[148:151], v240 offset:1024
	ds_read_b128 v[152:155], v240 offset:2048
	ds_read_b128 v[156:159], v240 offset:3072
	ds_read_b128 v[160:163], v240 offset:4096
	ds_read_b128 v[164:167], v240 offset:5120
	ds_read_b128 v[168:171], v240 offset:6144
	ds_read_b128 v[172:175], v240 offset:7168
	global_load_lds_dwordx4 v218, s[14:15]
	s_add_i32 m0, s28, 0xe000
	s_nop 0
	global_load_lds_dwordx4 v220, s[14:15]
	s_waitcnt lgkmcnt(8)
	s_barrier
	s_waitcnt lgkmcnt(0)
	v_mfma_f32_16x16x32_bf16 v[124:127], v[128:131], v[144:147], 0
	v_mfma_f32_16x16x32_bf16 v[120:123], v[136:139], v[144:147], 0
	s_add_i32 s44, 0, 0x14000
	v_mfma_f32_16x16x32_bf16 v[116:119], v[128:131], v[152:155], 0
	s_add_i32 s41, s41, s27
	v_mfma_f32_16x16x32_bf16 v[108:111], v[136:139], v[152:155], 0
	s_mov_b32 m0, s41
	v_mfma_f32_16x16x32_bf16 v[100:103], v[128:131], v[160:163], 0
	v_mfma_f32_16x16x32_bf16 v[92:95], v[136:139], v[160:163], 0
	v_mfma_f32_16x16x32_bf16 v[84:87], v[128:131], v[168:171], 0
	v_mfma_f32_16x16x32_bf16 v[76:79], v[136:139], v[168:171], 0
	v_mfma_f32_16x16x32_bf16 v[124:127], v[132:135], v[148:151], v[124:127]
	v_mfma_f32_16x16x32_bf16 v[120:123], v[140:143], v[148:151], v[120:123]
	v_mfma_f32_16x16x32_bf16 v[116:119], v[132:135], v[156:159], v[116:119]
	v_mfma_f32_16x16x32_bf16 v[108:111], v[140:143], v[156:159], v[108:111]
	v_mfma_f32_16x16x32_bf16 v[100:103], v[132:135], v[164:167], v[100:103]
	v_mfma_f32_16x16x32_bf16 v[92:95], v[140:143], v[164:167], v[92:95]
	v_mfma_f32_16x16x32_bf16 v[84:87], v[132:135], v[172:175], v[84:87]
	v_mfma_f32_16x16x32_bf16 v[76:79], v[140:143], v[172:175], v[76:79]
	s_barrier
	ds_read_b128 v[176:179], v222 offset:16384
	ds_read_b128 v[180:183], v222 offset:17408
	ds_read_b128 v[184:187], v222 offset:18432
	ds_read_b128 v[188:191], v222 offset:19456
	global_load_lds_dwordx4 v206, s[16:17]
	s_add_i32 m0, s41, 0x2000
	s_nop 0
	global_load_lds_dwordx4 v210, s[16:17]
	s_barrier
	s_waitcnt lgkmcnt(0)
	v_mfma_f32_16x16x32_bf16 v[112:115], v[176:179], v[144:147], 0
	v_mfma_f32_16x16x32_bf16 v[104:107], v[184:187], v[144:147], 0
	s_mov_b32 m0, s28
	v_mfma_f32_16x16x32_bf16 v[96:99], v[176:179], v[152:155], 0
	s_add_u32 s48, s18, 0x80
	v_mfma_f32_16x16x32_bf16 v[88:91], v[184:187], v[152:155], 0
	s_addc_u32 s49, s19, 0
	v_mfma_f32_16x16x32_bf16 v[80:83], v[176:179], v[160:163], 0
	v_mfma_f32_16x16x32_bf16 v[72:75], v[184:187], v[160:163], 0
	v_mfma_f32_16x16x32_bf16 v[68:71], v[176:179], v[168:171], 0
	v_mfma_f32_16x16x32_bf16 v[64:67], v[184:187], v[168:171], 0
	v_mfma_f32_16x16x32_bf16 v[112:115], v[180:183], v[148:151], v[112:115]
	v_mfma_f32_16x16x32_bf16 v[104:107], v[188:191], v[148:151], v[104:107]
	v_mfma_f32_16x16x32_bf16 v[96:99], v[180:183], v[156:159], v[96:99]
	v_mfma_f32_16x16x32_bf16 v[88:91], v[188:191], v[156:159], v[88:91]
	v_mfma_f32_16x16x32_bf16 v[80:83], v[180:183], v[164:167], v[80:83]
	v_mfma_f32_16x16x32_bf16 v[72:75], v[188:191], v[164:167], v[72:75]
	v_mfma_f32_16x16x32_bf16 v[68:71], v[180:183], v[172:175], v[68:71]
	v_mfma_f32_16x16x32_bf16 v[64:67], v[188:191], v[172:175], v[64:67]
	s_barrier
	ds_read_b128 v[144:147], v240 offset:16384
	ds_read_b128 v[148:151], v240 offset:17408
	ds_read_b128 v[152:155], v240 offset:18432
	ds_read_b128 v[156:159], v240 offset:19456
	ds_read_b128 v[160:163], v240 offset:20480
	ds_read_b128 v[164:167], v240 offset:21504
	ds_read_b128 v[168:171], v240 offset:22528
	ds_read_b128 v[172:175], v240 offset:23552
	global_load_lds_dwordx4 v204, s[18:19]
	s_mov_b32 m0, s29
	s_nop 0
	global_load_lds_dwordx4 v208, s[18:19]
	s_barrier
	s_waitcnt lgkmcnt(0)
	v_mfma_f32_16x16x32_bf16 v[60:63], v[128:131], v[144:147], 0
	v_mfma_f32_16x16x32_bf16 v[56:59], v[136:139], v[144:147], 0
	s_add_u32 s42, s16, 0x80000
	v_mfma_f32_16x16x32_bf16 v[52:55], v[128:131], v[152:155], 0
	s_addc_u32 s43, s17, 0
	v_mfma_f32_16x16x32_bf16 v[44:47], v[136:139], v[152:155], 0
	s_add_i32 s41, s44, s27
	v_mfma_f32_16x16x32_bf16 v[36:39], v[128:131], v[160:163], 0
	s_mov_b32 m0, s41
	v_mfma_f32_16x16x32_bf16 v[28:31], v[136:139], v[160:163], 0
	v_mfma_f32_16x16x32_bf16 v[20:23], v[128:131], v[168:171], 0
	v_mfma_f32_16x16x32_bf16 v[12:15], v[136:139], v[168:171], 0
	v_mfma_f32_16x16x32_bf16 v[60:63], v[132:135], v[148:151], v[60:63]
	v_mfma_f32_16x16x32_bf16 v[56:59], v[140:143], v[148:151], v[56:59]
	v_mfma_f32_16x16x32_bf16 v[52:55], v[132:135], v[156:159], v[52:55]
	v_mfma_f32_16x16x32_bf16 v[44:47], v[140:143], v[156:159], v[44:47]
	v_mfma_f32_16x16x32_bf16 v[36:39], v[132:135], v[164:167], v[36:39]
	v_mfma_f32_16x16x32_bf16 v[28:31], v[140:143], v[164:167], v[28:31]
	v_mfma_f32_16x16x32_bf16 v[20:23], v[132:135], v[172:175], v[20:23]
	v_mfma_f32_16x16x32_bf16 v[12:15], v[140:143], v[172:175], v[12:15]
	s_barrier
	global_load_lds_dwordx4 v206, s[42:43]
	s_add_i32 m0, s41, 0x2000
	s_nop 0
	global_load_lds_dwordx4 v210, s[42:43]
	s_waitcnt vmcnt(6)
	s_barrier
	v_mfma_f32_16x16x32_bf16 v[48:51], v[176:179], v[144:147], 0
	v_mfma_f32_16x16x32_bf16 v[40:43], v[184:187], v[144:147], 0
	s_add_i32 s41, 0, 0x18000
	v_mfma_f32_16x16x32_bf16 v[32:35], v[176:179], v[152:155], 0
	s_add_u32 s18, s18, 0x80000
	v_mfma_f32_16x16x32_bf16 v[24:27], v[184:187], v[152:155], 0
	s_addc_u32 s19, s19, 0
	v_mfma_f32_16x16x32_bf16 v[16:19], v[176:179], v[160:163], 0
	s_mov_b32 m0, s30
	v_mfma_f32_16x16x32_bf16 v[8:11], v[184:187], v[160:163], 0
	v_mfma_f32_16x16x32_bf16 v[4:7], v[176:179], v[168:171], 0
	v_mfma_f32_16x16x32_bf16 v[0:3], v[184:187], v[168:171], 0
	v_mfma_f32_16x16x32_bf16 v[48:51], v[180:183], v[148:151], v[48:51]
	v_mfma_f32_16x16x32_bf16 v[40:43], v[188:191], v[148:151], v[40:43]
	v_mfma_f32_16x16x32_bf16 v[32:35], v[180:183], v[156:159], v[32:35]
	v_mfma_f32_16x16x32_bf16 v[24:27], v[188:191], v[156:159], v[24:27]
	v_mfma_f32_16x16x32_bf16 v[16:19], v[180:183], v[164:167], v[16:19]
	v_mfma_f32_16x16x32_bf16 v[8:11], v[188:191], v[164:167], v[8:11]
	v_mfma_f32_16x16x32_bf16 v[4:7], v[180:183], v[172:175], v[4:7]
	v_mfma_f32_16x16x32_bf16 v[0:3], v[188:191], v[172:175], v[0:3]
	s_barrier
	ds_read_b128 v[128:131], v222 offset:32768
	ds_read_b128 v[132:135], v222 offset:33792
	ds_read_b128 v[136:139], v222 offset:34816
	ds_read_b128 v[140:143], v222 offset:35840
	ds_read_b128 v[144:147], v240 offset:32768
	ds_read_b128 v[148:151], v240 offset:33792
	ds_read_b128 v[152:155], v240 offset:34816
	ds_read_b128 v[156:159], v240 offset:35840
	ds_read_b128 v[160:163], v240 offset:36864
	ds_read_b128 v[164:167], v240 offset:37888
	ds_read_b128 v[168:171], v240 offset:38912
	ds_read_b128 v[172:175], v240 offset:39936
	global_load_lds_dwordx4 v204, s[18:19]
	s_mov_b32 m0, s31
	s_nop 0
	global_load_lds_dwordx4 v208, s[18:19]
	s_waitcnt lgkmcnt(8)
	s_barrier
	s_waitcnt lgkmcnt(0)
	v_mfma_f32_16x16x32_bf16 v[124:127], v[128:131], v[144:147], v[124:127]
	v_mfma_f32_16x16x32_bf16 v[120:123], v[136:139], v[144:147], v[120:123]
	s_add_i32 s18, 0, 0x1c000
	v_mfma_f32_16x16x32_bf16 v[116:119], v[128:131], v[152:155], v[116:119]
	s_add_i32 s19, s41, s27
	v_mfma_f32_16x16x32_bf16 v[108:111], v[136:139], v[152:155], v[108:111]
	s_add_i32 m0, s19, 0xffffff80
	v_mfma_f32_16x16x32_bf16 v[100:103], v[128:131], v[160:163], v[100:103]
	v_mfma_f32_16x16x32_bf16 v[92:95], v[136:139], v[160:163], v[92:95]
	v_mfma_f32_16x16x32_bf16 v[84:87], v[128:131], v[168:171], v[84:87]
	v_mfma_f32_16x16x32_bf16 v[76:79], v[136:139], v[168:171], v[76:79]
	v_mfma_f32_16x16x32_bf16 v[124:127], v[132:135], v[148:151], v[124:127]
	v_mfma_f32_16x16x32_bf16 v[120:123], v[140:143], v[148:151], v[120:123]
	v_mfma_f32_16x16x32_bf16 v[116:119], v[132:135], v[156:159], v[116:119]
	v_mfma_f32_16x16x32_bf16 v[108:111], v[140:143], v[156:159], v[108:111]
	v_mfma_f32_16x16x32_bf16 v[100:103], v[132:135], v[164:167], v[100:103]
	v_mfma_f32_16x16x32_bf16 v[92:95], v[140:143], v[164:167], v[92:95]
	v_mfma_f32_16x16x32_bf16 v[84:87], v[132:135], v[172:175], v[84:87]
	v_mfma_f32_16x16x32_bf16 v[76:79], v[140:143], v[172:175], v[76:79]
	s_barrier
	ds_read_b128 v[176:179], v222 offset:49152
	ds_read_b128 v[180:183], v222 offset:50176
	ds_read_b128 v[184:187], v222 offset:51200
	ds_read_b128 v[188:191], v222 offset:52224
	global_load_lds_dwordx4 v206, s[16:17] offset:128
	s_add_i32 m0, s19, 0x1f80
	s_nop 0
	global_load_lds_dwordx4 v210, s[16:17] offset:128
	s_barrier
	s_waitcnt lgkmcnt(0)
	v_mfma_f32_16x16x32_bf16 v[112:115], v[176:179], v[144:147], v[112:115]
	v_mfma_f32_16x16x32_bf16 v[104:107], v[184:187], v[144:147], v[104:107]
	s_mov_b32 m0, s33
	v_mfma_f32_16x16x32_bf16 v[96:99], v[176:179], v[152:155], v[96:99]
	v_mfma_f32_16x16x32_bf16 v[88:91], v[184:187], v[152:155], v[88:91]
	v_mfma_f32_16x16x32_bf16 v[80:83], v[176:179], v[160:163], v[80:83]
	v_mfma_f32_16x16x32_bf16 v[72:75], v[184:187], v[160:163], v[72:75]
	v_mfma_f32_16x16x32_bf16 v[68:71], v[176:179], v[168:171], v[68:71]
	v_mfma_f32_16x16x32_bf16 v[64:67], v[184:187], v[168:171], v[64:67]
	v_mfma_f32_16x16x32_bf16 v[112:115], v[180:183], v[148:151], v[112:115]
	v_mfma_f32_16x16x32_bf16 v[104:107], v[188:191], v[148:151], v[104:107]
	v_mfma_f32_16x16x32_bf16 v[96:99], v[180:183], v[156:159], v[96:99]
	v_mfma_f32_16x16x32_bf16 v[88:91], v[188:191], v[156:159], v[88:91]
	v_mfma_f32_16x16x32_bf16 v[80:83], v[180:183], v[164:167], v[80:83]
	v_mfma_f32_16x16x32_bf16 v[72:75], v[188:191], v[164:167], v[72:75]
	v_mfma_f32_16x16x32_bf16 v[68:71], v[180:183], v[172:175], v[68:71]
	v_mfma_f32_16x16x32_bf16 v[64:67], v[188:191], v[172:175], v[64:67]
	s_barrier
	ds_read_b128 v[144:147], v240 offset:49152
	ds_read_b128 v[148:151], v240 offset:50176
	ds_read_b128 v[152:155], v240 offset:51200
	ds_read_b128 v[156:159], v240 offset:52224
	ds_read_b128 v[160:163], v240 offset:53248
	ds_read_b128 v[164:167], v240 offset:54272
	ds_read_b128 v[168:171], v240 offset:55296
	ds_read_b128 v[172:175], v240 offset:56320
	global_load_lds_dwordx4 v204, s[48:49]
	s_mov_b32 m0, s34
	s_nop 0
	global_load_lds_dwordx4 v208, s[48:49]
	s_barrier
	s_waitcnt lgkmcnt(0)
	v_mfma_f32_16x16x32_bf16 v[60:63], v[128:131], v[144:147], v[60:63]
	v_mfma_f32_16x16x32_bf16 v[56:59], v[136:139], v[144:147], v[56:59]
	s_add_u32 s16, s16, 0x80080
	v_mfma_f32_16x16x32_bf16 v[52:55], v[128:131], v[152:155], v[52:55]
	s_addc_u32 s17, s17, 0
	v_mfma_f32_16x16x32_bf16 v[44:47], v[136:139], v[152:155], v[44:47]
	s_add_i32 s18, s18, s27
	v_mfma_f32_16x16x32_bf16 v[36:39], v[128:131], v[160:163], v[36:39]
	s_mov_b32 m0, s18
	v_mfma_f32_16x16x32_bf16 v[28:31], v[136:139], v[160:163], v[28:31]
	v_mfma_f32_16x16x32_bf16 v[20:23], v[128:131], v[168:171], v[20:23]
	v_mfma_f32_16x16x32_bf16 v[12:15], v[136:139], v[168:171], v[12:15]
	v_mfma_f32_16x16x32_bf16 v[60:63], v[132:135], v[148:151], v[60:63]
	v_mfma_f32_16x16x32_bf16 v[56:59], v[140:143], v[148:151], v[56:59]
	v_mfma_f32_16x16x32_bf16 v[52:55], v[132:135], v[156:159], v[52:55]
	v_mfma_f32_16x16x32_bf16 v[44:47], v[140:143], v[156:159], v[44:47]
	v_mfma_f32_16x16x32_bf16 v[36:39], v[132:135], v[164:167], v[36:39]
	v_mfma_f32_16x16x32_bf16 v[28:31], v[140:143], v[164:167], v[28:31]
	v_mfma_f32_16x16x32_bf16 v[20:23], v[132:135], v[172:175], v[20:23]
	v_mfma_f32_16x16x32_bf16 v[12:15], v[140:143], v[172:175], v[12:15]
	s_barrier
	global_load_lds_dwordx4 v206, s[16:17]
	s_add_i32 m0, s18, 0x2000
	s_nop 0
	global_load_lds_dwordx4 v210, s[16:17]
	s_waitcnt vmcnt(6)
	s_barrier
	v_mfma_f32_16x16x32_bf16 v[48:51], v[176:179], v[144:147], v[48:51]
	v_mfma_f32_16x16x32_bf16 v[40:43], v[184:187], v[144:147], v[40:43]
	s_add_i32 s40, s40, 2
	v_mfma_f32_16x16x32_bf16 v[32:35], v[176:179], v[152:155], v[32:35]
	s_add_u32 s14, s14, 0x100
	v_mfma_f32_16x16x32_bf16 v[24:27], v[184:187], v[152:155], v[24:27]
	s_addc_u32 s15, s15, 0
	v_mfma_f32_16x16x32_bf16 v[16:19], v[176:179], v[160:163], v[16:19]
	s_add_u32 s38, s38, 0x100
	v_mfma_f32_16x16x32_bf16 v[8:11], v[184:187], v[160:163], v[8:11]
	s_addc_u32 s39, s39, 0
	v_mfma_f32_16x16x32_bf16 v[4:7], v[176:179], v[168:171], v[4:7]
	s_add_u32 s16, s14, 0xfff80080
	s_addc_u32 s17, s15, -1
	v_mfma_f32_16x16x32_bf16 v[0:3], v[184:187], v[168:171], v[0:3]
	s_add_i32 s41, 0, 0x10000
	s_cmp_eq_u32 s40, 28
	v_mfma_f32_16x16x32_bf16 v[48:51], v[180:183], v[148:151], v[48:51]
	s_cselect_b32 s19, s5, s17
	s_cselect_b32 s18, s9, s16
	v_mfma_f32_16x16x32_bf16 v[40:43], v[188:191], v[148:151], v[40:43]
	s_cselect_b32 s17, s7, s39
	s_cselect_b32 s16, s37, s38
	v_mfma_f32_16x16x32_bf16 v[32:35], v[180:183], v[156:159], v[32:35]
	s_add_i32 m0, s28, 0xc000
	v_mfma_f32_16x16x32_bf16 v[24:27], v[188:191], v[156:159], v[24:27]
	v_mfma_f32_16x16x32_bf16 v[16:19], v[180:183], v[164:167], v[16:19]
	v_mfma_f32_16x16x32_bf16 v[8:11], v[188:191], v[164:167], v[8:11]
	v_mfma_f32_16x16x32_bf16 v[4:7], v[180:183], v[172:175], v[4:7]
	v_mfma_f32_16x16x32_bf16 v[0:3], v[188:191], v[172:175], v[0:3]
	s_cmp_gt_u32 s40, 29
	s_barrier
.LBB0_200:
	ds_read_b128 v[128:131], v222 offset:0
	ds_read_b128 v[132:135], v222 offset:1024
	ds_read_b128 v[136:139], v222 offset:2048
	ds_read_b128 v[140:143], v222 offset:3072
	ds_read_b128 v[144:147], v240
	ds_read_b128 v[148:151], v240 offset:1024
	ds_read_b128 v[152:155], v240 offset:2048
	ds_read_b128 v[156:159], v240 offset:3072
	ds_read_b128 v[160:163], v240 offset:4096
	ds_read_b128 v[164:167], v240 offset:5120
	ds_read_b128 v[168:171], v240 offset:6144
	ds_read_b128 v[172:175], v240 offset:7168
	global_load_lds_dwordx4 v218, s[14:15]
	s_add_i32 m0, s28, 0xe000
	s_nop 0
	global_load_lds_dwordx4 v220, s[14:15]
	s_waitcnt lgkmcnt(8)
	s_barrier
	s_waitcnt lgkmcnt(0)
	v_mfma_f32_16x16x32_bf16 v[124:127], v[128:131], v[144:147], v[124:127]
	v_mfma_f32_16x16x32_bf16 v[120:123], v[136:139], v[144:147], v[120:123]
	s_add_i32 s44, 0, 0x14000
	v_mfma_f32_16x16x32_bf16 v[116:119], v[128:131], v[152:155], v[116:119]
	s_add_i32 s41, s41, s27
	v_mfma_f32_16x16x32_bf16 v[108:111], v[136:139], v[152:155], v[108:111]
	s_mov_b32 m0, s41
	v_mfma_f32_16x16x32_bf16 v[100:103], v[128:131], v[160:163], v[100:103]
	v_mfma_f32_16x16x32_bf16 v[92:95], v[136:139], v[160:163], v[92:95]
	v_mfma_f32_16x16x32_bf16 v[84:87], v[128:131], v[168:171], v[84:87]
	v_mfma_f32_16x16x32_bf16 v[76:79], v[136:139], v[168:171], v[76:79]
	v_mfma_f32_16x16x32_bf16 v[124:127], v[132:135], v[148:151], v[124:127]
	v_mfma_f32_16x16x32_bf16 v[120:123], v[140:143], v[148:151], v[120:123]
	v_mfma_f32_16x16x32_bf16 v[116:119], v[132:135], v[156:159], v[116:119]
	v_mfma_f32_16x16x32_bf16 v[108:111], v[140:143], v[156:159], v[108:111]
	v_mfma_f32_16x16x32_bf16 v[100:103], v[132:135], v[164:167], v[100:103]
	v_mfma_f32_16x16x32_bf16 v[92:95], v[140:143], v[164:167], v[92:95]
	v_mfma_f32_16x16x32_bf16 v[84:87], v[132:135], v[172:175], v[84:87]
	v_mfma_f32_16x16x32_bf16 v[76:79], v[140:143], v[172:175], v[76:79]
	s_barrier
	ds_read_b128 v[176:179], v222 offset:16384
	ds_read_b128 v[180:183], v222 offset:17408
	ds_read_b128 v[184:187], v222 offset:18432
	ds_read_b128 v[188:191], v222 offset:19456
	global_load_lds_dwordx4 v206, s[16:17]
	s_add_i32 m0, s41, 0x2000
	s_nop 0
	global_load_lds_dwordx4 v210, s[16:17]
	s_barrier
	s_waitcnt lgkmcnt(0)
	v_mfma_f32_16x16x32_bf16 v[112:115], v[176:179], v[144:147], v[112:115]
	v_mfma_f32_16x16x32_bf16 v[104:107], v[184:187], v[144:147], v[104:107]
	s_mov_b32 m0, s28
	v_mfma_f32_16x16x32_bf16 v[96:99], v[176:179], v[152:155], v[96:99]
	s_add_u32 s48, s18, 0x80
	v_mfma_f32_16x16x32_bf16 v[88:91], v[184:187], v[152:155], v[88:91]
	s_addc_u32 s49, s19, 0
	v_mfma_f32_16x16x32_bf16 v[80:83], v[176:179], v[160:163], v[80:83]
	v_mfma_f32_16x16x32_bf16 v[72:75], v[184:187], v[160:163], v[72:75]
	v_mfma_f32_16x16x32_bf16 v[68:71], v[176:179], v[168:171], v[68:71]
	v_mfma_f32_16x16x32_bf16 v[64:67], v[184:187], v[168:171], v[64:67]
	v_mfma_f32_16x16x32_bf16 v[112:115], v[180:183], v[148:151], v[112:115]
	v_mfma_f32_16x16x32_bf16 v[104:107], v[188:191], v[148:151], v[104:107]
	v_mfma_f32_16x16x32_bf16 v[96:99], v[180:183], v[156:159], v[96:99]
	v_mfma_f32_16x16x32_bf16 v[88:91], v[188:191], v[156:159], v[88:91]
	v_mfma_f32_16x16x32_bf16 v[80:83], v[180:183], v[164:167], v[80:83]
	v_mfma_f32_16x16x32_bf16 v[72:75], v[188:191], v[164:167], v[72:75]
	v_mfma_f32_16x16x32_bf16 v[68:71], v[180:183], v[172:175], v[68:71]
	v_mfma_f32_16x16x32_bf16 v[64:67], v[188:191], v[172:175], v[64:67]
	s_barrier
	ds_read_b128 v[144:147], v240 offset:16384
	ds_read_b128 v[148:151], v240 offset:17408
	ds_read_b128 v[152:155], v240 offset:18432
	ds_read_b128 v[156:159], v240 offset:19456
	ds_read_b128 v[160:163], v240 offset:20480
	ds_read_b128 v[164:167], v240 offset:21504
	ds_read_b128 v[168:171], v240 offset:22528
	ds_read_b128 v[172:175], v240 offset:23552
	global_load_lds_dwordx4 v204, s[18:19]
	s_mov_b32 m0, s29
	s_nop 0
	global_load_lds_dwordx4 v208, s[18:19]
	s_barrier
	s_waitcnt lgkmcnt(0)
	v_mfma_f32_16x16x32_bf16 v[60:63], v[128:131], v[144:147], v[60:63]
	v_mfma_f32_16x16x32_bf16 v[56:59], v[136:139], v[144:147], v[56:59]
	s_add_u32 s42, s16, 0x80000
	v_mfma_f32_16x16x32_bf16 v[52:55], v[128:131], v[152:155], v[52:55]
	s_addc_u32 s43, s17, 0
	v_mfma_f32_16x16x32_bf16 v[44:47], v[136:139], v[152:155], v[44:47]
	s_add_i32 s41, s44, s27
	v_mfma_f32_16x16x32_bf16 v[36:39], v[128:131], v[160:163], v[36:39]
	s_mov_b32 m0, s41
	v_mfma_f32_16x16x32_bf16 v[28:31], v[136:139], v[160:163], v[28:31]
	v_mfma_f32_16x16x32_bf16 v[20:23], v[128:131], v[168:171], v[20:23]
	v_mfma_f32_16x16x32_bf16 v[12:15], v[136:139], v[168:171], v[12:15]
	v_mfma_f32_16x16x32_bf16 v[60:63], v[132:135], v[148:151], v[60:63]
	v_mfma_f32_16x16x32_bf16 v[56:59], v[140:143], v[148:151], v[56:59]
	v_mfma_f32_16x16x32_bf16 v[52:55], v[132:135], v[156:159], v[52:55]
	v_mfma_f32_16x16x32_bf16 v[44:47], v[140:143], v[156:159], v[44:47]
	v_mfma_f32_16x16x32_bf16 v[36:39], v[132:135], v[164:167], v[36:39]
	v_mfma_f32_16x16x32_bf16 v[28:31], v[140:143], v[164:167], v[28:31]
	v_mfma_f32_16x16x32_bf16 v[20:23], v[132:135], v[172:175], v[20:23]
	v_mfma_f32_16x16x32_bf16 v[12:15], v[140:143], v[172:175], v[12:15]
	s_barrier
	global_load_lds_dwordx4 v206, s[42:43]
	s_add_i32 m0, s41, 0x2000
	s_nop 0
	global_load_lds_dwordx4 v210, s[42:43]
	s_waitcnt vmcnt(6)
	s_barrier
	v_mfma_f32_16x16x32_bf16 v[48:51], v[176:179], v[144:147], v[48:51]
	v_mfma_f32_16x16x32_bf16 v[40:43], v[184:187], v[144:147], v[40:43]
	s_add_i32 s41, 0, 0x18000
	v_mfma_f32_16x16x32_bf16 v[32:35], v[176:179], v[152:155], v[32:35]
	s_add_u32 s18, s18, 0x80000
	v_mfma_f32_16x16x32_bf16 v[24:27], v[184:187], v[152:155], v[24:27]
	s_addc_u32 s19, s19, 0
	v_mfma_f32_16x16x32_bf16 v[16:19], v[176:179], v[160:163], v[16:19]
	s_mov_b32 m0, s30
	v_mfma_f32_16x16x32_bf16 v[8:11], v[184:187], v[160:163], v[8:11]
	v_mfma_f32_16x16x32_bf16 v[4:7], v[176:179], v[168:171], v[4:7]
	v_mfma_f32_16x16x32_bf16 v[0:3], v[184:187], v[168:171], v[0:3]
	v_mfma_f32_16x16x32_bf16 v[48:51], v[180:183], v[148:151], v[48:51]
	v_mfma_f32_16x16x32_bf16 v[40:43], v[188:191], v[148:151], v[40:43]
	v_mfma_f32_16x16x32_bf16 v[32:35], v[180:183], v[156:159], v[32:35]
	v_mfma_f32_16x16x32_bf16 v[24:27], v[188:191], v[156:159], v[24:27]
	v_mfma_f32_16x16x32_bf16 v[16:19], v[180:183], v[164:167], v[16:19]
	v_mfma_f32_16x16x32_bf16 v[8:11], v[188:191], v[164:167], v[8:11]
	v_mfma_f32_16x16x32_bf16 v[4:7], v[180:183], v[172:175], v[4:7]
	v_mfma_f32_16x16x32_bf16 v[0:3], v[188:191], v[172:175], v[0:3]
	s_barrier
	ds_read_b128 v[128:131], v222 offset:32768
	ds_read_b128 v[132:135], v222 offset:33792
	ds_read_b128 v[136:139], v222 offset:34816
	ds_read_b128 v[140:143], v222 offset:35840
	ds_read_b128 v[144:147], v240 offset:32768
	ds_read_b128 v[148:151], v240 offset:33792
	ds_read_b128 v[152:155], v240 offset:34816
	ds_read_b128 v[156:159], v240 offset:35840
	ds_read_b128 v[160:163], v240 offset:36864
	ds_read_b128 v[164:167], v240 offset:37888
	ds_read_b128 v[168:171], v240 offset:38912
	ds_read_b128 v[172:175], v240 offset:39936
	global_load_lds_dwordx4 v204, s[18:19]
	s_mov_b32 m0, s31
	s_nop 0
	global_load_lds_dwordx4 v208, s[18:19]
	s_waitcnt lgkmcnt(8)
	s_barrier
	s_waitcnt lgkmcnt(0)
	v_mfma_f32_16x16x32_bf16 v[124:127], v[128:131], v[144:147], v[124:127]
	v_mfma_f32_16x16x32_bf16 v[120:123], v[136:139], v[144:147], v[120:123]
	s_add_i32 s18, 0, 0x1c000
	v_mfma_f32_16x16x32_bf16 v[116:119], v[128:131], v[152:155], v[116:119]
	s_add_i32 s19, s41, s27
	v_mfma_f32_16x16x32_bf16 v[108:111], v[136:139], v[152:155], v[108:111]
	s_add_i32 m0, s19, 0xffffff80
	v_mfma_f32_16x16x32_bf16 v[100:103], v[128:131], v[160:163], v[100:103]
	v_mfma_f32_16x16x32_bf16 v[92:95], v[136:139], v[160:163], v[92:95]
	v_mfma_f32_16x16x32_bf16 v[84:87], v[128:131], v[168:171], v[84:87]
	v_mfma_f32_16x16x32_bf16 v[76:79], v[136:139], v[168:171], v[76:79]
	v_mfma_f32_16x16x32_bf16 v[124:127], v[132:135], v[148:151], v[124:127]
	v_mfma_f32_16x16x32_bf16 v[120:123], v[140:143], v[148:151], v[120:123]
	v_mfma_f32_16x16x32_bf16 v[116:119], v[132:135], v[156:159], v[116:119]
	v_mfma_f32_16x16x32_bf16 v[108:111], v[140:143], v[156:159], v[108:111]
	v_mfma_f32_16x16x32_bf16 v[100:103], v[132:135], v[164:167], v[100:103]
	v_mfma_f32_16x16x32_bf16 v[92:95], v[140:143], v[164:167], v[92:95]
	v_mfma_f32_16x16x32_bf16 v[84:87], v[132:135], v[172:175], v[84:87]
	v_mfma_f32_16x16x32_bf16 v[76:79], v[140:143], v[172:175], v[76:79]
	s_barrier
	ds_read_b128 v[176:179], v222 offset:49152
	ds_read_b128 v[180:183], v222 offset:50176
	ds_read_b128 v[184:187], v222 offset:51200
	ds_read_b128 v[188:191], v222 offset:52224
	global_load_lds_dwordx4 v206, s[16:17] offset:128
	s_add_i32 m0, s19, 0x1f80
	s_nop 0
	global_load_lds_dwordx4 v210, s[16:17] offset:128
	s_barrier
	s_waitcnt lgkmcnt(0)
	v_mfma_f32_16x16x32_bf16 v[112:115], v[176:179], v[144:147], v[112:115]
	v_mfma_f32_16x16x32_bf16 v[104:107], v[184:187], v[144:147], v[104:107]
	s_mov_b32 m0, s33
	v_mfma_f32_16x16x32_bf16 v[96:99], v[176:179], v[152:155], v[96:99]
	v_mfma_f32_16x16x32_bf16 v[88:91], v[184:187], v[152:155], v[88:91]
	v_mfma_f32_16x16x32_bf16 v[80:83], v[176:179], v[160:163], v[80:83]
	v_mfma_f32_16x16x32_bf16 v[72:75], v[184:187], v[160:163], v[72:75]
	v_mfma_f32_16x16x32_bf16 v[68:71], v[176:179], v[168:171], v[68:71]
	v_mfma_f32_16x16x32_bf16 v[64:67], v[184:187], v[168:171], v[64:67]
	v_mfma_f32_16x16x32_bf16 v[112:115], v[180:183], v[148:151], v[112:115]
	v_mfma_f32_16x16x32_bf16 v[104:107], v[188:191], v[148:151], v[104:107]
	v_mfma_f32_16x16x32_bf16 v[96:99], v[180:183], v[156:159], v[96:99]
	v_mfma_f32_16x16x32_bf16 v[88:91], v[188:191], v[156:159], v[88:91]
	v_mfma_f32_16x16x32_bf16 v[80:83], v[180:183], v[164:167], v[80:83]
	v_mfma_f32_16x16x32_bf16 v[72:75], v[188:191], v[164:167], v[72:75]
	v_mfma_f32_16x16x32_bf16 v[68:71], v[180:183], v[172:175], v[68:71]
	v_mfma_f32_16x16x32_bf16 v[64:67], v[188:191], v[172:175], v[64:67]
	s_barrier
	ds_read_b128 v[144:147], v240 offset:49152
	ds_read_b128 v[148:151], v240 offset:50176
	ds_read_b128 v[152:155], v240 offset:51200
	ds_read_b128 v[156:159], v240 offset:52224
	ds_read_b128 v[160:163], v240 offset:53248
	ds_read_b128 v[164:167], v240 offset:54272
	ds_read_b128 v[168:171], v240 offset:55296
	ds_read_b128 v[172:175], v240 offset:56320
	global_load_lds_dwordx4 v204, s[48:49]
	s_mov_b32 m0, s34
	s_nop 0
	global_load_lds_dwordx4 v208, s[48:49]
	s_barrier
	s_waitcnt lgkmcnt(0)
	v_mfma_f32_16x16x32_bf16 v[60:63], v[128:131], v[144:147], v[60:63]
	v_mfma_f32_16x16x32_bf16 v[56:59], v[136:139], v[144:147], v[56:59]
	s_add_u32 s16, s16, 0x80080
	v_mfma_f32_16x16x32_bf16 v[52:55], v[128:131], v[152:155], v[52:55]
	s_addc_u32 s17, s17, 0
	v_mfma_f32_16x16x32_bf16 v[44:47], v[136:139], v[152:155], v[44:47]
	s_add_i32 s18, s18, s27
	v_mfma_f32_16x16x32_bf16 v[36:39], v[128:131], v[160:163], v[36:39]
	s_mov_b32 m0, s18
	v_mfma_f32_16x16x32_bf16 v[28:31], v[136:139], v[160:163], v[28:31]
	v_mfma_f32_16x16x32_bf16 v[20:23], v[128:131], v[168:171], v[20:23]
	v_mfma_f32_16x16x32_bf16 v[12:15], v[136:139], v[168:171], v[12:15]
	v_mfma_f32_16x16x32_bf16 v[60:63], v[132:135], v[148:151], v[60:63]
	v_mfma_f32_16x16x32_bf16 v[56:59], v[140:143], v[148:151], v[56:59]
	v_mfma_f32_16x16x32_bf16 v[52:55], v[132:135], v[156:159], v[52:55]
	v_mfma_f32_16x16x32_bf16 v[44:47], v[140:143], v[156:159], v[44:47]
	v_mfma_f32_16x16x32_bf16 v[36:39], v[132:135], v[164:167], v[36:39]
	v_mfma_f32_16x16x32_bf16 v[28:31], v[140:143], v[164:167], v[28:31]
	v_mfma_f32_16x16x32_bf16 v[20:23], v[132:135], v[172:175], v[20:23]
	v_mfma_f32_16x16x32_bf16 v[12:15], v[140:143], v[172:175], v[12:15]
	s_barrier
	global_load_lds_dwordx4 v206, s[16:17]
	s_add_i32 m0, s18, 0x2000
	s_nop 0
	global_load_lds_dwordx4 v210, s[16:17]
	s_waitcnt vmcnt(6)
	s_barrier
	v_mfma_f32_16x16x32_bf16 v[48:51], v[176:179], v[144:147], v[48:51]
	v_mfma_f32_16x16x32_bf16 v[40:43], v[184:187], v[144:147], v[40:43]
	s_add_i32 s40, s40, 2
	v_mfma_f32_16x16x32_bf16 v[32:35], v[176:179], v[152:155], v[32:35]
	s_add_u32 s14, s14, 0x100
	v_mfma_f32_16x16x32_bf16 v[24:27], v[184:187], v[152:155], v[24:27]
	s_addc_u32 s15, s15, 0
	v_mfma_f32_16x16x32_bf16 v[16:19], v[176:179], v[160:163], v[16:19]
	s_add_u32 s38, s38, 0x100
	v_mfma_f32_16x16x32_bf16 v[8:11], v[184:187], v[160:163], v[8:11]
	s_addc_u32 s39, s39, 0
	v_mfma_f32_16x16x32_bf16 v[4:7], v[176:179], v[168:171], v[4:7]
	s_add_u32 s16, s14, 0xfff80080
	s_addc_u32 s17, s15, -1
	v_mfma_f32_16x16x32_bf16 v[0:3], v[184:187], v[168:171], v[0:3]
	s_add_i32 s41, 0, 0x10000
	s_cmp_eq_u32 s40, 28
	v_mfma_f32_16x16x32_bf16 v[48:51], v[180:183], v[148:151], v[48:51]
	s_cselect_b32 s19, s5, s17
	s_cselect_b32 s18, s9, s16
	v_mfma_f32_16x16x32_bf16 v[40:43], v[188:191], v[148:151], v[40:43]
	s_cselect_b32 s17, s7, s39
	s_cselect_b32 s16, s37, s38
	v_mfma_f32_16x16x32_bf16 v[32:35], v[180:183], v[156:159], v[32:35]
	s_add_i32 m0, s28, 0xc000
	v_mfma_f32_16x16x32_bf16 v[24:27], v[188:191], v[156:159], v[24:27]
	v_mfma_f32_16x16x32_bf16 v[16:19], v[180:183], v[164:167], v[16:19]
	v_mfma_f32_16x16x32_bf16 v[8:11], v[188:191], v[164:167], v[8:11]
	v_mfma_f32_16x16x32_bf16 v[4:7], v[180:183], v[172:175], v[4:7]
	v_mfma_f32_16x16x32_bf16 v[0:3], v[188:191], v[172:175], v[0:3]
	s_cmp_gt_u32 s40, 29
	s_barrier
	s_cbranch_scc0 .LBB0_200
	v_lshl_add_u32 v228, s4, 8, v237
	v_or_b32_e32 v226, 16, v228
	s_mov_b64 s[4:5], -1
	s_cmp_lt_i32 s36, 16
	v_ashrrev_i32_e32 v229, 31, v228
	v_lshlrev_b32_e32 v192, 1, v212
	v_ashrrev_i32_e32 v227, 31, v226
	v_or_b32_e32 v224, 32, v228
	v_or_b32_e32 v222, 48, v228
	s_cbranch_scc0 .LBB0_203
	s_and_b32 s7, s36, 7
	s_cmp_gt_i32 s36, 7
	s_cselect_b64 vcc, -1, 0
	s_and_b64 s[4:5], vcc, exec
	s_mov_b32 s4, 0x15000000
	s_cselect_b32 s4, s4, 0xd000000
	s_add_u32 s4, s50, s4
	s_addc_u32 s5, s51, 0
	s_lshl_b32 s9, s7, 9
	s_add_u32 s4, s4, s9
	v_cvt_f32_ubyte0_e32 v128, s7
	s_addc_u32 s5, s5, 0
	v_sub_f32_e32 v128, 0xc0a00000, v128
	s_mov_b32 s7, 0xc2fc0000
	v_lshl_add_u64 v[230:231], s[4:5], 0, v[192:193]
	v_cmp_gt_f32_e64 s[4:5], s7, v128
	v_ashrrev_i32_e32 v225, 31, v224
	s_nop 0
	v_cndmask_b32_e64 v129, 0, v234, s[4:5]
	v_add_f32_e32 v128, v128, v129
	v_exp_f32_e32 v128, v128
	s_and_b64 s[4:5], s[4:5], exec
	s_cselect_b32 s4, 0xffffffc0, 0
	v_mov_b32_e32 v129, v193
	v_ldexp_f32 v128, v128, s4
	v_sub_f32_e32 v128, 1.0, v128
	v_log_f32_e32 v241, v128
	v_lshlrev_b32_e32 v128, 9, v228
	v_and_b32_e32 v128, 0x1f9e00, v128
	v_lshl_add_u64 v[130:131], v[214:215], 0, v[128:129]
	v_lshl_add_u64 v[132:133], v[216:217], 0, v[128:129]
	global_load_dwordx4 v[180:183], v[130:131], off offset:16
	global_load_dwordx4 v[188:191], v[130:131], off
	global_load_dwordx4 v[176:179], v[132:133], off offset:16
	global_load_dwordx4 v[184:187], v[132:133], off
	v_or_b32_e32 v130, 0x2000, v128
	v_mov_b32_e32 v131, v193
	v_lshl_add_u64 v[132:133], v[214:215], 0, v[130:131]
	v_lshl_add_u64 v[130:131], v[216:217], 0, v[130:131]
	global_load_dwordx4 v[164:167], v[132:133], off offset:16
	global_load_dwordx4 v[172:175], v[132:133], off
	global_load_dwordx4 v[160:163], v[130:131], off offset:16
	global_load_dwordx4 v[168:171], v[130:131], off
	v_mul_f32_e64 v196, v241, -v239
	v_cmp_gt_f32_e64 s[4:5], s7, v196
	v_or_b32_e32 v130, 0x4000, v128
	v_mov_b32_e32 v131, v193
	v_cndmask_b32_e64 v196, 0, v234, s[4:5]
	v_fma_f32 v196, v241, -v239, v196
	v_exp_f32_e32 v196, v196
	v_cndmask_b32_e64 v197, 0, v235, s[4:5]
	v_lshl_add_u64 v[132:133], v[214:215], 0, v[130:131]
	v_lshl_add_u64 v[130:131], v[216:217], 0, v[130:131]
	v_ldexp_f32 v196, v196, v197
	v_mul_f32_e32 v196, 0x3d800000, v196
	v_cndmask_b32_e32 v242, 1.0, v196, vcc
	v_mov_b32_e32 v196, v124
	v_mov_b32_e32 v197, v112
	global_load_dwordx4 v[148:151], v[132:133], off offset:16
	global_load_dwordx4 v[156:159], v[132:133], off
	global_load_dwordx4 v[144:147], v[130:131], off offset:16
	global_load_dwordx4 v[152:155], v[130:131], off
	v_or_b32_e32 v128, 0x6000, v128
	v_lshl_add_u64 v[130:131], v[214:215], 0, v[128:129]
	v_lshl_add_u64 v[136:137], v[216:217], 0, v[128:129]
	global_load_dwordx4 v[132:135], v[130:131], off offset:16
	global_load_dwordx4 v[140:143], v[130:131], off
	s_nop 0
	global_load_dwordx4 v[128:131], v[136:137], off offset:16
	s_nop 0
	global_load_dwordx4 v[136:139], v[136:137], off
	s_movk_i32 s4, 0x5f
	s_waitcnt vmcnt(0)
	v_mov_b32_e32 v198, v188
	v_mov_b32_e32 v199, v184
	v_pk_mul_f32 v[196:197], v[196:197], v[198:199]
	s_nop 0
	v_sub_f32_e32 v184, v196, v197
	v_mov_b32_e32 v196, v112
	v_mov_b32_e32 v197, v124
	v_pk_mul_f32 v[196:197], v[196:197], v[198:199]
	v_mul_f32_e32 v223, v242, v184
	v_add_f32_e32 v184, v196, v197
	v_mul_f32_e32 v198, v242, v184
	v_mov_b32_e32 v196, v125
	v_mov_b32_e32 v197, v113
	v_mov_b32_e32 v184, v189
	v_pk_mul_f32 v[188:189], v[196:197], v[184:185]
	s_nop 0
	v_sub_f32_e32 v188, v188, v189
	v_mul_f32_e32 v196, v242, v188
	v_mov_b32_e32 v188, v113
	v_mov_b32_e32 v189, v125
	v_pk_mul_f32 v[184:185], v[188:189], v[184:185]
	v_mov_b32_e32 v188, v190
	v_add_f32_e32 v184, v184, v185
	v_mul_f32_e32 v197, v242, v184
	v_mov_b32_e32 v184, v126
	v_mov_b32_e32 v185, v114
	v_mov_b32_e32 v189, v186
	v_pk_mul_f32 v[184:185], v[184:185], v[188:189]
	v_mov_b32_e32 v186, v191
	v_sub_f32_e32 v184, v184, v185
	v_mul_f32_e32 v190, v242, v184
	v_mov_b32_e32 v184, v114
	v_mov_b32_e32 v185, v126
	v_pk_mul_f32 v[184:185], v[184:185], v[188:189]
	s_nop 0
	v_add_f32_e32 v184, v184, v185
	v_mul_f32_e32 v188, v242, v184
	v_mov_b32_e32 v184, v127
	v_mov_b32_e32 v185, v115
	v_pk_mul_f32 v[184:185], v[184:185], v[186:187]
	s_nop 0
	v_sub_f32_e32 v184, v184, v185
	v_mul_f32_e32 v189, v242, v184
	v_mov_b32_e32 v184, v115
	v_mov_b32_e32 v185, v127
	v_pk_mul_f32 v[184:185], v[184:185], v[186:187]
	v_mov_b32_e32 v186, v180
	v_add_f32_e32 v184, v184, v185
	v_mul_f32_e32 v191, v242, v184
	v_mov_b32_e32 v184, v120
	v_mov_b32_e32 v185, v104
	v_mov_b32_e32 v187, v176
	v_pk_mul_f32 v[184:185], v[184:185], v[186:187]
	s_nop 0
	v_sub_f32_e32 v176, v184, v185
	v_mov_b32_e32 v184, v104
	v_mov_b32_e32 v185, v120
	v_pk_mul_f32 v[184:185], v[184:185], v[186:187]
	v_mul_f32_e32 v199, v242, v176
	v_add_f32_e32 v176, v184, v185
	v_mul_f32_e32 v186, v242, v176
	v_mov_b32_e32 v184, v121
	v_mov_b32_e32 v185, v105
	v_mov_b32_e32 v176, v181
	v_pk_mul_f32 v[180:181], v[184:185], v[176:177]
	s_nop 0
	v_sub_f32_e32 v180, v180, v181
	v_mul_f32_e32 v184, v242, v180
	v_mov_b32_e32 v180, v105
	v_mov_b32_e32 v181, v121
	v_pk_mul_f32 v[176:177], v[180:181], v[176:177]
	v_mov_b32_e32 v180, v182
	v_add_f32_e32 v176, v176, v177
	v_mul_f32_e32 v185, v242, v176
	v_mov_b32_e32 v176, v122
	v_mov_b32_e32 v177, v106
	v_mov_b32_e32 v181, v178
	v_pk_mul_f32 v[176:177], v[176:177], v[180:181]
	v_mov_b32_e32 v178, v183
	v_sub_f32_e32 v176, v176, v177
	v_mul_f32_e32 v182, v242, v176
	v_mov_b32_e32 v176, v106
	v_mov_b32_e32 v177, v122
	v_pk_mul_f32 v[176:177], v[176:177], v[180:181]
	s_nop 0
	v_add_f32_e32 v176, v176, v177
	v_mul_f32_e32 v187, v242, v176
	v_mov_b32_e32 v176, v123
	v_mov_b32_e32 v177, v107
	v_pk_mul_f32 v[176:177], v[176:177], v[178:179]
	s_nop 0
	v_sub_f32_e32 v176, v176, v177
	v_mul_f32_e32 v181, v242, v176
	v_mov_b32_e32 v176, v107
	v_mov_b32_e32 v177, v123
	v_pk_mul_f32 v[176:177], v[176:177], v[178:179]
	v_cvt_pk_bf16_f32 v178, v223, v196
	v_cvt_pk_bf16_f32 v179, v190, v189
	v_cvt_pk_bf16_f32 v180, v199, v184
	v_cvt_pk_bf16_f32 v181, v182, v181
	v_cvt_pk_bf16_f32 v182, v198, v197
	s_nop 0
	v_add_f32_e32 v176, v176, v177
	v_mul_f32_e32 v176, v242, v176
	v_cvt_pk_bf16_f32 v183, v188, v191
	v_cvt_pk_bf16_f32 v184, v186, v185
	v_cvt_pk_bf16_f32 v185, v187, v176
	v_lshlrev_b64 v[176:177], 12, v[228:229]
	v_lshl_add_u64 v[176:177], v[230:231], 0, v[176:177]
	global_store_dwordx4 v[176:177], v[178:181], off
	global_store_dwordx4 v[176:177], v[182:185], off offset:256
	v_ashrrev_i32_e32 v223, 31, v222
	v_bitop3_b32 v178, v228, s4, 16 bitop3:0xc8
	v_add_u32_e32 v178, 1, v178
	v_cvt_f32_ubyte0_e32 v178, v178
	v_mul_f32_e64 v179, v241, -v178
	v_cmp_gt_f32_e64 s[4:5], s7, v179
	v_mov_b32_e32 v181, v168
	v_mov_b32_e32 v190, v60
	v_cndmask_b32_e64 v180, 0, v234, s[4:5]
	v_fma_f32 v178, v241, -v178, v180
	v_exp_f32_e32 v178, v178
	v_cndmask_b32_e64 v179, 0, v235, s[4:5]
	v_mov_b32_e32 v180, v172
	s_movk_i32 s4, 0x6f
	v_ldexp_f32 v178, v178, v179
	v_mul_f32_e32 v178, 0x3d800000, v178
	v_cndmask_b32_e32 v182, 1.0, v178, vcc
	v_mov_b32_e32 v178, v116
	v_mov_b32_e32 v179, v96
	v_pk_mul_f32 v[178:179], v[178:179], v[180:181]
	v_mov_b32_e32 v191, v48
	v_sub_f32_e32 v168, v178, v179
	v_mov_b32_e32 v178, v96
	v_mov_b32_e32 v179, v116
	v_pk_mul_f32 v[178:179], v[178:179], v[180:181]
	v_mul_f32_e32 v183, v182, v168
	v_add_f32_e32 v168, v178, v179
	v_mul_f32_e32 v180, v182, v168
	v_mov_b32_e32 v178, v117
	v_mov_b32_e32 v179, v97
	v_mov_b32_e32 v168, v173
	v_pk_mul_f32 v[172:173], v[178:179], v[168:169]
	s_nop 0
	v_sub_f32_e32 v172, v172, v173
	v_mul_f32_e32 v178, v182, v172
	v_mov_b32_e32 v172, v97
	v_mov_b32_e32 v173, v117
	v_pk_mul_f32 v[168:169], v[172:173], v[168:169]
	v_mov_b32_e32 v172, v174
	v_add_f32_e32 v168, v168, v169
	v_mul_f32_e32 v179, v182, v168
	v_mov_b32_e32 v168, v118
	v_mov_b32_e32 v169, v98
	v_mov_b32_e32 v173, v170
	v_pk_mul_f32 v[168:169], v[168:169], v[172:173]
	v_mov_b32_e32 v170, v175
	v_sub_f32_e32 v168, v168, v169
	v_mul_f32_e32 v174, v182, v168
	v_mov_b32_e32 v168, v98
	v_mov_b32_e32 v169, v118
	v_pk_mul_f32 v[168:169], v[168:169], v[172:173]
	s_nop 0
	v_add_f32_e32 v168, v168, v169
	v_mul_f32_e32 v172, v182, v168
	v_mov_b32_e32 v168, v119
	v_mov_b32_e32 v169, v99
	v_pk_mul_f32 v[168:169], v[168:169], v[170:171]
	s_nop 0
	v_sub_f32_e32 v168, v168, v169
	v_mul_f32_e32 v173, v182, v168
	v_mov_b32_e32 v168, v99
	v_mov_b32_e32 v169, v119
	v_pk_mul_f32 v[168:169], v[168:169], v[170:171]
	v_mov_b32_e32 v170, v164
	v_add_f32_e32 v168, v168, v169
	v_mul_f32_e32 v175, v182, v168
	v_mov_b32_e32 v168, v108
	v_mov_b32_e32 v169, v88
	v_mov_b32_e32 v171, v160
	v_pk_mul_f32 v[168:169], v[168:169], v[170:171]
	s_nop 0
	v_sub_f32_e32 v160, v168, v169
	v_mov_b32_e32 v168, v88
	v_mov_b32_e32 v169, v108
	v_pk_mul_f32 v[168:169], v[168:169], v[170:171]
	v_mul_f32_e32 v181, v182, v160
	v_add_f32_e32 v160, v168, v169
	v_mul_f32_e32 v170, v182, v160
	v_mov_b32_e32 v168, v109
	v_mov_b32_e32 v169, v89
	v_mov_b32_e32 v160, v165
	v_pk_mul_f32 v[164:165], v[168:169], v[160:161]
	s_nop 0
	v_sub_f32_e32 v164, v164, v165
	v_mul_f32_e32 v168, v182, v164
	v_mov_b32_e32 v164, v89
	v_mov_b32_e32 v165, v109
	v_pk_mul_f32 v[160:161], v[164:165], v[160:161]
	v_mov_b32_e32 v164, v166
	v_add_f32_e32 v160, v160, v161
	v_mul_f32_e32 v169, v182, v160
	v_mov_b32_e32 v160, v110
	v_mov_b32_e32 v161, v90
	v_mov_b32_e32 v165, v162
	v_pk_mul_f32 v[160:161], v[160:161], v[164:165]
	v_mov_b32_e32 v162, v167
	v_sub_f32_e32 v160, v160, v161
	v_mul_f32_e32 v166, v182, v160
	v_mov_b32_e32 v160, v90
	v_mov_b32_e32 v161, v110
	v_pk_mul_f32 v[160:161], v[160:161], v[164:165]
	s_nop 0
	v_add_f32_e32 v160, v160, v161
	v_mul_f32_e32 v171, v182, v160
	v_mov_b32_e32 v160, v111
	v_mov_b32_e32 v161, v91
	v_pk_mul_f32 v[160:161], v[160:161], v[162:163]
	s_nop 0
	v_sub_f32_e32 v160, v160, v161
	v_mul_f32_e32 v164, v182, v160
	v_mov_b32_e32 v160, v91
	v_mov_b32_e32 v161, v111
	v_pk_mul_f32 v[160:161], v[160:161], v[162:163]
	s_nop 0
	v_add_f32_e32 v160, v160, v161
	v_mul_f32_e32 v167, v182, v160
	v_cvt_pk_bf16_f32 v160, v183, v178
	v_cvt_pk_bf16_f32 v161, v174, v173
	v_cvt_pk_bf16_f32 v162, v181, v168
	v_cvt_pk_bf16_f32 v163, v166, v164
	v_cvt_pk_bf16_f32 v164, v180, v179
	v_cvt_pk_bf16_f32 v165, v172, v175
	v_cvt_pk_bf16_f32 v166, v170, v169
	v_lshlrev_b64 v[168:169], 12, v[226:227]
	v_lshl_add_u64 v[168:169], v[230:231], 0, v[168:169]
	v_cvt_pk_bf16_f32 v167, v171, v167
	global_store_dwordx4 v[168:169], v[160:163], off
	global_store_dwordx4 v[168:169], v[164:167], off offset:256
	s_nop 0
	v_bitop3_b32 v160, v228, s4, 32 bitop3:0xc8
	v_add_u32_e32 v160, 1, v160
	v_cvt_f32_ubyte0_e32 v160, v160
	v_mul_f32_e64 v161, v241, -v160
	v_cmp_gt_f32_e64 s[4:5], s7, v161
	v_mov_b32_e32 v163, v152
	s_nop 0
	v_cndmask_b32_e64 v162, 0, v234, s[4:5]
	v_fma_f32 v160, v241, -v160, v162
	v_exp_f32_e32 v160, v160
	v_cndmask_b32_e64 v161, 0, v235, s[4:5]
	v_mov_b32_e32 v162, v156
	s_movk_i32 s4, 0x7f
	v_ldexp_f32 v160, v160, v161
	v_mul_f32_e32 v160, 0x3d800000, v160
	v_cndmask_b32_e32 v164, 1.0, v160, vcc
	v_mov_b32_e32 v160, v100
	v_mov_b32_e32 v161, v80
	v_pk_mul_f32 v[160:161], v[160:161], v[162:163]
	s_nop 0
	v_sub_f32_e32 v152, v160, v161
	v_mov_b32_e32 v160, v80
	v_mov_b32_e32 v161, v100
	v_pk_mul_f32 v[160:161], v[160:161], v[162:163]
	v_mul_f32_e32 v165, v164, v152
	v_add_f32_e32 v152, v160, v161
	v_mul_f32_e32 v162, v164, v152
	v_mov_b32_e32 v160, v101
	v_mov_b32_e32 v161, v81
	v_mov_b32_e32 v152, v157
	v_pk_mul_f32 v[156:157], v[160:161], v[152:153]
	s_nop 0
	v_sub_f32_e32 v156, v156, v157
	v_mul_f32_e32 v160, v164, v156
	v_mov_b32_e32 v156, v81
	v_mov_b32_e32 v157, v101
	v_pk_mul_f32 v[152:153], v[156:157], v[152:153]
	v_mov_b32_e32 v156, v158
	v_add_f32_e32 v152, v152, v153
	v_mul_f32_e32 v161, v164, v152
	v_mov_b32_e32 v152, v102
	v_mov_b32_e32 v153, v82
	v_mov_b32_e32 v157, v154
	v_pk_mul_f32 v[152:153], v[152:153], v[156:157]
	v_mov_b32_e32 v154, v159
	v_sub_f32_e32 v152, v152, v153
	v_mul_f32_e32 v158, v164, v152
	v_mov_b32_e32 v152, v82
	v_mov_b32_e32 v153, v102
	v_pk_mul_f32 v[152:153], v[152:153], v[156:157]
	s_nop 0
	v_add_f32_e32 v152, v152, v153
	v_mul_f32_e32 v156, v164, v152
	v_mov_b32_e32 v152, v103
	v_mov_b32_e32 v153, v83
	v_pk_mul_f32 v[152:153], v[152:153], v[154:155]
	s_nop 0
	v_sub_f32_e32 v152, v152, v153
	v_mul_f32_e32 v157, v164, v152
	v_mov_b32_e32 v152, v83
	v_mov_b32_e32 v153, v103
	v_pk_mul_f32 v[152:153], v[152:153], v[154:155]
	v_mov_b32_e32 v154, v148
	v_add_f32_e32 v152, v152, v153
	v_mul_f32_e32 v159, v164, v152
	v_mov_b32_e32 v152, v92
	v_mov_b32_e32 v153, v72
	v_mov_b32_e32 v155, v144
	v_pk_mul_f32 v[152:153], v[152:153], v[154:155]
	s_nop 0
	v_sub_f32_e32 v144, v152, v153
	v_mov_b32_e32 v152, v72
	v_mov_b32_e32 v153, v92
	v_pk_mul_f32 v[152:153], v[152:153], v[154:155]
	v_mul_f32_e32 v163, v164, v144
	v_add_f32_e32 v144, v152, v153
	v_mul_f32_e32 v154, v164, v144
	v_mov_b32_e32 v152, v93
	v_mov_b32_e32 v153, v73
	v_mov_b32_e32 v144, v149
	v_pk_mul_f32 v[148:149], v[152:153], v[144:145]
	s_nop 0
	v_sub_f32_e32 v148, v148, v149
	v_mul_f32_e32 v152, v164, v148
	v_mov_b32_e32 v148, v73
	v_mov_b32_e32 v149, v93
	v_pk_mul_f32 v[144:145], v[148:149], v[144:145]
	v_mov_b32_e32 v148, v150
	v_add_f32_e32 v144, v144, v145
	v_mul_f32_e32 v153, v164, v144
	v_mov_b32_e32 v144, v94
	v_mov_b32_e32 v145, v74
	v_mov_b32_e32 v149, v146
	v_pk_mul_f32 v[144:145], v[144:145], v[148:149]
	v_mov_b32_e32 v146, v151
	v_sub_f32_e32 v144, v144, v145
	v_mul_f32_e32 v150, v164, v144
	v_mov_b32_e32 v144, v74
	v_mov_b32_e32 v145, v94
	v_pk_mul_f32 v[144:145], v[144:145], v[148:149]
	s_nop 0
	v_add_f32_e32 v144, v144, v145
	v_mul_f32_e32 v155, v164, v144
	v_mov_b32_e32 v144, v95
	v_mov_b32_e32 v145, v75
	v_pk_mul_f32 v[144:145], v[144:145], v[146:147]
	s_nop 0
	v_sub_f32_e32 v144, v144, v145
	v_mul_f32_e32 v148, v164, v144
	v_mov_b32_e32 v144, v75
	v_mov_b32_e32 v145, v95
	v_pk_mul_f32 v[144:145], v[144:145], v[146:147]
	s_nop 0
	v_add_f32_e32 v144, v144, v145
	v_mul_f32_e32 v151, v164, v144
	v_cvt_pk_bf16_f32 v144, v165, v160
	v_cvt_pk_bf16_f32 v145, v158, v157
	v_cvt_pk_bf16_f32 v146, v163, v152
	v_cvt_pk_bf16_f32 v147, v150, v148
	v_cvt_pk_bf16_f32 v148, v162, v161
	v_cvt_pk_bf16_f32 v149, v156, v159
	v_cvt_pk_bf16_f32 v150, v154, v153
	v_lshlrev_b64 v[152:153], 12, v[224:225]
	v_lshl_add_u64 v[152:153], v[230:231], 0, v[152:153]
	v_cvt_pk_bf16_f32 v151, v155, v151
	global_store_dwordx4 v[152:153], v[144:147], off
	global_store_dwordx4 v[152:153], v[148:151], off offset:256
	s_nop 0
	v_bitop3_b32 v144, v228, s4, 48 bitop3:0xc8
	v_add_u32_e32 v144, 1, v144
	v_cvt_f32_ubyte0_e32 v144, v144
	v_mul_f32_e64 v145, v241, -v144
	v_cmp_gt_f32_e64 s[4:5], s7, v145
	v_mov_b32_e32 v147, v136
	s_nop 0
	v_cndmask_b32_e64 v146, 0, v234, s[4:5]
	v_fma_f32 v144, v241, -v144, v146
	v_exp_f32_e32 v144, v144
	v_cndmask_b32_e64 v145, 0, v235, s[4:5]
	v_mov_b32_e32 v146, v140
	s_mov_b64 s[4:5], 0x80000
	v_ldexp_f32 v144, v144, v145
	v_mul_f32_e32 v144, 0x3d800000, v144
	v_cndmask_b32_e32 v148, 1.0, v144, vcc
	v_mov_b32_e32 v144, v84
	v_mov_b32_e32 v145, v68
	v_pk_mul_f32 v[144:145], v[144:145], v[146:147]
	s_nop 0
	v_sub_f32_e32 v136, v144, v145
	v_mov_b32_e32 v144, v68
	v_mov_b32_e32 v145, v84
	v_pk_mul_f32 v[144:145], v[144:145], v[146:147]
	v_mul_f32_e32 v149, v148, v136
	v_add_f32_e32 v136, v144, v145
	v_mul_f32_e32 v146, v148, v136
	v_mov_b32_e32 v144, v85
	v_mov_b32_e32 v145, v69
	v_mov_b32_e32 v136, v141
	v_pk_mul_f32 v[140:141], v[144:145], v[136:137]
	s_nop 0
	v_sub_f32_e32 v140, v140, v141
	v_mul_f32_e32 v144, v148, v140
	v_mov_b32_e32 v140, v69
	v_mov_b32_e32 v141, v85
	v_pk_mul_f32 v[136:137], v[140:141], v[136:137]
	v_mov_b32_e32 v140, v142
	v_add_f32_e32 v136, v136, v137
	v_mul_f32_e32 v145, v148, v136
	v_mov_b32_e32 v136, v86
	v_mov_b32_e32 v137, v70
	v_mov_b32_e32 v141, v138
	v_pk_mul_f32 v[136:137], v[136:137], v[140:141]
	v_mov_b32_e32 v138, v143
	v_sub_f32_e32 v136, v136, v137
	v_mul_f32_e32 v142, v148, v136
	v_mov_b32_e32 v136, v70
	v_mov_b32_e32 v137, v86
	v_pk_mul_f32 v[136:137], v[136:137], v[140:141]
	s_nop 0
	v_add_f32_e32 v136, v136, v137
	v_mul_f32_e32 v140, v148, v136
	v_mov_b32_e32 v136, v87
	v_mov_b32_e32 v137, v71
	v_pk_mul_f32 v[136:137], v[136:137], v[138:139]
	s_nop 0
	v_sub_f32_e32 v136, v136, v137
	v_mul_f32_e32 v141, v148, v136
	v_mov_b32_e32 v136, v71
	v_mov_b32_e32 v137, v87
	v_pk_mul_f32 v[136:137], v[136:137], v[138:139]
	v_mov_b32_e32 v138, v132
	v_add_f32_e32 v136, v136, v137
	v_mul_f32_e32 v143, v148, v136
	v_mov_b32_e32 v136, v76
	v_mov_b32_e32 v137, v64
	v_mov_b32_e32 v139, v128
	v_pk_mul_f32 v[136:137], v[136:137], v[138:139]
	s_nop 0
	v_sub_f32_e32 v128, v136, v137
	v_mov_b32_e32 v136, v64
	v_mov_b32_e32 v137, v76
	v_pk_mul_f32 v[136:137], v[136:137], v[138:139]
	v_mul_f32_e32 v147, v148, v128
	v_add_f32_e32 v128, v136, v137
	v_mul_f32_e32 v138, v148, v128
	v_mov_b32_e32 v136, v77
	v_mov_b32_e32 v137, v65
	v_mov_b32_e32 v128, v133
	v_pk_mul_f32 v[132:133], v[136:137], v[128:129]
	s_nop 0
	v_sub_f32_e32 v132, v132, v133
	v_mul_f32_e32 v136, v148, v132
	v_mov_b32_e32 v132, v65
	v_mov_b32_e32 v133, v77
	v_pk_mul_f32 v[128:129], v[132:133], v[128:129]
	v_mov_b32_e32 v132, v134
	v_add_f32_e32 v128, v128, v129
	v_mul_f32_e32 v137, v148, v128
	v_mov_b32_e32 v128, v78
	v_mov_b32_e32 v129, v66
	v_mov_b32_e32 v133, v130
	v_pk_mul_f32 v[128:129], v[128:129], v[132:133]
	v_mov_b32_e32 v130, v135
	v_sub_f32_e32 v128, v128, v129
	v_mul_f32_e32 v134, v148, v128
	v_mov_b32_e32 v128, v66
	v_mov_b32_e32 v129, v78
	v_pk_mul_f32 v[128:129], v[128:129], v[132:133]
	s_nop 0
	v_add_f32_e32 v128, v128, v129
	v_mul_f32_e32 v139, v148, v128
	v_mov_b32_e32 v128, v79
	v_mov_b32_e32 v129, v67
	v_pk_mul_f32 v[128:129], v[128:129], v[130:131]
	s_nop 0
	v_sub_f32_e32 v128, v128, v129
	v_mul_f32_e32 v132, v148, v128
	v_mov_b32_e32 v128, v67
	v_mov_b32_e32 v129, v79
	v_pk_mul_f32 v[128:129], v[128:129], v[130:131]
	s_nop 0
	v_add_f32_e32 v128, v128, v129
	v_mul_f32_e32 v135, v148, v128
	v_cvt_pk_bf16_f32 v128, v149, v144
	v_cvt_pk_bf16_f32 v129, v142, v141
	v_cvt_pk_bf16_f32 v130, v147, v136
	v_cvt_pk_bf16_f32 v131, v134, v132
	v_cvt_pk_bf16_f32 v132, v146, v145
	v_cvt_pk_bf16_f32 v133, v140, v143
	v_cvt_pk_bf16_f32 v134, v138, v137
	v_lshlrev_b64 v[136:137], 12, v[222:223]
	v_lshl_add_u64 v[136:137], v[230:231], 0, v[136:137]
	v_cvt_pk_bf16_f32 v135, v139, v135
	global_store_dwordx4 v[136:137], v[128:131], off
	global_store_dwordx4 v[136:137], v[132:135], off offset:256
	s_nop 0
	v_mov_b32_e32 v128, 0x4000
	v_lshl_add_u32 v128, v228, 7, v128
	v_and_b32_e32 v128, 0x7e780, v128
	v_lshlrev_b32_e32 v128, 2, v128
	v_mov_b32_e32 v129, v193
	v_lshl_add_u64 v[130:131], v[214:215], 0, v[128:129]
	v_lshl_add_u64 v[132:133], v[216:217], 0, v[128:129]
	global_load_dwordx4 v[168:171], v[130:131], off offset:16
	global_load_dwordx4 v[172:175], v[130:131], off
	global_load_dwordx4 v[178:181], v[132:133], off offset:16
	global_load_dwordx4 v[182:185], v[132:133], off
	v_or_b32_e32 v130, 0x2000, v128
	v_mov_b32_e32 v131, v193
	v_lshl_add_u64 v[132:133], v[214:215], 0, v[130:131]
	v_lshl_add_u64 v[130:131], v[216:217], 0, v[130:131]
	global_load_dwordx4 v[164:167], v[132:133], off offset:16
	global_load_dwordx4 v[186:189], v[132:133], off
	global_load_dwordx4 v[160:163], v[130:131], off offset:16
	global_load_dwordx4 v[196:199], v[130:131], off
	v_or_b32_e32 v130, 0x4000, v128
	v_mov_b32_e32 v131, v193
	v_lshl_add_u64 v[132:133], v[214:215], 0, v[130:131]
	v_lshl_add_u64 v[130:131], v[216:217], 0, v[130:131]
	global_load_dwordx4 v[148:151], v[132:133], off offset:16
	global_load_dwordx4 v[156:159], v[132:133], off
	global_load_dwordx4 v[144:147], v[130:131], off offset:16
	global_load_dwordx4 v[152:155], v[130:131], off
	v_or_b32_e32 v128, 0x6000, v128
	v_lshl_add_u64 v[130:131], v[214:215], 0, v[128:129]
	v_lshl_add_u64 v[136:137], v[216:217], 0, v[128:129]
	global_load_dwordx4 v[132:135], v[130:131], off offset:16
	global_load_dwordx4 v[140:143], v[130:131], off
	s_nop 0
	global_load_dwordx4 v[128:131], v[136:137], off offset:16
	s_nop 0
	global_load_dwordx4 v[136:139], v[136:137], off
	s_waitcnt vmcnt(0)
	v_mov_b32_e32 v244, v172
	v_mov_b32_e32 v245, v182
	v_pk_mul_f32 v[190:191], v[190:191], v[244:245]
	v_mov_b32_e32 v182, v173
	v_sub_f32_e32 v172, v190, v191
	v_mov_b32_e32 v190, v48
	v_mov_b32_e32 v191, v60
	v_pk_mul_f32 v[190:191], v[190:191], v[244:245]
	v_mul_f32_e32 v223, v242, v172
	v_add_f32_e32 v172, v190, v191
	v_mov_b32_e32 v190, v61
	v_mov_b32_e32 v191, v49
	v_mul_f32_e32 v225, v242, v172
	v_pk_mul_f32 v[172:173], v[190:191], v[182:183]
	s_nop 0
	v_sub_f32_e32 v172, v172, v173
	v_mul_f32_e32 v190, v242, v172
	v_mov_b32_e32 v172, v49
	v_mov_b32_e32 v173, v61
	v_pk_mul_f32 v[172:173], v[172:173], v[182:183]
	v_mov_b32_e32 v182, v174
	v_add_f32_e32 v172, v172, v173
	v_mul_f32_e32 v191, v242, v172
	v_mov_b32_e32 v172, v62
	v_mov_b32_e32 v173, v50
	v_mov_b32_e32 v183, v184
	v_pk_mul_f32 v[172:173], v[172:173], v[182:183]
	v_mov_b32_e32 v184, v175
	v_sub_f32_e32 v172, v172, v173
	v_mul_f32_e32 v243, v242, v172
	v_mov_b32_e32 v172, v50
	v_mov_b32_e32 v173, v62
	v_pk_mul_f32 v[172:173], v[172:173], v[182:183]
	v_mov_b32_e32 v174, v168
	v_add_f32_e32 v172, v172, v173
	v_mul_f32_e32 v182, v242, v172
	v_mov_b32_e32 v172, v63
	v_mov_b32_e32 v173, v51
	v_pk_mul_f32 v[172:173], v[172:173], v[184:185]
	v_mov_b32_e32 v175, v178
	v_sub_f32_e32 v172, v172, v173
	v_mul_f32_e32 v183, v242, v172
	v_mov_b32_e32 v172, v51
	v_mov_b32_e32 v173, v63
	v_pk_mul_f32 v[172:173], v[172:173], v[184:185]
	v_mov_b32_e32 v178, v169
	v_add_f32_e32 v172, v172, v173
	v_mul_f32_e32 v184, v242, v172
	v_mov_b32_e32 v172, v56
	v_mov_b32_e32 v173, v40
	v_pk_mul_f32 v[172:173], v[172:173], v[174:175]
	s_nop 0
	v_sub_f32_e32 v168, v172, v173
	v_mov_b32_e32 v172, v40
	v_mov_b32_e32 v173, v56
	v_pk_mul_f32 v[172:173], v[172:173], v[174:175]
	v_mul_f32_e32 v185, v242, v168
	v_add_f32_e32 v168, v172, v173
	v_mov_b32_e32 v172, v57
	v_mov_b32_e32 v173, v41
	v_mul_f32_e32 v174, v242, v168
	v_pk_mul_f32 v[168:169], v[172:173], v[178:179]
	v_mov_b32_e32 v172, v170
	v_sub_f32_e32 v168, v168, v169
	v_mul_f32_e32 v175, v242, v168
	v_mov_b32_e32 v168, v41
	v_mov_b32_e32 v169, v57
	v_pk_mul_f32 v[168:169], v[168:169], v[178:179]
	v_mov_b32_e32 v173, v180
	v_add_f32_e32 v168, v168, v169
	v_mul_f32_e32 v178, v242, v168
	v_mov_b32_e32 v168, v58
	v_mov_b32_e32 v169, v42
	v_pk_mul_f32 v[168:169], v[168:169], v[172:173]
	v_mov_b32_e32 v180, v171
	v_sub_f32_e32 v168, v168, v169
	v_mul_f32_e32 v179, v242, v168
	v_mov_b32_e32 v168, v42
	v_mov_b32_e32 v169, v58
	v_pk_mul_f32 v[168:169], v[168:169], v[172:173]
	s_nop 0
	v_add_f32_e32 v168, v168, v169
	v_mul_f32_e32 v244, v242, v168
	v_mov_b32_e32 v168, v59
	v_mov_b32_e32 v169, v43
	v_pk_mul_f32 v[168:169], v[168:169], v[180:181]
	s_nop 0
	v_sub_f32_e32 v168, v168, v169
	v_mul_f32_e32 v171, v242, v168
	v_mov_b32_e32 v168, v43
	v_mov_b32_e32 v169, v59
	v_pk_mul_f32 v[168:169], v[168:169], v[180:181]
	s_nop 0
	v_add_f32_e32 v168, v168, v169
	v_mul_f32_e32 v180, v242, v168
	v_cvt_pk_bf16_f32 v168, v223, v190
	v_cvt_pk_bf16_f32 v169, v243, v183
	v_cvt_pk_bf16_f32 v170, v185, v175
	v_cvt_pk_bf16_f32 v171, v179, v171
	v_cvt_pk_bf16_f32 v172, v225, v191
	v_cvt_pk_bf16_f32 v173, v182, v184
	v_cvt_pk_bf16_f32 v174, v174, v178
	v_lshl_add_u64 v[178:179], v[176:177], 0, s[4:5]
	s_mov_b32 s4, 0x80000
	v_add_co_u32_e64 v176, s[4:5], s4, v176
	v_cvt_pk_bf16_f32 v175, v244, v180
	s_nop 1
	v_addc_co_u32_e64 v177, s[4:5], 0, v177, s[4:5]
	global_store_dwordx4 v[176:177], v[168:171], off
	global_store_dwordx4 v[178:179], v[172:175], off offset:256
	s_nop 0
	v_add_u32_e32 v168, 0x90, v228
	v_and_b32_e32 v169, 0x5f, v168
	v_add_u32_e32 v169, 1, v169
	v_cvt_f32_ubyte0_e32 v169, v169
	v_mul_f32_e64 v170, v241, -v169
	v_cmp_gt_f32_e64 s[4:5], s7, v170
	v_mov_b32_e32 v171, v32
	v_mov_b32_e32 v172, v186
	v_cndmask_b32_e64 v170, 0, v234, s[4:5]
	v_fma_f32 v169, v241, -v169, v170
	v_exp_f32_e32 v169, v169
	v_cndmask_b32_e64 v170, 0, v235, s[4:5]
	v_mov_b32_e32 v173, v196
	v_mov_b32_e32 v196, v187
	v_ldexp_f32 v169, v169, v170
	v_mov_b32_e32 v170, v52
	v_mul_f32_e32 v169, 0x3d800000, v169
	v_pk_mul_f32 v[170:171], v[170:171], v[172:173]
	v_cndmask_b32_e32 v169, 1.0, v169, vcc
	v_sub_f32_e32 v170, v170, v171
	v_mul_f32_e32 v174, v169, v170
	v_mov_b32_e32 v170, v32
	v_mov_b32_e32 v171, v52
	v_pk_mul_f32 v[170:171], v[170:171], v[172:173]
	v_mov_b32_e32 v172, v188
	v_add_f32_e32 v170, v170, v171
	v_mul_f32_e32 v175, v169, v170
	v_mov_b32_e32 v170, v53
	v_mov_b32_e32 v171, v33
	v_pk_mul_f32 v[170:171], v[170:171], v[196:197]
	v_mov_b32_e32 v173, v198
	v_sub_f32_e32 v170, v170, v171
	v_mul_f32_e32 v176, v169, v170
	v_mov_b32_e32 v170, v33
	v_mov_b32_e32 v171, v53
	v_pk_mul_f32 v[170:171], v[170:171], v[196:197]
	v_mov_b32_e32 v198, v189
	v_add_f32_e32 v170, v170, v171
	v_mul_f32_e32 v177, v169, v170
	v_mov_b32_e32 v170, v54
	v_mov_b32_e32 v171, v34
	v_pk_mul_f32 v[170:171], v[170:171], v[172:173]
	s_nop 0
	v_sub_f32_e32 v170, v170, v171
	v_mul_f32_e32 v178, v169, v170
	v_mov_b32_e32 v170, v34
	v_mov_b32_e32 v171, v54
	v_pk_mul_f32 v[170:171], v[170:171], v[172:173]
	v_mov_b32_e32 v172, v164
	v_add_f32_e32 v170, v170, v171
	v_mul_f32_e32 v179, v169, v170
	v_mov_b32_e32 v170, v55
	v_mov_b32_e32 v171, v35
	v_pk_mul_f32 v[170:171], v[170:171], v[198:199]
	v_mov_b32_e32 v173, v160
	v_sub_f32_e32 v170, v170, v171
	v_mul_f32_e32 v180, v169, v170
	v_mov_b32_e32 v170, v35
	v_mov_b32_e32 v171, v55
	v_pk_mul_f32 v[170:171], v[170:171], v[198:199]
	s_nop 0
	v_add_f32_e32 v170, v170, v171
	v_mul_f32_e32 v181, v169, v170
	v_mov_b32_e32 v170, v44
	v_mov_b32_e32 v171, v24
	v_pk_mul_f32 v[170:171], v[170:171], v[172:173]
	s_nop 0
	v_sub_f32_e32 v160, v170, v171
	v_mov_b32_e32 v170, v24
	v_mov_b32_e32 v171, v44
	v_pk_mul_f32 v[170:171], v[170:171], v[172:173]
	v_mul_f32_e32 v182, v169, v160
	v_add_f32_e32 v160, v170, v171
	v_mul_f32_e32 v172, v169, v160
	v_mov_b32_e32 v170, v45
	v_mov_b32_e32 v171, v25
	v_mov_b32_e32 v160, v165
	v_pk_mul_f32 v[164:165], v[170:171], v[160:161]
	s_nop 0
	v_sub_f32_e32 v164, v164, v165
	v_mul_f32_e32 v170, v169, v164
	v_mov_b32_e32 v164, v25
	v_mov_b32_e32 v165, v45
	v_pk_mul_f32 v[160:161], v[164:165], v[160:161]
	v_mov_b32_e32 v164, v166
	v_add_f32_e32 v160, v160, v161
	v_mul_f32_e32 v171, v169, v160
	v_mov_b32_e32 v160, v46
	v_mov_b32_e32 v161, v26
	v_mov_b32_e32 v165, v162
	v_pk_mul_f32 v[160:161], v[160:161], v[164:165]
	v_mov_b32_e32 v162, v167
	v_sub_f32_e32 v160, v160, v161
	v_mul_f32_e32 v166, v169, v160
	v_mov_b32_e32 v160, v26
	v_mov_b32_e32 v161, v46
	v_pk_mul_f32 v[160:161], v[160:161], v[164:165]
	s_nop 0
	v_add_f32_e32 v160, v160, v161
	v_mul_f32_e32 v173, v169, v160
	v_mov_b32_e32 v160, v47
	v_mov_b32_e32 v161, v27
	v_pk_mul_f32 v[160:161], v[160:161], v[162:163]
	s_nop 0
	v_sub_f32_e32 v160, v160, v161
	v_mul_f32_e32 v164, v169, v160
	v_mov_b32_e32 v160, v27
	v_mov_b32_e32 v161, v47
	v_pk_mul_f32 v[160:161], v[160:161], v[162:163]
	s_nop 0
	v_add_f32_e32 v160, v160, v161
	v_mul_f32_e32 v167, v169, v160
	v_ashrrev_i32_e32 v169, 31, v168
	v_lshlrev_b64 v[168:169], 12, v[168:169]
	v_cvt_pk_bf16_f32 v160, v174, v176
	v_cvt_pk_bf16_f32 v161, v178, v180
	v_cvt_pk_bf16_f32 v162, v182, v170
	v_cvt_pk_bf16_f32 v163, v166, v164
	v_lshl_add_u64 v[168:169], v[230:231], 0, v[168:169]
	v_cvt_pk_bf16_f32 v164, v175, v177
	v_cvt_pk_bf16_f32 v165, v179, v181
	v_cvt_pk_bf16_f32 v166, v172, v171
	v_cvt_pk_bf16_f32 v167, v173, v167
	global_store_dwordx4 v[168:169], v[160:163], off
	global_store_dwordx4 v[168:169], v[164:167], off offset:256
	s_nop 0
	v_add_u32_e32 v160, 0xa0, v228
	v_and_b32_e32 v161, 0x6f, v160
	v_add_u32_e32 v161, 1, v161
	v_cvt_f32_ubyte0_e32 v161, v161
	v_mul_f32_e64 v162, v241, -v161
	v_cmp_gt_f32_e64 s[4:5], s7, v162
	v_mov_b32_e32 v163, v16
	v_mov_b32_e32 v164, v156
	v_cndmask_b32_e64 v162, 0, v234, s[4:5]
	v_fma_f32 v161, v241, -v161, v162
	v_exp_f32_e32 v161, v161
	v_cndmask_b32_e64 v162, 0, v235, s[4:5]
	v_mov_b32_e32 v165, v152
	v_ldexp_f32 v161, v161, v162
	v_mov_b32_e32 v162, v36
	v_pk_mul_f32 v[162:163], v[162:163], v[164:165]
	v_mul_f32_e32 v161, 0x3d800000, v161
	v_sub_f32_e32 v152, v162, v163
	v_mov_b32_e32 v162, v16
	v_mov_b32_e32 v163, v36
	v_cndmask_b32_e32 v161, 1.0, v161, vcc
	v_pk_mul_f32 v[162:163], v[162:163], v[164:165]
	v_mul_f32_e32 v166, v161, v152
	v_add_f32_e32 v152, v162, v163
	v_mul_f32_e32 v164, v161, v152
	v_mov_b32_e32 v162, v37
	v_mov_b32_e32 v163, v17
	v_mov_b32_e32 v152, v157
	v_pk_mul_f32 v[156:157], v[162:163], v[152:153]
	s_nop 0
	v_sub_f32_e32 v156, v156, v157
	v_mul_f32_e32 v162, v161, v156
	v_mov_b32_e32 v156, v17
	v_mov_b32_e32 v157, v37
	v_pk_mul_f32 v[152:153], v[156:157], v[152:153]
	v_mov_b32_e32 v156, v158
	v_add_f32_e32 v152, v152, v153
	v_mul_f32_e32 v163, v161, v152
	v_mov_b32_e32 v152, v38
	v_mov_b32_e32 v153, v18
	v_mov_b32_e32 v157, v154
	v_pk_mul_f32 v[152:153], v[152:153], v[156:157]
	v_mov_b32_e32 v154, v159
	v_sub_f32_e32 v152, v152, v153
	v_mul_f32_e32 v158, v161, v152
	v_mov_b32_e32 v152, v18
	v_mov_b32_e32 v153, v38
	v_pk_mul_f32 v[152:153], v[152:153], v[156:157]
	s_nop 0
	v_add_f32_e32 v152, v152, v153
	v_mul_f32_e32 v156, v161, v152
	v_mov_b32_e32 v152, v39
	v_mov_b32_e32 v153, v19
	v_pk_mul_f32 v[152:153], v[152:153], v[154:155]
	s_nop 0
	v_sub_f32_e32 v152, v152, v153
	v_mul_f32_e32 v157, v161, v152
	v_mov_b32_e32 v152, v19
	v_mov_b32_e32 v153, v39
	v_pk_mul_f32 v[152:153], v[152:153], v[154:155]
	v_mov_b32_e32 v154, v148
	v_add_f32_e32 v152, v152, v153
	v_mul_f32_e32 v159, v161, v152
	v_mov_b32_e32 v152, v28
	v_mov_b32_e32 v153, v8
	v_mov_b32_e32 v155, v144
	v_pk_mul_f32 v[152:153], v[152:153], v[154:155]
	s_nop 0
	v_sub_f32_e32 v144, v152, v153
	v_mov_b32_e32 v152, v8
	v_mov_b32_e32 v153, v28
	v_pk_mul_f32 v[152:153], v[152:153], v[154:155]
	v_mul_f32_e32 v165, v161, v144
	v_add_f32_e32 v144, v152, v153
	v_mul_f32_e32 v154, v161, v144
	v_mov_b32_e32 v152, v29
	v_mov_b32_e32 v153, v9
	v_mov_b32_e32 v144, v149
	v_pk_mul_f32 v[148:149], v[152:153], v[144:145]
	s_nop 0
	v_sub_f32_e32 v148, v148, v149
	v_mul_f32_e32 v152, v161, v148
	v_mov_b32_e32 v148, v9
	v_mov_b32_e32 v149, v29
	v_pk_mul_f32 v[144:145], v[148:149], v[144:145]
	v_mov_b32_e32 v148, v150
	v_add_f32_e32 v144, v144, v145
	v_mul_f32_e32 v153, v161, v144
	v_mov_b32_e32 v144, v30
	v_mov_b32_e32 v145, v10
	v_mov_b32_e32 v149, v146
	v_pk_mul_f32 v[144:145], v[144:145], v[148:149]
	v_mov_b32_e32 v146, v151
	v_sub_f32_e32 v144, v144, v145
	v_mul_f32_e32 v150, v161, v144
	v_mov_b32_e32 v144, v10
	v_mov_b32_e32 v145, v30
	v_pk_mul_f32 v[144:145], v[144:145], v[148:149]
	s_nop 0
	v_add_f32_e32 v144, v144, v145
	v_mul_f32_e32 v155, v161, v144
	v_mov_b32_e32 v144, v31
	v_mov_b32_e32 v145, v11
	v_pk_mul_f32 v[144:145], v[144:145], v[146:147]
	s_nop 0
	v_sub_f32_e32 v144, v144, v145
	v_mul_f32_e32 v148, v161, v144
	v_mov_b32_e32 v144, v11
	v_mov_b32_e32 v145, v31
	v_pk_mul_f32 v[144:145], v[144:145], v[146:147]
	s_nop 0
	v_add_f32_e32 v144, v144, v145
	v_mul_f32_e32 v151, v161, v144
	v_ashrrev_i32_e32 v161, 31, v160
	v_cvt_pk_bf16_f32 v144, v166, v162
	v_cvt_pk_bf16_f32 v145, v158, v157
	v_cvt_pk_bf16_f32 v146, v165, v152
	v_cvt_pk_bf16_f32 v147, v150, v148
	v_cvt_pk_bf16_f32 v148, v164, v163
	v_cvt_pk_bf16_f32 v149, v156, v159
	v_cvt_pk_bf16_f32 v150, v154, v153
	v_lshlrev_b64 v[152:153], 12, v[160:161]
	v_lshl_add_u64 v[152:153], v[230:231], 0, v[152:153]
	v_cvt_pk_bf16_f32 v151, v155, v151
	global_store_dwordx4 v[152:153], v[144:147], off
	global_store_dwordx4 v[152:153], v[148:151], off offset:256
	s_nop 0
	v_add_u32_e32 v144, 0xb0, v228
	v_and_b32_e32 v145, 0x7f, v144
	v_add_u32_e32 v145, 1, v145
	v_cvt_f32_ubyte0_e32 v145, v145
	v_mul_f32_e64 v146, v241, -v145
	v_cmp_gt_f32_e64 s[4:5], s7, v146
	v_mov_b32_e32 v147, v4
	v_mov_b32_e32 v148, v140
	v_cndmask_b32_e64 v146, 0, v234, s[4:5]
	v_fma_f32 v145, v241, -v145, v146
	v_exp_f32_e32 v145, v145
	v_cndmask_b32_e64 v146, 0, v235, s[4:5]
	v_mov_b32_e32 v149, v136
	s_mov_b64 s[4:5], 0
	v_ldexp_f32 v145, v145, v146
	v_mov_b32_e32 v146, v20
	v_pk_mul_f32 v[146:147], v[146:147], v[148:149]
	v_mul_f32_e32 v145, 0x3d800000, v145
	v_sub_f32_e32 v136, v146, v147
	v_mov_b32_e32 v146, v4
	v_mov_b32_e32 v147, v20
	v_cndmask_b32_e32 v145, 1.0, v145, vcc
	v_pk_mul_f32 v[146:147], v[146:147], v[148:149]
	v_mul_f32_e32 v150, v145, v136
	v_add_f32_e32 v136, v146, v147
	v_mul_f32_e32 v148, v145, v136
	v_mov_b32_e32 v146, v21
	v_mov_b32_e32 v147, v5
	v_mov_b32_e32 v136, v141
	v_pk_mul_f32 v[140:141], v[146:147], v[136:137]
	s_nop 0
	v_sub_f32_e32 v140, v140, v141
	v_mul_f32_e32 v146, v145, v140
	v_mov_b32_e32 v140, v5
	v_mov_b32_e32 v141, v21
	v_pk_mul_f32 v[136:137], v[140:141], v[136:137]
	v_mov_b32_e32 v140, v142
	v_add_f32_e32 v136, v136, v137
	v_mul_f32_e32 v147, v145, v136
	v_mov_b32_e32 v136, v22
	v_mov_b32_e32 v137, v6
	v_mov_b32_e32 v141, v138
	v_pk_mul_f32 v[136:137], v[136:137], v[140:141]
	v_mov_b32_e32 v138, v143
	v_sub_f32_e32 v136, v136, v137
	v_mul_f32_e32 v142, v145, v136
	v_mov_b32_e32 v136, v6
	v_mov_b32_e32 v137, v22
	v_pk_mul_f32 v[136:137], v[136:137], v[140:141]
	s_nop 0
	v_add_f32_e32 v136, v136, v137
	v_mul_f32_e32 v140, v145, v136
	v_mov_b32_e32 v136, v23
	v_mov_b32_e32 v137, v7
	v_pk_mul_f32 v[136:137], v[136:137], v[138:139]
	s_nop 0
	v_sub_f32_e32 v136, v136, v137
	v_mul_f32_e32 v141, v145, v136
	v_mov_b32_e32 v136, v7
	v_mov_b32_e32 v137, v23
	v_pk_mul_f32 v[136:137], v[136:137], v[138:139]
	v_mov_b32_e32 v138, v132
	v_add_f32_e32 v136, v136, v137
	v_mul_f32_e32 v143, v145, v136
	v_mov_b32_e32 v136, v12
	v_mov_b32_e32 v137, v0
	v_mov_b32_e32 v139, v128
	v_pk_mul_f32 v[136:137], v[136:137], v[138:139]
	s_nop 0
	v_sub_f32_e32 v128, v136, v137
	v_mov_b32_e32 v136, v0
	v_mov_b32_e32 v137, v12
	v_pk_mul_f32 v[136:137], v[136:137], v[138:139]
	v_mul_f32_e32 v149, v145, v128
	v_add_f32_e32 v128, v136, v137
	v_mul_f32_e32 v138, v145, v128
	v_mov_b32_e32 v136, v13
	v_mov_b32_e32 v137, v1
	v_mov_b32_e32 v128, v133
	v_pk_mul_f32 v[132:133], v[136:137], v[128:129]
	s_nop 0
	v_sub_f32_e32 v132, v132, v133
	v_mul_f32_e32 v136, v145, v132
	v_mov_b32_e32 v132, v1
	v_mov_b32_e32 v133, v13
	v_pk_mul_f32 v[128:129], v[132:133], v[128:129]
	v_mov_b32_e32 v132, v134
	v_add_f32_e32 v128, v128, v129
	v_mul_f32_e32 v139, v145, v128
	v_mov_b32_e32 v128, v14
	v_mov_b32_e32 v129, v2
	v_mov_b32_e32 v133, v130
	v_pk_mul_f32 v[128:129], v[128:129], v[132:133]
	v_mov_b32_e32 v130, v135
	v_sub_f32_e32 v128, v128, v129
	v_mul_f32_e32 v137, v145, v128
	v_mov_b32_e32 v128, v2
	v_mov_b32_e32 v129, v14
	v_pk_mul_f32 v[128:129], v[128:129], v[132:133]
	v_cvt_pk_bf16_f32 v134, v150, v146
	v_cvt_pk_bf16_f32 v135, v142, v141
	v_cvt_pk_bf16_f32 v136, v149, v136
	s_nop 0
	v_add_f32_e32 v128, v128, v129
	v_mul_f32_e32 v132, v145, v128
	v_mov_b32_e32 v128, v15
	v_mov_b32_e32 v129, v3
	v_pk_mul_f32 v[128:129], v[128:129], v[130:131]
	s_nop 0
	v_sub_f32_e32 v128, v128, v129
	v_mul_f32_e32 v133, v145, v128
	v_mov_b32_e32 v128, v3
	v_mov_b32_e32 v129, v15
	v_pk_mul_f32 v[128:129], v[128:129], v[130:131]
	v_cvt_pk_bf16_f32 v137, v137, v133
	s_nop 0
	v_add_f32_e32 v128, v128, v129
	v_mul_f32_e32 v131, v145, v128
	v_ashrrev_i32_e32 v145, 31, v144
	v_cvt_pk_bf16_f32 v128, v148, v147
	v_cvt_pk_bf16_f32 v129, v140, v143
	v_cvt_pk_bf16_f32 v130, v138, v139
	v_cvt_pk_bf16_f32 v131, v132, v131
	v_lshlrev_b64 v[132:133], 12, v[144:145]
	v_lshl_add_u64 v[132:133], v[230:231], 0, v[132:133]
	global_store_dwordx4 v[132:133], v[134:137], off

.LBB0_216:
	v_mov_b64_e32 v[0:1], 0x1600
	s_ashr_i32 s7, s6, 31
	v_cmp_lt_i64_e32 vcc, s[8:9], v[0:1]
	s_lshl_b64 s[8:9], s[6:7], 20
	s_add_u32 s8, s22, s8
	s_addc_u32 s9, s23, s9
	s_and_b64 s[10:11], vcc, exec
	s_cselect_b32 s7, s9, s15
	s_cselect_b32 s36, s8, s14
	s_ashr_i32 s5, s4, 31
	s_lshl_b64 s[10:11], s[4:5], 20
	s_add_u32 s10, s24, s10
	s_addc_u32 s11, s25, s11
	s_and_b64 s[18:19], vcc, exec
	s_cselect_b32 s5, s11, s17
	s_cselect_b32 s37, s10, s16
	s_add_u32 s14, s14, 0x80080
	s_addc_u32 s15, s15, 0
	s_add_u32 s38, s16, 0x100
	s_addc_u32 s39, s17, 0
	s_mov_b32 s40, -2
	s_mov_b64 s[48:49], 0x80
	v_add_u32_e32 v220, 0x10000, v141
	s_add_u32 s16, s14, 0xfff80080
	s_addc_u32 s17, s15, -1
	s_add_i32 s41, 0, 0x10000
	ds_read_b128 v[144:147], v220 offset:0
	ds_read_b128 v[148:151], v220 offset:1024
	ds_read_b128 v[152:155], v220 offset:2048
	ds_read_b128 v[156:159], v220 offset:3072
	s_cmp_eq_u32 s40, 28
	s_cselect_b32 s19, s7, s17
	s_cselect_b32 s18, s36, s16
	s_cselect_b32 s17, s5, s39
	s_cselect_b32 s16, s37, s38
	s_add_i32 m0, s13, 0xc000
	ds_read_b128 v[160:163], v143
	ds_read_b128 v[164:167], v143 offset:1024
	ds_read_b128 v[168:171], v143 offset:2048
	ds_read_b128 v[172:175], v143 offset:3072
	ds_read_b128 v[176:179], v143 offset:4096
	ds_read_b128 v[180:183], v143 offset:5120
	ds_read_b128 v[184:187], v143 offset:6144
	ds_read_b128 v[188:191], v143 offset:7168
	global_load_lds_dwordx4 v134, s[14:15]
	s_add_i32 m0, s13, 0xe000
	s_nop 0
	global_load_lds_dwordx4 v136, s[14:15]
	s_waitcnt lgkmcnt(8)
	s_barrier
	s_waitcnt lgkmcnt(0)
	v_mfma_f32_16x16x32_bf16 v[124:127], v[144:147], v[160:163], 0
	v_mfma_f32_16x16x32_bf16 v[116:119], v[152:155], v[160:163], 0
	s_add_i32 s44, 0, 0x14000
	v_mfma_f32_16x16x32_bf16 v[108:111], v[144:147], v[168:171], 0
	s_add_i32 s41, s41, s26
	v_mfma_f32_16x16x32_bf16 v[100:103], v[152:155], v[168:171], 0
	s_mov_b32 m0, s41
	v_mfma_f32_16x16x32_bf16 v[92:95], v[144:147], v[176:179], 0
	v_mfma_f32_16x16x32_bf16 v[84:87], v[152:155], v[176:179], 0
	v_mfma_f32_16x16x32_bf16 v[76:79], v[144:147], v[184:187], 0
	v_mfma_f32_16x16x32_bf16 v[68:71], v[152:155], v[184:187], 0
	v_mfma_f32_16x16x32_bf16 v[124:127], v[148:151], v[164:167], v[124:127]
	v_mfma_f32_16x16x32_bf16 v[116:119], v[156:159], v[164:167], v[116:119]
	v_mfma_f32_16x16x32_bf16 v[108:111], v[148:151], v[172:175], v[108:111]
	v_mfma_f32_16x16x32_bf16 v[100:103], v[156:159], v[172:175], v[100:103]
	v_mfma_f32_16x16x32_bf16 v[92:95], v[148:151], v[180:183], v[92:95]
	v_mfma_f32_16x16x32_bf16 v[84:87], v[156:159], v[180:183], v[84:87]
	v_mfma_f32_16x16x32_bf16 v[76:79], v[148:151], v[188:191], v[76:79]
	v_mfma_f32_16x16x32_bf16 v[68:71], v[156:159], v[188:191], v[68:71]
	s_barrier
	ds_read_b128 v[196:199], v220 offset:16384
	ds_read_b128 v[204:207], v220 offset:17408
	ds_read_b128 v[208:211], v220 offset:18432
	ds_read_b128 v[214:217], v220 offset:19456
	global_load_lds_dwordx4 v192, s[16:17]
	s_add_i32 m0, s41, 0x2000
	s_nop 0
	global_load_lds_dwordx4 v128, s[16:17]
	s_barrier
	s_waitcnt lgkmcnt(0)
	v_mfma_f32_16x16x32_bf16 v[120:123], v[196:199], v[160:163], 0
	v_mfma_f32_16x16x32_bf16 v[112:115], v[208:211], v[160:163], 0
	s_mov_b32 m0, s13
	v_mfma_f32_16x16x32_bf16 v[104:107], v[196:199], v[168:171], 0
	s_add_u32 s48, s18, 0x80
	v_mfma_f32_16x16x32_bf16 v[96:99], v[208:211], v[168:171], 0
	s_addc_u32 s49, s19, 0
	v_mfma_f32_16x16x32_bf16 v[88:91], v[196:199], v[176:179], 0
	v_mfma_f32_16x16x32_bf16 v[80:83], v[208:211], v[176:179], 0
	v_mfma_f32_16x16x32_bf16 v[72:75], v[196:199], v[184:187], 0
	v_mfma_f32_16x16x32_bf16 v[64:67], v[208:211], v[184:187], 0
	v_mfma_f32_16x16x32_bf16 v[120:123], v[204:207], v[164:167], v[120:123]
	v_mfma_f32_16x16x32_bf16 v[112:115], v[214:217], v[164:167], v[112:115]
	v_mfma_f32_16x16x32_bf16 v[104:107], v[204:207], v[172:175], v[104:107]
	v_mfma_f32_16x16x32_bf16 v[96:99], v[214:217], v[172:175], v[96:99]
	v_mfma_f32_16x16x32_bf16 v[88:91], v[204:207], v[180:183], v[88:91]
	v_mfma_f32_16x16x32_bf16 v[80:83], v[214:217], v[180:183], v[80:83]
	v_mfma_f32_16x16x32_bf16 v[72:75], v[204:207], v[188:191], v[72:75]
	v_mfma_f32_16x16x32_bf16 v[64:67], v[214:217], v[188:191], v[64:67]
	s_barrier
	ds_read_b128 v[160:163], v143 offset:16384
	ds_read_b128 v[164:167], v143 offset:17408
	ds_read_b128 v[168:171], v143 offset:18432
	ds_read_b128 v[172:175], v143 offset:19456
	ds_read_b128 v[176:179], v143 offset:20480
	ds_read_b128 v[180:183], v143 offset:21504
	ds_read_b128 v[184:187], v143 offset:22528
	ds_read_b128 v[188:191], v143 offset:23552
	global_load_lds_dwordx4 v132, s[18:19]
	s_mov_b32 m0, s28
	s_nop 0
	global_load_lds_dwordx4 v130, s[18:19]
	s_barrier
	s_waitcnt lgkmcnt(0)
	v_mfma_f32_16x16x32_bf16 v[60:63], v[144:147], v[160:163], 0
	v_mfma_f32_16x16x32_bf16 v[52:55], v[152:155], v[160:163], 0
	s_add_u32 s42, s16, 0x80000
	v_mfma_f32_16x16x32_bf16 v[44:47], v[144:147], v[168:171], 0
	s_addc_u32 s43, s17, 0
	v_mfma_f32_16x16x32_bf16 v[36:39], v[152:155], v[168:171], 0
	s_add_i32 s41, s44, s26
	v_mfma_f32_16x16x32_bf16 v[28:31], v[144:147], v[176:179], 0
	s_mov_b32 m0, s41
	v_mfma_f32_16x16x32_bf16 v[20:23], v[152:155], v[176:179], 0
	v_mfma_f32_16x16x32_bf16 v[12:15], v[144:147], v[184:187], 0
	v_mfma_f32_16x16x32_bf16 v[4:7], v[152:155], v[184:187], 0
	v_mfma_f32_16x16x32_bf16 v[60:63], v[148:151], v[164:167], v[60:63]
	v_mfma_f32_16x16x32_bf16 v[52:55], v[156:159], v[164:167], v[52:55]
	v_mfma_f32_16x16x32_bf16 v[44:47], v[148:151], v[172:175], v[44:47]
	v_mfma_f32_16x16x32_bf16 v[36:39], v[156:159], v[172:175], v[36:39]
	v_mfma_f32_16x16x32_bf16 v[28:31], v[148:151], v[180:183], v[28:31]
	v_mfma_f32_16x16x32_bf16 v[20:23], v[156:159], v[180:183], v[20:23]
	v_mfma_f32_16x16x32_bf16 v[12:15], v[148:151], v[188:191], v[12:15]
	v_mfma_f32_16x16x32_bf16 v[4:7], v[156:159], v[188:191], v[4:7]
	s_barrier
	global_load_lds_dwordx4 v192, s[42:43]
	s_add_i32 m0, s41, 0x2000
	s_nop 0
	global_load_lds_dwordx4 v128, s[42:43]
	s_waitcnt vmcnt(6)
	s_barrier
	v_mfma_f32_16x16x32_bf16 v[56:59], v[196:199], v[160:163], 0
	v_mfma_f32_16x16x32_bf16 v[48:51], v[208:211], v[160:163], 0
	s_add_i32 s41, 0, 0x18000
	v_mfma_f32_16x16x32_bf16 v[40:43], v[196:199], v[168:171], 0
	s_add_u32 s18, s18, 0x80000
	v_mfma_f32_16x16x32_bf16 v[32:35], v[208:211], v[168:171], 0
	s_addc_u32 s19, s19, 0
	v_mfma_f32_16x16x32_bf16 v[24:27], v[196:199], v[176:179], 0
	s_mov_b32 m0, s29
	v_mfma_f32_16x16x32_bf16 v[16:19], v[208:211], v[176:179], 0
	v_mfma_f32_16x16x32_bf16 v[8:11], v[196:199], v[184:187], 0
	v_mfma_f32_16x16x32_bf16 v[0:3], v[208:211], v[184:187], 0
	v_mfma_f32_16x16x32_bf16 v[56:59], v[204:207], v[164:167], v[56:59]
	v_mfma_f32_16x16x32_bf16 v[48:51], v[214:217], v[164:167], v[48:51]
	v_mfma_f32_16x16x32_bf16 v[40:43], v[204:207], v[172:175], v[40:43]
	v_mfma_f32_16x16x32_bf16 v[32:35], v[214:217], v[172:175], v[32:35]
	v_mfma_f32_16x16x32_bf16 v[24:27], v[204:207], v[180:183], v[24:27]
	v_mfma_f32_16x16x32_bf16 v[16:19], v[214:217], v[180:183], v[16:19]
	v_mfma_f32_16x16x32_bf16 v[8:11], v[204:207], v[188:191], v[8:11]
	v_mfma_f32_16x16x32_bf16 v[0:3], v[214:217], v[188:191], v[0:3]
	s_barrier
	ds_read_b128 v[144:147], v220 offset:32768
	ds_read_b128 v[148:151], v220 offset:33792
	ds_read_b128 v[152:155], v220 offset:34816
	ds_read_b128 v[156:159], v220 offset:35840
	ds_read_b128 v[160:163], v143 offset:32768
	ds_read_b128 v[164:167], v143 offset:33792
	ds_read_b128 v[168:171], v143 offset:34816
	ds_read_b128 v[172:175], v143 offset:35840
	ds_read_b128 v[176:179], v143 offset:36864
	ds_read_b128 v[180:183], v143 offset:37888
	ds_read_b128 v[184:187], v143 offset:38912
	ds_read_b128 v[188:191], v143 offset:39936
	global_load_lds_dwordx4 v132, s[18:19]
	s_mov_b32 m0, s30
	s_nop 0
	global_load_lds_dwordx4 v130, s[18:19]
	s_waitcnt lgkmcnt(8)
	s_barrier
	s_waitcnt lgkmcnt(0)
	v_mfma_f32_16x16x32_bf16 v[124:127], v[144:147], v[160:163], v[124:127]
	v_mfma_f32_16x16x32_bf16 v[116:119], v[152:155], v[160:163], v[116:119]
	s_add_i32 s18, 0, 0x1c000
	v_mfma_f32_16x16x32_bf16 v[108:111], v[144:147], v[168:171], v[108:111]
	s_add_i32 s19, s41, s26
	v_mfma_f32_16x16x32_bf16 v[100:103], v[152:155], v[168:171], v[100:103]
	s_add_i32 m0, s19, 0xffffff80
	v_mfma_f32_16x16x32_bf16 v[92:95], v[144:147], v[176:179], v[92:95]
	v_mfma_f32_16x16x32_bf16 v[84:87], v[152:155], v[176:179], v[84:87]
	v_mfma_f32_16x16x32_bf16 v[76:79], v[144:147], v[184:187], v[76:79]
	v_mfma_f32_16x16x32_bf16 v[68:71], v[152:155], v[184:187], v[68:71]
	v_mfma_f32_16x16x32_bf16 v[124:127], v[148:151], v[164:167], v[124:127]
	v_mfma_f32_16x16x32_bf16 v[116:119], v[156:159], v[164:167], v[116:119]
	v_mfma_f32_16x16x32_bf16 v[108:111], v[148:151], v[172:175], v[108:111]
	v_mfma_f32_16x16x32_bf16 v[100:103], v[156:159], v[172:175], v[100:103]
	v_mfma_f32_16x16x32_bf16 v[92:95], v[148:151], v[180:183], v[92:95]
	v_mfma_f32_16x16x32_bf16 v[84:87], v[156:159], v[180:183], v[84:87]
	v_mfma_f32_16x16x32_bf16 v[76:79], v[148:151], v[188:191], v[76:79]
	v_mfma_f32_16x16x32_bf16 v[68:71], v[156:159], v[188:191], v[68:71]
	s_barrier
	ds_read_b128 v[196:199], v220 offset:49152
	ds_read_b128 v[204:207], v220 offset:50176
	ds_read_b128 v[208:211], v220 offset:51200
	ds_read_b128 v[214:217], v220 offset:52224
	global_load_lds_dwordx4 v192, s[16:17] offset:128
	s_add_i32 m0, s19, 0x1f80
	s_nop 0
	global_load_lds_dwordx4 v128, s[16:17] offset:128
	s_barrier
	s_waitcnt lgkmcnt(0)
	v_mfma_f32_16x16x32_bf16 v[120:123], v[196:199], v[160:163], v[120:123]
	v_mfma_f32_16x16x32_bf16 v[112:115], v[208:211], v[160:163], v[112:115]
	s_mov_b32 m0, s33
	v_mfma_f32_16x16x32_bf16 v[104:107], v[196:199], v[168:171], v[104:107]
	v_mfma_f32_16x16x32_bf16 v[96:99], v[208:211], v[168:171], v[96:99]
	v_mfma_f32_16x16x32_bf16 v[88:91], v[196:199], v[176:179], v[88:91]
	v_mfma_f32_16x16x32_bf16 v[80:83], v[208:211], v[176:179], v[80:83]
	v_mfma_f32_16x16x32_bf16 v[72:75], v[196:199], v[184:187], v[72:75]
	v_mfma_f32_16x16x32_bf16 v[64:67], v[208:211], v[184:187], v[64:67]
	v_mfma_f32_16x16x32_bf16 v[120:123], v[204:207], v[164:167], v[120:123]
	v_mfma_f32_16x16x32_bf16 v[112:115], v[214:217], v[164:167], v[112:115]
	v_mfma_f32_16x16x32_bf16 v[104:107], v[204:207], v[172:175], v[104:107]
	v_mfma_f32_16x16x32_bf16 v[96:99], v[214:217], v[172:175], v[96:99]
	v_mfma_f32_16x16x32_bf16 v[88:91], v[204:207], v[180:183], v[88:91]
	v_mfma_f32_16x16x32_bf16 v[80:83], v[214:217], v[180:183], v[80:83]
	v_mfma_f32_16x16x32_bf16 v[72:75], v[204:207], v[188:191], v[72:75]
	v_mfma_f32_16x16x32_bf16 v[64:67], v[214:217], v[188:191], v[64:67]
	s_barrier
	ds_read_b128 v[160:163], v143 offset:49152
	ds_read_b128 v[164:167], v143 offset:50176
	ds_read_b128 v[168:171], v143 offset:51200
	ds_read_b128 v[172:175], v143 offset:52224
	ds_read_b128 v[176:179], v143 offset:53248
	ds_read_b128 v[180:183], v143 offset:54272
	ds_read_b128 v[184:187], v143 offset:55296
	ds_read_b128 v[188:191], v143 offset:56320
	global_load_lds_dwordx4 v132, s[48:49]
	s_mov_b32 m0, s34
	s_nop 0
	global_load_lds_dwordx4 v130, s[48:49]
	s_barrier
	s_waitcnt lgkmcnt(0)
	v_mfma_f32_16x16x32_bf16 v[60:63], v[144:147], v[160:163], v[60:63]
	v_mfma_f32_16x16x32_bf16 v[52:55], v[152:155], v[160:163], v[52:55]
	s_add_u32 s16, s16, 0x80080
	v_mfma_f32_16x16x32_bf16 v[44:47], v[144:147], v[168:171], v[44:47]
	s_addc_u32 s17, s17, 0
	v_mfma_f32_16x16x32_bf16 v[36:39], v[152:155], v[168:171], v[36:39]
	s_add_i32 s18, s18, s26
	v_mfma_f32_16x16x32_bf16 v[28:31], v[144:147], v[176:179], v[28:31]
	s_mov_b32 m0, s18
	v_mfma_f32_16x16x32_bf16 v[20:23], v[152:155], v[176:179], v[20:23]
	v_mfma_f32_16x16x32_bf16 v[12:15], v[144:147], v[184:187], v[12:15]
	v_mfma_f32_16x16x32_bf16 v[4:7], v[152:155], v[184:187], v[4:7]
	v_mfma_f32_16x16x32_bf16 v[60:63], v[148:151], v[164:167], v[60:63]
	v_mfma_f32_16x16x32_bf16 v[52:55], v[156:159], v[164:167], v[52:55]
	v_mfma_f32_16x16x32_bf16 v[44:47], v[148:151], v[172:175], v[44:47]
	v_mfma_f32_16x16x32_bf16 v[36:39], v[156:159], v[172:175], v[36:39]
	v_mfma_f32_16x16x32_bf16 v[28:31], v[148:151], v[180:183], v[28:31]
	v_mfma_f32_16x16x32_bf16 v[20:23], v[156:159], v[180:183], v[20:23]
	v_mfma_f32_16x16x32_bf16 v[12:15], v[148:151], v[188:191], v[12:15]
	v_mfma_f32_16x16x32_bf16 v[4:7], v[156:159], v[188:191], v[4:7]
	s_barrier
	global_load_lds_dwordx4 v192, s[16:17]
	s_add_i32 m0, s18, 0x2000
	s_nop 0
	global_load_lds_dwordx4 v128, s[16:17]
	s_waitcnt vmcnt(6)
	s_barrier
	v_mfma_f32_16x16x32_bf16 v[56:59], v[196:199], v[160:163], v[56:59]
	v_mfma_f32_16x16x32_bf16 v[48:51], v[208:211], v[160:163], v[48:51]
	s_add_i32 s40, s40, 2
	v_mfma_f32_16x16x32_bf16 v[40:43], v[196:199], v[168:171], v[40:43]
	s_add_u32 s14, s14, 0x100
	v_mfma_f32_16x16x32_bf16 v[32:35], v[208:211], v[168:171], v[32:35]
	s_addc_u32 s15, s15, 0
	v_mfma_f32_16x16x32_bf16 v[24:27], v[196:199], v[176:179], v[24:27]
	s_add_u32 s38, s38, 0x100
	v_mfma_f32_16x16x32_bf16 v[16:19], v[208:211], v[176:179], v[16:19]
	s_addc_u32 s39, s39, 0
	v_mfma_f32_16x16x32_bf16 v[8:11], v[196:199], v[184:187], v[8:11]
	s_add_u32 s16, s14, 0xfff80080
	s_addc_u32 s17, s15, -1
	v_mfma_f32_16x16x32_bf16 v[0:3], v[208:211], v[184:187], v[0:3]
	s_add_i32 s41, 0, 0x10000
	s_cmp_eq_u32 s40, 28
	v_mfma_f32_16x16x32_bf16 v[56:59], v[204:207], v[164:167], v[56:59]
	s_cselect_b32 s19, s7, s17
	s_cselect_b32 s18, s36, s16
	v_mfma_f32_16x16x32_bf16 v[48:51], v[214:217], v[164:167], v[48:51]
	s_cselect_b32 s17, s5, s39
	s_cselect_b32 s16, s37, s38
	v_mfma_f32_16x16x32_bf16 v[40:43], v[204:207], v[172:175], v[40:43]
	s_add_i32 m0, s13, 0xc000
	v_mfma_f32_16x16x32_bf16 v[32:35], v[214:217], v[172:175], v[32:35]
	v_mfma_f32_16x16x32_bf16 v[24:27], v[204:207], v[180:183], v[24:27]
	v_mfma_f32_16x16x32_bf16 v[16:19], v[214:217], v[180:183], v[16:19]
	v_mfma_f32_16x16x32_bf16 v[8:11], v[204:207], v[188:191], v[8:11]
	v_mfma_f32_16x16x32_bf16 v[0:3], v[214:217], v[188:191], v[0:3]
	s_cmp_gt_u32 s40, 29
	s_barrier
.LBB0_217:
	ds_read_b128 v[144:147], v220 offset:0
	ds_read_b128 v[148:151], v220 offset:1024
	ds_read_b128 v[152:155], v220 offset:2048
	ds_read_b128 v[156:159], v220 offset:3072
	ds_read_b128 v[160:163], v143
	ds_read_b128 v[164:167], v143 offset:1024
	ds_read_b128 v[168:171], v143 offset:2048
	ds_read_b128 v[172:175], v143 offset:3072
	ds_read_b128 v[176:179], v143 offset:4096
	ds_read_b128 v[180:183], v143 offset:5120
	ds_read_b128 v[184:187], v143 offset:6144
	ds_read_b128 v[188:191], v143 offset:7168
	global_load_lds_dwordx4 v134, s[14:15]
	s_add_i32 m0, s13, 0xe000
	s_nop 0
	global_load_lds_dwordx4 v136, s[14:15]
	s_waitcnt lgkmcnt(8)
	s_barrier
	s_waitcnt lgkmcnt(0)
	v_mfma_f32_16x16x32_bf16 v[124:127], v[144:147], v[160:163], v[124:127]
	v_mfma_f32_16x16x32_bf16 v[116:119], v[152:155], v[160:163], v[116:119]
	s_add_i32 s44, 0, 0x14000
	v_mfma_f32_16x16x32_bf16 v[108:111], v[144:147], v[168:171], v[108:111]
	s_add_i32 s41, s41, s26
	v_mfma_f32_16x16x32_bf16 v[100:103], v[152:155], v[168:171], v[100:103]
	s_mov_b32 m0, s41
	v_mfma_f32_16x16x32_bf16 v[92:95], v[144:147], v[176:179], v[92:95]
	v_mfma_f32_16x16x32_bf16 v[84:87], v[152:155], v[176:179], v[84:87]
	v_mfma_f32_16x16x32_bf16 v[76:79], v[144:147], v[184:187], v[76:79]
	v_mfma_f32_16x16x32_bf16 v[68:71], v[152:155], v[184:187], v[68:71]
	v_mfma_f32_16x16x32_bf16 v[124:127], v[148:151], v[164:167], v[124:127]
	v_mfma_f32_16x16x32_bf16 v[116:119], v[156:159], v[164:167], v[116:119]
	v_mfma_f32_16x16x32_bf16 v[108:111], v[148:151], v[172:175], v[108:111]
	v_mfma_f32_16x16x32_bf16 v[100:103], v[156:159], v[172:175], v[100:103]
	v_mfma_f32_16x16x32_bf16 v[92:95], v[148:151], v[180:183], v[92:95]
	v_mfma_f32_16x16x32_bf16 v[84:87], v[156:159], v[180:183], v[84:87]
	v_mfma_f32_16x16x32_bf16 v[76:79], v[148:151], v[188:191], v[76:79]
	v_mfma_f32_16x16x32_bf16 v[68:71], v[156:159], v[188:191], v[68:71]
	s_barrier
	ds_read_b128 v[196:199], v220 offset:16384
	ds_read_b128 v[204:207], v220 offset:17408
	ds_read_b128 v[208:211], v220 offset:18432
	ds_read_b128 v[214:217], v220 offset:19456
	global_load_lds_dwordx4 v192, s[16:17]
	s_add_i32 m0, s41, 0x2000
	s_nop 0
	global_load_lds_dwordx4 v128, s[16:17]
	s_barrier
	s_waitcnt lgkmcnt(0)
	v_mfma_f32_16x16x32_bf16 v[120:123], v[196:199], v[160:163], v[120:123]
	v_mfma_f32_16x16x32_bf16 v[112:115], v[208:211], v[160:163], v[112:115]
	s_mov_b32 m0, s13
	v_mfma_f32_16x16x32_bf16 v[104:107], v[196:199], v[168:171], v[104:107]
	s_add_u32 s48, s18, 0x80
	v_mfma_f32_16x16x32_bf16 v[96:99], v[208:211], v[168:171], v[96:99]
	s_addc_u32 s49, s19, 0
	v_mfma_f32_16x16x32_bf16 v[88:91], v[196:199], v[176:179], v[88:91]
	v_mfma_f32_16x16x32_bf16 v[80:83], v[208:211], v[176:179], v[80:83]
	v_mfma_f32_16x16x32_bf16 v[72:75], v[196:199], v[184:187], v[72:75]
	v_mfma_f32_16x16x32_bf16 v[64:67], v[208:211], v[184:187], v[64:67]
	v_mfma_f32_16x16x32_bf16 v[120:123], v[204:207], v[164:167], v[120:123]
	v_mfma_f32_16x16x32_bf16 v[112:115], v[214:217], v[164:167], v[112:115]
	v_mfma_f32_16x16x32_bf16 v[104:107], v[204:207], v[172:175], v[104:107]
	v_mfma_f32_16x16x32_bf16 v[96:99], v[214:217], v[172:175], v[96:99]
	v_mfma_f32_16x16x32_bf16 v[88:91], v[204:207], v[180:183], v[88:91]
	v_mfma_f32_16x16x32_bf16 v[80:83], v[214:217], v[180:183], v[80:83]
	v_mfma_f32_16x16x32_bf16 v[72:75], v[204:207], v[188:191], v[72:75]
	v_mfma_f32_16x16x32_bf16 v[64:67], v[214:217], v[188:191], v[64:67]
	s_barrier
	ds_read_b128 v[160:163], v143 offset:16384
	ds_read_b128 v[164:167], v143 offset:17408
	ds_read_b128 v[168:171], v143 offset:18432
	ds_read_b128 v[172:175], v143 offset:19456
	ds_read_b128 v[176:179], v143 offset:20480
	ds_read_b128 v[180:183], v143 offset:21504
	ds_read_b128 v[184:187], v143 offset:22528
	ds_read_b128 v[188:191], v143 offset:23552
	global_load_lds_dwordx4 v132, s[18:19]
	s_mov_b32 m0, s28
	s_nop 0
	global_load_lds_dwordx4 v130, s[18:19]
	s_barrier
	s_waitcnt lgkmcnt(0)
	v_mfma_f32_16x16x32_bf16 v[60:63], v[144:147], v[160:163], v[60:63]
	v_mfma_f32_16x16x32_bf16 v[52:55], v[152:155], v[160:163], v[52:55]
	s_add_u32 s42, s16, 0x80000
	v_mfma_f32_16x16x32_bf16 v[44:47], v[144:147], v[168:171], v[44:47]
	s_addc_u32 s43, s17, 0
	v_mfma_f32_16x16x32_bf16 v[36:39], v[152:155], v[168:171], v[36:39]
	s_add_i32 s41, s44, s26
	v_mfma_f32_16x16x32_bf16 v[28:31], v[144:147], v[176:179], v[28:31]
	s_mov_b32 m0, s41
	v_mfma_f32_16x16x32_bf16 v[20:23], v[152:155], v[176:179], v[20:23]
	v_mfma_f32_16x16x32_bf16 v[12:15], v[144:147], v[184:187], v[12:15]
	v_mfma_f32_16x16x32_bf16 v[4:7], v[152:155], v[184:187], v[4:7]
	v_mfma_f32_16x16x32_bf16 v[60:63], v[148:151], v[164:167], v[60:63]
	v_mfma_f32_16x16x32_bf16 v[52:55], v[156:159], v[164:167], v[52:55]
	v_mfma_f32_16x16x32_bf16 v[44:47], v[148:151], v[172:175], v[44:47]
	v_mfma_f32_16x16x32_bf16 v[36:39], v[156:159], v[172:175], v[36:39]
	v_mfma_f32_16x16x32_bf16 v[28:31], v[148:151], v[180:183], v[28:31]
	v_mfma_f32_16x16x32_bf16 v[20:23], v[156:159], v[180:183], v[20:23]
	v_mfma_f32_16x16x32_bf16 v[12:15], v[148:151], v[188:191], v[12:15]
	v_mfma_f32_16x16x32_bf16 v[4:7], v[156:159], v[188:191], v[4:7]
	s_barrier
	global_load_lds_dwordx4 v192, s[42:43]
	s_add_i32 m0, s41, 0x2000
	s_nop 0
	global_load_lds_dwordx4 v128, s[42:43]
	s_waitcnt vmcnt(6)
	s_barrier
	v_mfma_f32_16x16x32_bf16 v[56:59], v[196:199], v[160:163], v[56:59]
	v_mfma_f32_16x16x32_bf16 v[48:51], v[208:211], v[160:163], v[48:51]
	s_add_i32 s41, 0, 0x18000
	v_mfma_f32_16x16x32_bf16 v[40:43], v[196:199], v[168:171], v[40:43]
	s_add_u32 s18, s18, 0x80000
	v_mfma_f32_16x16x32_bf16 v[32:35], v[208:211], v[168:171], v[32:35]
	s_addc_u32 s19, s19, 0
	v_mfma_f32_16x16x32_bf16 v[24:27], v[196:199], v[176:179], v[24:27]
	s_mov_b32 m0, s29
	v_mfma_f32_16x16x32_bf16 v[16:19], v[208:211], v[176:179], v[16:19]
	v_mfma_f32_16x16x32_bf16 v[8:11], v[196:199], v[184:187], v[8:11]
	v_mfma_f32_16x16x32_bf16 v[0:3], v[208:211], v[184:187], v[0:3]
	v_mfma_f32_16x16x32_bf16 v[56:59], v[204:207], v[164:167], v[56:59]
	v_mfma_f32_16x16x32_bf16 v[48:51], v[214:217], v[164:167], v[48:51]
	v_mfma_f32_16x16x32_bf16 v[40:43], v[204:207], v[172:175], v[40:43]
	v_mfma_f32_16x16x32_bf16 v[32:35], v[214:217], v[172:175], v[32:35]
	v_mfma_f32_16x16x32_bf16 v[24:27], v[204:207], v[180:183], v[24:27]
	v_mfma_f32_16x16x32_bf16 v[16:19], v[214:217], v[180:183], v[16:19]
	v_mfma_f32_16x16x32_bf16 v[8:11], v[204:207], v[188:191], v[8:11]
	v_mfma_f32_16x16x32_bf16 v[0:3], v[214:217], v[188:191], v[0:3]
	s_barrier
	ds_read_b128 v[144:147], v220 offset:32768
	ds_read_b128 v[148:151], v220 offset:33792
	ds_read_b128 v[152:155], v220 offset:34816
	ds_read_b128 v[156:159], v220 offset:35840
	ds_read_b128 v[160:163], v143 offset:32768
	ds_read_b128 v[164:167], v143 offset:33792
	ds_read_b128 v[168:171], v143 offset:34816
	ds_read_b128 v[172:175], v143 offset:35840
	ds_read_b128 v[176:179], v143 offset:36864
	ds_read_b128 v[180:183], v143 offset:37888
	ds_read_b128 v[184:187], v143 offset:38912
	ds_read_b128 v[188:191], v143 offset:39936
	global_load_lds_dwordx4 v132, s[18:19]
	s_mov_b32 m0, s30
	s_nop 0
	global_load_lds_dwordx4 v130, s[18:19]
	s_waitcnt lgkmcnt(8)
	s_barrier
	s_waitcnt lgkmcnt(0)
	v_mfma_f32_16x16x32_bf16 v[124:127], v[144:147], v[160:163], v[124:127]
	v_mfma_f32_16x16x32_bf16 v[116:119], v[152:155], v[160:163], v[116:119]
	s_add_i32 s18, 0, 0x1c000
	v_mfma_f32_16x16x32_bf16 v[108:111], v[144:147], v[168:171], v[108:111]
	s_add_i32 s19, s41, s26
	v_mfma_f32_16x16x32_bf16 v[100:103], v[152:155], v[168:171], v[100:103]
	s_add_i32 m0, s19, 0xffffff80
	v_mfma_f32_16x16x32_bf16 v[92:95], v[144:147], v[176:179], v[92:95]
	v_mfma_f32_16x16x32_bf16 v[84:87], v[152:155], v[176:179], v[84:87]
	v_mfma_f32_16x16x32_bf16 v[76:79], v[144:147], v[184:187], v[76:79]
	v_mfma_f32_16x16x32_bf16 v[68:71], v[152:155], v[184:187], v[68:71]
	v_mfma_f32_16x16x32_bf16 v[124:127], v[148:151], v[164:167], v[124:127]
	v_mfma_f32_16x16x32_bf16 v[116:119], v[156:159], v[164:167], v[116:119]
	v_mfma_f32_16x16x32_bf16 v[108:111], v[148:151], v[172:175], v[108:111]
	v_mfma_f32_16x16x32_bf16 v[100:103], v[156:159], v[172:175], v[100:103]
	v_mfma_f32_16x16x32_bf16 v[92:95], v[148:151], v[180:183], v[92:95]
	v_mfma_f32_16x16x32_bf16 v[84:87], v[156:159], v[180:183], v[84:87]
	v_mfma_f32_16x16x32_bf16 v[76:79], v[148:151], v[188:191], v[76:79]
	v_mfma_f32_16x16x32_bf16 v[68:71], v[156:159], v[188:191], v[68:71]
	s_barrier
	ds_read_b128 v[196:199], v220 offset:49152
	ds_read_b128 v[204:207], v220 offset:50176
	ds_read_b128 v[208:211], v220 offset:51200
	ds_read_b128 v[214:217], v220 offset:52224
	global_load_lds_dwordx4 v192, s[16:17] offset:128
	s_add_i32 m0, s19, 0x1f80
	s_nop 0
	global_load_lds_dwordx4 v128, s[16:17] offset:128
	s_barrier
	s_waitcnt lgkmcnt(0)
	v_mfma_f32_16x16x32_bf16 v[120:123], v[196:199], v[160:163], v[120:123]
	v_mfma_f32_16x16x32_bf16 v[112:115], v[208:211], v[160:163], v[112:115]
	s_mov_b32 m0, s33
	v_mfma_f32_16x16x32_bf16 v[104:107], v[196:199], v[168:171], v[104:107]
	v_mfma_f32_16x16x32_bf16 v[96:99], v[208:211], v[168:171], v[96:99]
	v_mfma_f32_16x16x32_bf16 v[88:91], v[196:199], v[176:179], v[88:91]
	v_mfma_f32_16x16x32_bf16 v[80:83], v[208:211], v[176:179], v[80:83]
	v_mfma_f32_16x16x32_bf16 v[72:75], v[196:199], v[184:187], v[72:75]
	v_mfma_f32_16x16x32_bf16 v[64:67], v[208:211], v[184:187], v[64:67]
	v_mfma_f32_16x16x32_bf16 v[120:123], v[204:207], v[164:167], v[120:123]
	v_mfma_f32_16x16x32_bf16 v[112:115], v[214:217], v[164:167], v[112:115]
	v_mfma_f32_16x16x32_bf16 v[104:107], v[204:207], v[172:175], v[104:107]
	v_mfma_f32_16x16x32_bf16 v[96:99], v[214:217], v[172:175], v[96:99]
	v_mfma_f32_16x16x32_bf16 v[88:91], v[204:207], v[180:183], v[88:91]
	v_mfma_f32_16x16x32_bf16 v[80:83], v[214:217], v[180:183], v[80:83]
	v_mfma_f32_16x16x32_bf16 v[72:75], v[204:207], v[188:191], v[72:75]
	v_mfma_f32_16x16x32_bf16 v[64:67], v[214:217], v[188:191], v[64:67]
	s_barrier
	ds_read_b128 v[160:163], v143 offset:49152
	ds_read_b128 v[164:167], v143 offset:50176
	ds_read_b128 v[168:171], v143 offset:51200
	ds_read_b128 v[172:175], v143 offset:52224
	ds_read_b128 v[176:179], v143 offset:53248
	ds_read_b128 v[180:183], v143 offset:54272
	ds_read_b128 v[184:187], v143 offset:55296
	ds_read_b128 v[188:191], v143 offset:56320
	global_load_lds_dwordx4 v132, s[48:49]
	s_mov_b32 m0, s34
	s_nop 0
	global_load_lds_dwordx4 v130, s[48:49]
	s_barrier
	s_waitcnt lgkmcnt(0)
	v_mfma_f32_16x16x32_bf16 v[60:63], v[144:147], v[160:163], v[60:63]
	v_mfma_f32_16x16x32_bf16 v[52:55], v[152:155], v[160:163], v[52:55]
	s_add_u32 s16, s16, 0x80080
	v_mfma_f32_16x16x32_bf16 v[44:47], v[144:147], v[168:171], v[44:47]
	s_addc_u32 s17, s17, 0
	v_mfma_f32_16x16x32_bf16 v[36:39], v[152:155], v[168:171], v[36:39]
	s_add_i32 s18, s18, s26
	v_mfma_f32_16x16x32_bf16 v[28:31], v[144:147], v[176:179], v[28:31]
	s_mov_b32 m0, s18
	v_mfma_f32_16x16x32_bf16 v[20:23], v[152:155], v[176:179], v[20:23]
	v_mfma_f32_16x16x32_bf16 v[12:15], v[144:147], v[184:187], v[12:15]
	v_mfma_f32_16x16x32_bf16 v[4:7], v[152:155], v[184:187], v[4:7]
	v_mfma_f32_16x16x32_bf16 v[60:63], v[148:151], v[164:167], v[60:63]
	v_mfma_f32_16x16x32_bf16 v[52:55], v[156:159], v[164:167], v[52:55]
	v_mfma_f32_16x16x32_bf16 v[44:47], v[148:151], v[172:175], v[44:47]
	v_mfma_f32_16x16x32_bf16 v[36:39], v[156:159], v[172:175], v[36:39]
	v_mfma_f32_16x16x32_bf16 v[28:31], v[148:151], v[180:183], v[28:31]
	v_mfma_f32_16x16x32_bf16 v[20:23], v[156:159], v[180:183], v[20:23]
	v_mfma_f32_16x16x32_bf16 v[12:15], v[148:151], v[188:191], v[12:15]
	v_mfma_f32_16x16x32_bf16 v[4:7], v[156:159], v[188:191], v[4:7]
	s_barrier
	global_load_lds_dwordx4 v192, s[16:17]
	s_add_i32 m0, s18, 0x2000
	s_nop 0
	global_load_lds_dwordx4 v128, s[16:17]
	s_waitcnt vmcnt(6)
	s_barrier
	v_mfma_f32_16x16x32_bf16 v[56:59], v[196:199], v[160:163], v[56:59]
	v_mfma_f32_16x16x32_bf16 v[48:51], v[208:211], v[160:163], v[48:51]
	s_add_i32 s40, s40, 2
	v_mfma_f32_16x16x32_bf16 v[40:43], v[196:199], v[168:171], v[40:43]
	s_add_u32 s14, s14, 0x100
	v_mfma_f32_16x16x32_bf16 v[32:35], v[208:211], v[168:171], v[32:35]
	s_addc_u32 s15, s15, 0
	v_mfma_f32_16x16x32_bf16 v[24:27], v[196:199], v[176:179], v[24:27]
	s_add_u32 s38, s38, 0x100
	v_mfma_f32_16x16x32_bf16 v[16:19], v[208:211], v[176:179], v[16:19]
	s_addc_u32 s39, s39, 0
	v_mfma_f32_16x16x32_bf16 v[8:11], v[196:199], v[184:187], v[8:11]
	s_add_u32 s16, s14, 0xfff80080
	s_addc_u32 s17, s15, -1
	v_mfma_f32_16x16x32_bf16 v[0:3], v[208:211], v[184:187], v[0:3]
	s_add_i32 s41, 0, 0x10000
	s_cmp_eq_u32 s40, 28
	v_mfma_f32_16x16x32_bf16 v[56:59], v[204:207], v[164:167], v[56:59]
	s_cselect_b32 s19, s7, s17
	s_cselect_b32 s18, s36, s16
	v_mfma_f32_16x16x32_bf16 v[48:51], v[214:217], v[164:167], v[48:51]
	s_cselect_b32 s17, s5, s39
	s_cselect_b32 s16, s37, s38
	v_mfma_f32_16x16x32_bf16 v[40:43], v[204:207], v[172:175], v[40:43]
	s_add_i32 m0, s13, 0xc000
	v_mfma_f32_16x16x32_bf16 v[32:35], v[214:217], v[172:175], v[32:35]
	v_mfma_f32_16x16x32_bf16 v[24:27], v[204:207], v[180:183], v[24:27]
	v_mfma_f32_16x16x32_bf16 v[16:19], v[214:217], v[180:183], v[16:19]
	v_mfma_f32_16x16x32_bf16 v[8:11], v[204:207], v[188:191], v[8:11]
	v_mfma_f32_16x16x32_bf16 v[0:3], v[214:217], v[188:191], v[0:3]
	s_cmp_gt_u32 s40, 29
	s_barrier
	s_cbranch_scc0 .LBB0_217
	v_mul_f32_e32 v145, 0xbfb8aa3b, v124
	v_exp_f32_e32 v145, v145
	v_lshl_or_b32 v146, s35, 7, v142
	v_lshl_add_u32 v144, s12, 8, v140
	v_ashrrev_i32_e32 v147, 31, v146
	v_add_f32_e32 v145, 1.0, v145
	v_rcp_f32_e32 v145, v145
	v_mov_b64_e32 v[138:139], s[2:3]
	s_movk_i32 s5, 0x2c00
	v_mad_i64_i32 v[148:149], s[14:15], v144, s5, v[138:139]
	v_mul_f32_e32 v124, v124, v145
	v_mul_f32_e32 v120, v124, v120
	v_mul_f32_e32 v124, 0xbfb8aa3b, v125
	v_exp_f32_e32 v124, v124
	s_and_b64 vcc, exec, s[0:1]
	s_mov_b32 s35, s4
	s_mov_b32 s12, s6
	v_add_f32_e32 v124, 1.0, v124
	v_rcp_f32_e32 v124, v124
	s_mov_b64 s[16:17], s[10:11]
	v_mul_f32_e32 v124, v125, v124
	v_mul_f32_e32 v121, v124, v121
	v_mul_f32_e32 v124, 0xbfb8aa3b, v126
	v_exp_f32_e32 v124, v124
	s_nop 0
	v_add_f32_e32 v124, 1.0, v124
	v_rcp_f32_e32 v124, v124
	s_nop 0
	v_mul_f32_e32 v124, v126, v124
	v_mul_f32_e32 v122, v124, v122
	v_mul_f32_e32 v124, 0xbfb8aa3b, v127
	v_exp_f32_e32 v124, v124
	s_nop 0
	v_add_f32_e32 v124, 1.0, v124
	v_rcp_f32_e32 v124, v124
	s_nop 0
	v_mul_f32_e32 v124, v127, v124
	v_mul_f32_e32 v123, v124, v123
	v_mul_f32_e32 v124, 0xbfb8aa3b, v116
	v_exp_f32_e32 v124, v124
	s_nop 0
	v_add_f32_e32 v124, 1.0, v124
	v_rcp_f32_e32 v124, v124
	s_nop 0
	v_mul_f32_e32 v116, v116, v124
	v_mul_f32_e32 v116, v116, v112
	v_mul_f32_e32 v112, 0xbfb8aa3b, v117
	v_exp_f32_e32 v112, v112
	s_nop 0
	v_add_f32_e32 v112, 1.0, v112
	v_rcp_f32_e32 v112, v112
	s_nop 0
	v_mul_f32_e32 v112, v117, v112
	v_mul_f32_e32 v117, v112, v113
	v_mul_f32_e32 v112, 0xbfb8aa3b, v118
	v_exp_f32_e32 v112, v112
	s_nop 0
	v_add_f32_e32 v112, 1.0, v112
	v_rcp_f32_e32 v112, v112
	s_nop 0
	v_mul_f32_e32 v112, v118, v112
	v_mul_f32_e32 v124, v112, v114
	v_mul_f32_e32 v112, 0xbfb8aa3b, v119
	v_exp_f32_e32 v112, v112
	v_cvt_pk_bf16_f32 v114, v120, v121
	s_nop 0
	v_add_f32_e32 v112, 1.0, v112
	v_rcp_f32_e32 v112, v112
	s_nop 0
	v_mul_f32_e32 v112, v119, v112
	v_mul_f32_e32 v125, v112, v115
	v_lshlrev_b64 v[112:113], 1, v[146:147]
	v_lshl_add_u64 v[118:119], v[148:149], 0, v[112:113]
	v_cvt_pk_bf16_f32 v115, v122, v123
	v_cvt_pk_bf16_f32 v116, v116, v117
	v_cvt_pk_bf16_f32 v117, v124, v125
	global_store_dwordx4 v[118:119], v[114:117], off
	s_nop 1
	v_mul_f32_e32 v116, 0xbfb8aa3b, v108
	v_exp_f32_e32 v116, v116
	v_or_b32_e32 v114, 16, v144
	v_mad_i64_i32 v[114:115], s[14:15], v114, s5, v[138:139]
	v_add_f32_e32 v116, 1.0, v116
	v_rcp_f32_e32 v116, v116
	s_nop 0
	v_mul_f32_e32 v108, v108, v116
	v_mul_f32_e32 v104, v108, v104
	v_mul_f32_e32 v108, 0xbfb8aa3b, v109
	v_exp_f32_e32 v108, v108
	s_nop 0
	v_add_f32_e32 v108, 1.0, v108
	v_rcp_f32_e32 v108, v108
	s_nop 0
	v_mul_f32_e32 v108, v109, v108
	v_mul_f32_e32 v105, v108, v105
	v_mul_f32_e32 v108, 0xbfb8aa3b, v110
	v_exp_f32_e32 v108, v108
	s_nop 0
	v_add_f32_e32 v108, 1.0, v108
	v_rcp_f32_e32 v108, v108
	s_nop 0
	v_mul_f32_e32 v108, v110, v108
	v_mul_f32_e32 v106, v108, v106
	v_mul_f32_e32 v108, 0xbfb8aa3b, v111
	v_exp_f32_e32 v108, v108
	s_nop 0
	v_add_f32_e32 v108, 1.0, v108
	v_rcp_f32_e32 v108, v108
	s_nop 0
	v_mul_f32_e32 v108, v111, v108
	v_mul_f32_e32 v107, v108, v107
	v_mul_f32_e32 v108, 0xbfb8aa3b, v100
	v_exp_f32_e32 v108, v108
	s_nop 0
	v_add_f32_e32 v108, 1.0, v108
	v_rcp_f32_e32 v108, v108
	s_nop 0
	v_mul_f32_e32 v100, v100, v108
	v_mul_f32_e32 v108, v100, v96
	v_mul_f32_e32 v96, 0xbfb8aa3b, v101
	v_exp_f32_e32 v96, v96
	s_nop 0
	v_add_f32_e32 v96, 1.0, v96
	v_rcp_f32_e32 v96, v96
	s_nop 0
	v_mul_f32_e32 v96, v101, v96
	v_mul_f32_e32 v109, v96, v97
	v_mul_f32_e32 v96, 0xbfb8aa3b, v102
	v_exp_f32_e32 v96, v96
	v_lshl_add_u64 v[100:101], v[114:115], 0, v[112:113]
	v_add_f32_e32 v96, 1.0, v96
	v_rcp_f32_e32 v96, v96
	s_nop 0
	v_mul_f32_e32 v96, v102, v96
	v_mul_f32_e32 v102, v96, v98
	v_mul_f32_e32 v96, 0xbfb8aa3b, v103
	v_exp_f32_e32 v96, v96
	s_nop 0
	v_add_f32_e32 v96, 1.0, v96
	v_rcp_f32_e32 v96, v96
	s_nop 0
	v_mul_f32_e32 v96, v103, v96
	v_mul_f32_e32 v99, v96, v99
	v_cvt_pk_bf16_f32 v96, v104, v105
	v_cvt_pk_bf16_f32 v97, v106, v107
	v_cvt_pk_bf16_f32 v98, v108, v109
	v_cvt_pk_bf16_f32 v99, v102, v99
	global_store_dwordx4 v[100:101], v[96:99], off
	s_nop 1
	v_mul_f32_e32 v98, 0xbfb8aa3b, v92
	v_exp_f32_e32 v98, v98
	v_or_b32_e32 v96, 32, v144
	v_mad_i64_i32 v[96:97], s[14:15], v96, s5, v[138:139]
	v_add_f32_e32 v98, 1.0, v98
	v_rcp_f32_e32 v98, v98
	s_nop 0
	v_mul_f32_e32 v92, v92, v98
	v_mul_f32_e32 v88, v92, v88
	v_mul_f32_e32 v92, 0xbfb8aa3b, v93
	v_exp_f32_e32 v92, v92
	s_nop 0
	v_add_f32_e32 v92, 1.0, v92
	v_rcp_f32_e32 v92, v92
	s_nop 0
	v_mul_f32_e32 v92, v93, v92
	v_mul_f32_e32 v89, v92, v89
	v_mul_f32_e32 v92, 0xbfb8aa3b, v94
	v_exp_f32_e32 v92, v92
	s_nop 0
	v_add_f32_e32 v92, 1.0, v92
	v_rcp_f32_e32 v92, v92
	s_nop 0
	v_mul_f32_e32 v92, v94, v92
	v_mul_f32_e32 v90, v92, v90
	v_mul_f32_e32 v92, 0xbfb8aa3b, v95
	v_exp_f32_e32 v92, v92
	s_nop 0
	v_add_f32_e32 v92, 1.0, v92
	v_rcp_f32_e32 v92, v92
	s_nop 0
	v_mul_f32_e32 v92, v95, v92
	v_mul_f32_e32 v91, v92, v91
	v_mul_f32_e32 v92, 0xbfb8aa3b, v84
	v_exp_f32_e32 v92, v92
	s_nop 0
	v_add_f32_e32 v92, 1.0, v92
	v_rcp_f32_e32 v92, v92
	s_nop 0
	v_mul_f32_e32 v84, v84, v92
	v_mul_f32_e32 v92, v84, v80
	v_mul_f32_e32 v80, 0xbfb8aa3b, v85
	v_exp_f32_e32 v80, v80
	s_nop 0
	v_add_f32_e32 v80, 1.0, v80
	v_rcp_f32_e32 v80, v80
	s_nop 0
	v_mul_f32_e32 v80, v85, v80
	v_mul_f32_e32 v93, v80, v81
	v_mul_f32_e32 v80, 0xbfb8aa3b, v86
	v_exp_f32_e32 v80, v80
	v_lshl_add_u64 v[84:85], v[96:97], 0, v[112:113]
	v_add_f32_e32 v80, 1.0, v80
	v_rcp_f32_e32 v80, v80
	s_nop 0
	v_mul_f32_e32 v80, v86, v80
	v_mul_f32_e32 v86, v80, v82
	v_mul_f32_e32 v80, 0xbfb8aa3b, v87
	v_exp_f32_e32 v80, v80
	s_nop 0
	v_add_f32_e32 v80, 1.0, v80
	v_rcp_f32_e32 v80, v80
	s_nop 0
	v_mul_f32_e32 v80, v87, v80
	v_mul_f32_e32 v83, v80, v83
	v_cvt_pk_bf16_f32 v80, v88, v89
	v_cvt_pk_bf16_f32 v81, v90, v91
	v_cvt_pk_bf16_f32 v82, v92, v93
	v_cvt_pk_bf16_f32 v83, v86, v83
	global_store_dwordx4 v[84:85], v[80:83], off
	s_nop 1
	v_mul_f32_e32 v82, 0xbfb8aa3b, v76
	v_exp_f32_e32 v82, v82
	v_or_b32_e32 v80, 48, v144
	v_mad_i64_i32 v[80:81], s[14:15], v80, s5, v[138:139]
	v_add_f32_e32 v82, 1.0, v82
	v_rcp_f32_e32 v82, v82
	s_nop 0
	v_mul_f32_e32 v76, v76, v82
	v_mul_f32_e32 v72, v76, v72
	v_mul_f32_e32 v76, 0xbfb8aa3b, v77
	v_exp_f32_e32 v76, v76
	s_nop 0
	v_add_f32_e32 v76, 1.0, v76
	v_rcp_f32_e32 v76, v76
	s_nop 0
	v_mul_f32_e32 v76, v77, v76
	v_mul_f32_e32 v73, v76, v73
	v_mul_f32_e32 v76, 0xbfb8aa3b, v78
	v_exp_f32_e32 v76, v76
	s_nop 0
	v_add_f32_e32 v76, 1.0, v76
	v_rcp_f32_e32 v76, v76
	s_nop 0
	v_mul_f32_e32 v76, v78, v76
	v_mul_f32_e32 v74, v76, v74
	v_mul_f32_e32 v76, 0xbfb8aa3b, v79
	v_exp_f32_e32 v76, v76
	s_nop 0
	v_add_f32_e32 v76, 1.0, v76
	v_rcp_f32_e32 v76, v76
	s_nop 0
	v_mul_f32_e32 v76, v79, v76
	v_mul_f32_e32 v75, v76, v75
	v_mul_f32_e32 v76, 0xbfb8aa3b, v68
	v_exp_f32_e32 v76, v76
	s_nop 0
	v_add_f32_e32 v76, 1.0, v76
	v_rcp_f32_e32 v76, v76
	s_nop 0
	v_mul_f32_e32 v68, v68, v76
	v_mul_f32_e32 v76, v68, v64
	v_mul_f32_e32 v64, 0xbfb8aa3b, v69
	v_exp_f32_e32 v64, v64
	s_nop 0
	v_add_f32_e32 v64, 1.0, v64
	v_rcp_f32_e32 v64, v64
	s_nop 0
	v_mul_f32_e32 v64, v69, v64
	v_mul_f32_e32 v77, v64, v65
	v_mul_f32_e32 v64, 0xbfb8aa3b, v70
	v_exp_f32_e32 v64, v64
	v_lshl_add_u64 v[68:69], v[80:81], 0, v[112:113]
	v_add_f32_e32 v64, 1.0, v64
	v_rcp_f32_e32 v64, v64
	s_nop 0
	v_mul_f32_e32 v64, v70, v64
	v_mul_f32_e32 v70, v64, v66
	v_mul_f32_e32 v64, 0xbfb8aa3b, v71
	v_exp_f32_e32 v64, v64
	s_nop 0
	v_add_f32_e32 v64, 1.0, v64
	v_rcp_f32_e32 v64, v64
	s_nop 0
	v_mul_f32_e32 v64, v71, v64
	v_mul_f32_e32 v67, v64, v67
	v_cvt_pk_bf16_f32 v64, v72, v73
	v_cvt_pk_bf16_f32 v65, v74, v75
	v_cvt_pk_bf16_f32 v66, v76, v77
	v_cvt_pk_bf16_f32 v67, v70, v67
	global_store_dwordx4 v[68:69], v[64:67], off
	s_nop 1
	v_mul_f32_e32 v66, 0xbfb8aa3b, v60
	v_exp_f32_e32 v66, v66
	v_add_u32_e32 v64, 0x80, v144
	v_mad_i64_i32 v[64:65], s[14:15], v64, s5, v[138:139]
	v_add_f32_e32 v66, 1.0, v66
	v_rcp_f32_e32 v66, v66
	s_nop 0
	v_mul_f32_e32 v60, v60, v66
	v_mul_f32_e32 v56, v60, v56
	v_mul_f32_e32 v60, 0xbfb8aa3b, v61
	v_exp_f32_e32 v60, v60
	s_nop 0
	v_add_f32_e32 v60, 1.0, v60
	v_rcp_f32_e32 v60, v60
	s_nop 0
	v_mul_f32_e32 v60, v61, v60
	v_mul_f32_e32 v57, v60, v57
	v_mul_f32_e32 v60, 0xbfb8aa3b, v62
	v_exp_f32_e32 v60, v60
	s_nop 0
	v_add_f32_e32 v60, 1.0, v60
	v_rcp_f32_e32 v60, v60
	s_nop 0
	v_mul_f32_e32 v60, v62, v60
	v_mul_f32_e32 v58, v60, v58
	v_mul_f32_e32 v60, 0xbfb8aa3b, v63
	v_exp_f32_e32 v60, v60
	s_nop 0
	v_add_f32_e32 v60, 1.0, v60
	v_rcp_f32_e32 v60, v60
	s_nop 0
	v_mul_f32_e32 v60, v63, v60
	v_mul_f32_e32 v59, v60, v59
	v_mul_f32_e32 v60, 0xbfb8aa3b, v52
	v_exp_f32_e32 v60, v60
	s_nop 0
	v_add_f32_e32 v60, 1.0, v60
	v_rcp_f32_e32 v60, v60
	s_nop 0
	v_mul_f32_e32 v52, v52, v60
	v_mul_f32_e32 v60, v52, v48
	v_mul_f32_e32 v48, 0xbfb8aa3b, v53
	v_exp_f32_e32 v48, v48
	s_nop 0
	v_add_f32_e32 v48, 1.0, v48
	v_rcp_f32_e32 v48, v48
	s_nop 0
	v_mul_f32_e32 v48, v53, v48
	v_mul_f32_e32 v61, v48, v49
	v_mul_f32_e32 v48, 0xbfb8aa3b, v54
	v_exp_f32_e32 v48, v48
	v_lshl_add_u64 v[52:53], v[64:65], 0, v[112:113]
	v_add_f32_e32 v48, 1.0, v48
	v_rcp_f32_e32 v48, v48
	s_nop 0
	v_mul_f32_e32 v48, v54, v48
	v_mul_f32_e32 v54, v48, v50
	v_mul_f32_e32 v48, 0xbfb8aa3b, v55
	v_exp_f32_e32 v48, v48
	s_nop 0
	v_add_f32_e32 v48, 1.0, v48
	v_rcp_f32_e32 v48, v48
	s_nop 0
	v_mul_f32_e32 v48, v55, v48
	v_mul_f32_e32 v51, v48, v51
	v_cvt_pk_bf16_f32 v48, v56, v57
	v_cvt_pk_bf16_f32 v49, v58, v59
	v_cvt_pk_bf16_f32 v50, v60, v61
	v_cvt_pk_bf16_f32 v51, v54, v51
	global_store_dwordx4 v[52:53], v[48:51], off
	s_nop 1
	v_mul_f32_e32 v50, 0xbfb8aa3b, v44
	v_exp_f32_e32 v50, v50
	v_add_u32_e32 v48, 0x90, v144
	v_mad_i64_i32 v[48:49], s[14:15], v48, s5, v[138:139]
	v_add_f32_e32 v50, 1.0, v50
	v_rcp_f32_e32 v50, v50
	s_nop 0
	v_mul_f32_e32 v44, v44, v50
	v_mul_f32_e32 v40, v44, v40
	v_mul_f32_e32 v44, 0xbfb8aa3b, v45
	v_exp_f32_e32 v44, v44
	s_nop 0
	v_add_f32_e32 v44, 1.0, v44
	v_rcp_f32_e32 v44, v44
	s_nop 0
	v_mul_f32_e32 v44, v45, v44
	v_mul_f32_e32 v41, v44, v41
	v_mul_f32_e32 v44, 0xbfb8aa3b, v46
	v_exp_f32_e32 v44, v44
	s_nop 0
	v_add_f32_e32 v44, 1.0, v44
	v_rcp_f32_e32 v44, v44
	s_nop 0
	v_mul_f32_e32 v44, v46, v44
	v_mul_f32_e32 v42, v44, v42
	v_mul_f32_e32 v44, 0xbfb8aa3b, v47
	v_exp_f32_e32 v44, v44
	s_nop 0
	v_add_f32_e32 v44, 1.0, v44
	v_rcp_f32_e32 v44, v44
	s_nop 0
	v_mul_f32_e32 v44, v47, v44
	v_mul_f32_e32 v43, v44, v43
	v_mul_f32_e32 v44, 0xbfb8aa3b, v36
	v_exp_f32_e32 v44, v44
	s_nop 0
	v_add_f32_e32 v44, 1.0, v44
	v_rcp_f32_e32 v44, v44
	s_nop 0
	v_mul_f32_e32 v36, v36, v44
	v_mul_f32_e32 v44, v36, v32
	v_mul_f32_e32 v32, 0xbfb8aa3b, v37
	v_exp_f32_e32 v32, v32
	s_nop 0
	v_add_f32_e32 v32, 1.0, v32
	v_rcp_f32_e32 v32, v32
	s_nop 0
	v_mul_f32_e32 v32, v37, v32
	v_mul_f32_e32 v45, v32, v33
	v_mul_f32_e32 v32, 0xbfb8aa3b, v38
	v_exp_f32_e32 v32, v32
	v_lshl_add_u64 v[36:37], v[48:49], 0, v[112:113]
	v_add_f32_e32 v32, 1.0, v32
	v_rcp_f32_e32 v32, v32
	s_nop 0
	v_mul_f32_e32 v32, v38, v32
	v_mul_f32_e32 v38, v32, v34
	v_mul_f32_e32 v32, 0xbfb8aa3b, v39
	v_exp_f32_e32 v32, v32
	s_nop 0
	v_add_f32_e32 v32, 1.0, v32
	v_rcp_f32_e32 v32, v32
	s_nop 0
	v_mul_f32_e32 v32, v39, v32
	v_mul_f32_e32 v35, v32, v35
	v_cvt_pk_bf16_f32 v32, v40, v41
	v_cvt_pk_bf16_f32 v33, v42, v43
	v_cvt_pk_bf16_f32 v34, v44, v45
	v_cvt_pk_bf16_f32 v35, v38, v35
	global_store_dwordx4 v[36:37], v[32:35], off
	s_nop 1
	v_mul_f32_e32 v34, 0xbfb8aa3b, v28
	v_exp_f32_e32 v34, v34
	v_add_u32_e32 v32, 0xa0, v144
	v_mad_i64_i32 v[32:33], s[14:15], v32, s5, v[138:139]
	v_add_f32_e32 v34, 1.0, v34
	v_rcp_f32_e32 v34, v34
	s_nop 0
	v_mul_f32_e32 v28, v28, v34
	v_mul_f32_e32 v24, v28, v24
	v_mul_f32_e32 v28, 0xbfb8aa3b, v29
	v_exp_f32_e32 v28, v28
	s_nop 0
	v_add_f32_e32 v28, 1.0, v28
	v_rcp_f32_e32 v28, v28
	s_nop 0
	v_mul_f32_e32 v28, v29, v28
	v_mul_f32_e32 v25, v28, v25
	v_mul_f32_e32 v28, 0xbfb8aa3b, v30
	v_exp_f32_e32 v28, v28
	s_nop 0
	v_add_f32_e32 v28, 1.0, v28
	v_rcp_f32_e32 v28, v28
	s_nop 0
	v_mul_f32_e32 v28, v30, v28
	v_mul_f32_e32 v26, v28, v26
	v_mul_f32_e32 v28, 0xbfb8aa3b, v31
	v_exp_f32_e32 v28, v28
	s_nop 0
	v_add_f32_e32 v28, 1.0, v28
	v_rcp_f32_e32 v28, v28
	s_nop 0
	v_mul_f32_e32 v28, v31, v28
	v_mul_f32_e32 v27, v28, v27
	v_mul_f32_e32 v28, 0xbfb8aa3b, v20
	v_exp_f32_e32 v28, v28
	s_nop 0
	v_add_f32_e32 v28, 1.0, v28
	v_rcp_f32_e32 v28, v28
	s_nop 0
	v_mul_f32_e32 v20, v20, v28
	v_mul_f32_e32 v28, v20, v16
	v_mul_f32_e32 v16, 0xbfb8aa3b, v21
	v_exp_f32_e32 v16, v16
	s_nop 0
	v_add_f32_e32 v16, 1.0, v16
	v_rcp_f32_e32 v16, v16
	s_nop 0
	v_mul_f32_e32 v16, v21, v16
	v_mul_f32_e32 v29, v16, v17
	v_mul_f32_e32 v16, 0xbfb8aa3b, v22
	v_exp_f32_e32 v16, v16
	v_lshl_add_u64 v[20:21], v[32:33], 0, v[112:113]
	v_add_f32_e32 v16, 1.0, v16
	v_rcp_f32_e32 v16, v16
	s_nop 0
	v_mul_f32_e32 v16, v22, v16
	v_mul_f32_e32 v22, v16, v18
	v_mul_f32_e32 v16, 0xbfb8aa3b, v23
	v_exp_f32_e32 v16, v16
	s_nop 0
	v_add_f32_e32 v16, 1.0, v16
	v_rcp_f32_e32 v16, v16
	s_nop 0
	v_mul_f32_e32 v16, v23, v16
	v_mul_f32_e32 v19, v16, v19
	v_cvt_pk_bf16_f32 v16, v24, v25
	v_cvt_pk_bf16_f32 v17, v26, v27
	v_cvt_pk_bf16_f32 v18, v28, v29
	v_cvt_pk_bf16_f32 v19, v22, v19
	global_store_dwordx4 v[20:21], v[16:19], off
	s_nop 1
	v_mul_f32_e32 v18, 0xbfb8aa3b, v12
	v_exp_f32_e32 v18, v18
	v_add_u32_e32 v16, 0xb0, v144
	v_mad_i64_i32 v[16:17], s[14:15], v16, s5, v[138:139]
	v_add_f32_e32 v18, 1.0, v18
	v_rcp_f32_e32 v18, v18
	s_mov_b64 s[14:15], s[8:9]
	v_mul_f32_e32 v12, v12, v18
	v_mul_f32_e32 v8, v12, v8
	v_mul_f32_e32 v12, 0xbfb8aa3b, v13
	v_exp_f32_e32 v12, v12
	s_nop 0
	v_add_f32_e32 v12, 1.0, v12
	v_rcp_f32_e32 v12, v12
	s_nop 0
	v_mul_f32_e32 v12, v13, v12
	v_mul_f32_e32 v9, v12, v9
	v_mul_f32_e32 v12, 0xbfb8aa3b, v14
	v_exp_f32_e32 v12, v12
	s_nop 0
	v_add_f32_e32 v12, 1.0, v12
	v_rcp_f32_e32 v12, v12
	s_nop 0
	v_mul_f32_e32 v12, v14, v12
	v_mul_f32_e32 v10, v12, v10
	v_mul_f32_e32 v12, 0xbfb8aa3b, v15
	v_exp_f32_e32 v12, v12
	s_nop 0
	v_add_f32_e32 v12, 1.0, v12
	v_rcp_f32_e32 v12, v12
	s_nop 0
	v_mul_f32_e32 v12, v15, v12
	v_mul_f32_e32 v11, v12, v11
	v_mul_f32_e32 v12, 0xbfb8aa3b, v4
	v_exp_f32_e32 v12, v12
	s_nop 0
	v_add_f32_e32 v12, 1.0, v12
	v_rcp_f32_e32 v12, v12
	s_nop 0
	v_mul_f32_e32 v4, v4, v12
	v_mul_f32_e32 v12, v4, v0
	v_mul_f32_e32 v0, 0xbfb8aa3b, v5
	v_exp_f32_e32 v0, v0
	s_nop 0
	v_add_f32_e32 v0, 1.0, v0
	v_rcp_f32_e32 v0, v0
	s_nop 0
	v_mul_f32_e32 v0, v5, v0
	v_mul_f32_e32 v13, v0, v1
	v_mul_f32_e32 v0, 0xbfb8aa3b, v6
	v_exp_f32_e32 v0, v0
	v_lshl_add_u64 v[4:5], v[16:17], 0, v[112:113]
	v_add_f32_e32 v0, 1.0, v0
	v_rcp_f32_e32 v0, v0
	s_nop 0
	v_mul_f32_e32 v0, v6, v0
	v_mul_f32_e32 v6, v0, v2
	v_mul_f32_e32 v0, 0xbfb8aa3b, v7
	v_exp_f32_e32 v0, v0
	s_nop 0
	v_add_f32_e32 v0, 1.0, v0
	v_rcp_f32_e32 v0, v0
	s_nop 0
	v_mul_f32_e32 v0, v7, v0
	v_mul_f32_e32 v3, v0, v3
	v_cvt_pk_bf16_f32 v0, v8, v9
	v_cvt_pk_bf16_f32 v1, v10, v11
	v_cvt_pk_bf16_f32 v2, v12, v13
	v_cvt_pk_bf16_f32 v3, v6, v3
	global_store_dwordx4 v[4:5], v[0:3], off
	s_cbranch_vccz .LBB0_214
	s_waitcnt vmcnt(0)
	v_readlane_b32 s34, v254, 18
	s_cmpk_gt_u32 s21, 0xff
	v_readlane_b32 s35, v254, 19
	v_readlane_b32 s31, v254, 20
	s_cbranch_scc1 .LBB0_221
	s_barrier

.LBB0_245:
	s_add_u32 s10, s10, 0x80
	s_addc_u32 s11, s11, 0
	s_add_u32 s42, s12, 0x100
	s_addc_u32 s43, s13, 0
	s_mov_b32 s12, 0
	s_mov_b64 s[48:49], 0x80
	v_readlane_b32 s52, v254, 14
	v_readlane_b32 s53, v254, 15
	v_readlane_b32 s54, v254, 16
	v_readlane_b32 s55, v254, 17
	v_add_u32_e32 v218, 0x10000, v191
	s_add_i32 s44, s12, 2
	s_add_u32 s14, s10, 0x80
	s_addc_u32 s13, s11, 0
	s_add_i32 s45, 0, 0x10000
	ds_read_b128 v[120:123], v218 offset:0
	ds_read_b128 v[124:127], v218 offset:1024
	ds_read_b128 v[128:131], v218 offset:2048
	ds_read_b128 v[132:135], v218 offset:3072
	s_cmp_eq_u32 s36, s12
	s_cselect_b32 s12, s4, s14
	s_cselect_b32 s13, s5, s13
	s_cselect_b32 s15, s7, s43
	s_cselect_b32 s14, s6, s42
	s_add_i32 m0, s26, 0xc000
	ds_read_b128 v[144:147], v205
	ds_read_b128 v[148:151], v205 offset:1024
	ds_read_b128 v[152:155], v205 offset:2048
	ds_read_b128 v[156:159], v205 offset:3072
	ds_read_b128 v[160:163], v205 offset:4096
	ds_read_b128 v[164:167], v205 offset:5120
	ds_read_b128 v[178:181], v205 offset:6144
	ds_read_b128 v[182:185], v205 offset:7168
	global_load_lds_dwordx4 v174, s[10:11]
	s_add_i32 m0, s26, 0xe000
	s_nop 0
	global_load_lds_dwordx4 v176, s[10:11]
	s_waitcnt lgkmcnt(8)
	s_barrier
	s_waitcnt lgkmcnt(0)
	v_mfma_f32_16x16x32_bf16 v[140:143], v[120:123], v[144:147], 0
	v_mfma_f32_16x16x32_bf16 v[136:139], v[128:131], v[144:147], 0
	s_add_i32 s46, 0, 0x14000
	v_mfma_f32_16x16x32_bf16 v[108:111], v[120:123], v[152:155], 0
	s_add_i32 s45, s45, s25
	v_mfma_f32_16x16x32_bf16 v[104:107], v[128:131], v[152:155], 0
	s_add_u32 s68, s14, 0x80
	v_mfma_f32_16x16x32_bf16 v[92:95], v[120:123], v[160:163], 0
	s_addc_u32 s69, s15, 0
	v_mfma_f32_16x16x32_bf16 v[88:91], v[128:131], v[160:163], 0
	s_mov_b32 m0, s45
	v_mfma_f32_16x16x32_bf16 v[76:79], v[120:123], v[178:181], 0
	v_mfma_f32_16x16x32_bf16 v[72:75], v[128:131], v[178:181], 0
	v_mfma_f32_16x16x32_bf16 v[140:143], v[124:127], v[148:151], v[140:143]
	v_mfma_f32_16x16x32_bf16 v[136:139], v[132:135], v[148:151], v[136:139]
	v_mfma_f32_16x16x32_bf16 v[108:111], v[124:127], v[156:159], v[108:111]
	v_mfma_f32_16x16x32_bf16 v[104:107], v[132:135], v[156:159], v[104:107]
	v_mfma_f32_16x16x32_bf16 v[92:95], v[124:127], v[164:167], v[92:95]
	v_mfma_f32_16x16x32_bf16 v[88:91], v[132:135], v[164:167], v[88:91]
	v_mfma_f32_16x16x32_bf16 v[76:79], v[124:127], v[182:185], v[76:79]
	v_mfma_f32_16x16x32_bf16 v[72:75], v[132:135], v[182:185], v[72:75]
	s_barrier
	ds_read_b128 v[186:189], v218 offset:16384
	ds_read_b128 v[196:199], v218 offset:17408
	ds_read_b128 v[206:209], v218 offset:18432
	ds_read_b128 v[214:217], v218 offset:19456
	global_load_lds_dwordx4 v192, s[14:15]
	s_add_i32 m0, s45, 0x2000
	s_nop 0
	global_load_lds_dwordx4 v172, s[14:15]
	s_barrier
	s_waitcnt lgkmcnt(0)
	v_mfma_f32_16x16x32_bf16 v[116:119], v[186:189], v[144:147], 0
	v_mfma_f32_16x16x32_bf16 v[112:115], v[206:209], v[144:147], 0
	s_mov_b32 m0, s26
	v_mfma_f32_16x16x32_bf16 v[100:103], v[186:189], v[152:155], 0
	s_add_u32 s70, s12, 0x80
	v_mfma_f32_16x16x32_bf16 v[96:99], v[206:209], v[152:155], 0
	s_addc_u32 s71, s13, 0
	v_mfma_f32_16x16x32_bf16 v[84:87], v[186:189], v[160:163], 0
	v_mfma_f32_16x16x32_bf16 v[80:83], v[206:209], v[160:163], 0
	v_mfma_f32_16x16x32_bf16 v[68:71], v[186:189], v[178:181], 0
	v_mfma_f32_16x16x32_bf16 v[64:67], v[206:209], v[178:181], 0
	v_mfma_f32_16x16x32_bf16 v[116:119], v[196:199], v[148:151], v[116:119]
	v_mfma_f32_16x16x32_bf16 v[112:115], v[214:217], v[148:151], v[112:115]
	v_mfma_f32_16x16x32_bf16 v[100:103], v[196:199], v[156:159], v[100:103]
	v_mfma_f32_16x16x32_bf16 v[96:99], v[214:217], v[156:159], v[96:99]
	v_mfma_f32_16x16x32_bf16 v[84:87], v[196:199], v[164:167], v[84:87]
	v_mfma_f32_16x16x32_bf16 v[80:83], v[214:217], v[164:167], v[80:83]
	v_mfma_f32_16x16x32_bf16 v[68:71], v[196:199], v[182:185], v[68:71]
	v_mfma_f32_16x16x32_bf16 v[64:67], v[214:217], v[182:185], v[64:67]
	s_barrier
	ds_read_b128 v[144:147], v205 offset:16384
	ds_read_b128 v[148:151], v205 offset:17408
	ds_read_b128 v[152:155], v205 offset:18432
	ds_read_b128 v[156:159], v205 offset:19456
	ds_read_b128 v[160:163], v205 offset:20480
	ds_read_b128 v[164:167], v205 offset:21504
	ds_read_b128 v[178:181], v205 offset:22528
	ds_read_b128 v[182:185], v205 offset:23552
	global_load_lds_dwordx4 v168, s[12:13]
	s_mov_b32 m0, s27
	s_nop 0
	global_load_lds_dwordx4 v170, s[12:13]
	s_barrier
	s_waitcnt lgkmcnt(0)
	v_mfma_f32_16x16x32_bf16 v[60:63], v[120:123], v[144:147], 0
	v_mfma_f32_16x16x32_bf16 v[56:59], v[128:131], v[144:147], 0
	s_add_u32 s14, s14, s52
	v_mfma_f32_16x16x32_bf16 v[44:47], v[120:123], v[152:155], 0
	s_addc_u32 s15, s15, 0
	v_mfma_f32_16x16x32_bf16 v[40:43], v[128:131], v[152:155], 0
	s_add_i32 s45, s46, s25
	v_mfma_f32_16x16x32_bf16 v[28:31], v[120:123], v[160:163], 0
	s_mov_b32 m0, s45
	v_mfma_f32_16x16x32_bf16 v[24:27], v[128:131], v[160:163], 0
	v_mfma_f32_16x16x32_bf16 v[12:15], v[120:123], v[178:181], 0
	v_mfma_f32_16x16x32_bf16 v[8:11], v[128:131], v[178:181], 0
	v_mfma_f32_16x16x32_bf16 v[60:63], v[124:127], v[148:151], v[60:63]
	v_mfma_f32_16x16x32_bf16 v[56:59], v[132:135], v[148:151], v[56:59]
	v_mfma_f32_16x16x32_bf16 v[44:47], v[124:127], v[156:159], v[44:47]
	v_mfma_f32_16x16x32_bf16 v[40:43], v[132:135], v[156:159], v[40:43]
	v_mfma_f32_16x16x32_bf16 v[28:31], v[124:127], v[164:167], v[28:31]
	v_mfma_f32_16x16x32_bf16 v[24:27], v[132:135], v[164:167], v[24:27]
	v_mfma_f32_16x16x32_bf16 v[12:15], v[124:127], v[182:185], v[12:15]
	v_mfma_f32_16x16x32_bf16 v[8:11], v[132:135], v[182:185], v[8:11]
	s_barrier
	global_load_lds_dwordx4 v192, s[14:15]
	s_add_i32 m0, s45, 0x2000
	s_nop 0
	global_load_lds_dwordx4 v172, s[14:15]
	s_waitcnt vmcnt(6)
	s_barrier
	v_mfma_f32_16x16x32_bf16 v[52:55], v[186:189], v[144:147], 0
	v_mfma_f32_16x16x32_bf16 v[48:51], v[206:209], v[144:147], 0
	s_add_i32 s14, 0, 0x18000
	v_mfma_f32_16x16x32_bf16 v[36:39], v[186:189], v[152:155], 0
	s_add_u32 s12, s12, s52
	v_mfma_f32_16x16x32_bf16 v[32:35], v[206:209], v[152:155], 0
	s_addc_u32 s13, s13, 0
	v_mfma_f32_16x16x32_bf16 v[20:23], v[186:189], v[160:163], 0
	s_mov_b32 m0, s28
	v_mfma_f32_16x16x32_bf16 v[16:19], v[206:209], v[160:163], 0
	v_mfma_f32_16x16x32_bf16 v[4:7], v[186:189], v[178:181], 0
	v_mfma_f32_16x16x32_bf16 v[0:3], v[206:209], v[178:181], 0
	v_mfma_f32_16x16x32_bf16 v[52:55], v[196:199], v[148:151], v[52:55]
	v_mfma_f32_16x16x32_bf16 v[48:51], v[214:217], v[148:151], v[48:51]
	v_mfma_f32_16x16x32_bf16 v[36:39], v[196:199], v[156:159], v[36:39]
	v_mfma_f32_16x16x32_bf16 v[32:35], v[214:217], v[156:159], v[32:35]
	v_mfma_f32_16x16x32_bf16 v[20:23], v[196:199], v[164:167], v[20:23]
	v_mfma_f32_16x16x32_bf16 v[16:19], v[214:217], v[164:167], v[16:19]
	v_mfma_f32_16x16x32_bf16 v[4:7], v[196:199], v[182:185], v[4:7]
	v_mfma_f32_16x16x32_bf16 v[0:3], v[214:217], v[182:185], v[0:3]
	s_barrier
	ds_read_b128 v[120:123], v218 offset:32768
	ds_read_b128 v[124:127], v218 offset:33792
	ds_read_b128 v[128:131], v218 offset:34816
	ds_read_b128 v[132:135], v218 offset:35840
	ds_read_b128 v[144:147], v205 offset:32768
	ds_read_b128 v[148:151], v205 offset:33792
	ds_read_b128 v[152:155], v205 offset:34816
	ds_read_b128 v[156:159], v205 offset:35840
	ds_read_b128 v[160:163], v205 offset:36864
	ds_read_b128 v[164:167], v205 offset:37888
	ds_read_b128 v[178:181], v205 offset:38912
	ds_read_b128 v[182:185], v205 offset:39936
	global_load_lds_dwordx4 v168, s[12:13]
	s_mov_b32 m0, s29
	s_nop 0
	global_load_lds_dwordx4 v170, s[12:13]
	s_waitcnt lgkmcnt(8)
	s_barrier
	s_waitcnt lgkmcnt(0)
	v_mfma_f32_16x16x32_bf16 v[140:143], v[120:123], v[144:147], v[140:143]
	v_mfma_f32_16x16x32_bf16 v[136:139], v[128:131], v[144:147], v[136:139]
	s_add_i32 s12, 0, 0x1c000
	v_mfma_f32_16x16x32_bf16 v[108:111], v[120:123], v[152:155], v[108:111]
	s_add_i32 s13, s14, s25
	v_mfma_f32_16x16x32_bf16 v[104:107], v[128:131], v[152:155], v[104:107]
	s_mov_b32 m0, s13
	v_mfma_f32_16x16x32_bf16 v[92:95], v[120:123], v[160:163], v[92:95]
	v_mfma_f32_16x16x32_bf16 v[88:91], v[128:131], v[160:163], v[88:91]
	v_mfma_f32_16x16x32_bf16 v[76:79], v[120:123], v[178:181], v[76:79]
	v_mfma_f32_16x16x32_bf16 v[72:75], v[128:131], v[178:181], v[72:75]
	v_mfma_f32_16x16x32_bf16 v[140:143], v[124:127], v[148:151], v[140:143]
	v_mfma_f32_16x16x32_bf16 v[136:139], v[132:135], v[148:151], v[136:139]
	v_mfma_f32_16x16x32_bf16 v[108:111], v[124:127], v[156:159], v[108:111]
	v_mfma_f32_16x16x32_bf16 v[104:107], v[132:135], v[156:159], v[104:107]
	v_mfma_f32_16x16x32_bf16 v[92:95], v[124:127], v[164:167], v[92:95]
	v_mfma_f32_16x16x32_bf16 v[88:91], v[132:135], v[164:167], v[88:91]
	v_mfma_f32_16x16x32_bf16 v[76:79], v[124:127], v[182:185], v[76:79]
	v_mfma_f32_16x16x32_bf16 v[72:75], v[132:135], v[182:185], v[72:75]
	s_barrier
	ds_read_b128 v[186:189], v218 offset:49152
	ds_read_b128 v[196:199], v218 offset:50176
	ds_read_b128 v[206:209], v218 offset:51200
	ds_read_b128 v[214:217], v218 offset:52224
	global_load_lds_dwordx4 v192, s[68:69]
	s_add_i32 m0, s13, 0x2000
	s_nop 0
	global_load_lds_dwordx4 v172, s[68:69]
	s_barrier
	s_waitcnt lgkmcnt(0)
	v_mfma_f32_16x16x32_bf16 v[116:119], v[186:189], v[144:147], v[116:119]
	v_mfma_f32_16x16x32_bf16 v[112:115], v[206:209], v[144:147], v[112:115]
	s_mov_b32 m0, s34
	v_mfma_f32_16x16x32_bf16 v[100:103], v[186:189], v[152:155], v[100:103]
	v_mfma_f32_16x16x32_bf16 v[96:99], v[206:209], v[152:155], v[96:99]
	v_mfma_f32_16x16x32_bf16 v[84:87], v[186:189], v[160:163], v[84:87]
	v_mfma_f32_16x16x32_bf16 v[80:83], v[206:209], v[160:163], v[80:83]
	v_mfma_f32_16x16x32_bf16 v[68:71], v[186:189], v[178:181], v[68:71]
	v_mfma_f32_16x16x32_bf16 v[64:67], v[206:209], v[178:181], v[64:67]
	v_mfma_f32_16x16x32_bf16 v[116:119], v[196:199], v[148:151], v[116:119]
	v_mfma_f32_16x16x32_bf16 v[112:115], v[214:217], v[148:151], v[112:115]
	v_mfma_f32_16x16x32_bf16 v[100:103], v[196:199], v[156:159], v[100:103]
	v_mfma_f32_16x16x32_bf16 v[96:99], v[214:217], v[156:159], v[96:99]
	v_mfma_f32_16x16x32_bf16 v[84:87], v[196:199], v[164:167], v[84:87]
	v_mfma_f32_16x16x32_bf16 v[80:83], v[214:217], v[164:167], v[80:83]
	v_mfma_f32_16x16x32_bf16 v[68:71], v[196:199], v[182:185], v[68:71]
	v_mfma_f32_16x16x32_bf16 v[64:67], v[214:217], v[182:185], v[64:67]
	s_barrier
	ds_read_b128 v[144:147], v205 offset:49152
	ds_read_b128 v[148:151], v205 offset:50176
	ds_read_b128 v[152:155], v205 offset:51200
	ds_read_b128 v[156:159], v205 offset:52224
	ds_read_b128 v[160:163], v205 offset:53248
	ds_read_b128 v[164:167], v205 offset:54272
	ds_read_b128 v[178:181], v205 offset:55296
	ds_read_b128 v[182:185], v205 offset:56320
	global_load_lds_dwordx4 v168, s[70:71]
	s_mov_b32 m0, s35
	s_nop 0
	global_load_lds_dwordx4 v170, s[70:71]
	s_barrier
	s_waitcnt lgkmcnt(0)
	v_mfma_f32_16x16x32_bf16 v[60:63], v[120:123], v[144:147], v[60:63]
	v_mfma_f32_16x16x32_bf16 v[56:59], v[128:131], v[144:147], v[56:59]
	s_add_i32 s12, s12, s25
	v_mfma_f32_16x16x32_bf16 v[44:47], v[120:123], v[152:155], v[44:47]
	s_add_u32 s68, s68, s52
	v_mfma_f32_16x16x32_bf16 v[40:43], v[128:131], v[152:155], v[40:43]
	s_addc_u32 s69, s69, 0
	v_mfma_f32_16x16x32_bf16 v[28:31], v[120:123], v[160:163], v[28:31]
	s_mov_b32 m0, s12
	v_mfma_f32_16x16x32_bf16 v[24:27], v[128:131], v[160:163], v[24:27]
	v_mfma_f32_16x16x32_bf16 v[12:15], v[120:123], v[178:181], v[12:15]
	v_mfma_f32_16x16x32_bf16 v[8:11], v[128:131], v[178:181], v[8:11]
	v_mfma_f32_16x16x32_bf16 v[60:63], v[124:127], v[148:151], v[60:63]
	v_mfma_f32_16x16x32_bf16 v[56:59], v[132:135], v[148:151], v[56:59]
	v_mfma_f32_16x16x32_bf16 v[44:47], v[124:127], v[156:159], v[44:47]
	v_mfma_f32_16x16x32_bf16 v[40:43], v[132:135], v[156:159], v[40:43]
	v_mfma_f32_16x16x32_bf16 v[28:31], v[124:127], v[164:167], v[28:31]
	v_mfma_f32_16x16x32_bf16 v[24:27], v[132:135], v[164:167], v[24:27]
	v_mfma_f32_16x16x32_bf16 v[12:15], v[124:127], v[182:185], v[12:15]
	v_mfma_f32_16x16x32_bf16 v[8:11], v[132:135], v[182:185], v[8:11]
	s_barrier
	global_load_lds_dwordx4 v192, s[68:69]
	s_add_i32 m0, s12, 0x2000
	s_nop 0
	global_load_lds_dwordx4 v172, s[68:69]
	s_waitcnt vmcnt(6)
	s_barrier
	v_mfma_f32_16x16x32_bf16 v[52:55], v[186:189], v[144:147], v[52:55]
	v_mfma_f32_16x16x32_bf16 v[48:51], v[206:209], v[144:147], v[48:51]
	s_add_u32 s10, s10, 0x100
	v_mfma_f32_16x16x32_bf16 v[36:39], v[186:189], v[152:155], v[36:39]
	s_addc_u32 s11, s11, 0
	v_mfma_f32_16x16x32_bf16 v[32:35], v[206:209], v[152:155], v[32:35]
	s_add_u32 s42, s42, 0x100
	v_mfma_f32_16x16x32_bf16 v[20:23], v[186:189], v[160:163], v[20:23]
	s_addc_u32 s43, s43, 0
	v_mfma_f32_16x16x32_bf16 v[16:19], v[206:209], v[160:163], v[16:19]
	s_mov_b32 s12, s44
	v_mfma_f32_16x16x32_bf16 v[4:7], v[186:189], v[178:181], v[4:7]
	v_mfma_f32_16x16x32_bf16 v[0:3], v[206:209], v[178:181], v[0:3]
	v_mfma_f32_16x16x32_bf16 v[52:55], v[196:199], v[148:151], v[52:55]
	v_mfma_f32_16x16x32_bf16 v[48:51], v[214:217], v[148:151], v[48:51]
	v_mfma_f32_16x16x32_bf16 v[36:39], v[196:199], v[156:159], v[36:39]
	v_mfma_f32_16x16x32_bf16 v[32:35], v[214:217], v[156:159], v[32:35]
	v_mfma_f32_16x16x32_bf16 v[20:23], v[196:199], v[164:167], v[20:23]
	v_mfma_f32_16x16x32_bf16 v[16:19], v[214:217], v[164:167], v[16:19]
	v_mfma_f32_16x16x32_bf16 v[4:7], v[196:199], v[182:185], v[4:7]
	v_mfma_f32_16x16x32_bf16 v[0:3], v[214:217], v[182:185], v[0:3]
	s_cmp_ge_u32 s44, s33
	s_barrier
.LBB0_246:
	s_add_i32 s44, s12, 2
	s_add_u32 s14, s10, 0x80
	s_addc_u32 s13, s11, 0
	s_add_i32 s45, 0, 0x10000
	ds_read_b128 v[120:123], v218 offset:0
	ds_read_b128 v[124:127], v218 offset:1024
	ds_read_b128 v[128:131], v218 offset:2048
	ds_read_b128 v[132:135], v218 offset:3072
	s_cmp_eq_u32 s36, s12
	s_cselect_b32 s12, s4, s14
	s_cselect_b32 s13, s5, s13
	s_cselect_b32 s15, s7, s43
	s_cselect_b32 s14, s6, s42
	s_add_i32 m0, s26, 0xc000
	ds_read_b128 v[144:147], v205
	ds_read_b128 v[148:151], v205 offset:1024
	ds_read_b128 v[152:155], v205 offset:2048
	ds_read_b128 v[156:159], v205 offset:3072
	ds_read_b128 v[160:163], v205 offset:4096
	ds_read_b128 v[164:167], v205 offset:5120
	ds_read_b128 v[178:181], v205 offset:6144
	ds_read_b128 v[182:185], v205 offset:7168
	global_load_lds_dwordx4 v174, s[10:11]
	s_add_i32 m0, s26, 0xe000
	s_nop 0
	global_load_lds_dwordx4 v176, s[10:11]
	s_waitcnt lgkmcnt(8)
	s_barrier
	s_waitcnt lgkmcnt(0)
	v_mfma_f32_16x16x32_bf16 v[140:143], v[120:123], v[144:147], v[140:143]
	v_mfma_f32_16x16x32_bf16 v[136:139], v[128:131], v[144:147], v[136:139]
	s_add_i32 s46, 0, 0x14000
	v_mfma_f32_16x16x32_bf16 v[108:111], v[120:123], v[152:155], v[108:111]
	s_add_i32 s45, s45, s25
	v_mfma_f32_16x16x32_bf16 v[104:107], v[128:131], v[152:155], v[104:107]
	s_add_u32 s68, s14, 0x80
	v_mfma_f32_16x16x32_bf16 v[92:95], v[120:123], v[160:163], v[92:95]
	s_addc_u32 s69, s15, 0
	v_mfma_f32_16x16x32_bf16 v[88:91], v[128:131], v[160:163], v[88:91]
	s_mov_b32 m0, s45
	v_mfma_f32_16x16x32_bf16 v[76:79], v[120:123], v[178:181], v[76:79]
	v_mfma_f32_16x16x32_bf16 v[72:75], v[128:131], v[178:181], v[72:75]
	v_mfma_f32_16x16x32_bf16 v[140:143], v[124:127], v[148:151], v[140:143]
	v_mfma_f32_16x16x32_bf16 v[136:139], v[132:135], v[148:151], v[136:139]
	v_mfma_f32_16x16x32_bf16 v[108:111], v[124:127], v[156:159], v[108:111]
	v_mfma_f32_16x16x32_bf16 v[104:107], v[132:135], v[156:159], v[104:107]
	v_mfma_f32_16x16x32_bf16 v[92:95], v[124:127], v[164:167], v[92:95]
	v_mfma_f32_16x16x32_bf16 v[88:91], v[132:135], v[164:167], v[88:91]
	v_mfma_f32_16x16x32_bf16 v[76:79], v[124:127], v[182:185], v[76:79]
	v_mfma_f32_16x16x32_bf16 v[72:75], v[132:135], v[182:185], v[72:75]
	s_barrier
	ds_read_b128 v[186:189], v218 offset:16384
	ds_read_b128 v[196:199], v218 offset:17408
	ds_read_b128 v[206:209], v218 offset:18432
	ds_read_b128 v[214:217], v218 offset:19456
	global_load_lds_dwordx4 v192, s[14:15]
	s_add_i32 m0, s45, 0x2000
	s_nop 0
	global_load_lds_dwordx4 v172, s[14:15]
	s_barrier
	s_waitcnt lgkmcnt(0)
	v_mfma_f32_16x16x32_bf16 v[116:119], v[186:189], v[144:147], v[116:119]
	v_mfma_f32_16x16x32_bf16 v[112:115], v[206:209], v[144:147], v[112:115]
	s_mov_b32 m0, s26
	v_mfma_f32_16x16x32_bf16 v[100:103], v[186:189], v[152:155], v[100:103]
	s_add_u32 s70, s12, 0x80
	v_mfma_f32_16x16x32_bf16 v[96:99], v[206:209], v[152:155], v[96:99]
	s_addc_u32 s71, s13, 0
	v_mfma_f32_16x16x32_bf16 v[84:87], v[186:189], v[160:163], v[84:87]
	v_mfma_f32_16x16x32_bf16 v[80:83], v[206:209], v[160:163], v[80:83]
	v_mfma_f32_16x16x32_bf16 v[68:71], v[186:189], v[178:181], v[68:71]
	v_mfma_f32_16x16x32_bf16 v[64:67], v[206:209], v[178:181], v[64:67]
	v_mfma_f32_16x16x32_bf16 v[116:119], v[196:199], v[148:151], v[116:119]
	v_mfma_f32_16x16x32_bf16 v[112:115], v[214:217], v[148:151], v[112:115]
	v_mfma_f32_16x16x32_bf16 v[100:103], v[196:199], v[156:159], v[100:103]
	v_mfma_f32_16x16x32_bf16 v[96:99], v[214:217], v[156:159], v[96:99]
	v_mfma_f32_16x16x32_bf16 v[84:87], v[196:199], v[164:167], v[84:87]
	v_mfma_f32_16x16x32_bf16 v[80:83], v[214:217], v[164:167], v[80:83]
	v_mfma_f32_16x16x32_bf16 v[68:71], v[196:199], v[182:185], v[68:71]
	v_mfma_f32_16x16x32_bf16 v[64:67], v[214:217], v[182:185], v[64:67]
	s_barrier
	ds_read_b128 v[144:147], v205 offset:16384
	ds_read_b128 v[148:151], v205 offset:17408
	ds_read_b128 v[152:155], v205 offset:18432
	ds_read_b128 v[156:159], v205 offset:19456
	ds_read_b128 v[160:163], v205 offset:20480
	ds_read_b128 v[164:167], v205 offset:21504
	ds_read_b128 v[178:181], v205 offset:22528
	ds_read_b128 v[182:185], v205 offset:23552
	global_load_lds_dwordx4 v168, s[12:13]
	s_mov_b32 m0, s27
	s_nop 0
	global_load_lds_dwordx4 v170, s[12:13]
	s_barrier
	s_waitcnt lgkmcnt(0)
	v_mfma_f32_16x16x32_bf16 v[60:63], v[120:123], v[144:147], v[60:63]
	v_mfma_f32_16x16x32_bf16 v[56:59], v[128:131], v[144:147], v[56:59]
	s_add_u32 s14, s14, s52
	v_mfma_f32_16x16x32_bf16 v[44:47], v[120:123], v[152:155], v[44:47]
	s_addc_u32 s15, s15, 0
	v_mfma_f32_16x16x32_bf16 v[40:43], v[128:131], v[152:155], v[40:43]
	s_add_i32 s45, s46, s25
	v_mfma_f32_16x16x32_bf16 v[28:31], v[120:123], v[160:163], v[28:31]
	s_mov_b32 m0, s45
	v_mfma_f32_16x16x32_bf16 v[24:27], v[128:131], v[160:163], v[24:27]
	v_mfma_f32_16x16x32_bf16 v[12:15], v[120:123], v[178:181], v[12:15]
	v_mfma_f32_16x16x32_bf16 v[8:11], v[128:131], v[178:181], v[8:11]
	v_mfma_f32_16x16x32_bf16 v[60:63], v[124:127], v[148:151], v[60:63]
	v_mfma_f32_16x16x32_bf16 v[56:59], v[132:135], v[148:151], v[56:59]
	v_mfma_f32_16x16x32_bf16 v[44:47], v[124:127], v[156:159], v[44:47]
	v_mfma_f32_16x16x32_bf16 v[40:43], v[132:135], v[156:159], v[40:43]
	v_mfma_f32_16x16x32_bf16 v[28:31], v[124:127], v[164:167], v[28:31]
	v_mfma_f32_16x16x32_bf16 v[24:27], v[132:135], v[164:167], v[24:27]
	v_mfma_f32_16x16x32_bf16 v[12:15], v[124:127], v[182:185], v[12:15]
	v_mfma_f32_16x16x32_bf16 v[8:11], v[132:135], v[182:185], v[8:11]
	s_barrier
	global_load_lds_dwordx4 v192, s[14:15]
	s_add_i32 m0, s45, 0x2000
	s_nop 0
	global_load_lds_dwordx4 v172, s[14:15]
	s_waitcnt vmcnt(6)
	s_barrier
	v_mfma_f32_16x16x32_bf16 v[52:55], v[186:189], v[144:147], v[52:55]
	v_mfma_f32_16x16x32_bf16 v[48:51], v[206:209], v[144:147], v[48:51]
	s_add_i32 s14, 0, 0x18000
	v_mfma_f32_16x16x32_bf16 v[36:39], v[186:189], v[152:155], v[36:39]
	s_add_u32 s12, s12, s52
	v_mfma_f32_16x16x32_bf16 v[32:35], v[206:209], v[152:155], v[32:35]
	s_addc_u32 s13, s13, 0
	v_mfma_f32_16x16x32_bf16 v[20:23], v[186:189], v[160:163], v[20:23]
	s_mov_b32 m0, s28
	v_mfma_f32_16x16x32_bf16 v[16:19], v[206:209], v[160:163], v[16:19]
	v_mfma_f32_16x16x32_bf16 v[4:7], v[186:189], v[178:181], v[4:7]
	v_mfma_f32_16x16x32_bf16 v[0:3], v[206:209], v[178:181], v[0:3]
	v_mfma_f32_16x16x32_bf16 v[52:55], v[196:199], v[148:151], v[52:55]
	v_mfma_f32_16x16x32_bf16 v[48:51], v[214:217], v[148:151], v[48:51]
	v_mfma_f32_16x16x32_bf16 v[36:39], v[196:199], v[156:159], v[36:39]
	v_mfma_f32_16x16x32_bf16 v[32:35], v[214:217], v[156:159], v[32:35]
	v_mfma_f32_16x16x32_bf16 v[20:23], v[196:199], v[164:167], v[20:23]
	v_mfma_f32_16x16x32_bf16 v[16:19], v[214:217], v[164:167], v[16:19]
	v_mfma_f32_16x16x32_bf16 v[4:7], v[196:199], v[182:185], v[4:7]
	v_mfma_f32_16x16x32_bf16 v[0:3], v[214:217], v[182:185], v[0:3]
	s_barrier
	ds_read_b128 v[120:123], v218 offset:32768
	ds_read_b128 v[124:127], v218 offset:33792
	ds_read_b128 v[128:131], v218 offset:34816
	ds_read_b128 v[132:135], v218 offset:35840
	ds_read_b128 v[144:147], v205 offset:32768
	ds_read_b128 v[148:151], v205 offset:33792
	ds_read_b128 v[152:155], v205 offset:34816
	ds_read_b128 v[156:159], v205 offset:35840
	ds_read_b128 v[160:163], v205 offset:36864
	ds_read_b128 v[164:167], v205 offset:37888
	ds_read_b128 v[178:181], v205 offset:38912
	ds_read_b128 v[182:185], v205 offset:39936
	global_load_lds_dwordx4 v168, s[12:13]
	s_mov_b32 m0, s29
	s_nop 0
	global_load_lds_dwordx4 v170, s[12:13]
	s_waitcnt lgkmcnt(8)
	s_barrier
	s_waitcnt lgkmcnt(0)
	v_mfma_f32_16x16x32_bf16 v[140:143], v[120:123], v[144:147], v[140:143]
	v_mfma_f32_16x16x32_bf16 v[136:139], v[128:131], v[144:147], v[136:139]
	s_add_i32 s12, 0, 0x1c000
	v_mfma_f32_16x16x32_bf16 v[108:111], v[120:123], v[152:155], v[108:111]
	s_add_i32 s13, s14, s25
	v_mfma_f32_16x16x32_bf16 v[104:107], v[128:131], v[152:155], v[104:107]
	s_mov_b32 m0, s13
	v_mfma_f32_16x16x32_bf16 v[92:95], v[120:123], v[160:163], v[92:95]
	v_mfma_f32_16x16x32_bf16 v[88:91], v[128:131], v[160:163], v[88:91]
	v_mfma_f32_16x16x32_bf16 v[76:79], v[120:123], v[178:181], v[76:79]
	v_mfma_f32_16x16x32_bf16 v[72:75], v[128:131], v[178:181], v[72:75]
	v_mfma_f32_16x16x32_bf16 v[140:143], v[124:127], v[148:151], v[140:143]
	v_mfma_f32_16x16x32_bf16 v[136:139], v[132:135], v[148:151], v[136:139]
	v_mfma_f32_16x16x32_bf16 v[108:111], v[124:127], v[156:159], v[108:111]
	v_mfma_f32_16x16x32_bf16 v[104:107], v[132:135], v[156:159], v[104:107]
	v_mfma_f32_16x16x32_bf16 v[92:95], v[124:127], v[164:167], v[92:95]
	v_mfma_f32_16x16x32_bf16 v[88:91], v[132:135], v[164:167], v[88:91]
	v_mfma_f32_16x16x32_bf16 v[76:79], v[124:127], v[182:185], v[76:79]
	v_mfma_f32_16x16x32_bf16 v[72:75], v[132:135], v[182:185], v[72:75]
	s_barrier
	ds_read_b128 v[186:189], v218 offset:49152
	ds_read_b128 v[196:199], v218 offset:50176
	ds_read_b128 v[206:209], v218 offset:51200
	ds_read_b128 v[214:217], v218 offset:52224
	global_load_lds_dwordx4 v192, s[68:69]
	s_add_i32 m0, s13, 0x2000
	s_nop 0
	global_load_lds_dwordx4 v172, s[68:69]
	s_barrier
	s_waitcnt lgkmcnt(0)
	v_mfma_f32_16x16x32_bf16 v[116:119], v[186:189], v[144:147], v[116:119]
	v_mfma_f32_16x16x32_bf16 v[112:115], v[206:209], v[144:147], v[112:115]
	s_mov_b32 m0, s34
	v_mfma_f32_16x16x32_bf16 v[100:103], v[186:189], v[152:155], v[100:103]
	v_mfma_f32_16x16x32_bf16 v[96:99], v[206:209], v[152:155], v[96:99]
	v_mfma_f32_16x16x32_bf16 v[84:87], v[186:189], v[160:163], v[84:87]
	v_mfma_f32_16x16x32_bf16 v[80:83], v[206:209], v[160:163], v[80:83]
	v_mfma_f32_16x16x32_bf16 v[68:71], v[186:189], v[178:181], v[68:71]
	v_mfma_f32_16x16x32_bf16 v[64:67], v[206:209], v[178:181], v[64:67]
	v_mfma_f32_16x16x32_bf16 v[116:119], v[196:199], v[148:151], v[116:119]
	v_mfma_f32_16x16x32_bf16 v[112:115], v[214:217], v[148:151], v[112:115]
	v_mfma_f32_16x16x32_bf16 v[100:103], v[196:199], v[156:159], v[100:103]
	v_mfma_f32_16x16x32_bf16 v[96:99], v[214:217], v[156:159], v[96:99]
	v_mfma_f32_16x16x32_bf16 v[84:87], v[196:199], v[164:167], v[84:87]
	v_mfma_f32_16x16x32_bf16 v[80:83], v[214:217], v[164:167], v[80:83]
	v_mfma_f32_16x16x32_bf16 v[68:71], v[196:199], v[182:185], v[68:71]
	v_mfma_f32_16x16x32_bf16 v[64:67], v[214:217], v[182:185], v[64:67]
	s_barrier
	ds_read_b128 v[144:147], v205 offset:49152
	ds_read_b128 v[148:151], v205 offset:50176
	ds_read_b128 v[152:155], v205 offset:51200
	ds_read_b128 v[156:159], v205 offset:52224
	ds_read_b128 v[160:163], v205 offset:53248
	ds_read_b128 v[164:167], v205 offset:54272
	ds_read_b128 v[178:181], v205 offset:55296
	ds_read_b128 v[182:185], v205 offset:56320
	global_load_lds_dwordx4 v168, s[70:71]
	s_mov_b32 m0, s35
	s_nop 0
	global_load_lds_dwordx4 v170, s[70:71]
	s_barrier
	s_waitcnt lgkmcnt(0)
	v_mfma_f32_16x16x32_bf16 v[60:63], v[120:123], v[144:147], v[60:63]
	v_mfma_f32_16x16x32_bf16 v[56:59], v[128:131], v[144:147], v[56:59]
	s_add_i32 s12, s12, s25
	v_mfma_f32_16x16x32_bf16 v[44:47], v[120:123], v[152:155], v[44:47]
	s_add_u32 s68, s68, s52
	v_mfma_f32_16x16x32_bf16 v[40:43], v[128:131], v[152:155], v[40:43]
	s_addc_u32 s69, s69, 0
	v_mfma_f32_16x16x32_bf16 v[28:31], v[120:123], v[160:163], v[28:31]
	s_mov_b32 m0, s12
	v_mfma_f32_16x16x32_bf16 v[24:27], v[128:131], v[160:163], v[24:27]
	v_mfma_f32_16x16x32_bf16 v[12:15], v[120:123], v[178:181], v[12:15]
	v_mfma_f32_16x16x32_bf16 v[8:11], v[128:131], v[178:181], v[8:11]
	v_mfma_f32_16x16x32_bf16 v[60:63], v[124:127], v[148:151], v[60:63]
	v_mfma_f32_16x16x32_bf16 v[56:59], v[132:135], v[148:151], v[56:59]
	v_mfma_f32_16x16x32_bf16 v[44:47], v[124:127], v[156:159], v[44:47]
	v_mfma_f32_16x16x32_bf16 v[40:43], v[132:135], v[156:159], v[40:43]
	v_mfma_f32_16x16x32_bf16 v[28:31], v[124:127], v[164:167], v[28:31]
	v_mfma_f32_16x16x32_bf16 v[24:27], v[132:135], v[164:167], v[24:27]
	v_mfma_f32_16x16x32_bf16 v[12:15], v[124:127], v[182:185], v[12:15]
	v_mfma_f32_16x16x32_bf16 v[8:11], v[132:135], v[182:185], v[8:11]
	s_barrier
	global_load_lds_dwordx4 v192, s[68:69]
	s_add_i32 m0, s12, 0x2000
	s_nop 0
	global_load_lds_dwordx4 v172, s[68:69]
	s_waitcnt vmcnt(6)
	s_barrier
	v_mfma_f32_16x16x32_bf16 v[52:55], v[186:189], v[144:147], v[52:55]
	v_mfma_f32_16x16x32_bf16 v[48:51], v[206:209], v[144:147], v[48:51]
	s_add_u32 s10, s10, 0x100
	v_mfma_f32_16x16x32_bf16 v[36:39], v[186:189], v[152:155], v[36:39]
	s_addc_u32 s11, s11, 0
	v_mfma_f32_16x16x32_bf16 v[32:35], v[206:209], v[152:155], v[32:35]
	s_add_u32 s42, s42, 0x100
	v_mfma_f32_16x16x32_bf16 v[20:23], v[186:189], v[160:163], v[20:23]
	s_addc_u32 s43, s43, 0
	v_mfma_f32_16x16x32_bf16 v[16:19], v[206:209], v[160:163], v[16:19]
	s_mov_b32 s12, s44
	v_mfma_f32_16x16x32_bf16 v[4:7], v[186:189], v[178:181], v[4:7]
	v_mfma_f32_16x16x32_bf16 v[0:3], v[206:209], v[178:181], v[0:3]
	v_mfma_f32_16x16x32_bf16 v[52:55], v[196:199], v[148:151], v[52:55]
	v_mfma_f32_16x16x32_bf16 v[48:51], v[214:217], v[148:151], v[48:51]
	v_mfma_f32_16x16x32_bf16 v[36:39], v[196:199], v[156:159], v[36:39]
	v_mfma_f32_16x16x32_bf16 v[32:35], v[214:217], v[156:159], v[32:35]
	v_mfma_f32_16x16x32_bf16 v[20:23], v[196:199], v[164:167], v[20:23]
	v_mfma_f32_16x16x32_bf16 v[16:19], v[214:217], v[164:167], v[16:19]
	v_mfma_f32_16x16x32_bf16 v[4:7], v[196:199], v[182:185], v[4:7]
	v_mfma_f32_16x16x32_bf16 v[0:3], v[214:217], v[182:185], v[0:3]
	s_cmp_ge_u32 s44, s33
	s_barrier
	s_cbranch_scc0 .LBB0_246
	v_lshl_or_b32 v144, s41, 8, v204
	s_ashr_i32 s10, s40, 4
	s_mul_hi_i32 s11, s10, 0xc000
	s_mul_i32 s10, s10, 0xc000
	v_ashrrev_i32_e32 v145, 31, v144
	v_lshl_add_u32 v146, s40, 8, v190
	s_add_u32 s10, s30, s10
	v_lshlrev_b64 v[178:179], 1, v[144:145]
	v_ashrrev_i32_e32 v147, 31, v146
	s_addc_u32 s11, s31, s11
	v_lshl_add_u64 v[180:181], s[2:3], 0, v[178:179]
	v_lshlrev_b64 v[182:183], 12, v[146:147]
	v_lshl_add_u64 v[124:125], v[144:145], 2, s[10:11]
	v_lshl_add_u64 v[144:145], v[180:181], 0, v[182:183]
	global_load_dwordx4 v[128:131], v[124:125], off offset:16
	global_load_dwordx4 v[132:135], v[124:125], off
	global_load_dwordx4 v[120:123], v[124:125], off offset:528
	s_nop 0
	global_load_dwordx4 v[124:127], v[124:125], off offset:512
	s_nop 0
	global_load_dwordx4 v[196:199], v[144:145], off
	global_load_dwordx4 v[206:209], v[144:145], off offset:256
	v_or_b32_e32 v144, 16, v146
	v_ashrrev_i32_e32 v145, 31, v144
	v_lshlrev_b64 v[188:189], 12, v[144:145]
	v_lshl_add_u64 v[144:145], v[180:181], 0, v[188:189]
	global_load_dwordx4 v[164:167], v[144:145], off
	global_load_dwordx4 v[160:163], v[144:145], off offset:256
	v_or_b32_e32 v144, 32, v146
	v_ashrrev_i32_e32 v145, 31, v144
	v_lshlrev_b64 v[186:187], 12, v[144:145]
	v_lshl_add_u64 v[144:145], v[180:181], 0, v[186:187]
	global_load_dwordx4 v[156:159], v[144:145], off
	global_load_dwordx4 v[152:155], v[144:145], off offset:256
	v_or_b32_e32 v144, 48, v146
	v_ashrrev_i32_e32 v145, 31, v144
	v_lshlrev_b64 v[184:185], 12, v[144:145]
	v_lshl_add_u64 v[144:145], v[180:181], 0, v[184:185]
	global_load_dwordx4 v[148:151], v[144:145], off
	s_nop 0
	global_load_dwordx4 v[144:147], v[144:145], off offset:256
	s_mov_b64 s[10:11], 0x80000
	s_and_b64 vcc, exec, s[0:1]
	s_mov_b32 s41, s38
	s_mov_b32 s40, s39
	s_mov_b64 s[12:13], s[6:7]
	v_readlane_b32 s14, v254, 21
	s_movk_i32 s15, 0x2000
	s_waitcnt vmcnt(0)
	v_lshlrev_b32_e32 v210, 16, v196
	v_and_b32_e32 v211, 0xffff0000, v196
	v_lshlrev_b32_e32 v196, 16, v197
	v_and_b32_e32 v197, 0xffff0000, v197
	v_lshlrev_b32_e32 v214, 16, v198
	v_and_b32_e32 v215, 0xffff0000, v198
	v_lshlrev_b32_e32 v198, 16, v199
	v_and_b32_e32 v199, 0xffff0000, v199
	v_pk_fma_f32 v[140:141], v[140:141], v[132:133], v[210:211]
	v_pk_fma_f32 v[142:143], v[142:143], v[134:135], v[196:197]
	v_pk_fma_f32 v[196:197], v[138:139], v[130:131], v[198:199]
	v_pk_fma_f32 v[138:139], v[136:137], v[128:129], v[214:215]
	v_cvt_pk_bf16_f32 v136, v140, v141
	v_lshl_add_u64 v[140:141], s[8:9], 0, v[182:183]
	v_cvt_pk_bf16_f32 v137, v142, v143
	v_cvt_pk_bf16_f32 v138, v138, v139
	v_cvt_pk_bf16_f32 v139, v196, v197
	v_lshl_add_u64 v[140:141], v[140:141], 0, v[178:179]
	global_store_dwordx4 v[140:141], v[136:139], off
	v_lshlrev_b32_e32 v142, 16, v208
	v_and_b32_e32 v143, 0xffff0000, v208
	v_lshlrev_b32_e32 v136, 16, v206
	v_and_b32_e32 v137, 0xffff0000, v206
	v_lshlrev_b32_e32 v138, 16, v207
	v_and_b32_e32 v139, 0xffff0000, v207
	v_lshlrev_b32_e32 v196, 16, v209
	v_and_b32_e32 v197, 0xffff0000, v209
	v_pk_fma_f32 v[118:119], v[118:119], v[126:127], v[138:139]
	v_pk_fma_f32 v[116:117], v[116:117], v[124:125], v[136:137]
	v_pk_fma_f32 v[136:137], v[114:115], v[122:123], v[196:197]
	v_pk_fma_f32 v[114:115], v[112:113], v[120:121], v[142:143]
	v_cvt_pk_bf16_f32 v112, v116, v117
	v_cvt_pk_bf16_f32 v113, v118, v119
	v_lshlrev_b32_e32 v116, 16, v166
	v_cvt_pk_bf16_f32 v114, v114, v115
	v_cvt_pk_bf16_f32 v115, v136, v137
	global_store_dwordx4 v[140:141], v[112:115], off offset:256
	v_and_b32_e32 v117, 0xffff0000, v166
	v_lshlrev_b32_e32 v118, 16, v167
	v_lshlrev_b32_e32 v112, 16, v164
	v_and_b32_e32 v113, 0xffff0000, v164
	v_and_b32_e32 v119, 0xffff0000, v167
	v_pk_fma_f32 v[108:109], v[108:109], v[132:133], v[112:113]
	v_lshlrev_b32_e32 v114, 16, v165
	v_and_b32_e32 v115, 0xffff0000, v165
	v_pk_fma_f32 v[112:113], v[106:107], v[130:131], v[118:119]
	v_pk_fma_f32 v[106:107], v[104:105], v[128:129], v[116:117]
	v_cvt_pk_bf16_f32 v104, v108, v109
	v_lshl_add_u64 v[108:109], s[8:9], 0, v[188:189]
	v_pk_fma_f32 v[110:111], v[110:111], v[134:135], v[114:115]
	v_lshl_add_u64 v[108:109], v[108:109], 0, v[178:179]
	v_cvt_pk_bf16_f32 v105, v110, v111
	v_cvt_pk_bf16_f32 v106, v106, v107
	v_cvt_pk_bf16_f32 v107, v112, v113
	global_store_dwordx4 v[108:109], v[104:107], off
	v_lshlrev_b32_e32 v110, 16, v162
	v_and_b32_e32 v111, 0xffff0000, v162
	v_lshlrev_b32_e32 v104, 16, v160
	v_and_b32_e32 v105, 0xffff0000, v160
	v_lshlrev_b32_e32 v106, 16, v161
	v_and_b32_e32 v107, 0xffff0000, v161
	v_lshlrev_b32_e32 v112, 16, v163
	v_and_b32_e32 v113, 0xffff0000, v163
	v_pk_fma_f32 v[102:103], v[102:103], v[126:127], v[106:107]
	v_pk_fma_f32 v[100:101], v[100:101], v[124:125], v[104:105]
	v_pk_fma_f32 v[104:105], v[98:99], v[122:123], v[112:113]
	v_pk_fma_f32 v[98:99], v[96:97], v[120:121], v[110:111]
	v_cvt_pk_bf16_f32 v96, v100, v101
	v_cvt_pk_bf16_f32 v97, v102, v103
	v_lshlrev_b32_e32 v100, 16, v158
	v_cvt_pk_bf16_f32 v98, v98, v99
	v_cvt_pk_bf16_f32 v99, v104, v105
	global_store_dwordx4 v[108:109], v[96:99], off offset:256
	v_and_b32_e32 v101, 0xffff0000, v158
	v_lshlrev_b32_e32 v102, 16, v159
	v_lshlrev_b32_e32 v96, 16, v156
	v_and_b32_e32 v97, 0xffff0000, v156
	v_and_b32_e32 v103, 0xffff0000, v159
	v_pk_fma_f32 v[92:93], v[92:93], v[132:133], v[96:97]
	v_lshlrev_b32_e32 v98, 16, v157
	v_and_b32_e32 v99, 0xffff0000, v157
	v_pk_fma_f32 v[96:97], v[90:91], v[130:131], v[102:103]
	v_pk_fma_f32 v[90:91], v[88:89], v[128:129], v[100:101]
	v_cvt_pk_bf16_f32 v88, v92, v93
	v_lshl_add_u64 v[92:93], s[8:9], 0, v[186:187]
	v_pk_fma_f32 v[94:95], v[94:95], v[134:135], v[98:99]
	v_lshl_add_u64 v[92:93], v[92:93], 0, v[178:179]
	v_cvt_pk_bf16_f32 v89, v94, v95
	v_cvt_pk_bf16_f32 v90, v90, v91
	v_cvt_pk_bf16_f32 v91, v96, v97
	global_store_dwordx4 v[92:93], v[88:91], off
	v_lshlrev_b32_e32 v94, 16, v154
	v_and_b32_e32 v95, 0xffff0000, v154
	v_lshlrev_b32_e32 v88, 16, v152
	v_and_b32_e32 v89, 0xffff0000, v152
	v_lshlrev_b32_e32 v90, 16, v153
	v_and_b32_e32 v91, 0xffff0000, v153
	v_lshlrev_b32_e32 v96, 16, v155
	v_and_b32_e32 v97, 0xffff0000, v155
	v_pk_fma_f32 v[86:87], v[86:87], v[126:127], v[90:91]
	v_pk_fma_f32 v[84:85], v[84:85], v[124:125], v[88:89]
	v_pk_fma_f32 v[88:89], v[82:83], v[122:123], v[96:97]
	v_pk_fma_f32 v[82:83], v[80:81], v[120:121], v[94:95]
	v_cvt_pk_bf16_f32 v80, v84, v85
	v_cvt_pk_bf16_f32 v81, v86, v87
	v_lshlrev_b32_e32 v84, 16, v150
	v_cvt_pk_bf16_f32 v82, v82, v83
	v_cvt_pk_bf16_f32 v83, v88, v89
	global_store_dwordx4 v[92:93], v[80:83], off offset:256
	v_and_b32_e32 v85, 0xffff0000, v150
	v_lshlrev_b32_e32 v86, 16, v151
	v_lshlrev_b32_e32 v80, 16, v148
	v_and_b32_e32 v81, 0xffff0000, v148
	v_and_b32_e32 v87, 0xffff0000, v151
	v_pk_fma_f32 v[76:77], v[76:77], v[132:133], v[80:81]
	v_lshlrev_b32_e32 v82, 16, v149
	v_and_b32_e32 v83, 0xffff0000, v149
	v_pk_fma_f32 v[80:81], v[74:75], v[130:131], v[86:87]
	v_pk_fma_f32 v[74:75], v[72:73], v[128:129], v[84:85]
	v_cvt_pk_bf16_f32 v72, v76, v77
	v_lshl_add_u64 v[76:77], s[8:9], 0, v[184:185]
	v_pk_fma_f32 v[78:79], v[78:79], v[134:135], v[82:83]
	v_lshl_add_u64 v[76:77], v[76:77], 0, v[178:179]
	v_cvt_pk_bf16_f32 v73, v78, v79
	v_cvt_pk_bf16_f32 v74, v74, v75
	v_cvt_pk_bf16_f32 v75, v80, v81
	global_store_dwordx4 v[76:77], v[72:75], off
	v_lshlrev_b32_e32 v78, 16, v146
	v_and_b32_e32 v79, 0xffff0000, v146
	v_lshlrev_b32_e32 v72, 16, v144
	v_and_b32_e32 v73, 0xffff0000, v144
	v_lshlrev_b32_e32 v74, 16, v145
	v_and_b32_e32 v75, 0xffff0000, v145
	v_lshlrev_b32_e32 v80, 16, v147
	v_and_b32_e32 v81, 0xffff0000, v147
	v_pk_fma_f32 v[70:71], v[70:71], v[126:127], v[74:75]
	v_pk_fma_f32 v[68:69], v[68:69], v[124:125], v[72:73]
	v_pk_fma_f32 v[72:73], v[66:67], v[122:123], v[80:81]
	v_pk_fma_f32 v[66:67], v[64:65], v[120:121], v[78:79]
	v_cvt_pk_bf16_f32 v64, v68, v69
	v_cvt_pk_bf16_f32 v65, v70, v71
	v_lshl_add_u64 v[98:99], v[182:183], 0, s[10:11]
	v_cvt_pk_bf16_f32 v66, v66, v67
	v_cvt_pk_bf16_f32 v67, v72, v73
	global_store_dwordx4 v[76:77], v[64:67], off offset:256
	s_mov_b64 s[10:11], 0x90000
	v_lshl_add_u64 v[100:101], v[182:183], 0, s[10:11]
	v_lshl_add_u64 v[64:65], v[180:181], 0, v[98:99]
	global_load_dwordx4 v[74:77], v[64:65], off
	global_load_dwordx4 v[78:81], v[64:65], off offset:256
	v_lshl_add_u64 v[64:65], v[180:181], 0, v[100:101]
	global_load_dwordx4 v[82:85], v[64:65], off
	global_load_dwordx4 v[86:89], v[64:65], off offset:256
	s_mov_b64 s[10:11], 0xa0000
	v_lshl_add_u64 v[102:103], v[182:183], 0, s[10:11]
	v_lshl_add_u64 v[64:65], v[180:181], 0, v[102:103]
	global_load_dwordx4 v[90:93], v[64:65], off
	global_load_dwordx4 v[94:97], v[64:65], off offset:256
	s_mov_b64 s[10:11], 0xb0000
	v_lshl_add_u64 v[72:73], v[182:183], 0, s[10:11]
	v_lshl_add_u64 v[64:65], v[180:181], 0, v[72:73]
	global_load_dwordx4 v[68:71], v[64:65], off
	s_nop 0
	global_load_dwordx4 v[64:67], v[64:65], off offset:256
	s_mov_b64 s[10:11], s[4:5]
	s_waitcnt vmcnt(0)
	v_lshlrev_b32_e32 v104, 16, v74
	v_and_b32_e32 v105, 0xffff0000, v74
	v_lshlrev_b32_e32 v74, 16, v75
	v_and_b32_e32 v75, 0xffff0000, v75
	v_lshlrev_b32_e32 v106, 16, v76
	v_and_b32_e32 v107, 0xffff0000, v76
	v_lshlrev_b32_e32 v76, 16, v77
	v_and_b32_e32 v77, 0xffff0000, v77
	v_pk_fma_f32 v[60:61], v[60:61], v[132:133], v[104:105]
	v_pk_fma_f32 v[62:63], v[62:63], v[134:135], v[74:75]
	v_pk_fma_f32 v[74:75], v[58:59], v[130:131], v[76:77]
	v_pk_fma_f32 v[58:59], v[56:57], v[128:129], v[106:107]
	v_cvt_pk_bf16_f32 v56, v60, v61
	v_lshl_add_u64 v[60:61], s[8:9], 0, v[98:99]
	v_cvt_pk_bf16_f32 v57, v62, v63
	v_cvt_pk_bf16_f32 v58, v58, v59
	v_cvt_pk_bf16_f32 v59, v74, v75
	v_lshl_add_u64 v[60:61], v[60:61], 0, v[178:179]
	global_store_dwordx4 v[60:61], v[56:59], off
	v_lshlrev_b32_e32 v62, 16, v80
	v_and_b32_e32 v63, 0xffff0000, v80
	v_lshlrev_b32_e32 v56, 16, v78
	v_and_b32_e32 v57, 0xffff0000, v78
	v_lshlrev_b32_e32 v58, 16, v79
	v_and_b32_e32 v59, 0xffff0000, v79
	v_lshlrev_b32_e32 v74, 16, v81
	v_and_b32_e32 v75, 0xffff0000, v81
	v_pk_fma_f32 v[54:55], v[54:55], v[126:127], v[58:59]
	v_pk_fma_f32 v[52:53], v[52:53], v[124:125], v[56:57]
	v_pk_fma_f32 v[56:57], v[50:51], v[122:123], v[74:75]
	v_pk_fma_f32 v[50:51], v[48:49], v[120:121], v[62:63]
	v_cvt_pk_bf16_f32 v48, v52, v53
	v_cvt_pk_bf16_f32 v49, v54, v55
	v_lshlrev_b32_e32 v52, 16, v84
	v_cvt_pk_bf16_f32 v50, v50, v51
	v_cvt_pk_bf16_f32 v51, v56, v57
	global_store_dwordx4 v[60:61], v[48:51], off offset:256
	v_and_b32_e32 v53, 0xffff0000, v84
	v_lshlrev_b32_e32 v54, 16, v85
	v_lshlrev_b32_e32 v48, 16, v82
	v_and_b32_e32 v49, 0xffff0000, v82
	v_and_b32_e32 v55, 0xffff0000, v85
	v_pk_fma_f32 v[44:45], v[44:45], v[132:133], v[48:49]
	v_lshlrev_b32_e32 v50, 16, v83
	v_and_b32_e32 v51, 0xffff0000, v83
	v_pk_fma_f32 v[48:49], v[42:43], v[130:131], v[54:55]
	v_pk_fma_f32 v[42:43], v[40:41], v[128:129], v[52:53]
	v_cvt_pk_bf16_f32 v40, v44, v45
	v_lshl_add_u64 v[44:45], s[8:9], 0, v[100:101]
	v_pk_fma_f32 v[46:47], v[46:47], v[134:135], v[50:51]
	v_lshl_add_u64 v[44:45], v[44:45], 0, v[178:179]
	v_cvt_pk_bf16_f32 v41, v46, v47
	v_cvt_pk_bf16_f32 v42, v42, v43
	v_cvt_pk_bf16_f32 v43, v48, v49
	global_store_dwordx4 v[44:45], v[40:43], off
	v_lshlrev_b32_e32 v46, 16, v88
	v_and_b32_e32 v47, 0xffff0000, v88
	v_lshlrev_b32_e32 v40, 16, v86
	v_and_b32_e32 v41, 0xffff0000, v86
	v_lshlrev_b32_e32 v42, 16, v87
	v_and_b32_e32 v43, 0xffff0000, v87
	v_lshlrev_b32_e32 v48, 16, v89
	v_and_b32_e32 v49, 0xffff0000, v89
	v_pk_fma_f32 v[38:39], v[38:39], v[126:127], v[42:43]
	v_pk_fma_f32 v[36:37], v[36:37], v[124:125], v[40:41]
	v_pk_fma_f32 v[40:41], v[34:35], v[122:123], v[48:49]
	v_pk_fma_f32 v[34:35], v[32:33], v[120:121], v[46:47]
	v_cvt_pk_bf16_f32 v32, v36, v37
	v_cvt_pk_bf16_f32 v33, v38, v39
	v_lshlrev_b32_e32 v36, 16, v92
	v_cvt_pk_bf16_f32 v34, v34, v35
	v_cvt_pk_bf16_f32 v35, v40, v41
	global_store_dwordx4 v[44:45], v[32:35], off offset:256
	v_and_b32_e32 v37, 0xffff0000, v92
	v_lshlrev_b32_e32 v38, 16, v93
	v_lshlrev_b32_e32 v32, 16, v90
	v_and_b32_e32 v33, 0xffff0000, v90
	v_and_b32_e32 v39, 0xffff0000, v93
	v_pk_fma_f32 v[28:29], v[28:29], v[132:133], v[32:33]
	v_lshlrev_b32_e32 v34, 16, v91
	v_and_b32_e32 v35, 0xffff0000, v91
	v_pk_fma_f32 v[32:33], v[26:27], v[130:131], v[38:39]
	v_pk_fma_f32 v[26:27], v[24:25], v[128:129], v[36:37]
	v_cvt_pk_bf16_f32 v24, v28, v29
	v_lshl_add_u64 v[28:29], s[8:9], 0, v[102:103]
	v_pk_fma_f32 v[30:31], v[30:31], v[134:135], v[34:35]
	v_lshl_add_u64 v[28:29], v[28:29], 0, v[178:179]
	v_cvt_pk_bf16_f32 v25, v30, v31
	v_cvt_pk_bf16_f32 v26, v26, v27
	v_cvt_pk_bf16_f32 v27, v32, v33
	global_store_dwordx4 v[28:29], v[24:27], off
	v_lshlrev_b32_e32 v30, 16, v96
	v_and_b32_e32 v31, 0xffff0000, v96
	v_lshlrev_b32_e32 v24, 16, v94
	v_and_b32_e32 v25, 0xffff0000, v94
	v_lshlrev_b32_e32 v26, 16, v95
	v_and_b32_e32 v27, 0xffff0000, v95
	v_lshlrev_b32_e32 v32, 16, v97
	v_and_b32_e32 v33, 0xffff0000, v97
	v_pk_fma_f32 v[22:23], v[22:23], v[126:127], v[26:27]
	v_pk_fma_f32 v[20:21], v[20:21], v[124:125], v[24:25]
	v_pk_fma_f32 v[24:25], v[18:19], v[122:123], v[32:33]
	v_pk_fma_f32 v[18:19], v[16:17], v[120:121], v[30:31]
	v_cvt_pk_bf16_f32 v16, v20, v21
	v_cvt_pk_bf16_f32 v17, v22, v23
	v_lshlrev_b32_e32 v20, 16, v70
	v_cvt_pk_bf16_f32 v18, v18, v19
	v_cvt_pk_bf16_f32 v19, v24, v25
	global_store_dwordx4 v[28:29], v[16:19], off offset:256
	v_and_b32_e32 v21, 0xffff0000, v70
	v_lshlrev_b32_e32 v22, 16, v71
	v_lshlrev_b32_e32 v16, 16, v68
	v_and_b32_e32 v17, 0xffff0000, v68
	v_and_b32_e32 v23, 0xffff0000, v71
	v_pk_fma_f32 v[12:13], v[12:13], v[132:133], v[16:17]
	v_lshlrev_b32_e32 v18, 16, v69
	v_and_b32_e32 v19, 0xffff0000, v69
	v_pk_fma_f32 v[16:17], v[10:11], v[130:131], v[22:23]
	v_pk_fma_f32 v[10:11], v[8:9], v[128:129], v[20:21]
	v_cvt_pk_bf16_f32 v8, v12, v13
	v_lshl_add_u64 v[12:13], s[8:9], 0, v[72:73]
	v_pk_fma_f32 v[14:15], v[14:15], v[134:135], v[18:19]
	v_lshl_add_u64 v[12:13], v[12:13], 0, v[178:179]
	v_cvt_pk_bf16_f32 v9, v14, v15
	v_cvt_pk_bf16_f32 v10, v10, v11
	v_cvt_pk_bf16_f32 v11, v16, v17
	global_store_dwordx4 v[12:13], v[8:11], off
	v_lshlrev_b32_e32 v14, 16, v66
	v_and_b32_e32 v15, 0xffff0000, v66
	v_lshlrev_b32_e32 v8, 16, v64
	v_and_b32_e32 v9, 0xffff0000, v64
	v_lshlrev_b32_e32 v16, 16, v67
	v_and_b32_e32 v17, 0xffff0000, v67
	v_lshlrev_b32_e32 v10, 16, v65
	v_and_b32_e32 v11, 0xffff0000, v65
	v_pk_fma_f32 v[4:5], v[4:5], v[124:125], v[8:9]
	v_pk_fma_f32 v[8:9], v[2:3], v[122:123], v[16:17]
	v_pk_fma_f32 v[2:3], v[0:1], v[120:121], v[14:15]
	v_pk_fma_f32 v[6:7], v[6:7], v[126:127], v[10:11]
	v_cvt_pk_bf16_f32 v0, v4, v5
	s_nop 0
	v_cvt_pk_bf16_f32 v1, v6, v7
	v_cvt_pk_bf16_f32 v2, v2, v3
	v_cvt_pk_bf16_f32 v3, v8, v9
	global_store_dwordx4 v[12:13], v[0:3], off offset:256
	s_cbranch_vccz .LBB0_235
	s_waitcnt vmcnt(0)
	s_cmpk_gt_u32 s16, 0xff
	s_cbranch_scc1 .LBB0_250
	s_barrier

.LBB0_271:
	s_add_u32 s39, s10, 0x100
	s_addc_u32 s40, s11, 0
	s_mov_b32 s41, -2
	s_mov_b64 s[44:45], 0x80
	v_add_u32_e32 v220, 0x10000, v187
	s_add_u32 s10, s8, 0x100
	s_addc_u32 s11, s9, 0
	s_add_i32 s42, 0, 0x10000
	ds_read_b128 v[108:111], v220 offset:0
	ds_read_b128 v[112:115], v220 offset:1024
	ds_read_b128 v[116:119], v220 offset:2048
	ds_read_b128 v[120:123], v220 offset:3072
	s_cmpk_eq_i32 s41, 0x54
	s_cselect_b32 s15, s5, s11
	s_cselect_b32 s14, s4, s10
	s_cselect_b32 s13, s7, s40
	s_cselect_b32 s12, s6, s39
	s_add_i32 m0, s25, 0xc000
	ds_read_b128 v[144:147], v189
	ds_read_b128 v[148:151], v189 offset:1024
	ds_read_b128 v[152:155], v189 offset:2048
	ds_read_b128 v[156:159], v189 offset:3072
	ds_read_b128 v[160:163], v189 offset:4096
	ds_read_b128 v[174:177], v189 offset:5120
	ds_read_b128 v[178:181], v189 offset:6144
	ds_read_b128 v[182:185], v189 offset:7168
	global_load_lds_dwordx4 v170, s[8:9]
	s_add_i32 m0, s25, 0xe000
	s_nop 0
	global_load_lds_dwordx4 v172, s[8:9]
	s_waitcnt lgkmcnt(8)
	s_barrier
	s_waitcnt lgkmcnt(0)
	v_mfma_f32_16x16x32_bf16 v[140:143], v[108:111], v[144:147], 0
	v_mfma_f32_16x16x32_bf16 v[136:139], v[116:119], v[144:147], 0
	s_add_i32 s43, 0, 0x14000
	v_mfma_f32_16x16x32_bf16 v[132:135], v[108:111], v[152:155], 0
	s_add_i32 s8, s42, s19
	v_mfma_f32_16x16x32_bf16 v[104:107], v[116:119], v[152:155], 0
	s_mov_b32 m0, s8
	v_mfma_f32_16x16x32_bf16 v[96:99], v[108:111], v[160:163], 0
	v_mfma_f32_16x16x32_bf16 v[88:91], v[116:119], v[160:163], 0
	v_mfma_f32_16x16x32_bf16 v[80:83], v[108:111], v[178:181], 0
	v_mfma_f32_16x16x32_bf16 v[72:75], v[116:119], v[178:181], 0
	v_mfma_f32_16x16x32_bf16 v[140:143], v[112:115], v[148:151], v[140:143]
	v_mfma_f32_16x16x32_bf16 v[136:139], v[120:123], v[148:151], v[136:139]
	v_mfma_f32_16x16x32_bf16 v[132:135], v[112:115], v[156:159], v[132:135]
	v_mfma_f32_16x16x32_bf16 v[104:107], v[120:123], v[156:159], v[104:107]
	v_mfma_f32_16x16x32_bf16 v[96:99], v[112:115], v[174:177], v[96:99]
	v_mfma_f32_16x16x32_bf16 v[88:91], v[120:123], v[174:177], v[88:91]
	v_mfma_f32_16x16x32_bf16 v[80:83], v[112:115], v[182:185], v[80:83]
	v_mfma_f32_16x16x32_bf16 v[72:75], v[120:123], v[182:185], v[72:75]
	s_barrier
	ds_read_b128 v[196:199], v220 offset:16384
	ds_read_b128 v[204:207], v220 offset:17408
	ds_read_b128 v[208:211], v220 offset:18432
	ds_read_b128 v[214:217], v220 offset:19456
	global_load_lds_dwordx4 v192, s[12:13]
	s_add_i32 m0, s8, 0x2000
	s_nop 0
	global_load_lds_dwordx4 v168, s[12:13]
	s_barrier
	s_waitcnt lgkmcnt(0)
	v_mfma_f32_16x16x32_bf16 v[128:131], v[196:199], v[144:147], 0
	v_mfma_f32_16x16x32_bf16 v[124:127], v[208:211], v[144:147], 0
	s_mov_b32 m0, s25
	v_mfma_f32_16x16x32_bf16 v[100:103], v[196:199], v[152:155], 0
	s_add_u32 s44, s14, 0x80
	v_mfma_f32_16x16x32_bf16 v[92:95], v[208:211], v[152:155], 0
	s_addc_u32 s45, s15, 0
	v_mfma_f32_16x16x32_bf16 v[84:87], v[196:199], v[160:163], 0
	v_mfma_f32_16x16x32_bf16 v[76:79], v[208:211], v[160:163], 0
	v_mfma_f32_16x16x32_bf16 v[68:71], v[196:199], v[178:181], 0
	v_mfma_f32_16x16x32_bf16 v[64:67], v[208:211], v[178:181], 0
	v_mfma_f32_16x16x32_bf16 v[128:131], v[204:207], v[148:151], v[128:131]
	v_mfma_f32_16x16x32_bf16 v[124:127], v[214:217], v[148:151], v[124:127]
	v_mfma_f32_16x16x32_bf16 v[100:103], v[204:207], v[156:159], v[100:103]
	v_mfma_f32_16x16x32_bf16 v[92:95], v[214:217], v[156:159], v[92:95]
	v_mfma_f32_16x16x32_bf16 v[84:87], v[204:207], v[174:177], v[84:87]
	v_mfma_f32_16x16x32_bf16 v[76:79], v[214:217], v[174:177], v[76:79]
	v_mfma_f32_16x16x32_bf16 v[68:71], v[204:207], v[182:185], v[68:71]
	v_mfma_f32_16x16x32_bf16 v[64:67], v[214:217], v[182:185], v[64:67]
	s_barrier
	ds_read_b128 v[144:147], v189 offset:16384
	ds_read_b128 v[148:151], v189 offset:17408
	ds_read_b128 v[152:155], v189 offset:18432
	ds_read_b128 v[156:159], v189 offset:19456
	ds_read_b128 v[160:163], v189 offset:20480
	ds_read_b128 v[174:177], v189 offset:21504
	ds_read_b128 v[178:181], v189 offset:22528
	ds_read_b128 v[182:185], v189 offset:23552
	global_load_lds_dwordx4 v164, s[14:15]
	s_mov_b32 m0, s26
	s_nop 0
	global_load_lds_dwordx4 v166, s[14:15]
	s_barrier
	s_waitcnt lgkmcnt(0)
	v_mfma_f32_16x16x32_bf16 v[60:63], v[108:111], v[144:147], 0
	v_mfma_f32_16x16x32_bf16 v[56:59], v[116:119], v[144:147], 0
	s_add_u32 s8, s12, 0x160000
	v_mfma_f32_16x16x32_bf16 v[48:51], v[108:111], v[152:155], 0
	s_addc_u32 s9, s13, 0
	v_mfma_f32_16x16x32_bf16 v[40:43], v[116:119], v[152:155], 0
	s_add_i32 s42, s43, s19
	v_mfma_f32_16x16x32_bf16 v[32:35], v[108:111], v[160:163], 0
	s_mov_b32 m0, s42
	v_mfma_f32_16x16x32_bf16 v[24:27], v[116:119], v[160:163], 0
	v_mfma_f32_16x16x32_bf16 v[16:19], v[108:111], v[178:181], 0
	v_mfma_f32_16x16x32_bf16 v[8:11], v[116:119], v[178:181], 0
	v_mfma_f32_16x16x32_bf16 v[60:63], v[112:115], v[148:151], v[60:63]
	v_mfma_f32_16x16x32_bf16 v[56:59], v[120:123], v[148:151], v[56:59]
	v_mfma_f32_16x16x32_bf16 v[48:51], v[112:115], v[156:159], v[48:51]
	v_mfma_f32_16x16x32_bf16 v[40:43], v[120:123], v[156:159], v[40:43]
	v_mfma_f32_16x16x32_bf16 v[32:35], v[112:115], v[174:177], v[32:35]
	v_mfma_f32_16x16x32_bf16 v[24:27], v[120:123], v[174:177], v[24:27]
	v_mfma_f32_16x16x32_bf16 v[16:19], v[112:115], v[182:185], v[16:19]
	v_mfma_f32_16x16x32_bf16 v[8:11], v[120:123], v[182:185], v[8:11]
	s_barrier
	global_load_lds_dwordx4 v192, s[8:9]
	s_add_i32 m0, s42, 0x2000
	s_nop 0
	global_load_lds_dwordx4 v168, s[8:9]
	s_waitcnt vmcnt(6)
	s_barrier
	v_mfma_f32_16x16x32_bf16 v[52:55], v[196:199], v[144:147], 0
	v_mfma_f32_16x16x32_bf16 v[44:47], v[208:211], v[144:147], 0
	s_add_i32 s42, 0, 0x18000
	v_mfma_f32_16x16x32_bf16 v[36:39], v[196:199], v[152:155], 0
	s_add_u32 s8, s14, 0x160000
	v_mfma_f32_16x16x32_bf16 v[28:31], v[208:211], v[152:155], 0
	s_addc_u32 s9, s15, 0
	v_mfma_f32_16x16x32_bf16 v[20:23], v[196:199], v[160:163], 0
	s_mov_b32 m0, s27
	v_mfma_f32_16x16x32_bf16 v[12:15], v[208:211], v[160:163], 0
	v_mfma_f32_16x16x32_bf16 v[4:7], v[196:199], v[178:181], 0
	v_mfma_f32_16x16x32_bf16 v[0:3], v[208:211], v[178:181], 0
	v_mfma_f32_16x16x32_bf16 v[52:55], v[204:207], v[148:151], v[52:55]
	v_mfma_f32_16x16x32_bf16 v[44:47], v[214:217], v[148:151], v[44:47]
	v_mfma_f32_16x16x32_bf16 v[36:39], v[204:207], v[156:159], v[36:39]
	v_mfma_f32_16x16x32_bf16 v[28:31], v[214:217], v[156:159], v[28:31]
	v_mfma_f32_16x16x32_bf16 v[20:23], v[204:207], v[174:177], v[20:23]
	v_mfma_f32_16x16x32_bf16 v[12:15], v[214:217], v[174:177], v[12:15]
	v_mfma_f32_16x16x32_bf16 v[4:7], v[204:207], v[182:185], v[4:7]
	v_mfma_f32_16x16x32_bf16 v[0:3], v[214:217], v[182:185], v[0:3]
	s_barrier
	ds_read_b128 v[108:111], v220 offset:32768
	ds_read_b128 v[112:115], v220 offset:33792
	ds_read_b128 v[116:119], v220 offset:34816
	ds_read_b128 v[120:123], v220 offset:35840
	ds_read_b128 v[144:147], v189 offset:32768
	ds_read_b128 v[148:151], v189 offset:33792
	ds_read_b128 v[152:155], v189 offset:34816
	ds_read_b128 v[156:159], v189 offset:35840
	ds_read_b128 v[160:163], v189 offset:36864
	ds_read_b128 v[174:177], v189 offset:37888
	ds_read_b128 v[178:181], v189 offset:38912
	ds_read_b128 v[182:185], v189 offset:39936
	global_load_lds_dwordx4 v164, s[8:9]
	s_mov_b32 m0, s28
	s_nop 0
	global_load_lds_dwordx4 v166, s[8:9]
	s_waitcnt lgkmcnt(8)
	s_barrier
	s_waitcnt lgkmcnt(0)
	v_mfma_f32_16x16x32_bf16 v[140:143], v[108:111], v[144:147], v[140:143]
	v_mfma_f32_16x16x32_bf16 v[136:139], v[116:119], v[144:147], v[136:139]
	s_add_i32 s14, 0, 0x1c000
	v_mfma_f32_16x16x32_bf16 v[132:135], v[108:111], v[152:155], v[132:135]
	s_add_i32 s8, s42, s19
	v_mfma_f32_16x16x32_bf16 v[104:107], v[116:119], v[152:155], v[104:107]
	s_add_i32 m0, s8, 0xffffff80
	v_mfma_f32_16x16x32_bf16 v[96:99], v[108:111], v[160:163], v[96:99]
	v_mfma_f32_16x16x32_bf16 v[88:91], v[116:119], v[160:163], v[88:91]
	v_mfma_f32_16x16x32_bf16 v[80:83], v[108:111], v[178:181], v[80:83]
	v_mfma_f32_16x16x32_bf16 v[72:75], v[116:119], v[178:181], v[72:75]
	v_mfma_f32_16x16x32_bf16 v[140:143], v[112:115], v[148:151], v[140:143]
	v_mfma_f32_16x16x32_bf16 v[136:139], v[120:123], v[148:151], v[136:139]
	v_mfma_f32_16x16x32_bf16 v[132:135], v[112:115], v[156:159], v[132:135]
	v_mfma_f32_16x16x32_bf16 v[104:107], v[120:123], v[156:159], v[104:107]
	v_mfma_f32_16x16x32_bf16 v[96:99], v[112:115], v[174:177], v[96:99]
	v_mfma_f32_16x16x32_bf16 v[88:91], v[120:123], v[174:177], v[88:91]
	v_mfma_f32_16x16x32_bf16 v[80:83], v[112:115], v[182:185], v[80:83]
	v_mfma_f32_16x16x32_bf16 v[72:75], v[120:123], v[182:185], v[72:75]
	s_barrier
	ds_read_b128 v[196:199], v220 offset:49152
	ds_read_b128 v[204:207], v220 offset:50176
	ds_read_b128 v[208:211], v220 offset:51200
	ds_read_b128 v[214:217], v220 offset:52224
	global_load_lds_dwordx4 v192, s[12:13] offset:128
	s_add_i32 m0, s8, 0x1f80
	s_nop 0
	global_load_lds_dwordx4 v168, s[12:13] offset:128
	s_barrier
	s_waitcnt lgkmcnt(0)
	v_mfma_f32_16x16x32_bf16 v[128:131], v[196:199], v[144:147], v[128:131]
	v_mfma_f32_16x16x32_bf16 v[124:127], v[208:211], v[144:147], v[124:127]
	s_mov_b32 m0, s31
	v_mfma_f32_16x16x32_bf16 v[100:103], v[196:199], v[152:155], v[100:103]
	v_mfma_f32_16x16x32_bf16 v[92:95], v[208:211], v[152:155], v[92:95]
	v_mfma_f32_16x16x32_bf16 v[84:87], v[196:199], v[160:163], v[84:87]
	v_mfma_f32_16x16x32_bf16 v[76:79], v[208:211], v[160:163], v[76:79]
	v_mfma_f32_16x16x32_bf16 v[68:71], v[196:199], v[178:181], v[68:71]
	v_mfma_f32_16x16x32_bf16 v[64:67], v[208:211], v[178:181], v[64:67]
	v_mfma_f32_16x16x32_bf16 v[128:131], v[204:207], v[148:151], v[128:131]
	v_mfma_f32_16x16x32_bf16 v[124:127], v[214:217], v[148:151], v[124:127]
	v_mfma_f32_16x16x32_bf16 v[100:103], v[204:207], v[156:159], v[100:103]
	v_mfma_f32_16x16x32_bf16 v[92:95], v[214:217], v[156:159], v[92:95]
	v_mfma_f32_16x16x32_bf16 v[84:87], v[204:207], v[174:177], v[84:87]
	v_mfma_f32_16x16x32_bf16 v[76:79], v[214:217], v[174:177], v[76:79]
	v_mfma_f32_16x16x32_bf16 v[68:71], v[204:207], v[182:185], v[68:71]
	v_mfma_f32_16x16x32_bf16 v[64:67], v[214:217], v[182:185], v[64:67]
	s_barrier
	ds_read_b128 v[144:147], v189 offset:49152
	ds_read_b128 v[148:151], v189 offset:50176
	ds_read_b128 v[152:155], v189 offset:51200
	ds_read_b128 v[156:159], v189 offset:52224
	ds_read_b128 v[160:163], v189 offset:53248
	ds_read_b128 v[174:177], v189 offset:54272
	ds_read_b128 v[178:181], v189 offset:55296
	ds_read_b128 v[182:185], v189 offset:56320
	global_load_lds_dwordx4 v164, s[44:45]
	s_mov_b32 m0, s33
	s_nop 0
	global_load_lds_dwordx4 v166, s[44:45]
	s_barrier
	s_waitcnt lgkmcnt(0)
	v_mfma_f32_16x16x32_bf16 v[60:63], v[108:111], v[144:147], v[60:63]
	v_mfma_f32_16x16x32_bf16 v[56:59], v[116:119], v[144:147], v[56:59]
	s_add_u32 s8, s12, 0x160080
	v_mfma_f32_16x16x32_bf16 v[48:51], v[108:111], v[152:155], v[48:51]
	s_addc_u32 s9, s13, 0
	v_mfma_f32_16x16x32_bf16 v[40:43], v[116:119], v[152:155], v[40:43]
	s_add_i32 s12, s14, s19
	v_mfma_f32_16x16x32_bf16 v[32:35], v[108:111], v[160:163], v[32:35]
	s_mov_b32 m0, s12
	v_mfma_f32_16x16x32_bf16 v[24:27], v[116:119], v[160:163], v[24:27]
	v_mfma_f32_16x16x32_bf16 v[16:19], v[108:111], v[178:181], v[16:19]
	v_mfma_f32_16x16x32_bf16 v[8:11], v[116:119], v[178:181], v[8:11]
	v_mfma_f32_16x16x32_bf16 v[60:63], v[112:115], v[148:151], v[60:63]
	v_mfma_f32_16x16x32_bf16 v[56:59], v[120:123], v[148:151], v[56:59]
	v_mfma_f32_16x16x32_bf16 v[48:51], v[112:115], v[156:159], v[48:51]
	v_mfma_f32_16x16x32_bf16 v[40:43], v[120:123], v[156:159], v[40:43]
	v_mfma_f32_16x16x32_bf16 v[32:35], v[112:115], v[174:177], v[32:35]
	v_mfma_f32_16x16x32_bf16 v[24:27], v[120:123], v[174:177], v[24:27]
	v_mfma_f32_16x16x32_bf16 v[16:19], v[112:115], v[182:185], v[16:19]
	v_mfma_f32_16x16x32_bf16 v[8:11], v[120:123], v[182:185], v[8:11]
	s_barrier
	global_load_lds_dwordx4 v192, s[8:9]
	s_add_i32 m0, s12, 0x2000
	s_nop 0
	global_load_lds_dwordx4 v168, s[8:9]
	s_waitcnt vmcnt(6)
	s_barrier
	v_mfma_f32_16x16x32_bf16 v[52:55], v[196:199], v[144:147], v[52:55]
	v_mfma_f32_16x16x32_bf16 v[44:47], v[208:211], v[144:147], v[44:47]
	s_add_i32 s41, s41, 2
	v_mfma_f32_16x16x32_bf16 v[36:39], v[196:199], v[152:155], v[36:39]
	s_add_u32 s39, s39, 0x100
	v_mfma_f32_16x16x32_bf16 v[28:31], v[208:211], v[152:155], v[28:31]
	s_addc_u32 s40, s40, 0
	v_mfma_f32_16x16x32_bf16 v[20:23], v[196:199], v[160:163], v[20:23]
	s_mov_b64 s[8:9], s[10:11]
	v_mfma_f32_16x16x32_bf16 v[12:15], v[208:211], v[160:163], v[12:15]
	s_add_u32 s10, s8, 0x100
	s_addc_u32 s11, s9, 0
	v_mfma_f32_16x16x32_bf16 v[4:7], v[196:199], v[178:181], v[4:7]
	s_add_i32 s42, 0, 0x10000
	s_cmpk_eq_i32 s41, 0x54
	v_mfma_f32_16x16x32_bf16 v[0:3], v[208:211], v[178:181], v[0:3]
	s_cselect_b32 s15, s5, s11
	s_cselect_b32 s14, s4, s10
	v_mfma_f32_16x16x32_bf16 v[52:55], v[204:207], v[148:151], v[52:55]
	s_cselect_b32 s13, s7, s40
	s_cselect_b32 s12, s6, s39
	v_mfma_f32_16x16x32_bf16 v[44:47], v[214:217], v[148:151], v[44:47]
	s_add_i32 m0, s25, 0xc000
	v_mfma_f32_16x16x32_bf16 v[36:39], v[204:207], v[156:159], v[36:39]
	v_mfma_f32_16x16x32_bf16 v[28:31], v[214:217], v[156:159], v[28:31]
	v_mfma_f32_16x16x32_bf16 v[20:23], v[204:207], v[174:177], v[20:23]
	v_mfma_f32_16x16x32_bf16 v[12:15], v[214:217], v[174:177], v[12:15]
	v_mfma_f32_16x16x32_bf16 v[4:7], v[204:207], v[182:185], v[4:7]
	v_mfma_f32_16x16x32_bf16 v[0:3], v[214:217], v[182:185], v[0:3]
	s_cmpk_gt_u32 s41, 0x55
	s_barrier
.LBB0_272:
	ds_read_b128 v[108:111], v220 offset:0
	ds_read_b128 v[112:115], v220 offset:1024
	ds_read_b128 v[116:119], v220 offset:2048
	ds_read_b128 v[120:123], v220 offset:3072
	ds_read_b128 v[144:147], v189
	ds_read_b128 v[148:151], v189 offset:1024
	ds_read_b128 v[152:155], v189 offset:2048
	ds_read_b128 v[156:159], v189 offset:3072
	ds_read_b128 v[160:163], v189 offset:4096
	ds_read_b128 v[174:177], v189 offset:5120
	ds_read_b128 v[178:181], v189 offset:6144
	ds_read_b128 v[182:185], v189 offset:7168
	global_load_lds_dwordx4 v170, s[8:9]
	s_add_i32 m0, s25, 0xe000
	s_nop 0
	global_load_lds_dwordx4 v172, s[8:9]
	s_waitcnt lgkmcnt(8)
	s_barrier
	s_waitcnt lgkmcnt(0)
	v_mfma_f32_16x16x32_bf16 v[140:143], v[108:111], v[144:147], v[140:143]
	v_mfma_f32_16x16x32_bf16 v[136:139], v[116:119], v[144:147], v[136:139]
	s_add_i32 s43, 0, 0x14000
	v_mfma_f32_16x16x32_bf16 v[132:135], v[108:111], v[152:155], v[132:135]
	s_add_i32 s8, s42, s19
	v_mfma_f32_16x16x32_bf16 v[104:107], v[116:119], v[152:155], v[104:107]
	s_mov_b32 m0, s8
	v_mfma_f32_16x16x32_bf16 v[96:99], v[108:111], v[160:163], v[96:99]
	v_mfma_f32_16x16x32_bf16 v[88:91], v[116:119], v[160:163], v[88:91]
	v_mfma_f32_16x16x32_bf16 v[80:83], v[108:111], v[178:181], v[80:83]
	v_mfma_f32_16x16x32_bf16 v[72:75], v[116:119], v[178:181], v[72:75]
	v_mfma_f32_16x16x32_bf16 v[140:143], v[112:115], v[148:151], v[140:143]
	v_mfma_f32_16x16x32_bf16 v[136:139], v[120:123], v[148:151], v[136:139]
	v_mfma_f32_16x16x32_bf16 v[132:135], v[112:115], v[156:159], v[132:135]
	v_mfma_f32_16x16x32_bf16 v[104:107], v[120:123], v[156:159], v[104:107]
	v_mfma_f32_16x16x32_bf16 v[96:99], v[112:115], v[174:177], v[96:99]
	v_mfma_f32_16x16x32_bf16 v[88:91], v[120:123], v[174:177], v[88:91]
	v_mfma_f32_16x16x32_bf16 v[80:83], v[112:115], v[182:185], v[80:83]
	v_mfma_f32_16x16x32_bf16 v[72:75], v[120:123], v[182:185], v[72:75]
	s_barrier
	ds_read_b128 v[196:199], v220 offset:16384
	ds_read_b128 v[204:207], v220 offset:17408
	ds_read_b128 v[208:211], v220 offset:18432
	ds_read_b128 v[214:217], v220 offset:19456
	global_load_lds_dwordx4 v192, s[12:13]
	s_add_i32 m0, s8, 0x2000
	s_nop 0
	global_load_lds_dwordx4 v168, s[12:13]
	s_barrier
	s_waitcnt lgkmcnt(0)
	v_mfma_f32_16x16x32_bf16 v[128:131], v[196:199], v[144:147], v[128:131]
	v_mfma_f32_16x16x32_bf16 v[124:127], v[208:211], v[144:147], v[124:127]
	s_mov_b32 m0, s25
	v_mfma_f32_16x16x32_bf16 v[100:103], v[196:199], v[152:155], v[100:103]
	s_add_u32 s44, s14, 0x80
	v_mfma_f32_16x16x32_bf16 v[92:95], v[208:211], v[152:155], v[92:95]
	s_addc_u32 s45, s15, 0
	v_mfma_f32_16x16x32_bf16 v[84:87], v[196:199], v[160:163], v[84:87]
	v_mfma_f32_16x16x32_bf16 v[76:79], v[208:211], v[160:163], v[76:79]
	v_mfma_f32_16x16x32_bf16 v[68:71], v[196:199], v[178:181], v[68:71]
	v_mfma_f32_16x16x32_bf16 v[64:67], v[208:211], v[178:181], v[64:67]
	v_mfma_f32_16x16x32_bf16 v[128:131], v[204:207], v[148:151], v[128:131]
	v_mfma_f32_16x16x32_bf16 v[124:127], v[214:217], v[148:151], v[124:127]
	v_mfma_f32_16x16x32_bf16 v[100:103], v[204:207], v[156:159], v[100:103]
	v_mfma_f32_16x16x32_bf16 v[92:95], v[214:217], v[156:159], v[92:95]
	v_mfma_f32_16x16x32_bf16 v[84:87], v[204:207], v[174:177], v[84:87]
	v_mfma_f32_16x16x32_bf16 v[76:79], v[214:217], v[174:177], v[76:79]
	v_mfma_f32_16x16x32_bf16 v[68:71], v[204:207], v[182:185], v[68:71]
	v_mfma_f32_16x16x32_bf16 v[64:67], v[214:217], v[182:185], v[64:67]
	s_barrier
	ds_read_b128 v[144:147], v189 offset:16384
	ds_read_b128 v[148:151], v189 offset:17408
	ds_read_b128 v[152:155], v189 offset:18432
	ds_read_b128 v[156:159], v189 offset:19456
	ds_read_b128 v[160:163], v189 offset:20480
	ds_read_b128 v[174:177], v189 offset:21504
	ds_read_b128 v[178:181], v189 offset:22528
	ds_read_b128 v[182:185], v189 offset:23552
	global_load_lds_dwordx4 v164, s[14:15]
	s_mov_b32 m0, s26
	s_nop 0
	global_load_lds_dwordx4 v166, s[14:15]
	s_barrier
	s_waitcnt lgkmcnt(0)
	v_mfma_f32_16x16x32_bf16 v[60:63], v[108:111], v[144:147], v[60:63]
	v_mfma_f32_16x16x32_bf16 v[56:59], v[116:119], v[144:147], v[56:59]
	s_add_u32 s8, s12, 0x160000
	v_mfma_f32_16x16x32_bf16 v[48:51], v[108:111], v[152:155], v[48:51]
	s_addc_u32 s9, s13, 0
	v_mfma_f32_16x16x32_bf16 v[40:43], v[116:119], v[152:155], v[40:43]
	s_add_i32 s42, s43, s19
	v_mfma_f32_16x16x32_bf16 v[32:35], v[108:111], v[160:163], v[32:35]
	s_mov_b32 m0, s42
	v_mfma_f32_16x16x32_bf16 v[24:27], v[116:119], v[160:163], v[24:27]
	v_mfma_f32_16x16x32_bf16 v[16:19], v[108:111], v[178:181], v[16:19]
	v_mfma_f32_16x16x32_bf16 v[8:11], v[116:119], v[178:181], v[8:11]
	v_mfma_f32_16x16x32_bf16 v[60:63], v[112:115], v[148:151], v[60:63]
	v_mfma_f32_16x16x32_bf16 v[56:59], v[120:123], v[148:151], v[56:59]
	v_mfma_f32_16x16x32_bf16 v[48:51], v[112:115], v[156:159], v[48:51]
	v_mfma_f32_16x16x32_bf16 v[40:43], v[120:123], v[156:159], v[40:43]
	v_mfma_f32_16x16x32_bf16 v[32:35], v[112:115], v[174:177], v[32:35]
	v_mfma_f32_16x16x32_bf16 v[24:27], v[120:123], v[174:177], v[24:27]
	v_mfma_f32_16x16x32_bf16 v[16:19], v[112:115], v[182:185], v[16:19]
	v_mfma_f32_16x16x32_bf16 v[8:11], v[120:123], v[182:185], v[8:11]
	s_barrier
	global_load_lds_dwordx4 v192, s[8:9]
	s_add_i32 m0, s42, 0x2000
	s_nop 0
	global_load_lds_dwordx4 v168, s[8:9]
	s_waitcnt vmcnt(6)
	s_barrier
	v_mfma_f32_16x16x32_bf16 v[52:55], v[196:199], v[144:147], v[52:55]
	v_mfma_f32_16x16x32_bf16 v[44:47], v[208:211], v[144:147], v[44:47]
	s_add_i32 s42, 0, 0x18000
	v_mfma_f32_16x16x32_bf16 v[36:39], v[196:199], v[152:155], v[36:39]
	s_add_u32 s8, s14, 0x160000
	v_mfma_f32_16x16x32_bf16 v[28:31], v[208:211], v[152:155], v[28:31]
	s_addc_u32 s9, s15, 0
	v_mfma_f32_16x16x32_bf16 v[20:23], v[196:199], v[160:163], v[20:23]
	s_mov_b32 m0, s27
	v_mfma_f32_16x16x32_bf16 v[12:15], v[208:211], v[160:163], v[12:15]
	v_mfma_f32_16x16x32_bf16 v[4:7], v[196:199], v[178:181], v[4:7]
	v_mfma_f32_16x16x32_bf16 v[0:3], v[208:211], v[178:181], v[0:3]
	v_mfma_f32_16x16x32_bf16 v[52:55], v[204:207], v[148:151], v[52:55]
	v_mfma_f32_16x16x32_bf16 v[44:47], v[214:217], v[148:151], v[44:47]
	v_mfma_f32_16x16x32_bf16 v[36:39], v[204:207], v[156:159], v[36:39]
	v_mfma_f32_16x16x32_bf16 v[28:31], v[214:217], v[156:159], v[28:31]
	v_mfma_f32_16x16x32_bf16 v[20:23], v[204:207], v[174:177], v[20:23]
	v_mfma_f32_16x16x32_bf16 v[12:15], v[214:217], v[174:177], v[12:15]
	v_mfma_f32_16x16x32_bf16 v[4:7], v[204:207], v[182:185], v[4:7]
	v_mfma_f32_16x16x32_bf16 v[0:3], v[214:217], v[182:185], v[0:3]
	s_barrier
	ds_read_b128 v[108:111], v220 offset:32768
	ds_read_b128 v[112:115], v220 offset:33792
	ds_read_b128 v[116:119], v220 offset:34816
	ds_read_b128 v[120:123], v220 offset:35840
	ds_read_b128 v[144:147], v189 offset:32768
	ds_read_b128 v[148:151], v189 offset:33792
	ds_read_b128 v[152:155], v189 offset:34816
	ds_read_b128 v[156:159], v189 offset:35840
	ds_read_b128 v[160:163], v189 offset:36864
	ds_read_b128 v[174:177], v189 offset:37888
	ds_read_b128 v[178:181], v189 offset:38912
	ds_read_b128 v[182:185], v189 offset:39936
	global_load_lds_dwordx4 v164, s[8:9]
	s_mov_b32 m0, s28
	s_nop 0
	global_load_lds_dwordx4 v166, s[8:9]
	s_waitcnt lgkmcnt(8)
	s_barrier
	s_waitcnt lgkmcnt(0)
	v_mfma_f32_16x16x32_bf16 v[140:143], v[108:111], v[144:147], v[140:143]
	v_mfma_f32_16x16x32_bf16 v[136:139], v[116:119], v[144:147], v[136:139]
	s_add_i32 s14, 0, 0x1c000
	v_mfma_f32_16x16x32_bf16 v[132:135], v[108:111], v[152:155], v[132:135]
	s_add_i32 s8, s42, s19
	v_mfma_f32_16x16x32_bf16 v[104:107], v[116:119], v[152:155], v[104:107]
	s_add_i32 m0, s8, 0xffffff80
	v_mfma_f32_16x16x32_bf16 v[96:99], v[108:111], v[160:163], v[96:99]
	v_mfma_f32_16x16x32_bf16 v[88:91], v[116:119], v[160:163], v[88:91]
	v_mfma_f32_16x16x32_bf16 v[80:83], v[108:111], v[178:181], v[80:83]
	v_mfma_f32_16x16x32_bf16 v[72:75], v[116:119], v[178:181], v[72:75]
	v_mfma_f32_16x16x32_bf16 v[140:143], v[112:115], v[148:151], v[140:143]
	v_mfma_f32_16x16x32_bf16 v[136:139], v[120:123], v[148:151], v[136:139]
	v_mfma_f32_16x16x32_bf16 v[132:135], v[112:115], v[156:159], v[132:135]
	v_mfma_f32_16x16x32_bf16 v[104:107], v[120:123], v[156:159], v[104:107]
	v_mfma_f32_16x16x32_bf16 v[96:99], v[112:115], v[174:177], v[96:99]
	v_mfma_f32_16x16x32_bf16 v[88:91], v[120:123], v[174:177], v[88:91]
	v_mfma_f32_16x16x32_bf16 v[80:83], v[112:115], v[182:185], v[80:83]
	v_mfma_f32_16x16x32_bf16 v[72:75], v[120:123], v[182:185], v[72:75]
	s_barrier
	ds_read_b128 v[196:199], v220 offset:49152
	ds_read_b128 v[204:207], v220 offset:50176
	ds_read_b128 v[208:211], v220 offset:51200
	ds_read_b128 v[214:217], v220 offset:52224
	global_load_lds_dwordx4 v192, s[12:13] offset:128
	s_add_i32 m0, s8, 0x1f80
	s_nop 0
	global_load_lds_dwordx4 v168, s[12:13] offset:128
	s_barrier
	s_waitcnt lgkmcnt(0)
	v_mfma_f32_16x16x32_bf16 v[128:131], v[196:199], v[144:147], v[128:131]
	v_mfma_f32_16x16x32_bf16 v[124:127], v[208:211], v[144:147], v[124:127]
	s_mov_b32 m0, s31
	v_mfma_f32_16x16x32_bf16 v[100:103], v[196:199], v[152:155], v[100:103]
	v_mfma_f32_16x16x32_bf16 v[92:95], v[208:211], v[152:155], v[92:95]
	v_mfma_f32_16x16x32_bf16 v[84:87], v[196:199], v[160:163], v[84:87]
	v_mfma_f32_16x16x32_bf16 v[76:79], v[208:211], v[160:163], v[76:79]
	v_mfma_f32_16x16x32_bf16 v[68:71], v[196:199], v[178:181], v[68:71]
	v_mfma_f32_16x16x32_bf16 v[64:67], v[208:211], v[178:181], v[64:67]
	v_mfma_f32_16x16x32_bf16 v[128:131], v[204:207], v[148:151], v[128:131]
	v_mfma_f32_16x16x32_bf16 v[124:127], v[214:217], v[148:151], v[124:127]
	v_mfma_f32_16x16x32_bf16 v[100:103], v[204:207], v[156:159], v[100:103]
	v_mfma_f32_16x16x32_bf16 v[92:95], v[214:217], v[156:159], v[92:95]
	v_mfma_f32_16x16x32_bf16 v[84:87], v[204:207], v[174:177], v[84:87]
	v_mfma_f32_16x16x32_bf16 v[76:79], v[214:217], v[174:177], v[76:79]
	v_mfma_f32_16x16x32_bf16 v[68:71], v[204:207], v[182:185], v[68:71]
	v_mfma_f32_16x16x32_bf16 v[64:67], v[214:217], v[182:185], v[64:67]
	s_barrier
	ds_read_b128 v[144:147], v189 offset:49152
	ds_read_b128 v[148:151], v189 offset:50176
	ds_read_b128 v[152:155], v189 offset:51200
	ds_read_b128 v[156:159], v189 offset:52224
	ds_read_b128 v[160:163], v189 offset:53248
	ds_read_b128 v[174:177], v189 offset:54272
	ds_read_b128 v[178:181], v189 offset:55296
	ds_read_b128 v[182:185], v189 offset:56320
	global_load_lds_dwordx4 v164, s[44:45]
	s_mov_b32 m0, s33
	s_nop 0
	global_load_lds_dwordx4 v166, s[44:45]
	s_barrier
	s_waitcnt lgkmcnt(0)
	v_mfma_f32_16x16x32_bf16 v[60:63], v[108:111], v[144:147], v[60:63]
	v_mfma_f32_16x16x32_bf16 v[56:59], v[116:119], v[144:147], v[56:59]
	s_add_u32 s8, s12, 0x160080
	v_mfma_f32_16x16x32_bf16 v[48:51], v[108:111], v[152:155], v[48:51]
	s_addc_u32 s9, s13, 0
	v_mfma_f32_16x16x32_bf16 v[40:43], v[116:119], v[152:155], v[40:43]
	s_add_i32 s12, s14, s19
	v_mfma_f32_16x16x32_bf16 v[32:35], v[108:111], v[160:163], v[32:35]
	s_mov_b32 m0, s12
	v_mfma_f32_16x16x32_bf16 v[24:27], v[116:119], v[160:163], v[24:27]
	v_mfma_f32_16x16x32_bf16 v[16:19], v[108:111], v[178:181], v[16:19]
	v_mfma_f32_16x16x32_bf16 v[8:11], v[116:119], v[178:181], v[8:11]
	v_mfma_f32_16x16x32_bf16 v[60:63], v[112:115], v[148:151], v[60:63]
	v_mfma_f32_16x16x32_bf16 v[56:59], v[120:123], v[148:151], v[56:59]
	v_mfma_f32_16x16x32_bf16 v[48:51], v[112:115], v[156:159], v[48:51]
	v_mfma_f32_16x16x32_bf16 v[40:43], v[120:123], v[156:159], v[40:43]
	v_mfma_f32_16x16x32_bf16 v[32:35], v[112:115], v[174:177], v[32:35]
	v_mfma_f32_16x16x32_bf16 v[24:27], v[120:123], v[174:177], v[24:27]
	v_mfma_f32_16x16x32_bf16 v[16:19], v[112:115], v[182:185], v[16:19]
	v_mfma_f32_16x16x32_bf16 v[8:11], v[120:123], v[182:185], v[8:11]
	s_barrier
	global_load_lds_dwordx4 v192, s[8:9]
	s_add_i32 m0, s12, 0x2000
	s_nop 0
	global_load_lds_dwordx4 v168, s[8:9]
	s_waitcnt vmcnt(6)
	s_barrier
	v_mfma_f32_16x16x32_bf16 v[52:55], v[196:199], v[144:147], v[52:55]
	v_mfma_f32_16x16x32_bf16 v[44:47], v[208:211], v[144:147], v[44:47]
	s_add_i32 s41, s41, 2
	v_mfma_f32_16x16x32_bf16 v[36:39], v[196:199], v[152:155], v[36:39]
	s_add_u32 s39, s39, 0x100
	v_mfma_f32_16x16x32_bf16 v[28:31], v[208:211], v[152:155], v[28:31]
	s_addc_u32 s40, s40, 0
	v_mfma_f32_16x16x32_bf16 v[20:23], v[196:199], v[160:163], v[20:23]
	s_mov_b64 s[8:9], s[10:11]
	v_mfma_f32_16x16x32_bf16 v[12:15], v[208:211], v[160:163], v[12:15]
	s_add_u32 s10, s8, 0x100
	s_addc_u32 s11, s9, 0
	v_mfma_f32_16x16x32_bf16 v[4:7], v[196:199], v[178:181], v[4:7]
	s_add_i32 s42, 0, 0x10000
	s_cmpk_eq_i32 s41, 0x54
	v_mfma_f32_16x16x32_bf16 v[0:3], v[208:211], v[178:181], v[0:3]
	s_cselect_b32 s15, s5, s11
	s_cselect_b32 s14, s4, s10
	v_mfma_f32_16x16x32_bf16 v[52:55], v[204:207], v[148:151], v[52:55]
	s_cselect_b32 s13, s7, s40
	s_cselect_b32 s12, s6, s39
	v_mfma_f32_16x16x32_bf16 v[44:47], v[214:217], v[148:151], v[44:47]
	s_add_i32 m0, s25, 0xc000
	v_mfma_f32_16x16x32_bf16 v[36:39], v[204:207], v[156:159], v[36:39]
	v_mfma_f32_16x16x32_bf16 v[28:31], v[214:217], v[156:159], v[28:31]
	v_mfma_f32_16x16x32_bf16 v[20:23], v[204:207], v[174:177], v[20:23]
	v_mfma_f32_16x16x32_bf16 v[12:15], v[214:217], v[174:177], v[12:15]
	v_mfma_f32_16x16x32_bf16 v[4:7], v[204:207], v[182:185], v[4:7]
	v_mfma_f32_16x16x32_bf16 v[0:3], v[214:217], v[182:185], v[0:3]
	s_cmpk_gt_u32 s41, 0x55
	s_barrier
	s_cbranch_scc0 .LBB0_272
	s_ashr_i32 s8, s37, 4
	v_lshl_or_b32 v144, s38, 8, v188
	s_mul_hi_i32 s9, s8, 0xc000
	s_mul_i32 s8, s8, 0xc000
	v_lshl_add_u32 v178, s37, 8, v186
	s_add_u32 s8, s29, s8
	v_ashrrev_i32_e32 v145, 31, v144
	v_ashrrev_i32_e32 v179, 31, v178
	s_addc_u32 s9, s30, s9
	v_lshlrev_b64 v[174:175], 2, v[144:145]
	v_lshl_add_u64 v[176:177], v[144:145], 1, s[2:3]
	v_lshlrev_b64 v[144:145], 12, v[178:179]
	v_lshl_add_u64 v[112:113], s[8:9], 0, v[174:175]
	v_lshl_add_u64 v[144:145], v[176:177], 0, v[144:145]
	global_load_dwordx4 v[116:119], v[112:113], off offset:16
	global_load_dwordx4 v[120:123], v[112:113], off
	global_load_dwordx4 v[108:111], v[112:113], off offset:528
	s_nop 0
	global_load_dwordx4 v[112:115], v[112:113], off offset:512
	s_nop 0
	global_load_dwordx4 v[196:199], v[144:145], off
	global_load_dwordx4 v[204:207], v[144:145], off offset:256
	v_or_b32_e32 v184, 16, v178
	v_ashrrev_i32_e32 v185, 31, v184
	v_lshlrev_b64 v[144:145], 12, v[184:185]
	v_lshl_add_u64 v[144:145], v[176:177], 0, v[144:145]
	global_load_dwordx4 v[208:211], v[144:145], off
	global_load_dwordx4 v[160:163], v[144:145], off offset:256
	v_or_b32_e32 v182, 32, v178
	v_ashrrev_i32_e32 v183, 31, v182
	v_lshlrev_b64 v[144:145], 12, v[182:183]
	v_lshl_add_u64 v[144:145], v[176:177], 0, v[144:145]
	global_load_dwordx4 v[156:159], v[144:145], off
	global_load_dwordx4 v[152:155], v[144:145], off offset:256
	v_or_b32_e32 v180, 48, v178
	v_ashrrev_i32_e32 v181, 31, v180
	v_lshlrev_b64 v[144:145], 12, v[180:181]
	v_lshl_add_u64 v[144:145], v[176:177], 0, v[144:145]
	global_load_dwordx4 v[148:151], v[144:145], off
	s_nop 0
	global_load_dwordx4 v[144:147], v[144:145], off offset:256
	v_readlane_b32 s52, v254, 39
	v_readlane_b32 s66, v254, 53
	v_readlane_b32 s67, v254, 54
	s_and_b64 vcc, exec, s[0:1]
	s_mov_b32 s38, s35
	s_mov_b32 s37, s36
	s_mov_b64 s[10:11], s[6:7]
	s_mov_b64 s[8:9], s[4:5]
	v_readlane_b32 s14, v254, 21
	s_movk_i32 s15, 0x2000
	v_readlane_b32 s53, v254, 40
	v_readlane_b32 s54, v254, 41
	v_readlane_b32 s55, v254, 42
	v_readlane_b32 s56, v254, 43
	v_readlane_b32 s57, v254, 44
	v_readlane_b32 s58, v254, 45
	v_readlane_b32 s59, v254, 46
	v_readlane_b32 s60, v254, 47
	v_readlane_b32 s61, v254, 48
	v_readlane_b32 s62, v254, 49
	v_readlane_b32 s63, v254, 50
	v_readlane_b32 s64, v254, 51
	v_readlane_b32 s65, v254, 52
	s_waitcnt vmcnt(0)
	v_lshlrev_b32_e32 v190, 16, v196
	v_and_b32_e32 v191, 0xffff0000, v196
	v_pk_fma_f32 v[140:141], v[140:141], v[120:121], v[190:191]
	v_lshlrev_b64 v[190:191], 13, v[178:179]
	v_lshlrev_b32_e32 v196, 16, v197
	v_and_b32_e32 v197, 0xffff0000, v197
	v_lshl_add_u64 v[190:191], s[66:67], 0, v[190:191]
	v_pk_fma_f32 v[142:143], v[142:143], v[122:123], v[196:197]
	v_lshl_add_u64 v[190:191], v[190:191], 0, v[174:175]
	global_store_dwordx4 v[190:191], v[140:143], off
	v_lshlrev_b32_e32 v214, 16, v198
	v_and_b32_e32 v215, 0xffff0000, v198
	v_lshlrev_b32_e32 v140, 16, v206
	v_and_b32_e32 v141, 0xffff0000, v206
	v_lshlrev_b32_e32 v142, 16, v207
	v_and_b32_e32 v143, 0xffff0000, v207
	v_pk_fma_f32 v[126:127], v[126:127], v[110:111], v[142:143]
	v_pk_fma_f32 v[124:125], v[124:125], v[108:109], v[140:141]
	global_store_dwordx4 v[190:191], v[124:127], off offset:528
	v_lshlrev_b32_e32 v198, 16, v199
	v_and_b32_e32 v199, 0xffff0000, v199
	v_lshlrev_b32_e32 v124, 16, v208
	v_and_b32_e32 v125, 0xffff0000, v208
	v_pk_fma_f32 v[124:125], v[132:133], v[120:121], v[124:125]
	v_lshlrev_b64 v[132:133], 13, v[184:185]
	v_lshlrev_b32_e32 v126, 16, v209
	v_and_b32_e32 v127, 0xffff0000, v209
	v_lshl_add_u64 v[132:133], s[66:67], 0, v[132:133]
	v_pk_fma_f32 v[126:127], v[134:135], v[122:123], v[126:127]
	v_lshl_add_u64 v[132:133], v[132:133], 0, v[174:175]
	v_pk_fma_f32 v[138:139], v[138:139], v[118:119], v[198:199]
	v_pk_fma_f32 v[136:137], v[136:137], v[116:117], v[214:215]
	global_store_dwordx4 v[132:133], v[124:127], off
	global_store_dwordx4 v[190:191], v[136:139], off offset:16
	s_nop 0
	v_lshlrev_b32_e32 v124, 16, v162
	v_and_b32_e32 v125, 0xffff0000, v162
	v_lshlrev_b32_e32 v126, 16, v163
	v_and_b32_e32 v127, 0xffff0000, v163
	v_lshlrev_b32_e32 v136, 16, v204
	v_and_b32_e32 v137, 0xffff0000, v204
	v_lshlrev_b32_e32 v138, 16, v205
	v_and_b32_e32 v139, 0xffff0000, v205
	v_pk_fma_f32 v[94:95], v[94:95], v[110:111], v[126:127]
	v_pk_fma_f32 v[92:93], v[92:93], v[108:109], v[124:125]
	v_pk_fma_f32 v[130:131], v[130:131], v[114:115], v[138:139]
	v_pk_fma_f32 v[128:129], v[128:129], v[112:113], v[136:137]
	global_store_dwordx4 v[132:133], v[92:95], off offset:528
	global_store_dwordx4 v[190:191], v[128:131], off offset:512
	s_nop 0
	v_lshlrev_b32_e32 v92, 16, v156
	v_and_b32_e32 v93, 0xffff0000, v156
	v_lshlrev_b32_e32 v128, 16, v210
	v_and_b32_e32 v129, 0xffff0000, v210
	v_lshlrev_b32_e32 v130, 16, v211
	v_and_b32_e32 v131, 0xffff0000, v211
	v_pk_fma_f32 v[92:93], v[96:97], v[120:121], v[92:93]
	v_lshlrev_b64 v[96:97], 13, v[182:183]
	v_pk_fma_f32 v[106:107], v[106:107], v[118:119], v[130:131]
	v_pk_fma_f32 v[104:105], v[104:105], v[116:117], v[128:129]
	v_lshlrev_b32_e32 v94, 16, v157
	v_and_b32_e32 v95, 0xffff0000, v157
	v_lshl_add_u64 v[96:97], s[66:67], 0, v[96:97]
	global_store_dwordx4 v[132:133], v[104:107], off offset:16
	v_pk_fma_f32 v[94:95], v[98:99], v[122:123], v[94:95]
	v_lshl_add_u64 v[96:97], v[96:97], 0, v[174:175]
	v_lshlrev_b32_e32 v104, 16, v160
	v_and_b32_e32 v105, 0xffff0000, v160
	v_lshlrev_b32_e32 v106, 16, v161
	v_and_b32_e32 v107, 0xffff0000, v161
	v_pk_fma_f32 v[102:103], v[102:103], v[114:115], v[106:107]
	v_pk_fma_f32 v[100:101], v[100:101], v[112:113], v[104:105]
	global_store_dwordx4 v[96:97], v[92:95], off
	global_store_dwordx4 v[132:133], v[100:103], off offset:512
	v_add_u32_e32 v98, 0x90, v178
	v_lshlrev_b32_e32 v92, 16, v154
	v_and_b32_e32 v93, 0xffff0000, v154
	v_lshlrev_b32_e32 v94, 16, v155
	v_and_b32_e32 v95, 0xffff0000, v155
	v_lshlrev_b32_e32 v100, 16, v158
	v_and_b32_e32 v101, 0xffff0000, v158
	v_lshlrev_b32_e32 v102, 16, v159
	v_and_b32_e32 v103, 0xffff0000, v159
	v_pk_fma_f32 v[78:79], v[78:79], v[110:111], v[94:95]
	v_pk_fma_f32 v[76:77], v[76:77], v[108:109], v[92:93]
	v_pk_fma_f32 v[90:91], v[90:91], v[118:119], v[102:103]
	v_pk_fma_f32 v[88:89], v[88:89], v[116:117], v[100:101]
	global_store_dwordx4 v[96:97], v[76:79], off offset:528
	global_store_dwordx4 v[96:97], v[88:91], off offset:16
	v_ashrrev_i32_e32 v99, 31, v98
	v_lshlrev_b32_e32 v76, 16, v148
	v_and_b32_e32 v77, 0xffff0000, v148
	v_lshlrev_b32_e32 v88, 16, v152
	v_and_b32_e32 v89, 0xffff0000, v152
	v_lshlrev_b32_e32 v90, 16, v153
	v_and_b32_e32 v91, 0xffff0000, v153
	v_pk_fma_f32 v[76:77], v[80:81], v[120:121], v[76:77]
	v_lshlrev_b64 v[80:81], 13, v[180:181]
	v_pk_fma_f32 v[86:87], v[86:87], v[114:115], v[90:91]
	v_pk_fma_f32 v[84:85], v[84:85], v[112:113], v[88:89]
	v_lshlrev_b32_e32 v78, 16, v149
	v_and_b32_e32 v79, 0xffff0000, v149
	v_lshl_add_u64 v[80:81], s[66:67], 0, v[80:81]
	global_store_dwordx4 v[96:97], v[84:87], off offset:512
	v_pk_fma_f32 v[78:79], v[82:83], v[122:123], v[78:79]
	v_lshl_add_u64 v[80:81], v[80:81], 0, v[174:175]
	v_lshlrev_b32_e32 v84, 16, v150
	v_and_b32_e32 v85, 0xffff0000, v150
	v_lshlrev_b32_e32 v86, 16, v151
	v_and_b32_e32 v87, 0xffff0000, v151
	global_store_dwordx4 v[80:81], v[76:79], off
	v_pk_fma_f32 v[74:75], v[74:75], v[118:119], v[86:87]
	v_pk_fma_f32 v[72:73], v[72:73], v[116:117], v[84:85]
	v_lshlrev_b32_e32 v76, 16, v146
	v_and_b32_e32 v77, 0xffff0000, v146
	v_lshlrev_b32_e32 v78, 16, v147
	v_and_b32_e32 v79, 0xffff0000, v147
	v_add_u32_e32 v96, 0x80, v178
	global_store_dwordx4 v[80:81], v[72:75], off offset:16
	v_pk_fma_f32 v[66:67], v[66:67], v[110:111], v[78:79]
	v_pk_fma_f32 v[64:65], v[64:65], v[108:109], v[76:77]
	v_lshlrev_b32_e32 v72, 16, v144
	v_and_b32_e32 v73, 0xffff0000, v144
	v_lshlrev_b32_e32 v74, 16, v145
	v_and_b32_e32 v75, 0xffff0000, v145
	v_ashrrev_i32_e32 v97, 31, v96
	v_pk_fma_f32 v[70:71], v[70:71], v[114:115], v[74:75]
	v_pk_fma_f32 v[68:69], v[68:69], v[112:113], v[72:73]
	global_store_dwordx4 v[80:81], v[64:67], off offset:528
	global_store_dwordx4 v[80:81], v[68:71], off offset:512
	v_add_u32_e32 v100, 0xa0, v178
	v_lshlrev_b64 v[64:65], 12, v[96:97]
	v_lshl_add_u64 v[64:65], v[176:177], 0, v[64:65]
	global_load_dwordx4 v[68:71], v[64:65], off
	global_load_dwordx4 v[72:75], v[64:65], off offset:256
	v_lshlrev_b64 v[64:65], 12, v[98:99]
	v_lshl_add_u64 v[64:65], v[176:177], 0, v[64:65]
	global_load_dwordx4 v[76:79], v[64:65], off
	global_load_dwordx4 v[80:83], v[64:65], off offset:256
	v_ashrrev_i32_e32 v101, 31, v100
	v_lshlrev_b64 v[64:65], 12, v[100:101]
	v_lshl_add_u64 v[64:65], v[176:177], 0, v[64:65]
	global_load_dwordx4 v[84:87], v[64:65], off
	global_load_dwordx4 v[88:91], v[64:65], off offset:256
	v_add_u32_e32 v102, 0xb0, v178
	v_ashrrev_i32_e32 v103, 31, v102
	v_lshlrev_b64 v[64:65], 12, v[102:103]
	v_lshl_add_u64 v[64:65], v[176:177], 0, v[64:65]
	global_load_dwordx4 v[92:95], v[64:65], off
	s_nop 0
	global_load_dwordx4 v[64:67], v[64:65], off offset:256
	s_waitcnt vmcnt(0)
	v_lshlrev_b32_e32 v104, 16, v68
	v_and_b32_e32 v105, 0xffff0000, v68
	v_lshlrev_b32_e32 v68, 16, v69
	v_and_b32_e32 v69, 0xffff0000, v69
	v_pk_fma_f32 v[62:63], v[62:63], v[122:123], v[68:69]
	v_lshlrev_b64 v[68:69], 13, v[96:97]
	v_lshl_add_u64 v[68:69], s[66:67], 0, v[68:69]
	v_pk_fma_f32 v[60:61], v[60:61], v[120:121], v[104:105]
	v_lshl_add_u64 v[68:69], v[68:69], 0, v[174:175]
	global_store_dwordx4 v[68:69], v[60:63], off
	v_lshlrev_b32_e32 v106, 16, v70
	v_and_b32_e32 v107, 0xffff0000, v70
	v_lshlrev_b32_e32 v60, 16, v74
	v_and_b32_e32 v61, 0xffff0000, v74
	v_lshlrev_b32_e32 v62, 16, v75
	v_and_b32_e32 v63, 0xffff0000, v75
	v_pk_fma_f32 v[46:47], v[46:47], v[110:111], v[62:63]
	v_pk_fma_f32 v[44:45], v[44:45], v[108:109], v[60:61]
	global_store_dwordx4 v[68:69], v[44:47], off offset:528
	v_lshlrev_b32_e32 v70, 16, v71
	v_and_b32_e32 v71, 0xffff0000, v71
	v_lshlrev_b32_e32 v44, 16, v76
	v_and_b32_e32 v45, 0xffff0000, v76
	v_pk_fma_f32 v[44:45], v[48:49], v[120:121], v[44:45]
	v_lshlrev_b64 v[48:49], 13, v[98:99]
	v_lshlrev_b32_e32 v46, 16, v77
	v_and_b32_e32 v47, 0xffff0000, v77
	v_lshl_add_u64 v[48:49], s[66:67], 0, v[48:49]
	v_pk_fma_f32 v[58:59], v[58:59], v[118:119], v[70:71]
	v_pk_fma_f32 v[56:57], v[56:57], v[116:117], v[106:107]
	v_pk_fma_f32 v[46:47], v[50:51], v[122:123], v[46:47]
	v_lshl_add_u64 v[48:49], v[48:49], 0, v[174:175]
	global_store_dwordx4 v[68:69], v[56:59], off offset:16
	global_store_dwordx4 v[48:49], v[44:47], off
	s_nop 0
	v_lshlrev_b32_e32 v56, 16, v72
	v_and_b32_e32 v57, 0xffff0000, v72
	v_lshlrev_b32_e32 v58, 16, v73
	v_and_b32_e32 v59, 0xffff0000, v73
	v_lshlrev_b32_e32 v44, 16, v82
	v_and_b32_e32 v45, 0xffff0000, v82
	v_lshlrev_b32_e32 v46, 16, v83
	v_and_b32_e32 v47, 0xffff0000, v83
	v_pk_fma_f32 v[54:55], v[54:55], v[114:115], v[58:59]
	v_pk_fma_f32 v[52:53], v[52:53], v[112:113], v[56:57]
	v_pk_fma_f32 v[30:31], v[30:31], v[110:111], v[46:47]
	v_pk_fma_f32 v[28:29], v[28:29], v[108:109], v[44:45]
	global_store_dwordx4 v[68:69], v[52:55], off offset:512
	global_store_dwordx4 v[48:49], v[28:31], off offset:528
	s_nop 0
	v_lshlrev_b32_e32 v52, 16, v78
	v_and_b32_e32 v53, 0xffff0000, v78
	v_lshlrev_b32_e32 v54, 16, v79
	v_and_b32_e32 v55, 0xffff0000, v79
	v_lshlrev_b32_e32 v28, 16, v84
	v_and_b32_e32 v29, 0xffff0000, v84
	v_pk_fma_f32 v[42:43], v[42:43], v[118:119], v[54:55]
	v_pk_fma_f32 v[40:41], v[40:41], v[116:117], v[52:53]
	v_pk_fma_f32 v[28:29], v[32:33], v[120:121], v[28:29]
	v_lshlrev_b64 v[32:33], 13, v[100:101]
	global_store_dwordx4 v[48:49], v[40:43], off offset:16
	v_lshlrev_b32_e32 v30, 16, v85
	v_and_b32_e32 v31, 0xffff0000, v85
	v_lshlrev_b32_e32 v40, 16, v80
	v_and_b32_e32 v41, 0xffff0000, v80
	v_lshlrev_b32_e32 v42, 16, v81
	v_and_b32_e32 v43, 0xffff0000, v81
	v_lshl_add_u64 v[32:33], s[66:67], 0, v[32:33]
	v_pk_fma_f32 v[38:39], v[38:39], v[114:115], v[42:43]
	v_pk_fma_f32 v[36:37], v[36:37], v[112:113], v[40:41]
	v_pk_fma_f32 v[30:31], v[34:35], v[122:123], v[30:31]
	v_lshl_add_u64 v[32:33], v[32:33], 0, v[174:175]
	global_store_dwordx4 v[48:49], v[36:39], off offset:512
	global_store_dwordx4 v[32:33], v[28:31], off
	s_nop 0
	v_lshlrev_b32_e32 v36, 16, v86
	v_and_b32_e32 v37, 0xffff0000, v86
	v_lshlrev_b32_e32 v38, 16, v87
	v_and_b32_e32 v39, 0xffff0000, v87
	v_lshlrev_b32_e32 v28, 16, v90
	v_and_b32_e32 v29, 0xffff0000, v90
	v_lshlrev_b32_e32 v30, 16, v91
	v_and_b32_e32 v31, 0xffff0000, v91
	v_pk_fma_f32 v[26:27], v[26:27], v[118:119], v[38:39]
	v_pk_fma_f32 v[24:25], v[24:25], v[116:117], v[36:37]
	v_pk_fma_f32 v[14:15], v[14:15], v[110:111], v[30:31]
	v_pk_fma_f32 v[12:13], v[12:13], v[108:109], v[28:29]
	global_store_dwordx4 v[32:33], v[24:27], off offset:16
	global_store_dwordx4 v[32:33], v[12:15], off offset:528
	s_nop 0
	v_lshlrev_b32_e32 v24, 16, v88
	v_and_b32_e32 v25, 0xffff0000, v88
	v_lshlrev_b32_e32 v26, 16, v89
	v_and_b32_e32 v27, 0xffff0000, v89
	v_lshlrev_b32_e32 v12, 16, v92
	v_and_b32_e32 v13, 0xffff0000, v92
	v_pk_fma_f32 v[22:23], v[22:23], v[114:115], v[26:27]
	v_pk_fma_f32 v[20:21], v[20:21], v[112:113], v[24:25]
	v_pk_fma_f32 v[12:13], v[16:17], v[120:121], v[12:13]
	v_lshlrev_b64 v[16:17], 13, v[102:103]
	global_store_dwordx4 v[32:33], v[20:23], off offset:512
	v_lshlrev_b32_e32 v14, 16, v93
	v_and_b32_e32 v15, 0xffff0000, v93
	v_lshlrev_b32_e32 v20, 16, v94
	v_and_b32_e32 v21, 0xffff0000, v94
	v_lshlrev_b32_e32 v22, 16, v95
	v_and_b32_e32 v23, 0xffff0000, v95
	v_lshl_add_u64 v[16:17], s[66:67], 0, v[16:17]
	v_pk_fma_f32 v[14:15], v[18:19], v[122:123], v[14:15]
	v_lshl_add_u64 v[16:17], v[16:17], 0, v[174:175]
	v_pk_fma_f32 v[10:11], v[10:11], v[118:119], v[22:23]
	v_pk_fma_f32 v[8:9], v[8:9], v[116:117], v[20:21]
	global_store_dwordx4 v[16:17], v[12:15], off
	global_store_dwordx4 v[16:17], v[8:11], off offset:16
	s_nop 0
	v_lshlrev_b32_e32 v12, 16, v66
	v_lshlrev_b32_e32 v8, 16, v64
	v_and_b32_e32 v9, 0xffff0000, v64
	v_lshlrev_b32_e32 v10, 16, v65
	v_and_b32_e32 v11, 0xffff0000, v65
	v_and_b32_e32 v13, 0xffff0000, v66
	v_lshlrev_b32_e32 v14, 16, v67
	v_and_b32_e32 v15, 0xffff0000, v67
	v_pk_fma_f32 v[6:7], v[6:7], v[114:115], v[10:11]
	v_pk_fma_f32 v[4:5], v[4:5], v[112:113], v[8:9]
	v_pk_fma_f32 v[2:3], v[2:3], v[110:111], v[14:15]
	v_pk_fma_f32 v[0:1], v[0:1], v[108:109], v[12:13]
	global_store_dwordx4 v[16:17], v[4:7], off offset:512
	global_store_dwordx4 v[16:17], v[0:3], off offset:528
	s_cbranch_vccz .LBB0_261
	s_waitcnt vmcnt(0)
	s_cmpk_gt_u32 s16, 0xff
	s_cbranch_scc1 .LBB0_276
	s_barrier

.LBB0_293:
	v_mov_b64_e32 v[0:1], 0x400
	s_ashr_i32 s7, s6, 31
	v_cmp_lt_i64_e32 vcc, s[8:9], v[0:1]
	s_lshl_b64 s[8:9], s[6:7], 20
	s_add_u32 s8, s20, s8
	s_addc_u32 s9, s21, s9
	s_and_b64 s[10:11], vcc, exec
	s_cselect_b32 s7, s9, s15
	s_cselect_b32 s38, s8, s14
	s_ashr_i32 s5, s4, 31
	s_lshl_b64 s[10:11], s[4:5], 20
	s_add_u32 s10, s22, s10
	s_addc_u32 s11, s23, s11
	s_and_b64 s[18:19], vcc, exec
	s_cselect_b32 s5, s11, s17
	s_cselect_b32 s39, s10, s16
	s_add_u32 s14, s14, 0x80080
	s_addc_u32 s15, s15, 0
	s_add_u32 s40, s16, 0x100
	s_addc_u32 s41, s17, 0
	s_mov_b32 s42, -2
	s_mov_b64 s[48:49], 0x80
	v_add_u32_e32 v220, 0x10000, v159
	s_add_u32 s16, s14, 0xfff80080
	s_addc_u32 s17, s15, -1
	s_add_i32 s43, 0, 0x10000
	ds_read_b128 v[64:67], v220 offset:0
	ds_read_b128 v[68:71], v220 offset:1024
	ds_read_b128 v[72:75], v220 offset:2048
	ds_read_b128 v[76:79], v220 offset:3072
	s_cmp_eq_u32 s42, 28
	s_cselect_b32 s19, s7, s17
	s_cselect_b32 s18, s38, s16
	s_cselect_b32 s17, s5, s41
	s_cselect_b32 s16, s39, s40
	s_add_i32 m0, s13, 0xc000
	ds_read_b128 v[154:157], v161
	ds_read_b128 v[162:165], v161 offset:1024
	ds_read_b128 v[166:169], v161 offset:2048
	ds_read_b128 v[170:173], v161 offset:3072
	ds_read_b128 v[174:177], v161 offset:4096
	ds_read_b128 v[178:181], v161 offset:5120
	ds_read_b128 v[182:185], v161 offset:6144
	ds_read_b128 v[186:189], v161 offset:7168
	global_load_lds_dwordx4 v150, s[14:15]
	s_add_i32 m0, s13, 0xe000
	s_nop 0
	global_load_lds_dwordx4 v152, s[14:15]
	s_waitcnt lgkmcnt(8)
	s_barrier
	s_waitcnt lgkmcnt(0)
	v_mfma_f32_16x16x32_bf16 v[140:143], v[64:67], v[154:157], 0
	v_mfma_f32_16x16x32_bf16 v[136:139], v[72:75], v[154:157], 0
	s_add_i32 s46, 0, 0x14000
	v_mfma_f32_16x16x32_bf16 v[132:135], v[64:67], v[166:169], 0
	s_add_i32 s43, s43, s27
	v_mfma_f32_16x16x32_bf16 v[128:131], v[72:75], v[166:169], 0
	s_mov_b32 m0, s43
	v_mfma_f32_16x16x32_bf16 v[108:111], v[64:67], v[174:177], 0
	v_mfma_f32_16x16x32_bf16 v[104:107], v[72:75], v[174:177], 0
	v_mfma_f32_16x16x32_bf16 v[100:103], v[64:67], v[182:185], 0
	v_mfma_f32_16x16x32_bf16 v[96:99], v[72:75], v[182:185], 0
	v_mfma_f32_16x16x32_bf16 v[140:143], v[68:71], v[162:165], v[140:143]
	v_mfma_f32_16x16x32_bf16 v[136:139], v[76:79], v[162:165], v[136:139]
	v_mfma_f32_16x16x32_bf16 v[132:135], v[68:71], v[170:173], v[132:135]
	v_mfma_f32_16x16x32_bf16 v[128:131], v[76:79], v[170:173], v[128:131]
	v_mfma_f32_16x16x32_bf16 v[108:111], v[68:71], v[178:181], v[108:111]
	v_mfma_f32_16x16x32_bf16 v[104:107], v[76:79], v[178:181], v[104:107]
	v_mfma_f32_16x16x32_bf16 v[100:103], v[68:71], v[186:189], v[100:103]
	v_mfma_f32_16x16x32_bf16 v[96:99], v[76:79], v[186:189], v[96:99]
	s_barrier
	ds_read_b128 v[196:199], v220 offset:16384
	ds_read_b128 v[204:207], v220 offset:17408
	ds_read_b128 v[208:211], v220 offset:18432
	ds_read_b128 v[214:217], v220 offset:19456
	global_load_lds_dwordx4 v192, s[16:17]
	s_add_i32 m0, s43, 0x2000
	s_nop 0
	global_load_lds_dwordx4 v148, s[16:17]
	s_barrier
	s_waitcnt lgkmcnt(0)
	v_mfma_f32_16x16x32_bf16 v[124:127], v[196:199], v[154:157], 0
	v_mfma_f32_16x16x32_bf16 v[120:123], v[208:211], v[154:157], 0
	s_mov_b32 m0, s13
	v_mfma_f32_16x16x32_bf16 v[116:119], v[196:199], v[166:169], 0
	s_add_u32 s48, s18, 0x80
	v_mfma_f32_16x16x32_bf16 v[112:115], v[208:211], v[166:169], 0
	s_addc_u32 s49, s19, 0
	v_mfma_f32_16x16x32_bf16 v[92:95], v[196:199], v[174:177], 0
	v_mfma_f32_16x16x32_bf16 v[88:91], v[208:211], v[174:177], 0
	v_mfma_f32_16x16x32_bf16 v[84:87], v[196:199], v[182:185], 0
	v_mfma_f32_16x16x32_bf16 v[80:83], v[208:211], v[182:185], 0
	v_mfma_f32_16x16x32_bf16 v[124:127], v[204:207], v[162:165], v[124:127]
	v_mfma_f32_16x16x32_bf16 v[120:123], v[214:217], v[162:165], v[120:123]
	v_mfma_f32_16x16x32_bf16 v[116:119], v[204:207], v[170:173], v[116:119]
	v_mfma_f32_16x16x32_bf16 v[112:115], v[214:217], v[170:173], v[112:115]
	v_mfma_f32_16x16x32_bf16 v[92:95], v[204:207], v[178:181], v[92:95]
	v_mfma_f32_16x16x32_bf16 v[88:91], v[214:217], v[178:181], v[88:91]
	v_mfma_f32_16x16x32_bf16 v[84:87], v[204:207], v[186:189], v[84:87]
	v_mfma_f32_16x16x32_bf16 v[80:83], v[214:217], v[186:189], v[80:83]
	s_barrier
	ds_read_b128 v[154:157], v161 offset:16384
	ds_read_b128 v[162:165], v161 offset:17408
	ds_read_b128 v[166:169], v161 offset:18432
	ds_read_b128 v[170:173], v161 offset:19456
	ds_read_b128 v[174:177], v161 offset:20480
	ds_read_b128 v[178:181], v161 offset:21504
	ds_read_b128 v[182:185], v161 offset:22528
	ds_read_b128 v[186:189], v161 offset:23552
	global_load_lds_dwordx4 v144, s[18:19]
	s_mov_b32 m0, s28
	s_nop 0
	global_load_lds_dwordx4 v146, s[18:19]
	s_barrier
	s_waitcnt lgkmcnt(0)
	v_mfma_f32_16x16x32_bf16 v[60:63], v[64:67], v[154:157], 0
	v_mfma_f32_16x16x32_bf16 v[56:59], v[72:75], v[154:157], 0
	s_add_u32 s44, s16, 0x80000
	v_mfma_f32_16x16x32_bf16 v[52:55], v[64:67], v[166:169], 0
	s_addc_u32 s45, s17, 0
	v_mfma_f32_16x16x32_bf16 v[48:51], v[72:75], v[166:169], 0
	s_add_i32 s43, s46, s27
	v_mfma_f32_16x16x32_bf16 v[28:31], v[64:67], v[174:177], 0
	s_mov_b32 m0, s43
	v_mfma_f32_16x16x32_bf16 v[24:27], v[72:75], v[174:177], 0
	v_mfma_f32_16x16x32_bf16 v[20:23], v[64:67], v[182:185], 0
	v_mfma_f32_16x16x32_bf16 v[16:19], v[72:75], v[182:185], 0
	v_mfma_f32_16x16x32_bf16 v[60:63], v[68:71], v[162:165], v[60:63]
	v_mfma_f32_16x16x32_bf16 v[56:59], v[76:79], v[162:165], v[56:59]
	v_mfma_f32_16x16x32_bf16 v[52:55], v[68:71], v[170:173], v[52:55]
	v_mfma_f32_16x16x32_bf16 v[48:51], v[76:79], v[170:173], v[48:51]
	v_mfma_f32_16x16x32_bf16 v[28:31], v[68:71], v[178:181], v[28:31]
	v_mfma_f32_16x16x32_bf16 v[24:27], v[76:79], v[178:181], v[24:27]
	v_mfma_f32_16x16x32_bf16 v[20:23], v[68:71], v[186:189], v[20:23]
	v_mfma_f32_16x16x32_bf16 v[16:19], v[76:79], v[186:189], v[16:19]
	s_barrier
	global_load_lds_dwordx4 v192, s[44:45]
	s_add_i32 m0, s43, 0x2000
	s_nop 0
	global_load_lds_dwordx4 v148, s[44:45]
	s_waitcnt vmcnt(6)
	s_barrier
	v_mfma_f32_16x16x32_bf16 v[44:47], v[196:199], v[154:157], 0
	v_mfma_f32_16x16x32_bf16 v[40:43], v[208:211], v[154:157], 0
	s_add_i32 s43, 0, 0x18000
	v_mfma_f32_16x16x32_bf16 v[36:39], v[196:199], v[166:169], 0
	s_add_u32 s18, s18, 0x80000
	v_mfma_f32_16x16x32_bf16 v[32:35], v[208:211], v[166:169], 0
	s_addc_u32 s19, s19, 0
	v_mfma_f32_16x16x32_bf16 v[12:15], v[196:199], v[174:177], 0
	s_mov_b32 m0, s29
	v_mfma_f32_16x16x32_bf16 v[8:11], v[208:211], v[174:177], 0
	v_mfma_f32_16x16x32_bf16 v[4:7], v[196:199], v[182:185], 0
	v_mfma_f32_16x16x32_bf16 v[0:3], v[208:211], v[182:185], 0
	v_mfma_f32_16x16x32_bf16 v[44:47], v[204:207], v[162:165], v[44:47]
	v_mfma_f32_16x16x32_bf16 v[40:43], v[214:217], v[162:165], v[40:43]
	v_mfma_f32_16x16x32_bf16 v[36:39], v[204:207], v[170:173], v[36:39]
	v_mfma_f32_16x16x32_bf16 v[32:35], v[214:217], v[170:173], v[32:35]
	v_mfma_f32_16x16x32_bf16 v[12:15], v[204:207], v[178:181], v[12:15]
	v_mfma_f32_16x16x32_bf16 v[8:11], v[214:217], v[178:181], v[8:11]
	v_mfma_f32_16x16x32_bf16 v[4:7], v[204:207], v[186:189], v[4:7]
	v_mfma_f32_16x16x32_bf16 v[0:3], v[214:217], v[186:189], v[0:3]
	s_barrier
	ds_read_b128 v[64:67], v220 offset:32768
	ds_read_b128 v[68:71], v220 offset:33792
	ds_read_b128 v[72:75], v220 offset:34816
	ds_read_b128 v[76:79], v220 offset:35840
	ds_read_b128 v[154:157], v161 offset:32768
	ds_read_b128 v[162:165], v161 offset:33792
	ds_read_b128 v[166:169], v161 offset:34816
	ds_read_b128 v[170:173], v161 offset:35840
	ds_read_b128 v[174:177], v161 offset:36864
	ds_read_b128 v[178:181], v161 offset:37888
	ds_read_b128 v[182:185], v161 offset:38912
	ds_read_b128 v[186:189], v161 offset:39936
	global_load_lds_dwordx4 v144, s[18:19]
	s_mov_b32 m0, s30
	s_nop 0
	global_load_lds_dwordx4 v146, s[18:19]
	s_waitcnt lgkmcnt(8)
	s_barrier
	s_waitcnt lgkmcnt(0)
	v_mfma_f32_16x16x32_bf16 v[140:143], v[64:67], v[154:157], v[140:143]
	v_mfma_f32_16x16x32_bf16 v[136:139], v[72:75], v[154:157], v[136:139]
	s_add_i32 s18, 0, 0x1c000
	v_mfma_f32_16x16x32_bf16 v[132:135], v[64:67], v[166:169], v[132:135]
	s_add_i32 s19, s43, s27
	v_mfma_f32_16x16x32_bf16 v[128:131], v[72:75], v[166:169], v[128:131]
	s_add_i32 m0, s19, 0xffffff80
	v_mfma_f32_16x16x32_bf16 v[108:111], v[64:67], v[174:177], v[108:111]
	v_mfma_f32_16x16x32_bf16 v[104:107], v[72:75], v[174:177], v[104:107]
	v_mfma_f32_16x16x32_bf16 v[100:103], v[64:67], v[182:185], v[100:103]
	v_mfma_f32_16x16x32_bf16 v[96:99], v[72:75], v[182:185], v[96:99]
	v_mfma_f32_16x16x32_bf16 v[140:143], v[68:71], v[162:165], v[140:143]
	v_mfma_f32_16x16x32_bf16 v[136:139], v[76:79], v[162:165], v[136:139]
	v_mfma_f32_16x16x32_bf16 v[132:135], v[68:71], v[170:173], v[132:135]
	v_mfma_f32_16x16x32_bf16 v[128:131], v[76:79], v[170:173], v[128:131]
	v_mfma_f32_16x16x32_bf16 v[108:111], v[68:71], v[178:181], v[108:111]
	v_mfma_f32_16x16x32_bf16 v[104:107], v[76:79], v[178:181], v[104:107]
	v_mfma_f32_16x16x32_bf16 v[100:103], v[68:71], v[186:189], v[100:103]
	v_mfma_f32_16x16x32_bf16 v[96:99], v[76:79], v[186:189], v[96:99]
	s_barrier
	ds_read_b128 v[196:199], v220 offset:49152
	ds_read_b128 v[204:207], v220 offset:50176
	ds_read_b128 v[208:211], v220 offset:51200
	ds_read_b128 v[214:217], v220 offset:52224
	global_load_lds_dwordx4 v192, s[16:17] offset:128
	s_add_i32 m0, s19, 0x1f80
	s_nop 0
	global_load_lds_dwordx4 v148, s[16:17] offset:128
	s_barrier
	s_waitcnt lgkmcnt(0)
	v_mfma_f32_16x16x32_bf16 v[124:127], v[196:199], v[154:157], v[124:127]
	v_mfma_f32_16x16x32_bf16 v[120:123], v[208:211], v[154:157], v[120:123]
	s_mov_b32 m0, s34
	v_mfma_f32_16x16x32_bf16 v[116:119], v[196:199], v[166:169], v[116:119]
	v_mfma_f32_16x16x32_bf16 v[112:115], v[208:211], v[166:169], v[112:115]
	v_mfma_f32_16x16x32_bf16 v[92:95], v[196:199], v[174:177], v[92:95]
	v_mfma_f32_16x16x32_bf16 v[88:91], v[208:211], v[174:177], v[88:91]
	v_mfma_f32_16x16x32_bf16 v[84:87], v[196:199], v[182:185], v[84:87]
	v_mfma_f32_16x16x32_bf16 v[80:83], v[208:211], v[182:185], v[80:83]
	v_mfma_f32_16x16x32_bf16 v[124:127], v[204:207], v[162:165], v[124:127]
	v_mfma_f32_16x16x32_bf16 v[120:123], v[214:217], v[162:165], v[120:123]
	v_mfma_f32_16x16x32_bf16 v[116:119], v[204:207], v[170:173], v[116:119]
	v_mfma_f32_16x16x32_bf16 v[112:115], v[214:217], v[170:173], v[112:115]
	v_mfma_f32_16x16x32_bf16 v[92:95], v[204:207], v[178:181], v[92:95]
	v_mfma_f32_16x16x32_bf16 v[88:91], v[214:217], v[178:181], v[88:91]
	v_mfma_f32_16x16x32_bf16 v[84:87], v[204:207], v[186:189], v[84:87]
	v_mfma_f32_16x16x32_bf16 v[80:83], v[214:217], v[186:189], v[80:83]
	s_barrier
	ds_read_b128 v[154:157], v161 offset:49152
	ds_read_b128 v[162:165], v161 offset:50176
	ds_read_b128 v[166:169], v161 offset:51200
	ds_read_b128 v[170:173], v161 offset:52224
	ds_read_b128 v[174:177], v161 offset:53248
	ds_read_b128 v[178:181], v161 offset:54272
	ds_read_b128 v[182:185], v161 offset:55296
	ds_read_b128 v[186:189], v161 offset:56320
	global_load_lds_dwordx4 v144, s[48:49]
	s_mov_b32 m0, s35
	s_nop 0
	global_load_lds_dwordx4 v146, s[48:49]
	s_barrier
	s_waitcnt lgkmcnt(0)
	v_mfma_f32_16x16x32_bf16 v[60:63], v[64:67], v[154:157], v[60:63]
	v_mfma_f32_16x16x32_bf16 v[56:59], v[72:75], v[154:157], v[56:59]
	s_add_u32 s16, s16, 0x80080
	v_mfma_f32_16x16x32_bf16 v[52:55], v[64:67], v[166:169], v[52:55]
	s_addc_u32 s17, s17, 0
	v_mfma_f32_16x16x32_bf16 v[48:51], v[72:75], v[166:169], v[48:51]
	s_add_i32 s18, s18, s27
	v_mfma_f32_16x16x32_bf16 v[28:31], v[64:67], v[174:177], v[28:31]
	s_mov_b32 m0, s18
	v_mfma_f32_16x16x32_bf16 v[24:27], v[72:75], v[174:177], v[24:27]
	v_mfma_f32_16x16x32_bf16 v[20:23], v[64:67], v[182:185], v[20:23]
	v_mfma_f32_16x16x32_bf16 v[16:19], v[72:75], v[182:185], v[16:19]
	v_mfma_f32_16x16x32_bf16 v[60:63], v[68:71], v[162:165], v[60:63]
	v_mfma_f32_16x16x32_bf16 v[56:59], v[76:79], v[162:165], v[56:59]
	v_mfma_f32_16x16x32_bf16 v[52:55], v[68:71], v[170:173], v[52:55]
	v_mfma_f32_16x16x32_bf16 v[48:51], v[76:79], v[170:173], v[48:51]
	v_mfma_f32_16x16x32_bf16 v[28:31], v[68:71], v[178:181], v[28:31]
	v_mfma_f32_16x16x32_bf16 v[24:27], v[76:79], v[178:181], v[24:27]
	v_mfma_f32_16x16x32_bf16 v[20:23], v[68:71], v[186:189], v[20:23]
	v_mfma_f32_16x16x32_bf16 v[16:19], v[76:79], v[186:189], v[16:19]
	s_barrier
	global_load_lds_dwordx4 v192, s[16:17]
	s_add_i32 m0, s18, 0x2000
	s_nop 0
	global_load_lds_dwordx4 v148, s[16:17]
	s_waitcnt vmcnt(6)
	s_barrier
	v_mfma_f32_16x16x32_bf16 v[44:47], v[196:199], v[154:157], v[44:47]
	v_mfma_f32_16x16x32_bf16 v[40:43], v[208:211], v[154:157], v[40:43]
	s_add_i32 s42, s42, 2
	v_mfma_f32_16x16x32_bf16 v[36:39], v[196:199], v[166:169], v[36:39]
	s_add_u32 s14, s14, 0x100
	v_mfma_f32_16x16x32_bf16 v[32:35], v[208:211], v[166:169], v[32:35]
	s_addc_u32 s15, s15, 0
	v_mfma_f32_16x16x32_bf16 v[12:15], v[196:199], v[174:177], v[12:15]
	s_add_u32 s40, s40, 0x100
	v_mfma_f32_16x16x32_bf16 v[8:11], v[208:211], v[174:177], v[8:11]
	s_addc_u32 s41, s41, 0
	v_mfma_f32_16x16x32_bf16 v[4:7], v[196:199], v[182:185], v[4:7]
	s_add_u32 s16, s14, 0xfff80080
	s_addc_u32 s17, s15, -1
	v_mfma_f32_16x16x32_bf16 v[0:3], v[208:211], v[182:185], v[0:3]
	s_add_i32 s43, 0, 0x10000
	s_cmp_eq_u32 s42, 28
	v_mfma_f32_16x16x32_bf16 v[44:47], v[204:207], v[162:165], v[44:47]
	s_cselect_b32 s19, s7, s17
	s_cselect_b32 s18, s38, s16
	v_mfma_f32_16x16x32_bf16 v[40:43], v[214:217], v[162:165], v[40:43]
	s_cselect_b32 s17, s5, s41
	s_cselect_b32 s16, s39, s40
	v_mfma_f32_16x16x32_bf16 v[36:39], v[204:207], v[170:173], v[36:39]
	s_add_i32 m0, s13, 0xc000
	v_mfma_f32_16x16x32_bf16 v[32:35], v[214:217], v[170:173], v[32:35]
	v_mfma_f32_16x16x32_bf16 v[12:15], v[204:207], v[178:181], v[12:15]
	v_mfma_f32_16x16x32_bf16 v[8:11], v[214:217], v[178:181], v[8:11]
	v_mfma_f32_16x16x32_bf16 v[4:7], v[204:207], v[186:189], v[4:7]
	v_mfma_f32_16x16x32_bf16 v[0:3], v[214:217], v[186:189], v[0:3]
	s_cmp_gt_u32 s42, 29
	s_barrier
.LBB0_294:
	ds_read_b128 v[64:67], v220 offset:0
	ds_read_b128 v[68:71], v220 offset:1024
	ds_read_b128 v[72:75], v220 offset:2048
	ds_read_b128 v[76:79], v220 offset:3072
	ds_read_b128 v[154:157], v161
	ds_read_b128 v[162:165], v161 offset:1024
	ds_read_b128 v[166:169], v161 offset:2048
	ds_read_b128 v[170:173], v161 offset:3072
	ds_read_b128 v[174:177], v161 offset:4096
	ds_read_b128 v[178:181], v161 offset:5120
	ds_read_b128 v[182:185], v161 offset:6144
	ds_read_b128 v[186:189], v161 offset:7168
	global_load_lds_dwordx4 v150, s[14:15]
	s_add_i32 m0, s13, 0xe000
	s_nop 0
	global_load_lds_dwordx4 v152, s[14:15]
	s_waitcnt lgkmcnt(8)
	s_barrier
	s_waitcnt lgkmcnt(0)
	v_mfma_f32_16x16x32_bf16 v[140:143], v[64:67], v[154:157], v[140:143]
	v_mfma_f32_16x16x32_bf16 v[136:139], v[72:75], v[154:157], v[136:139]
	s_add_i32 s46, 0, 0x14000
	v_mfma_f32_16x16x32_bf16 v[132:135], v[64:67], v[166:169], v[132:135]
	s_add_i32 s43, s43, s27
	v_mfma_f32_16x16x32_bf16 v[128:131], v[72:75], v[166:169], v[128:131]
	s_mov_b32 m0, s43
	v_mfma_f32_16x16x32_bf16 v[108:111], v[64:67], v[174:177], v[108:111]
	v_mfma_f32_16x16x32_bf16 v[104:107], v[72:75], v[174:177], v[104:107]
	v_mfma_f32_16x16x32_bf16 v[100:103], v[64:67], v[182:185], v[100:103]
	v_mfma_f32_16x16x32_bf16 v[96:99], v[72:75], v[182:185], v[96:99]
	v_mfma_f32_16x16x32_bf16 v[140:143], v[68:71], v[162:165], v[140:143]
	v_mfma_f32_16x16x32_bf16 v[136:139], v[76:79], v[162:165], v[136:139]
	v_mfma_f32_16x16x32_bf16 v[132:135], v[68:71], v[170:173], v[132:135]
	v_mfma_f32_16x16x32_bf16 v[128:131], v[76:79], v[170:173], v[128:131]
	v_mfma_f32_16x16x32_bf16 v[108:111], v[68:71], v[178:181], v[108:111]
	v_mfma_f32_16x16x32_bf16 v[104:107], v[76:79], v[178:181], v[104:107]
	v_mfma_f32_16x16x32_bf16 v[100:103], v[68:71], v[186:189], v[100:103]
	v_mfma_f32_16x16x32_bf16 v[96:99], v[76:79], v[186:189], v[96:99]
	s_barrier
	ds_read_b128 v[196:199], v220 offset:16384
	ds_read_b128 v[204:207], v220 offset:17408
	ds_read_b128 v[208:211], v220 offset:18432
	ds_read_b128 v[214:217], v220 offset:19456
	global_load_lds_dwordx4 v192, s[16:17]
	s_add_i32 m0, s43, 0x2000
	s_nop 0
	global_load_lds_dwordx4 v148, s[16:17]
	s_barrier
	s_waitcnt lgkmcnt(0)
	v_mfma_f32_16x16x32_bf16 v[124:127], v[196:199], v[154:157], v[124:127]
	v_mfma_f32_16x16x32_bf16 v[120:123], v[208:211], v[154:157], v[120:123]
	s_mov_b32 m0, s13
	v_mfma_f32_16x16x32_bf16 v[116:119], v[196:199], v[166:169], v[116:119]
	s_add_u32 s48, s18, 0x80
	v_mfma_f32_16x16x32_bf16 v[112:115], v[208:211], v[166:169], v[112:115]
	s_addc_u32 s49, s19, 0
	v_mfma_f32_16x16x32_bf16 v[92:95], v[196:199], v[174:177], v[92:95]
	v_mfma_f32_16x16x32_bf16 v[88:91], v[208:211], v[174:177], v[88:91]
	v_mfma_f32_16x16x32_bf16 v[84:87], v[196:199], v[182:185], v[84:87]
	v_mfma_f32_16x16x32_bf16 v[80:83], v[208:211], v[182:185], v[80:83]
	v_mfma_f32_16x16x32_bf16 v[124:127], v[204:207], v[162:165], v[124:127]
	v_mfma_f32_16x16x32_bf16 v[120:123], v[214:217], v[162:165], v[120:123]
	v_mfma_f32_16x16x32_bf16 v[116:119], v[204:207], v[170:173], v[116:119]
	v_mfma_f32_16x16x32_bf16 v[112:115], v[214:217], v[170:173], v[112:115]
	v_mfma_f32_16x16x32_bf16 v[92:95], v[204:207], v[178:181], v[92:95]
	v_mfma_f32_16x16x32_bf16 v[88:91], v[214:217], v[178:181], v[88:91]
	v_mfma_f32_16x16x32_bf16 v[84:87], v[204:207], v[186:189], v[84:87]
	v_mfma_f32_16x16x32_bf16 v[80:83], v[214:217], v[186:189], v[80:83]
	s_barrier
	ds_read_b128 v[154:157], v161 offset:16384
	ds_read_b128 v[162:165], v161 offset:17408
	ds_read_b128 v[166:169], v161 offset:18432
	ds_read_b128 v[170:173], v161 offset:19456
	ds_read_b128 v[174:177], v161 offset:20480
	ds_read_b128 v[178:181], v161 offset:21504
	ds_read_b128 v[182:185], v161 offset:22528
	ds_read_b128 v[186:189], v161 offset:23552
	global_load_lds_dwordx4 v144, s[18:19]
	s_mov_b32 m0, s28
	s_nop 0
	global_load_lds_dwordx4 v146, s[18:19]
	s_barrier
	s_waitcnt lgkmcnt(0)
	v_mfma_f32_16x16x32_bf16 v[60:63], v[64:67], v[154:157], v[60:63]
	v_mfma_f32_16x16x32_bf16 v[56:59], v[72:75], v[154:157], v[56:59]
	s_add_u32 s44, s16, 0x80000
	v_mfma_f32_16x16x32_bf16 v[52:55], v[64:67], v[166:169], v[52:55]
	s_addc_u32 s45, s17, 0
	v_mfma_f32_16x16x32_bf16 v[48:51], v[72:75], v[166:169], v[48:51]
	s_add_i32 s43, s46, s27
	v_mfma_f32_16x16x32_bf16 v[28:31], v[64:67], v[174:177], v[28:31]
	s_mov_b32 m0, s43
	v_mfma_f32_16x16x32_bf16 v[24:27], v[72:75], v[174:177], v[24:27]
	v_mfma_f32_16x16x32_bf16 v[20:23], v[64:67], v[182:185], v[20:23]
	v_mfma_f32_16x16x32_bf16 v[16:19], v[72:75], v[182:185], v[16:19]
	v_mfma_f32_16x16x32_bf16 v[60:63], v[68:71], v[162:165], v[60:63]
	v_mfma_f32_16x16x32_bf16 v[56:59], v[76:79], v[162:165], v[56:59]
	v_mfma_f32_16x16x32_bf16 v[52:55], v[68:71], v[170:173], v[52:55]
	v_mfma_f32_16x16x32_bf16 v[48:51], v[76:79], v[170:173], v[48:51]
	v_mfma_f32_16x16x32_bf16 v[28:31], v[68:71], v[178:181], v[28:31]
	v_mfma_f32_16x16x32_bf16 v[24:27], v[76:79], v[178:181], v[24:27]
	v_mfma_f32_16x16x32_bf16 v[20:23], v[68:71], v[186:189], v[20:23]
	v_mfma_f32_16x16x32_bf16 v[16:19], v[76:79], v[186:189], v[16:19]
	s_barrier
	global_load_lds_dwordx4 v192, s[44:45]
	s_add_i32 m0, s43, 0x2000
	s_nop 0
	global_load_lds_dwordx4 v148, s[44:45]
	s_waitcnt vmcnt(6)
	s_barrier
	v_mfma_f32_16x16x32_bf16 v[44:47], v[196:199], v[154:157], v[44:47]
	v_mfma_f32_16x16x32_bf16 v[40:43], v[208:211], v[154:157], v[40:43]
	s_add_i32 s43, 0, 0x18000
	v_mfma_f32_16x16x32_bf16 v[36:39], v[196:199], v[166:169], v[36:39]
	s_add_u32 s18, s18, 0x80000
	v_mfma_f32_16x16x32_bf16 v[32:35], v[208:211], v[166:169], v[32:35]
	s_addc_u32 s19, s19, 0
	v_mfma_f32_16x16x32_bf16 v[12:15], v[196:199], v[174:177], v[12:15]
	s_mov_b32 m0, s29
	v_mfma_f32_16x16x32_bf16 v[8:11], v[208:211], v[174:177], v[8:11]
	v_mfma_f32_16x16x32_bf16 v[4:7], v[196:199], v[182:185], v[4:7]
	v_mfma_f32_16x16x32_bf16 v[0:3], v[208:211], v[182:185], v[0:3]
	v_mfma_f32_16x16x32_bf16 v[44:47], v[204:207], v[162:165], v[44:47]
	v_mfma_f32_16x16x32_bf16 v[40:43], v[214:217], v[162:165], v[40:43]
	v_mfma_f32_16x16x32_bf16 v[36:39], v[204:207], v[170:173], v[36:39]
	v_mfma_f32_16x16x32_bf16 v[32:35], v[214:217], v[170:173], v[32:35]
	v_mfma_f32_16x16x32_bf16 v[12:15], v[204:207], v[178:181], v[12:15]
	v_mfma_f32_16x16x32_bf16 v[8:11], v[214:217], v[178:181], v[8:11]
	v_mfma_f32_16x16x32_bf16 v[4:7], v[204:207], v[186:189], v[4:7]
	v_mfma_f32_16x16x32_bf16 v[0:3], v[214:217], v[186:189], v[0:3]
	s_barrier
	ds_read_b128 v[64:67], v220 offset:32768
	ds_read_b128 v[68:71], v220 offset:33792
	ds_read_b128 v[72:75], v220 offset:34816
	ds_read_b128 v[76:79], v220 offset:35840
	ds_read_b128 v[154:157], v161 offset:32768
	ds_read_b128 v[162:165], v161 offset:33792
	ds_read_b128 v[166:169], v161 offset:34816
	ds_read_b128 v[170:173], v161 offset:35840
	ds_read_b128 v[174:177], v161 offset:36864
	ds_read_b128 v[178:181], v161 offset:37888
	ds_read_b128 v[182:185], v161 offset:38912
	ds_read_b128 v[186:189], v161 offset:39936
	global_load_lds_dwordx4 v144, s[18:19]
	s_mov_b32 m0, s30
	s_nop 0
	global_load_lds_dwordx4 v146, s[18:19]
	s_waitcnt lgkmcnt(8)
	s_barrier
	s_waitcnt lgkmcnt(0)
	v_mfma_f32_16x16x32_bf16 v[140:143], v[64:67], v[154:157], v[140:143]
	v_mfma_f32_16x16x32_bf16 v[136:139], v[72:75], v[154:157], v[136:139]
	s_add_i32 s18, 0, 0x1c000
	v_mfma_f32_16x16x32_bf16 v[132:135], v[64:67], v[166:169], v[132:135]
	s_add_i32 s19, s43, s27
	v_mfma_f32_16x16x32_bf16 v[128:131], v[72:75], v[166:169], v[128:131]
	s_add_i32 m0, s19, 0xffffff80
	v_mfma_f32_16x16x32_bf16 v[108:111], v[64:67], v[174:177], v[108:111]
	v_mfma_f32_16x16x32_bf16 v[104:107], v[72:75], v[174:177], v[104:107]
	v_mfma_f32_16x16x32_bf16 v[100:103], v[64:67], v[182:185], v[100:103]
	v_mfma_f32_16x16x32_bf16 v[96:99], v[72:75], v[182:185], v[96:99]
	v_mfma_f32_16x16x32_bf16 v[140:143], v[68:71], v[162:165], v[140:143]
	v_mfma_f32_16x16x32_bf16 v[136:139], v[76:79], v[162:165], v[136:139]
	v_mfma_f32_16x16x32_bf16 v[132:135], v[68:71], v[170:173], v[132:135]
	v_mfma_f32_16x16x32_bf16 v[128:131], v[76:79], v[170:173], v[128:131]
	v_mfma_f32_16x16x32_bf16 v[108:111], v[68:71], v[178:181], v[108:111]
	v_mfma_f32_16x16x32_bf16 v[104:107], v[76:79], v[178:181], v[104:107]
	v_mfma_f32_16x16x32_bf16 v[100:103], v[68:71], v[186:189], v[100:103]
	v_mfma_f32_16x16x32_bf16 v[96:99], v[76:79], v[186:189], v[96:99]
	s_barrier
	ds_read_b128 v[196:199], v220 offset:49152
	ds_read_b128 v[204:207], v220 offset:50176
	ds_read_b128 v[208:211], v220 offset:51200
	ds_read_b128 v[214:217], v220 offset:52224
	global_load_lds_dwordx4 v192, s[16:17] offset:128
	s_add_i32 m0, s19, 0x1f80
	s_nop 0
	global_load_lds_dwordx4 v148, s[16:17] offset:128
	s_barrier
	s_waitcnt lgkmcnt(0)
	v_mfma_f32_16x16x32_bf16 v[124:127], v[196:199], v[154:157], v[124:127]
	v_mfma_f32_16x16x32_bf16 v[120:123], v[208:211], v[154:157], v[120:123]
	s_mov_b32 m0, s34
	v_mfma_f32_16x16x32_bf16 v[116:119], v[196:199], v[166:169], v[116:119]
	v_mfma_f32_16x16x32_bf16 v[112:115], v[208:211], v[166:169], v[112:115]
	v_mfma_f32_16x16x32_bf16 v[92:95], v[196:199], v[174:177], v[92:95]
	v_mfma_f32_16x16x32_bf16 v[88:91], v[208:211], v[174:177], v[88:91]
	v_mfma_f32_16x16x32_bf16 v[84:87], v[196:199], v[182:185], v[84:87]
	v_mfma_f32_16x16x32_bf16 v[80:83], v[208:211], v[182:185], v[80:83]
	v_mfma_f32_16x16x32_bf16 v[124:127], v[204:207], v[162:165], v[124:127]
	v_mfma_f32_16x16x32_bf16 v[120:123], v[214:217], v[162:165], v[120:123]
	v_mfma_f32_16x16x32_bf16 v[116:119], v[204:207], v[170:173], v[116:119]
	v_mfma_f32_16x16x32_bf16 v[112:115], v[214:217], v[170:173], v[112:115]
	v_mfma_f32_16x16x32_bf16 v[92:95], v[204:207], v[178:181], v[92:95]
	v_mfma_f32_16x16x32_bf16 v[88:91], v[214:217], v[178:181], v[88:91]
	v_mfma_f32_16x16x32_bf16 v[84:87], v[204:207], v[186:189], v[84:87]
	v_mfma_f32_16x16x32_bf16 v[80:83], v[214:217], v[186:189], v[80:83]
	s_barrier
	ds_read_b128 v[154:157], v161 offset:49152
	ds_read_b128 v[162:165], v161 offset:50176
	ds_read_b128 v[166:169], v161 offset:51200
	ds_read_b128 v[170:173], v161 offset:52224
	ds_read_b128 v[174:177], v161 offset:53248
	ds_read_b128 v[178:181], v161 offset:54272
	ds_read_b128 v[182:185], v161 offset:55296
	ds_read_b128 v[186:189], v161 offset:56320
	global_load_lds_dwordx4 v144, s[48:49]
	s_mov_b32 m0, s35
	s_nop 0
	global_load_lds_dwordx4 v146, s[48:49]
	s_barrier
	s_waitcnt lgkmcnt(0)
	v_mfma_f32_16x16x32_bf16 v[60:63], v[64:67], v[154:157], v[60:63]
	v_mfma_f32_16x16x32_bf16 v[56:59], v[72:75], v[154:157], v[56:59]
	s_add_u32 s16, s16, 0x80080
	v_mfma_f32_16x16x32_bf16 v[52:55], v[64:67], v[166:169], v[52:55]
	s_addc_u32 s17, s17, 0
	v_mfma_f32_16x16x32_bf16 v[48:51], v[72:75], v[166:169], v[48:51]
	s_add_i32 s18, s18, s27
	v_mfma_f32_16x16x32_bf16 v[28:31], v[64:67], v[174:177], v[28:31]
	s_mov_b32 m0, s18
	v_mfma_f32_16x16x32_bf16 v[24:27], v[72:75], v[174:177], v[24:27]
	v_mfma_f32_16x16x32_bf16 v[20:23], v[64:67], v[182:185], v[20:23]
	v_mfma_f32_16x16x32_bf16 v[16:19], v[72:75], v[182:185], v[16:19]
	v_mfma_f32_16x16x32_bf16 v[60:63], v[68:71], v[162:165], v[60:63]
	v_mfma_f32_16x16x32_bf16 v[56:59], v[76:79], v[162:165], v[56:59]
	v_mfma_f32_16x16x32_bf16 v[52:55], v[68:71], v[170:173], v[52:55]
	v_mfma_f32_16x16x32_bf16 v[48:51], v[76:79], v[170:173], v[48:51]
	v_mfma_f32_16x16x32_bf16 v[28:31], v[68:71], v[178:181], v[28:31]
	v_mfma_f32_16x16x32_bf16 v[24:27], v[76:79], v[178:181], v[24:27]
	v_mfma_f32_16x16x32_bf16 v[20:23], v[68:71], v[186:189], v[20:23]
	v_mfma_f32_16x16x32_bf16 v[16:19], v[76:79], v[186:189], v[16:19]
	s_barrier
	global_load_lds_dwordx4 v192, s[16:17]
	s_add_i32 m0, s18, 0x2000
	s_nop 0
	global_load_lds_dwordx4 v148, s[16:17]
	s_waitcnt vmcnt(6)
	s_barrier
	v_mfma_f32_16x16x32_bf16 v[44:47], v[196:199], v[154:157], v[44:47]
	v_mfma_f32_16x16x32_bf16 v[40:43], v[208:211], v[154:157], v[40:43]
	s_add_i32 s42, s42, 2
	v_mfma_f32_16x16x32_bf16 v[36:39], v[196:199], v[166:169], v[36:39]
	s_add_u32 s14, s14, 0x100
	v_mfma_f32_16x16x32_bf16 v[32:35], v[208:211], v[166:169], v[32:35]
	s_addc_u32 s15, s15, 0
	v_mfma_f32_16x16x32_bf16 v[12:15], v[196:199], v[174:177], v[12:15]
	s_add_u32 s40, s40, 0x100
	v_mfma_f32_16x16x32_bf16 v[8:11], v[208:211], v[174:177], v[8:11]
	s_addc_u32 s41, s41, 0
	v_mfma_f32_16x16x32_bf16 v[4:7], v[196:199], v[182:185], v[4:7]
	s_add_u32 s16, s14, 0xfff80080
	s_addc_u32 s17, s15, -1
	v_mfma_f32_16x16x32_bf16 v[0:3], v[208:211], v[182:185], v[0:3]
	s_add_i32 s43, 0, 0x10000
	s_cmp_eq_u32 s42, 28
	v_mfma_f32_16x16x32_bf16 v[44:47], v[204:207], v[162:165], v[44:47]
	s_cselect_b32 s19, s7, s17
	s_cselect_b32 s18, s38, s16
	v_mfma_f32_16x16x32_bf16 v[40:43], v[214:217], v[162:165], v[40:43]
	s_cselect_b32 s17, s5, s41
	s_cselect_b32 s16, s39, s40
	v_mfma_f32_16x16x32_bf16 v[36:39], v[204:207], v[170:173], v[36:39]
	s_add_i32 m0, s13, 0xc000
	v_mfma_f32_16x16x32_bf16 v[32:35], v[214:217], v[170:173], v[32:35]
	v_mfma_f32_16x16x32_bf16 v[12:15], v[204:207], v[178:181], v[12:15]
	v_mfma_f32_16x16x32_bf16 v[8:11], v[214:217], v[178:181], v[8:11]
	v_mfma_f32_16x16x32_bf16 v[4:7], v[204:207], v[186:189], v[4:7]
	v_mfma_f32_16x16x32_bf16 v[0:3], v[214:217], v[186:189], v[0:3]
	s_cmp_gt_u32 s42, 29
	s_barrier
	s_cbranch_scc0 .LBB0_294
	s_ashr_i32 s5, s12, 4
	v_lshl_or_b32 v190, s37, 8, v160
	s_mul_hi_i32 s7, s5, 0xc000
	s_mul_i32 s5, s5, 0xc000
	s_add_u32 s14, s31, s5
	v_ashrrev_i32_e32 v191, 31, v190
	v_lshl_add_u32 v154, s12, 8, v158
	v_readlane_b32 s52, v254, 23
	s_addc_u32 s15, s33, s7
	v_lshlrev_b64 v[156:157], 2, v[190:191]
	v_readlane_b32 s53, v254, 24
	v_ashrrev_i32_e32 v155, 31, v154
	v_lshl_add_u64 v[68:69], s[14:15], 0, v[156:157]
	v_lshl_add_u64 v[156:157], s[52:53], 0, v[156:157]
	v_lshlrev_b64 v[162:163], 13, v[154:155]
	v_lshl_add_u64 v[174:175], v[156:157], 0, v[162:163]
	global_load_dwordx4 v[72:75], v[68:69], off offset:16
	global_load_dwordx4 v[76:79], v[68:69], off
	global_load_dwordx4 v[64:67], v[68:69], off offset:528
	s_nop 0
	global_load_dwordx4 v[68:71], v[68:69], off offset:512
	s_nop 0
	global_load_dwordx4 v[162:165], v[174:175], off offset:16
	global_load_dwordx4 v[166:169], v[174:175], off
	global_load_dwordx4 v[170:173], v[174:175], off offset:528
	s_nop 0
	global_load_dwordx4 v[174:177], v[174:175], off offset:512
	v_or_b32_e32 v204, 16, v154
	v_ashrrev_i32_e32 v205, 31, v204
	v_lshlrev_b64 v[178:179], 13, v[204:205]
	v_lshl_add_u64 v[196:197], v[156:157], 0, v[178:179]
	global_load_dwordx4 v[178:181], v[196:197], off offset:16
	global_load_dwordx4 v[182:185], v[196:197], off
	global_load_dwordx4 v[186:189], v[196:197], off offset:528
	s_nop 0
	global_load_dwordx4 v[196:199], v[196:197], off offset:512
	v_lshlrev_b64 v[206:207], 12, v[154:155]
	s_and_b64 vcc, exec, s[0:1]
	s_mov_b32 s37, s4
	s_mov_b32 s12, s6
	s_mov_b64 s[16:17], s[10:11]
	s_mov_b64 s[14:15], s[8:9]
	s_mov_b32 s11, 0xc000
	v_readlane_b32 s54, v254, 25
	v_readlane_b32 s55, v254, 26
	v_readlane_b32 s56, v254, 27
	v_readlane_b32 s57, v254, 28
	v_readlane_b32 s58, v254, 29
	v_readlane_b32 s59, v254, 30
	v_readlane_b32 s60, v254, 31
	v_readlane_b32 s61, v254, 32
	v_readlane_b32 s62, v254, 33
	v_readlane_b32 s63, v254, 34
	v_readlane_b32 s64, v254, 35
	v_readlane_b32 s65, v254, 36
	v_readlane_b32 s66, v254, 37
	v_readlane_b32 s67, v254, 38
	s_waitcnt vmcnt(0)
	v_pk_fma_f32 v[136:137], v[136:137], v[72:73], v[162:163]
	v_pk_fma_f32 v[142:143], v[142:143], v[78:79], v[168:169]
	v_pk_fma_f32 v[140:141], v[140:141], v[76:77], v[166:167]
	v_pk_fma_f32 v[164:165], v[138:139], v[74:75], v[164:165]
	v_cvt_pk_bf16_f32 v138, v140, v141
	v_cvt_pk_bf16_f32 v139, v142, v143
	v_cvt_pk_bf16_f32 v140, v136, v137
	v_lshl_add_u64 v[142:143], s[2:3], 0, v[206:207]
	v_lshlrev_b64 v[136:137], 1, v[190:191]
	v_lshl_add_u64 v[142:143], v[142:143], 0, v[136:137]
	v_pk_fma_f32 v[124:125], v[124:125], v[68:69], v[174:175]
	v_cvt_pk_bf16_f32 v141, v164, v165
	global_store_dwordx4 v[142:143], v[138:141], off
	v_pk_fma_f32 v[126:127], v[126:127], v[70:71], v[176:177]
	v_pk_fma_f32 v[128:129], v[128:129], v[72:73], v[178:179]
	v_pk_fma_f32 v[138:139], v[122:123], v[66:67], v[172:173]
	v_pk_fma_f32 v[122:123], v[120:121], v[64:65], v[170:171]
	v_cvt_pk_bf16_f32 v120, v124, v125
	v_cvt_pk_bf16_f32 v121, v126, v127
	v_lshlrev_b64 v[124:125], 12, v[204:205]
	v_cvt_pk_bf16_f32 v122, v122, v123
	v_cvt_pk_bf16_f32 v123, v138, v139
	global_store_dwordx4 v[142:143], v[120:123], off offset:256
	v_lshl_add_u64 v[124:125], s[2:3], 0, v[124:125]
	v_lshl_add_u64 v[124:125], v[124:125], 0, v[136:137]
	v_pk_fma_f32 v[120:121], v[132:133], v[76:77], v[182:183]
	v_pk_fma_f32 v[122:123], v[134:135], v[78:79], v[184:185]
	v_cvt_pk_bf16_f32 v120, v120, v121
	v_or_b32_e32 v142, 32, v154
	v_cvt_pk_bf16_f32 v121, v122, v123
	v_pk_fma_f32 v[126:127], v[130:131], v[74:75], v[180:181]
	v_cvt_pk_bf16_f32 v122, v128, v129
	v_pk_fma_f32 v[118:119], v[118:119], v[70:71], v[198:199]
	v_cvt_pk_bf16_f32 v123, v126, v127
	global_store_dwordx4 v[124:125], v[120:123], off
	v_pk_fma_f32 v[116:117], v[116:117], v[68:69], v[196:197]
	v_ashrrev_i32_e32 v143, 31, v142
	v_pk_fma_f32 v[120:121], v[114:115], v[66:67], v[188:189]
	v_pk_fma_f32 v[114:115], v[112:113], v[64:65], v[186:187]
	v_cvt_pk_bf16_f32 v112, v116, v117
	v_cvt_pk_bf16_f32 v113, v118, v119
	v_or_b32_e32 v166, 48, v154
	v_cvt_pk_bf16_f32 v114, v114, v115
	v_cvt_pk_bf16_f32 v115, v120, v121
	global_store_dwordx4 v[124:125], v[112:115], off offset:256
	v_ashrrev_i32_e32 v167, 31, v166
	v_lshlrev_b64 v[128:129], 13, v[166:167]
	v_lshlrev_b64 v[112:113], 13, v[142:143]
	v_lshl_add_u64 v[124:125], v[156:157], 0, v[112:113]
	global_load_dwordx4 v[112:115], v[124:125], off offset:16
	global_load_dwordx4 v[116:119], v[124:125], off
	global_load_dwordx4 v[120:123], v[124:125], off offset:528
	s_nop 0
	global_load_dwordx4 v[124:127], v[124:125], off offset:512
	v_lshl_add_u64 v[162:163], v[156:157], 0, v[128:129]
	global_load_dwordx4 v[128:131], v[162:163], off offset:16
	global_load_dwordx4 v[132:135], v[162:163], off
	global_load_dwordx4 v[138:141], v[162:163], off offset:528
	s_nop 0
	global_load_dwordx4 v[162:165], v[162:163], off offset:512
	v_lshlrev_b64 v[142:143], 12, v[142:143]
	s_waitcnt vmcnt(0)
	v_pk_fma_f32 v[114:115], v[106:107], v[74:75], v[114:115]
	v_pk_fma_f32 v[108:109], v[108:109], v[76:77], v[116:117]
	v_pk_fma_f32 v[106:107], v[104:105], v[72:73], v[112:113]
	v_cvt_pk_bf16_f32 v104, v108, v109
	v_lshl_add_u64 v[108:109], s[2:3], 0, v[142:143]
	v_pk_fma_f32 v[110:111], v[110:111], v[78:79], v[118:119]
	v_lshl_add_u64 v[108:109], v[108:109], 0, v[136:137]
	v_cvt_pk_bf16_f32 v105, v110, v111
	v_pk_fma_f32 v[92:93], v[92:93], v[68:69], v[124:125]
	v_cvt_pk_bf16_f32 v106, v106, v107
	v_cvt_pk_bf16_f32 v107, v114, v115
	global_store_dwordx4 v[108:109], v[104:107], off
	v_pk_fma_f32 v[94:95], v[94:95], v[70:71], v[126:127]
	v_add_u32_e32 v112, 0x80, v154
	v_pk_fma_f32 v[104:105], v[90:91], v[66:67], v[122:123]
	v_pk_fma_f32 v[90:91], v[88:89], v[64:65], v[120:121]
	v_cvt_pk_bf16_f32 v88, v92, v93
	v_cvt_pk_bf16_f32 v89, v94, v95
	v_lshlrev_b64 v[92:93], 12, v[166:167]
	v_cvt_pk_bf16_f32 v90, v90, v91
	v_cvt_pk_bf16_f32 v91, v104, v105
	global_store_dwordx4 v[108:109], v[88:91], off offset:256
	v_lshl_add_u64 v[92:93], s[2:3], 0, v[92:93]
	v_lshl_add_u64 v[92:93], v[92:93], 0, v[136:137]
	v_pk_fma_f32 v[88:89], v[100:101], v[76:77], v[132:133]
	v_pk_fma_f32 v[90:91], v[102:103], v[78:79], v[134:135]
	v_cvt_pk_bf16_f32 v88, v88, v89
	v_pk_fma_f32 v[94:95], v[98:99], v[74:75], v[130:131]
	v_cvt_pk_bf16_f32 v89, v90, v91
	v_pk_fma_f32 v[96:97], v[96:97], v[72:73], v[128:129]
	v_pk_fma_f32 v[86:87], v[86:87], v[70:71], v[164:165]
	v_cvt_pk_bf16_f32 v90, v96, v97
	v_cvt_pk_bf16_f32 v91, v94, v95
	global_store_dwordx4 v[92:93], v[88:91], off
	v_pk_fma_f32 v[84:85], v[84:85], v[68:69], v[162:163]
	v_ashrrev_i32_e32 v113, 31, v112
	v_pk_fma_f32 v[88:89], v[82:83], v[66:67], v[140:141]
	v_pk_fma_f32 v[82:83], v[80:81], v[64:65], v[138:139]
	v_cvt_pk_bf16_f32 v80, v84, v85
	v_cvt_pk_bf16_f32 v81, v86, v87
	v_add_u32_e32 v114, 0x90, v154
	v_cvt_pk_bf16_f32 v82, v82, v83
	v_cvt_pk_bf16_f32 v83, v88, v89
	global_store_dwordx4 v[92:93], v[80:83], off offset:256
	v_ashrrev_i32_e32 v115, 31, v114
	v_lshlrev_b64 v[96:97], 13, v[114:115]
	v_lshlrev_b64 v[80:81], 13, v[112:113]
	v_lshl_add_u64 v[92:93], v[156:157], 0, v[80:81]
	global_load_dwordx4 v[80:83], v[92:93], off offset:16
	global_load_dwordx4 v[84:87], v[92:93], off
	global_load_dwordx4 v[88:91], v[92:93], off offset:528
	s_nop 0
	global_load_dwordx4 v[92:95], v[92:93], off offset:512
	v_lshl_add_u64 v[108:109], v[156:157], 0, v[96:97]
	global_load_dwordx4 v[96:99], v[108:109], off offset:16
	global_load_dwordx4 v[100:103], v[108:109], off
	global_load_dwordx4 v[104:107], v[108:109], off offset:528
	s_nop 0
	global_load_dwordx4 v[108:111], v[108:109], off offset:512
	v_lshlrev_b64 v[112:113], 12, v[112:113]
	s_waitcnt vmcnt(0)
	v_pk_fma_f32 v[82:83], v[58:59], v[74:75], v[82:83]
	v_pk_fma_f32 v[60:61], v[60:61], v[76:77], v[84:85]
	v_pk_fma_f32 v[58:59], v[56:57], v[72:73], v[80:81]
	v_cvt_pk_bf16_f32 v56, v60, v61
	v_lshl_add_u64 v[60:61], s[2:3], 0, v[112:113]
	v_pk_fma_f32 v[62:63], v[62:63], v[78:79], v[86:87]
	v_lshl_add_u64 v[60:61], v[60:61], 0, v[136:137]
	v_cvt_pk_bf16_f32 v57, v62, v63
	v_pk_fma_f32 v[44:45], v[44:45], v[68:69], v[92:93]
	v_cvt_pk_bf16_f32 v58, v58, v59
	v_cvt_pk_bf16_f32 v59, v82, v83
	global_store_dwordx4 v[60:61], v[56:59], off
	v_pk_fma_f32 v[46:47], v[46:47], v[70:71], v[94:95]
	v_add_u32_e32 v80, 0xa0, v154
	v_pk_fma_f32 v[56:57], v[42:43], v[66:67], v[90:91]
	v_pk_fma_f32 v[42:43], v[40:41], v[64:65], v[88:89]
	v_cvt_pk_bf16_f32 v40, v44, v45
	v_cvt_pk_bf16_f32 v41, v46, v47
	v_lshlrev_b64 v[44:45], 12, v[114:115]
	v_cvt_pk_bf16_f32 v42, v42, v43
	v_cvt_pk_bf16_f32 v43, v56, v57
	global_store_dwordx4 v[60:61], v[40:43], off offset:256
	v_lshl_add_u64 v[44:45], s[2:3], 0, v[44:45]
	v_lshl_add_u64 v[44:45], v[44:45], 0, v[136:137]
	v_pk_fma_f32 v[40:41], v[52:53], v[76:77], v[100:101]
	v_pk_fma_f32 v[42:43], v[54:55], v[78:79], v[102:103]
	v_cvt_pk_bf16_f32 v40, v40, v41
	v_pk_fma_f32 v[46:47], v[50:51], v[74:75], v[98:99]
	v_cvt_pk_bf16_f32 v41, v42, v43
	v_pk_fma_f32 v[48:49], v[48:49], v[72:73], v[96:97]
	v_pk_fma_f32 v[38:39], v[38:39], v[70:71], v[110:111]
	v_cvt_pk_bf16_f32 v42, v48, v49
	v_cvt_pk_bf16_f32 v43, v46, v47
	global_store_dwordx4 v[44:45], v[40:43], off
	v_pk_fma_f32 v[36:37], v[36:37], v[68:69], v[108:109]
	v_ashrrev_i32_e32 v81, 31, v80
	v_pk_fma_f32 v[40:41], v[34:35], v[66:67], v[106:107]
	v_pk_fma_f32 v[34:35], v[32:33], v[64:65], v[104:105]
	v_cvt_pk_bf16_f32 v32, v36, v37
	v_cvt_pk_bf16_f32 v33, v38, v39
	v_add_u32_e32 v82, 0xb0, v154
	v_cvt_pk_bf16_f32 v34, v34, v35
	v_cvt_pk_bf16_f32 v35, v40, v41
	global_store_dwordx4 v[44:45], v[32:35], off offset:256
	v_ashrrev_i32_e32 v83, 31, v82
	v_lshlrev_b64 v[48:49], 13, v[82:83]
	v_lshlrev_b64 v[32:33], 13, v[80:81]
	v_lshl_add_u64 v[44:45], v[156:157], 0, v[32:33]
	global_load_dwordx4 v[32:35], v[44:45], off offset:16
	global_load_dwordx4 v[36:39], v[44:45], off
	global_load_dwordx4 v[40:43], v[44:45], off offset:528
	s_nop 0
	global_load_dwordx4 v[44:47], v[44:45], off offset:512
	v_lshl_add_u64 v[60:61], v[156:157], 0, v[48:49]
	global_load_dwordx4 v[48:51], v[60:61], off offset:16
	global_load_dwordx4 v[52:55], v[60:61], off
	global_load_dwordx4 v[56:59], v[60:61], off offset:528
	s_nop 0
	global_load_dwordx4 v[60:63], v[60:61], off offset:512
	v_lshlrev_b64 v[80:81], 12, v[80:81]
	s_waitcnt vmcnt(0)
	v_pk_fma_f32 v[34:35], v[26:27], v[74:75], v[34:35]
	v_pk_fma_f32 v[28:29], v[28:29], v[76:77], v[36:37]
	v_pk_fma_f32 v[26:27], v[24:25], v[72:73], v[32:33]
	v_cvt_pk_bf16_f32 v24, v28, v29
	v_lshl_add_u64 v[28:29], s[2:3], 0, v[80:81]
	v_pk_fma_f32 v[30:31], v[30:31], v[78:79], v[38:39]
	v_lshl_add_u64 v[28:29], v[28:29], 0, v[136:137]
	v_cvt_pk_bf16_f32 v25, v30, v31
	v_pk_fma_f32 v[12:13], v[12:13], v[68:69], v[44:45]
	v_cvt_pk_bf16_f32 v26, v26, v27
	v_cvt_pk_bf16_f32 v27, v34, v35
	global_store_dwordx4 v[28:29], v[24:27], off
	v_pk_fma_f32 v[14:15], v[14:15], v[70:71], v[46:47]
	v_pk_fma_f32 v[16:17], v[16:17], v[72:73], v[48:49]
	v_pk_fma_f32 v[24:25], v[10:11], v[66:67], v[42:43]
	v_pk_fma_f32 v[10:11], v[8:9], v[64:65], v[40:41]
	v_cvt_pk_bf16_f32 v8, v12, v13
	v_cvt_pk_bf16_f32 v9, v14, v15
	v_lshlrev_b64 v[12:13], 12, v[82:83]
	v_cvt_pk_bf16_f32 v10, v10, v11
	v_cvt_pk_bf16_f32 v11, v24, v25
	global_store_dwordx4 v[28:29], v[8:11], off offset:256
	v_lshl_add_u64 v[12:13], s[2:3], 0, v[12:13]
	v_lshl_add_u64 v[12:13], v[12:13], 0, v[136:137]
	v_pk_fma_f32 v[8:9], v[20:21], v[76:77], v[52:53]
	v_pk_fma_f32 v[10:11], v[22:23], v[78:79], v[54:55]
	v_cvt_pk_bf16_f32 v8, v8, v9
	v_pk_fma_f32 v[14:15], v[18:19], v[74:75], v[50:51]
	v_cvt_pk_bf16_f32 v9, v10, v11
	v_cvt_pk_bf16_f32 v10, v16, v17
	v_pk_fma_f32 v[6:7], v[6:7], v[70:71], v[62:63]
	v_cvt_pk_bf16_f32 v11, v14, v15
	global_store_dwordx4 v[12:13], v[8:11], off
	v_pk_fma_f32 v[4:5], v[4:5], v[68:69], v[60:61]
	s_nop 0
	v_pk_fma_f32 v[8:9], v[2:3], v[66:67], v[58:59]
	v_pk_fma_f32 v[2:3], v[0:1], v[64:65], v[56:57]
	v_cvt_pk_bf16_f32 v0, v4, v5
	v_cvt_pk_bf16_f32 v1, v6, v7
	s_nop 0
	v_cvt_pk_bf16_f32 v2, v2, v3
	v_cvt_pk_bf16_f32 v3, v8, v9
	global_store_dwordx4 v[12:13], v[0:3], off offset:256
	s_cbranch_vccz .LBB0_287
	s_waitcnt vmcnt(0)
	s_cmpk_gt_u32 s25, 0xff
	s_cbranch_scc1 .LBB0_298
	s_barrier

.LBB0_414:
	s_ashr_i32 s9, s8, 31
	v_cmp_lt_i64_e32 vcc, s[10:11], v[202:203]
	s_lshl_b64 s[10:11], s[8:9], 20
	s_add_u32 s10, s24, s10
	s_addc_u32 s11, s25, s11
	s_and_b64 s[12:13], vcc, exec
	s_cselect_b32 s9, s11, s17
	s_cselect_b32 s38, s10, s16
	s_ashr_i32 s7, s6, 31
	s_lshl_b64 s[12:13], s[6:7], 20
	s_add_u32 s12, s26, s12
	s_addc_u32 s13, s27, s13
	s_and_b64 s[20:21], vcc, exec
	s_cselect_b32 s7, s13, s19
	s_cselect_b32 s39, s12, s18
	s_add_u32 s16, s16, 0x80080
	s_addc_u32 s17, s17, 0
	s_add_u32 s40, s18, 0x100
	s_addc_u32 s41, s19, 0
	s_mov_b32 s42, -2
	s_mov_b64 s[48:49], 0x80
	v_add_u32_e32 v196, 0x10000, v143
	s_add_u32 s18, s16, 0xfff80080
	s_addc_u32 s19, s17, -1
	s_add_i32 s43, 0, 0x10000
	ds_read_b128 v[146:149], v196 offset:0
	ds_read_b128 v[150:153], v196 offset:1024
	ds_read_b128 v[154:157], v196 offset:2048
	ds_read_b128 v[158:161], v196 offset:3072
	s_cmp_eq_u32 s42, 28
	s_cselect_b32 s21, s9, s19
	s_cselect_b32 s20, s38, s18
	s_cselect_b32 s19, s7, s41
	s_cselect_b32 s18, s39, s40
	s_add_i32 m0, s30, 0xc000
	ds_read_b128 v[162:165], v145
	ds_read_b128 v[166:169], v145 offset:1024
	ds_read_b128 v[170:173], v145 offset:2048
	ds_read_b128 v[174:177], v145 offset:3072
	ds_read_b128 v[178:181], v145 offset:4096
	ds_read_b128 v[182:185], v145 offset:5120
	ds_read_b128 v[186:189], v145 offset:6144
	ds_read_b128 v[204:207], v145 offset:7168
	global_load_lds_dwordx4 v136, s[16:17]
	s_add_i32 m0, s30, 0xe000
	s_nop 0
	global_load_lds_dwordx4 v138, s[16:17]
	s_waitcnt lgkmcnt(8)
	s_barrier
	s_waitcnt lgkmcnt(0)
	v_mfma_f32_16x16x32_bf16 v[124:127], v[146:149], v[162:165], 0
	v_mfma_f32_16x16x32_bf16 v[120:123], v[154:157], v[162:165], 0
	s_add_i32 s46, 0, 0x14000
	v_mfma_f32_16x16x32_bf16 v[116:119], v[146:149], v[170:173], 0
	s_add_i32 s43, s43, s28
	v_mfma_f32_16x16x32_bf16 v[108:111], v[154:157], v[170:173], 0
	s_mov_b32 m0, s43
	v_mfma_f32_16x16x32_bf16 v[100:103], v[146:149], v[178:181], 0
	v_mfma_f32_16x16x32_bf16 v[92:95], v[154:157], v[178:181], 0
	v_mfma_f32_16x16x32_bf16 v[84:87], v[146:149], v[186:189], 0
	v_mfma_f32_16x16x32_bf16 v[76:79], v[154:157], v[186:189], 0
	v_mfma_f32_16x16x32_bf16 v[124:127], v[150:153], v[166:169], v[124:127]
	v_mfma_f32_16x16x32_bf16 v[120:123], v[158:161], v[166:169], v[120:123]
	v_mfma_f32_16x16x32_bf16 v[116:119], v[150:153], v[174:177], v[116:119]
	v_mfma_f32_16x16x32_bf16 v[108:111], v[158:161], v[174:177], v[108:111]
	v_mfma_f32_16x16x32_bf16 v[100:103], v[150:153], v[182:185], v[100:103]
	v_mfma_f32_16x16x32_bf16 v[92:95], v[158:161], v[182:185], v[92:95]
	v_mfma_f32_16x16x32_bf16 v[84:87], v[150:153], v[204:207], v[84:87]
	v_mfma_f32_16x16x32_bf16 v[76:79], v[158:161], v[204:207], v[76:79]
	s_barrier
	ds_read_b128 v[208:211], v196 offset:16384
	ds_read_b128 v[214:217], v196 offset:17408
	ds_read_b128 v[218:221], v196 offset:18432
	ds_read_b128 v[222:225], v196 offset:19456
	global_load_lds_dwordx4 v192, s[18:19]
	s_add_i32 m0, s43, 0x2000
	s_nop 0
	global_load_lds_dwordx4 v128, s[18:19]
	s_barrier
	s_waitcnt lgkmcnt(0)
	v_mfma_f32_16x16x32_bf16 v[112:115], v[208:211], v[162:165], 0
	v_mfma_f32_16x16x32_bf16 v[104:107], v[218:221], v[162:165], 0
	s_mov_b32 m0, s30
	v_mfma_f32_16x16x32_bf16 v[96:99], v[208:211], v[170:173], 0
	s_add_u32 s48, s20, 0x80
	v_mfma_f32_16x16x32_bf16 v[88:91], v[218:221], v[170:173], 0
	s_addc_u32 s49, s21, 0
	v_mfma_f32_16x16x32_bf16 v[80:83], v[208:211], v[178:181], 0
	v_mfma_f32_16x16x32_bf16 v[72:75], v[218:221], v[178:181], 0
	v_mfma_f32_16x16x32_bf16 v[68:71], v[208:211], v[186:189], 0
	v_mfma_f32_16x16x32_bf16 v[64:67], v[218:221], v[186:189], 0
	v_mfma_f32_16x16x32_bf16 v[112:115], v[214:217], v[166:169], v[112:115]
	v_mfma_f32_16x16x32_bf16 v[104:107], v[222:225], v[166:169], v[104:107]
	v_mfma_f32_16x16x32_bf16 v[96:99], v[214:217], v[174:177], v[96:99]
	v_mfma_f32_16x16x32_bf16 v[88:91], v[222:225], v[174:177], v[88:91]
	v_mfma_f32_16x16x32_bf16 v[80:83], v[214:217], v[182:185], v[80:83]
	v_mfma_f32_16x16x32_bf16 v[72:75], v[222:225], v[182:185], v[72:75]
	v_mfma_f32_16x16x32_bf16 v[68:71], v[214:217], v[204:207], v[68:71]
	v_mfma_f32_16x16x32_bf16 v[64:67], v[222:225], v[204:207], v[64:67]
	s_barrier
	ds_read_b128 v[162:165], v145 offset:16384
	ds_read_b128 v[166:169], v145 offset:17408
	ds_read_b128 v[170:173], v145 offset:18432
	ds_read_b128 v[174:177], v145 offset:19456
	ds_read_b128 v[178:181], v145 offset:20480
	ds_read_b128 v[182:185], v145 offset:21504
	ds_read_b128 v[186:189], v145 offset:22528
	ds_read_b128 v[204:207], v145 offset:23552
	global_load_lds_dwordx4 v132, s[20:21]
	s_mov_b32 m0, s31
	s_nop 0
	global_load_lds_dwordx4 v130, s[20:21]
	s_barrier
	s_waitcnt lgkmcnt(0)
	v_mfma_f32_16x16x32_bf16 v[60:63], v[146:149], v[162:165], 0
	v_mfma_f32_16x16x32_bf16 v[56:59], v[154:157], v[162:165], 0
	s_add_u32 s44, s18, 0x80000
	v_mfma_f32_16x16x32_bf16 v[52:55], v[146:149], v[170:173], 0
	s_addc_u32 s45, s19, 0
	v_mfma_f32_16x16x32_bf16 v[44:47], v[154:157], v[170:173], 0
	s_add_i32 s43, s46, s28
	v_mfma_f32_16x16x32_bf16 v[36:39], v[146:149], v[178:181], 0
	s_mov_b32 m0, s43
	v_mfma_f32_16x16x32_bf16 v[28:31], v[154:157], v[178:181], 0
	v_mfma_f32_16x16x32_bf16 v[20:23], v[146:149], v[186:189], 0
	v_mfma_f32_16x16x32_bf16 v[12:15], v[154:157], v[186:189], 0
	v_mfma_f32_16x16x32_bf16 v[60:63], v[150:153], v[166:169], v[60:63]
	v_mfma_f32_16x16x32_bf16 v[56:59], v[158:161], v[166:169], v[56:59]
	v_mfma_f32_16x16x32_bf16 v[52:55], v[150:153], v[174:177], v[52:55]
	v_mfma_f32_16x16x32_bf16 v[44:47], v[158:161], v[174:177], v[44:47]
	v_mfma_f32_16x16x32_bf16 v[36:39], v[150:153], v[182:185], v[36:39]
	v_mfma_f32_16x16x32_bf16 v[28:31], v[158:161], v[182:185], v[28:31]
	v_mfma_f32_16x16x32_bf16 v[20:23], v[150:153], v[204:207], v[20:23]
	v_mfma_f32_16x16x32_bf16 v[12:15], v[158:161], v[204:207], v[12:15]
	s_barrier
	global_load_lds_dwordx4 v192, s[44:45]
	s_add_i32 m0, s43, 0x2000
	s_nop 0
	global_load_lds_dwordx4 v128, s[44:45]
	s_waitcnt vmcnt(6)
	s_barrier
	v_mfma_f32_16x16x32_bf16 v[48:51], v[208:211], v[162:165], 0
	v_mfma_f32_16x16x32_bf16 v[40:43], v[218:221], v[162:165], 0
	s_add_i32 s43, 0, 0x18000
	v_mfma_f32_16x16x32_bf16 v[32:35], v[208:211], v[170:173], 0
	s_add_u32 s20, s20, 0x80000
	v_mfma_f32_16x16x32_bf16 v[24:27], v[218:221], v[170:173], 0
	s_addc_u32 s21, s21, 0
	v_mfma_f32_16x16x32_bf16 v[16:19], v[208:211], v[178:181], 0
	s_mov_b32 m0, s33
	v_mfma_f32_16x16x32_bf16 v[8:11], v[218:221], v[178:181], 0
	v_mfma_f32_16x16x32_bf16 v[4:7], v[208:211], v[186:189], 0
	v_mfma_f32_16x16x32_bf16 v[0:3], v[218:221], v[186:189], 0
	v_mfma_f32_16x16x32_bf16 v[48:51], v[214:217], v[166:169], v[48:51]
	v_mfma_f32_16x16x32_bf16 v[40:43], v[222:225], v[166:169], v[40:43]
	v_mfma_f32_16x16x32_bf16 v[32:35], v[214:217], v[174:177], v[32:35]
	v_mfma_f32_16x16x32_bf16 v[24:27], v[222:225], v[174:177], v[24:27]
	v_mfma_f32_16x16x32_bf16 v[16:19], v[214:217], v[182:185], v[16:19]
	v_mfma_f32_16x16x32_bf16 v[8:11], v[222:225], v[182:185], v[8:11]
	v_mfma_f32_16x16x32_bf16 v[4:7], v[214:217], v[204:207], v[4:7]
	v_mfma_f32_16x16x32_bf16 v[0:3], v[222:225], v[204:207], v[0:3]
	s_barrier
	ds_read_b128 v[146:149], v196 offset:32768
	ds_read_b128 v[150:153], v196 offset:33792
	ds_read_b128 v[154:157], v196 offset:34816
	ds_read_b128 v[158:161], v196 offset:35840
	ds_read_b128 v[162:165], v145 offset:32768
	ds_read_b128 v[166:169], v145 offset:33792
	ds_read_b128 v[170:173], v145 offset:34816
	ds_read_b128 v[174:177], v145 offset:35840
	ds_read_b128 v[178:181], v145 offset:36864
	ds_read_b128 v[182:185], v145 offset:37888
	ds_read_b128 v[186:189], v145 offset:38912
	ds_read_b128 v[204:207], v145 offset:39936
	global_load_lds_dwordx4 v132, s[20:21]
	s_mov_b32 m0, s34
	s_nop 0
	global_load_lds_dwordx4 v130, s[20:21]
	s_waitcnt lgkmcnt(8)
	s_barrier
	s_waitcnt lgkmcnt(0)
	v_mfma_f32_16x16x32_bf16 v[124:127], v[146:149], v[162:165], v[124:127]
	v_mfma_f32_16x16x32_bf16 v[120:123], v[154:157], v[162:165], v[120:123]
	s_add_i32 s20, 0, 0x1c000
	v_mfma_f32_16x16x32_bf16 v[116:119], v[146:149], v[170:173], v[116:119]
	s_add_i32 s21, s43, s28
	v_mfma_f32_16x16x32_bf16 v[108:111], v[154:157], v[170:173], v[108:111]
	s_add_i32 m0, s21, 0xffffff80
	v_mfma_f32_16x16x32_bf16 v[100:103], v[146:149], v[178:181], v[100:103]
	v_mfma_f32_16x16x32_bf16 v[92:95], v[154:157], v[178:181], v[92:95]
	v_mfma_f32_16x16x32_bf16 v[84:87], v[146:149], v[186:189], v[84:87]
	v_mfma_f32_16x16x32_bf16 v[76:79], v[154:157], v[186:189], v[76:79]
	v_mfma_f32_16x16x32_bf16 v[124:127], v[150:153], v[166:169], v[124:127]
	v_mfma_f32_16x16x32_bf16 v[120:123], v[158:161], v[166:169], v[120:123]
	v_mfma_f32_16x16x32_bf16 v[116:119], v[150:153], v[174:177], v[116:119]
	v_mfma_f32_16x16x32_bf16 v[108:111], v[158:161], v[174:177], v[108:111]
	v_mfma_f32_16x16x32_bf16 v[100:103], v[150:153], v[182:185], v[100:103]
	v_mfma_f32_16x16x32_bf16 v[92:95], v[158:161], v[182:185], v[92:95]
	v_mfma_f32_16x16x32_bf16 v[84:87], v[150:153], v[204:207], v[84:87]
	v_mfma_f32_16x16x32_bf16 v[76:79], v[158:161], v[204:207], v[76:79]
	s_barrier
	ds_read_b128 v[208:211], v196 offset:49152
	ds_read_b128 v[214:217], v196 offset:50176
	ds_read_b128 v[218:221], v196 offset:51200
	ds_read_b128 v[222:225], v196 offset:52224
	global_load_lds_dwordx4 v192, s[18:19] offset:128
	s_add_i32 m0, s21, 0x1f80
	s_nop 0
	global_load_lds_dwordx4 v128, s[18:19] offset:128
	s_barrier
	s_waitcnt lgkmcnt(0)
	v_mfma_f32_16x16x32_bf16 v[112:115], v[208:211], v[162:165], v[112:115]
	v_mfma_f32_16x16x32_bf16 v[104:107], v[218:221], v[162:165], v[104:107]
	s_mov_b32 m0, s35
	v_mfma_f32_16x16x32_bf16 v[96:99], v[208:211], v[170:173], v[96:99]
	v_mfma_f32_16x16x32_bf16 v[88:91], v[218:221], v[170:173], v[88:91]
	v_mfma_f32_16x16x32_bf16 v[80:83], v[208:211], v[178:181], v[80:83]
	v_mfma_f32_16x16x32_bf16 v[72:75], v[218:221], v[178:181], v[72:75]
	v_mfma_f32_16x16x32_bf16 v[68:71], v[208:211], v[186:189], v[68:71]
	v_mfma_f32_16x16x32_bf16 v[64:67], v[218:221], v[186:189], v[64:67]
	v_mfma_f32_16x16x32_bf16 v[112:115], v[214:217], v[166:169], v[112:115]
	v_mfma_f32_16x16x32_bf16 v[104:107], v[222:225], v[166:169], v[104:107]
	v_mfma_f32_16x16x32_bf16 v[96:99], v[214:217], v[174:177], v[96:99]
	v_mfma_f32_16x16x32_bf16 v[88:91], v[222:225], v[174:177], v[88:91]
	v_mfma_f32_16x16x32_bf16 v[80:83], v[214:217], v[182:185], v[80:83]
	v_mfma_f32_16x16x32_bf16 v[72:75], v[222:225], v[182:185], v[72:75]
	v_mfma_f32_16x16x32_bf16 v[68:71], v[214:217], v[204:207], v[68:71]
	v_mfma_f32_16x16x32_bf16 v[64:67], v[222:225], v[204:207], v[64:67]
	s_barrier
	ds_read_b128 v[162:165], v145 offset:49152
	ds_read_b128 v[166:169], v145 offset:50176
	ds_read_b128 v[170:173], v145 offset:51200
	ds_read_b128 v[174:177], v145 offset:52224
	ds_read_b128 v[178:181], v145 offset:53248
	ds_read_b128 v[182:185], v145 offset:54272
	ds_read_b128 v[186:189], v145 offset:55296
	ds_read_b128 v[204:207], v145 offset:56320
	global_load_lds_dwordx4 v132, s[48:49]
	s_mov_b32 m0, s36
	s_nop 0
	global_load_lds_dwordx4 v130, s[48:49]
	s_barrier
	s_waitcnt lgkmcnt(0)
	v_mfma_f32_16x16x32_bf16 v[60:63], v[146:149], v[162:165], v[60:63]
	v_mfma_f32_16x16x32_bf16 v[56:59], v[154:157], v[162:165], v[56:59]
	s_add_u32 s18, s18, 0x80080
	v_mfma_f32_16x16x32_bf16 v[52:55], v[146:149], v[170:173], v[52:55]
	s_addc_u32 s19, s19, 0
	v_mfma_f32_16x16x32_bf16 v[44:47], v[154:157], v[170:173], v[44:47]
	s_add_i32 s20, s20, s28
	v_mfma_f32_16x16x32_bf16 v[36:39], v[146:149], v[178:181], v[36:39]
	s_mov_b32 m0, s20
	v_mfma_f32_16x16x32_bf16 v[28:31], v[154:157], v[178:181], v[28:31]
	v_mfma_f32_16x16x32_bf16 v[20:23], v[146:149], v[186:189], v[20:23]
	v_mfma_f32_16x16x32_bf16 v[12:15], v[154:157], v[186:189], v[12:15]
	v_mfma_f32_16x16x32_bf16 v[60:63], v[150:153], v[166:169], v[60:63]
	v_mfma_f32_16x16x32_bf16 v[56:59], v[158:161], v[166:169], v[56:59]
	v_mfma_f32_16x16x32_bf16 v[52:55], v[150:153], v[174:177], v[52:55]
	v_mfma_f32_16x16x32_bf16 v[44:47], v[158:161], v[174:177], v[44:47]
	v_mfma_f32_16x16x32_bf16 v[36:39], v[150:153], v[182:185], v[36:39]
	v_mfma_f32_16x16x32_bf16 v[28:31], v[158:161], v[182:185], v[28:31]
	v_mfma_f32_16x16x32_bf16 v[20:23], v[150:153], v[204:207], v[20:23]
	v_mfma_f32_16x16x32_bf16 v[12:15], v[158:161], v[204:207], v[12:15]
	s_barrier
	global_load_lds_dwordx4 v192, s[18:19]
	s_add_i32 m0, s20, 0x2000
	s_nop 0
	global_load_lds_dwordx4 v128, s[18:19]
	s_waitcnt vmcnt(6)
	s_barrier
	v_mfma_f32_16x16x32_bf16 v[48:51], v[208:211], v[162:165], v[48:51]
	v_mfma_f32_16x16x32_bf16 v[40:43], v[218:221], v[162:165], v[40:43]
	s_add_i32 s42, s42, 2
	v_mfma_f32_16x16x32_bf16 v[32:35], v[208:211], v[170:173], v[32:35]
	s_add_u32 s16, s16, 0x100
	v_mfma_f32_16x16x32_bf16 v[24:27], v[218:221], v[170:173], v[24:27]
	s_addc_u32 s17, s17, 0
	v_mfma_f32_16x16x32_bf16 v[16:19], v[208:211], v[178:181], v[16:19]
	s_add_u32 s40, s40, 0x100
	v_mfma_f32_16x16x32_bf16 v[8:11], v[218:221], v[178:181], v[8:11]
	s_addc_u32 s41, s41, 0
	v_mfma_f32_16x16x32_bf16 v[4:7], v[208:211], v[186:189], v[4:7]
	s_add_u32 s18, s16, 0xfff80080
	s_addc_u32 s19, s17, -1
	v_mfma_f32_16x16x32_bf16 v[0:3], v[218:221], v[186:189], v[0:3]
	s_add_i32 s43, 0, 0x10000
	s_cmp_eq_u32 s42, 28
	v_mfma_f32_16x16x32_bf16 v[48:51], v[214:217], v[166:169], v[48:51]
	s_cselect_b32 s21, s9, s19
	s_cselect_b32 s20, s38, s18
	v_mfma_f32_16x16x32_bf16 v[40:43], v[222:225], v[166:169], v[40:43]
	s_cselect_b32 s19, s7, s41
	s_cselect_b32 s18, s39, s40
	v_mfma_f32_16x16x32_bf16 v[32:35], v[214:217], v[174:177], v[32:35]
	s_add_i32 m0, s30, 0xc000
	v_mfma_f32_16x16x32_bf16 v[24:27], v[222:225], v[174:177], v[24:27]
	v_mfma_f32_16x16x32_bf16 v[16:19], v[214:217], v[182:185], v[16:19]
	v_mfma_f32_16x16x32_bf16 v[8:11], v[222:225], v[182:185], v[8:11]
	v_mfma_f32_16x16x32_bf16 v[4:7], v[214:217], v[204:207], v[4:7]
	v_mfma_f32_16x16x32_bf16 v[0:3], v[222:225], v[204:207], v[0:3]
	s_cmp_gt_u32 s42, 29
	s_barrier
.LBB0_415:
	ds_read_b128 v[146:149], v196 offset:0
	ds_read_b128 v[150:153], v196 offset:1024
	ds_read_b128 v[154:157], v196 offset:2048
	ds_read_b128 v[158:161], v196 offset:3072
	ds_read_b128 v[162:165], v145
	ds_read_b128 v[166:169], v145 offset:1024
	ds_read_b128 v[170:173], v145 offset:2048
	ds_read_b128 v[174:177], v145 offset:3072
	ds_read_b128 v[178:181], v145 offset:4096
	ds_read_b128 v[182:185], v145 offset:5120
	ds_read_b128 v[186:189], v145 offset:6144
	ds_read_b128 v[204:207], v145 offset:7168
	global_load_lds_dwordx4 v136, s[16:17]
	s_add_i32 m0, s30, 0xe000
	s_nop 0
	global_load_lds_dwordx4 v138, s[16:17]
	s_waitcnt lgkmcnt(8)
	s_barrier
	s_waitcnt lgkmcnt(0)
	v_mfma_f32_16x16x32_bf16 v[124:127], v[146:149], v[162:165], v[124:127]
	v_mfma_f32_16x16x32_bf16 v[120:123], v[154:157], v[162:165], v[120:123]
	s_add_i32 s46, 0, 0x14000
	v_mfma_f32_16x16x32_bf16 v[116:119], v[146:149], v[170:173], v[116:119]
	s_add_i32 s43, s43, s28
	v_mfma_f32_16x16x32_bf16 v[108:111], v[154:157], v[170:173], v[108:111]
	s_mov_b32 m0, s43
	v_mfma_f32_16x16x32_bf16 v[100:103], v[146:149], v[178:181], v[100:103]
	v_mfma_f32_16x16x32_bf16 v[92:95], v[154:157], v[178:181], v[92:95]
	v_mfma_f32_16x16x32_bf16 v[84:87], v[146:149], v[186:189], v[84:87]
	v_mfma_f32_16x16x32_bf16 v[76:79], v[154:157], v[186:189], v[76:79]
	v_mfma_f32_16x16x32_bf16 v[124:127], v[150:153], v[166:169], v[124:127]
	v_mfma_f32_16x16x32_bf16 v[120:123], v[158:161], v[166:169], v[120:123]
	v_mfma_f32_16x16x32_bf16 v[116:119], v[150:153], v[174:177], v[116:119]
	v_mfma_f32_16x16x32_bf16 v[108:111], v[158:161], v[174:177], v[108:111]
	v_mfma_f32_16x16x32_bf16 v[100:103], v[150:153], v[182:185], v[100:103]
	v_mfma_f32_16x16x32_bf16 v[92:95], v[158:161], v[182:185], v[92:95]
	v_mfma_f32_16x16x32_bf16 v[84:87], v[150:153], v[204:207], v[84:87]
	v_mfma_f32_16x16x32_bf16 v[76:79], v[158:161], v[204:207], v[76:79]
	s_barrier
	ds_read_b128 v[208:211], v196 offset:16384
	ds_read_b128 v[214:217], v196 offset:17408
	ds_read_b128 v[218:221], v196 offset:18432
	ds_read_b128 v[222:225], v196 offset:19456
	global_load_lds_dwordx4 v192, s[18:19]
	s_add_i32 m0, s43, 0x2000
	s_nop 0
	global_load_lds_dwordx4 v128, s[18:19]
	s_barrier
	s_waitcnt lgkmcnt(0)
	v_mfma_f32_16x16x32_bf16 v[112:115], v[208:211], v[162:165], v[112:115]
	v_mfma_f32_16x16x32_bf16 v[104:107], v[218:221], v[162:165], v[104:107]
	s_mov_b32 m0, s30
	v_mfma_f32_16x16x32_bf16 v[96:99], v[208:211], v[170:173], v[96:99]
	s_add_u32 s48, s20, 0x80
	v_mfma_f32_16x16x32_bf16 v[88:91], v[218:221], v[170:173], v[88:91]
	s_addc_u32 s49, s21, 0
	v_mfma_f32_16x16x32_bf16 v[80:83], v[208:211], v[178:181], v[80:83]
	v_mfma_f32_16x16x32_bf16 v[72:75], v[218:221], v[178:181], v[72:75]
	v_mfma_f32_16x16x32_bf16 v[68:71], v[208:211], v[186:189], v[68:71]
	v_mfma_f32_16x16x32_bf16 v[64:67], v[218:221], v[186:189], v[64:67]
	v_mfma_f32_16x16x32_bf16 v[112:115], v[214:217], v[166:169], v[112:115]
	v_mfma_f32_16x16x32_bf16 v[104:107], v[222:225], v[166:169], v[104:107]
	v_mfma_f32_16x16x32_bf16 v[96:99], v[214:217], v[174:177], v[96:99]
	v_mfma_f32_16x16x32_bf16 v[88:91], v[222:225], v[174:177], v[88:91]
	v_mfma_f32_16x16x32_bf16 v[80:83], v[214:217], v[182:185], v[80:83]
	v_mfma_f32_16x16x32_bf16 v[72:75], v[222:225], v[182:185], v[72:75]
	v_mfma_f32_16x16x32_bf16 v[68:71], v[214:217], v[204:207], v[68:71]
	v_mfma_f32_16x16x32_bf16 v[64:67], v[222:225], v[204:207], v[64:67]
	s_barrier
	ds_read_b128 v[162:165], v145 offset:16384
	ds_read_b128 v[166:169], v145 offset:17408
	ds_read_b128 v[170:173], v145 offset:18432
	ds_read_b128 v[174:177], v145 offset:19456
	ds_read_b128 v[178:181], v145 offset:20480
	ds_read_b128 v[182:185], v145 offset:21504
	ds_read_b128 v[186:189], v145 offset:22528
	ds_read_b128 v[204:207], v145 offset:23552
	global_load_lds_dwordx4 v132, s[20:21]
	s_mov_b32 m0, s31
	s_nop 0
	global_load_lds_dwordx4 v130, s[20:21]
	s_barrier
	s_waitcnt lgkmcnt(0)
	v_mfma_f32_16x16x32_bf16 v[60:63], v[146:149], v[162:165], v[60:63]
	v_mfma_f32_16x16x32_bf16 v[56:59], v[154:157], v[162:165], v[56:59]
	s_add_u32 s44, s18, 0x80000
	v_mfma_f32_16x16x32_bf16 v[52:55], v[146:149], v[170:173], v[52:55]
	s_addc_u32 s45, s19, 0
	v_mfma_f32_16x16x32_bf16 v[44:47], v[154:157], v[170:173], v[44:47]
	s_add_i32 s43, s46, s28
	v_mfma_f32_16x16x32_bf16 v[36:39], v[146:149], v[178:181], v[36:39]
	s_mov_b32 m0, s43
	v_mfma_f32_16x16x32_bf16 v[28:31], v[154:157], v[178:181], v[28:31]
	v_mfma_f32_16x16x32_bf16 v[20:23], v[146:149], v[186:189], v[20:23]
	v_mfma_f32_16x16x32_bf16 v[12:15], v[154:157], v[186:189], v[12:15]
	v_mfma_f32_16x16x32_bf16 v[60:63], v[150:153], v[166:169], v[60:63]
	v_mfma_f32_16x16x32_bf16 v[56:59], v[158:161], v[166:169], v[56:59]
	v_mfma_f32_16x16x32_bf16 v[52:55], v[150:153], v[174:177], v[52:55]
	v_mfma_f32_16x16x32_bf16 v[44:47], v[158:161], v[174:177], v[44:47]
	v_mfma_f32_16x16x32_bf16 v[36:39], v[150:153], v[182:185], v[36:39]
	v_mfma_f32_16x16x32_bf16 v[28:31], v[158:161], v[182:185], v[28:31]
	v_mfma_f32_16x16x32_bf16 v[20:23], v[150:153], v[204:207], v[20:23]
	v_mfma_f32_16x16x32_bf16 v[12:15], v[158:161], v[204:207], v[12:15]
	s_barrier
	global_load_lds_dwordx4 v192, s[44:45]
	s_add_i32 m0, s43, 0x2000
	s_nop 0
	global_load_lds_dwordx4 v128, s[44:45]
	s_waitcnt vmcnt(6)
	s_barrier
	v_mfma_f32_16x16x32_bf16 v[48:51], v[208:211], v[162:165], v[48:51]
	v_mfma_f32_16x16x32_bf16 v[40:43], v[218:221], v[162:165], v[40:43]
	s_add_i32 s43, 0, 0x18000
	v_mfma_f32_16x16x32_bf16 v[32:35], v[208:211], v[170:173], v[32:35]
	s_add_u32 s20, s20, 0x80000
	v_mfma_f32_16x16x32_bf16 v[24:27], v[218:221], v[170:173], v[24:27]
	s_addc_u32 s21, s21, 0
	v_mfma_f32_16x16x32_bf16 v[16:19], v[208:211], v[178:181], v[16:19]
	s_mov_b32 m0, s33
	v_mfma_f32_16x16x32_bf16 v[8:11], v[218:221], v[178:181], v[8:11]
	v_mfma_f32_16x16x32_bf16 v[4:7], v[208:211], v[186:189], v[4:7]
	v_mfma_f32_16x16x32_bf16 v[0:3], v[218:221], v[186:189], v[0:3]
	v_mfma_f32_16x16x32_bf16 v[48:51], v[214:217], v[166:169], v[48:51]
	v_mfma_f32_16x16x32_bf16 v[40:43], v[222:225], v[166:169], v[40:43]
	v_mfma_f32_16x16x32_bf16 v[32:35], v[214:217], v[174:177], v[32:35]
	v_mfma_f32_16x16x32_bf16 v[24:27], v[222:225], v[174:177], v[24:27]
	v_mfma_f32_16x16x32_bf16 v[16:19], v[214:217], v[182:185], v[16:19]
	v_mfma_f32_16x16x32_bf16 v[8:11], v[222:225], v[182:185], v[8:11]
	v_mfma_f32_16x16x32_bf16 v[4:7], v[214:217], v[204:207], v[4:7]
	v_mfma_f32_16x16x32_bf16 v[0:3], v[222:225], v[204:207], v[0:3]
	s_barrier
	ds_read_b128 v[146:149], v196 offset:32768
	ds_read_b128 v[150:153], v196 offset:33792
	ds_read_b128 v[154:157], v196 offset:34816
	ds_read_b128 v[158:161], v196 offset:35840
	ds_read_b128 v[162:165], v145 offset:32768
	ds_read_b128 v[166:169], v145 offset:33792
	ds_read_b128 v[170:173], v145 offset:34816
	ds_read_b128 v[174:177], v145 offset:35840
	ds_read_b128 v[178:181], v145 offset:36864
	ds_read_b128 v[182:185], v145 offset:37888
	ds_read_b128 v[186:189], v145 offset:38912
	ds_read_b128 v[204:207], v145 offset:39936
	global_load_lds_dwordx4 v132, s[20:21]
	s_mov_b32 m0, s34
	s_nop 0
	global_load_lds_dwordx4 v130, s[20:21]
	s_waitcnt lgkmcnt(8)
	s_barrier
	s_waitcnt lgkmcnt(0)
	v_mfma_f32_16x16x32_bf16 v[124:127], v[146:149], v[162:165], v[124:127]
	v_mfma_f32_16x16x32_bf16 v[120:123], v[154:157], v[162:165], v[120:123]
	s_add_i32 s20, 0, 0x1c000
	v_mfma_f32_16x16x32_bf16 v[116:119], v[146:149], v[170:173], v[116:119]
	s_add_i32 s21, s43, s28
	v_mfma_f32_16x16x32_bf16 v[108:111], v[154:157], v[170:173], v[108:111]
	s_add_i32 m0, s21, 0xffffff80
	v_mfma_f32_16x16x32_bf16 v[100:103], v[146:149], v[178:181], v[100:103]
	v_mfma_f32_16x16x32_bf16 v[92:95], v[154:157], v[178:181], v[92:95]
	v_mfma_f32_16x16x32_bf16 v[84:87], v[146:149], v[186:189], v[84:87]
	v_mfma_f32_16x16x32_bf16 v[76:79], v[154:157], v[186:189], v[76:79]
	v_mfma_f32_16x16x32_bf16 v[124:127], v[150:153], v[166:169], v[124:127]
	v_mfma_f32_16x16x32_bf16 v[120:123], v[158:161], v[166:169], v[120:123]
	v_mfma_f32_16x16x32_bf16 v[116:119], v[150:153], v[174:177], v[116:119]
	v_mfma_f32_16x16x32_bf16 v[108:111], v[158:161], v[174:177], v[108:111]
	v_mfma_f32_16x16x32_bf16 v[100:103], v[150:153], v[182:185], v[100:103]
	v_mfma_f32_16x16x32_bf16 v[92:95], v[158:161], v[182:185], v[92:95]
	v_mfma_f32_16x16x32_bf16 v[84:87], v[150:153], v[204:207], v[84:87]
	v_mfma_f32_16x16x32_bf16 v[76:79], v[158:161], v[204:207], v[76:79]
	s_barrier
	ds_read_b128 v[208:211], v196 offset:49152
	ds_read_b128 v[214:217], v196 offset:50176
	ds_read_b128 v[218:221], v196 offset:51200
	ds_read_b128 v[222:225], v196 offset:52224
	global_load_lds_dwordx4 v192, s[18:19] offset:128
	s_add_i32 m0, s21, 0x1f80
	s_nop 0
	global_load_lds_dwordx4 v128, s[18:19] offset:128
	s_barrier
	s_waitcnt lgkmcnt(0)
	v_mfma_f32_16x16x32_bf16 v[112:115], v[208:211], v[162:165], v[112:115]
	v_mfma_f32_16x16x32_bf16 v[104:107], v[218:221], v[162:165], v[104:107]
	s_mov_b32 m0, s35
	v_mfma_f32_16x16x32_bf16 v[96:99], v[208:211], v[170:173], v[96:99]
	v_mfma_f32_16x16x32_bf16 v[88:91], v[218:221], v[170:173], v[88:91]
	v_mfma_f32_16x16x32_bf16 v[80:83], v[208:211], v[178:181], v[80:83]
	v_mfma_f32_16x16x32_bf16 v[72:75], v[218:221], v[178:181], v[72:75]
	v_mfma_f32_16x16x32_bf16 v[68:71], v[208:211], v[186:189], v[68:71]
	v_mfma_f32_16x16x32_bf16 v[64:67], v[218:221], v[186:189], v[64:67]
	v_mfma_f32_16x16x32_bf16 v[112:115], v[214:217], v[166:169], v[112:115]
	v_mfma_f32_16x16x32_bf16 v[104:107], v[222:225], v[166:169], v[104:107]
	v_mfma_f32_16x16x32_bf16 v[96:99], v[214:217], v[174:177], v[96:99]
	v_mfma_f32_16x16x32_bf16 v[88:91], v[222:225], v[174:177], v[88:91]
	v_mfma_f32_16x16x32_bf16 v[80:83], v[214:217], v[182:185], v[80:83]
	v_mfma_f32_16x16x32_bf16 v[72:75], v[222:225], v[182:185], v[72:75]
	v_mfma_f32_16x16x32_bf16 v[68:71], v[214:217], v[204:207], v[68:71]
	v_mfma_f32_16x16x32_bf16 v[64:67], v[222:225], v[204:207], v[64:67]
	s_barrier
	ds_read_b128 v[162:165], v145 offset:49152
	ds_read_b128 v[166:169], v145 offset:50176
	ds_read_b128 v[170:173], v145 offset:51200
	ds_read_b128 v[174:177], v145 offset:52224
	ds_read_b128 v[178:181], v145 offset:53248
	ds_read_b128 v[182:185], v145 offset:54272
	ds_read_b128 v[186:189], v145 offset:55296
	ds_read_b128 v[204:207], v145 offset:56320
	global_load_lds_dwordx4 v132, s[48:49]
	s_mov_b32 m0, s36
	s_nop 0
	global_load_lds_dwordx4 v130, s[48:49]
	s_barrier
	s_waitcnt lgkmcnt(0)
	v_mfma_f32_16x16x32_bf16 v[60:63], v[146:149], v[162:165], v[60:63]
	v_mfma_f32_16x16x32_bf16 v[56:59], v[154:157], v[162:165], v[56:59]
	s_add_u32 s18, s18, 0x80080
	v_mfma_f32_16x16x32_bf16 v[52:55], v[146:149], v[170:173], v[52:55]
	s_addc_u32 s19, s19, 0
	v_mfma_f32_16x16x32_bf16 v[44:47], v[154:157], v[170:173], v[44:47]
	s_add_i32 s20, s20, s28
	v_mfma_f32_16x16x32_bf16 v[36:39], v[146:149], v[178:181], v[36:39]
	s_mov_b32 m0, s20
	v_mfma_f32_16x16x32_bf16 v[28:31], v[154:157], v[178:181], v[28:31]
	v_mfma_f32_16x16x32_bf16 v[20:23], v[146:149], v[186:189], v[20:23]
	v_mfma_f32_16x16x32_bf16 v[12:15], v[154:157], v[186:189], v[12:15]
	v_mfma_f32_16x16x32_bf16 v[60:63], v[150:153], v[166:169], v[60:63]
	v_mfma_f32_16x16x32_bf16 v[56:59], v[158:161], v[166:169], v[56:59]
	v_mfma_f32_16x16x32_bf16 v[52:55], v[150:153], v[174:177], v[52:55]
	v_mfma_f32_16x16x32_bf16 v[44:47], v[158:161], v[174:177], v[44:47]
	v_mfma_f32_16x16x32_bf16 v[36:39], v[150:153], v[182:185], v[36:39]
	v_mfma_f32_16x16x32_bf16 v[28:31], v[158:161], v[182:185], v[28:31]
	v_mfma_f32_16x16x32_bf16 v[20:23], v[150:153], v[204:207], v[20:23]
	v_mfma_f32_16x16x32_bf16 v[12:15], v[158:161], v[204:207], v[12:15]
	s_barrier
	global_load_lds_dwordx4 v192, s[18:19]
	s_add_i32 m0, s20, 0x2000
	s_nop 0
	global_load_lds_dwordx4 v128, s[18:19]
	s_waitcnt vmcnt(6)
	s_barrier
	v_mfma_f32_16x16x32_bf16 v[48:51], v[208:211], v[162:165], v[48:51]
	v_mfma_f32_16x16x32_bf16 v[40:43], v[218:221], v[162:165], v[40:43]
	s_add_i32 s42, s42, 2
	v_mfma_f32_16x16x32_bf16 v[32:35], v[208:211], v[170:173], v[32:35]
	s_add_u32 s16, s16, 0x100
	v_mfma_f32_16x16x32_bf16 v[24:27], v[218:221], v[170:173], v[24:27]
	s_addc_u32 s17, s17, 0
	v_mfma_f32_16x16x32_bf16 v[16:19], v[208:211], v[178:181], v[16:19]
	s_add_u32 s40, s40, 0x100
	v_mfma_f32_16x16x32_bf16 v[8:11], v[218:221], v[178:181], v[8:11]
	s_addc_u32 s41, s41, 0
	v_mfma_f32_16x16x32_bf16 v[4:7], v[208:211], v[186:189], v[4:7]
	s_add_u32 s18, s16, 0xfff80080
	s_addc_u32 s19, s17, -1
	v_mfma_f32_16x16x32_bf16 v[0:3], v[218:221], v[186:189], v[0:3]
	s_add_i32 s43, 0, 0x10000
	s_cmp_eq_u32 s42, 28
	v_mfma_f32_16x16x32_bf16 v[48:51], v[214:217], v[166:169], v[48:51]
	s_cselect_b32 s21, s9, s19
	s_cselect_b32 s20, s38, s18
	v_mfma_f32_16x16x32_bf16 v[40:43], v[222:225], v[166:169], v[40:43]
	s_cselect_b32 s19, s7, s41
	s_cselect_b32 s18, s39, s40
	v_mfma_f32_16x16x32_bf16 v[32:35], v[214:217], v[174:177], v[32:35]
	s_add_i32 m0, s30, 0xc000
	v_mfma_f32_16x16x32_bf16 v[24:27], v[222:225], v[174:177], v[24:27]
	v_mfma_f32_16x16x32_bf16 v[16:19], v[214:217], v[182:185], v[16:19]
	v_mfma_f32_16x16x32_bf16 v[8:11], v[222:225], v[182:185], v[8:11]
	v_mfma_f32_16x16x32_bf16 v[4:7], v[214:217], v[204:207], v[4:7]
	v_mfma_f32_16x16x32_bf16 v[0:3], v[222:225], v[204:207], v[0:3]
	s_cmp_gt_u32 s42, 29
	s_barrier
	s_cbranch_scc0 .LBB0_415
	s_mul_hi_i32 s9, s15, 0x2aaaaaab
	v_lshl_add_u32 v153, s14, 8, v142
	s_lshr_b32 s14, s9, 31
	s_lshr_b32 s9, s9, 2
	s_add_i32 s9, s9, s14
	s_lshl_b32 s7, s15, 8
	s_mul_i32 s16, s9, 0x1800
	v_readlane_b32 s40, v254, 14
	v_readlane_b32 s41, v254, 15
	s_sub_i32 s40, s7, s16
	s_mov_b64 s[20:21], s[40:41]
	v_readlane_b32 s42, v254, 16
	v_readlane_b32 s43, v254, 17
	v_writelane_b32 v254, s20, 14
	s_mov_b64 s[14:15], -1
	s_cmpk_gt_i32 s40, 0xfff
	v_writelane_b32 v254, s21, 15
	v_writelane_b32 v254, s22, 16
	v_writelane_b32 v254, s23, 17
	v_or_b32_e32 v152, 16, v153
	v_or_b32_e32 v151, 32, v153
	v_or_b32_e32 v150, 48, v153
	v_add_u32_e32 v149, 0x80, v153
	v_add_u32_e32 v148, 0x90, v153
	v_add_u32_e32 v147, 0xa0, v153
	v_add_u32_e32 v146, 0xb0, v153
	s_cbranch_scc0 .LBB0_418
	v_mov_b32_e32 v156, v193
	v_mov_b32_e32 v157, v193
	s_ashr_i32 s17, s16, 31
	v_mov_b64_e32 v[140:141], s[2:3]
	s_mov_b32 s9, 0x9000
	v_cvt_pk_fp8_f32 v156, v124, v125
	v_cvt_pk_fp8_f32 v157, v120, v121
	s_lshl_b64 s[14:15], s[16:17], 1
	v_mad_i64_i32 v[154:155], s[16:17], v153, s9, v[140:141]
	s_add_u32 s14, s14, 0x2000
	v_readlane_b32 s16, v254, 14
	s_addc_u32 s15, s15, 0
	v_readlane_b32 s17, v254, 15
	v_lshl_add_u64 v[154:155], v[154:155], 0, s[14:15]
	s_mov_b64 s[20:21], s[16:17]
	v_cvt_pk_fp8_f32 v156, v126, v127 op_sel:[0,0,1]
	v_cvt_pk_fp8_f32 v157, v122, v123 op_sel:[0,0,1]
	v_lshl_add_u64 v[154:155], v[154:155], 0, s[20:21]
	v_lshl_add_u64 v[154:155], v[154:155], 0, s[4:5]
	v_lshl_add_u64 v[154:155], v[154:155], 0, v[134:135]
	global_store_dwordx2 v[154:155], v[156:157], off offset:-4096
	v_mov_b32_e32 v156, v193
	v_mov_b32_e32 v157, v193
	v_cvt_pk_fp8_f32 v156, v112, v113
	v_cvt_pk_fp8_f32 v157, v104, v105
	v_readlane_b32 s18, v254, 16
	v_readlane_b32 s19, v254, 17
	v_cvt_pk_fp8_f32 v156, v114, v115 op_sel:[0,0,1]
	v_cvt_pk_fp8_f32 v157, v106, v107 op_sel:[0,0,1]
	global_store_dwordx2 v[154:155], v[156:157], off offset:-3968
	v_mov_b32_e32 v156, v193
	v_mov_b32_e32 v157, v193
	v_cvt_pk_fp8_f32 v156, v116, v117
	v_cvt_pk_fp8_f32 v157, v108, v109
	v_mad_i64_i32 v[154:155], s[16:17], v152, s9, v[140:141]
	v_lshl_add_u64 v[154:155], v[154:155], 0, s[14:15]
	v_cvt_pk_fp8_f32 v156, v118, v119 op_sel:[0,0,1]
	v_cvt_pk_fp8_f32 v157, v110, v111 op_sel:[0,0,1]
	v_lshl_add_u64 v[154:155], v[154:155], 0, s[20:21]
	v_lshl_add_u64 v[154:155], v[154:155], 0, s[4:5]
	v_lshl_add_u64 v[154:155], v[154:155], 0, v[134:135]
	global_store_dwordx2 v[154:155], v[156:157], off offset:-4096
	v_mov_b32_e32 v156, v193
	v_mov_b32_e32 v157, v193
	v_cvt_pk_fp8_f32 v156, v96, v97
	v_cvt_pk_fp8_f32 v157, v88, v89
	v_cvt_pk_fp8_f32 v156, v98, v99 op_sel:[0,0,1]
	v_cvt_pk_fp8_f32 v157, v90, v91 op_sel:[0,0,1]
	global_store_dwordx2 v[154:155], v[156:157], off offset:-3968
	v_mov_b32_e32 v156, v193
	v_mov_b32_e32 v157, v193
	v_cvt_pk_fp8_f32 v156, v100, v101
	v_cvt_pk_fp8_f32 v157, v92, v93
	v_mad_i64_i32 v[154:155], s[16:17], v151, s9, v[140:141]
	v_lshl_add_u64 v[154:155], v[154:155], 0, s[14:15]
	v_cvt_pk_fp8_f32 v156, v102, v103 op_sel:[0,0,1]
	v_cvt_pk_fp8_f32 v157, v94, v95 op_sel:[0,0,1]
	v_lshl_add_u64 v[154:155], v[154:155], 0, s[20:21]
	v_lshl_add_u64 v[154:155], v[154:155], 0, s[4:5]
	v_lshl_add_u64 v[154:155], v[154:155], 0, v[134:135]
	global_store_dwordx2 v[154:155], v[156:157], off offset:-4096
	v_mov_b32_e32 v156, v193
	v_mov_b32_e32 v157, v193
	v_cvt_pk_fp8_f32 v156, v80, v81
	v_cvt_pk_fp8_f32 v157, v72, v73
	v_cvt_pk_fp8_f32 v156, v82, v83 op_sel:[0,0,1]
	v_cvt_pk_fp8_f32 v157, v74, v75 op_sel:[0,0,1]
	global_store_dwordx2 v[154:155], v[156:157], off offset:-3968
	v_mov_b32_e32 v156, v193
	v_mov_b32_e32 v157, v193
	v_cvt_pk_fp8_f32 v156, v84, v85
	v_cvt_pk_fp8_f32 v157, v76, v77
	v_mad_i64_i32 v[154:155], s[16:17], v150, s9, v[140:141]
	v_lshl_add_u64 v[154:155], v[154:155], 0, s[14:15]
	v_cvt_pk_fp8_f32 v156, v86, v87 op_sel:[0,0,1]
	v_cvt_pk_fp8_f32 v157, v78, v79 op_sel:[0,0,1]
	v_lshl_add_u64 v[154:155], v[154:155], 0, s[20:21]
	v_lshl_add_u64 v[154:155], v[154:155], 0, s[4:5]
	v_lshl_add_u64 v[154:155], v[154:155], 0, v[134:135]
	global_store_dwordx2 v[154:155], v[156:157], off offset:-4096
	v_mov_b32_e32 v156, v193
	v_mov_b32_e32 v157, v193
	v_cvt_pk_fp8_f32 v156, v68, v69
	v_cvt_pk_fp8_f32 v157, v64, v65
	v_cvt_pk_fp8_f32 v156, v70, v71 op_sel:[0,0,1]
	v_cvt_pk_fp8_f32 v157, v66, v67 op_sel:[0,0,1]
	global_store_dwordx2 v[154:155], v[156:157], off offset:-3968
	v_mov_b32_e32 v156, v193
	v_mov_b32_e32 v157, v193
	v_cvt_pk_fp8_f32 v156, v60, v61
	v_cvt_pk_fp8_f32 v157, v56, v57
	v_mad_i64_i32 v[154:155], s[16:17], v149, s9, v[140:141]
	v_lshl_add_u64 v[154:155], v[154:155], 0, s[14:15]
	v_cvt_pk_fp8_f32 v156, v62, v63 op_sel:[0,0,1]
	v_cvt_pk_fp8_f32 v157, v58, v59 op_sel:[0,0,1]
	v_lshl_add_u64 v[154:155], v[154:155], 0, s[20:21]
	v_lshl_add_u64 v[154:155], v[154:155], 0, s[4:5]
	v_lshl_add_u64 v[154:155], v[154:155], 0, v[134:135]
	global_store_dwordx2 v[154:155], v[156:157], off offset:-4096
	v_mov_b32_e32 v156, v193
	v_mov_b32_e32 v157, v193
	v_cvt_pk_fp8_f32 v156, v48, v49
	v_cvt_pk_fp8_f32 v157, v40, v41
	v_cvt_pk_fp8_f32 v156, v50, v51 op_sel:[0,0,1]
	v_cvt_pk_fp8_f32 v157, v42, v43 op_sel:[0,0,1]
	global_store_dwordx2 v[154:155], v[156:157], off offset:-3968
	v_mov_b32_e32 v156, v193
	v_mov_b32_e32 v157, v193
	v_cvt_pk_fp8_f32 v156, v52, v53
	v_cvt_pk_fp8_f32 v157, v44, v45
	v_mad_i64_i32 v[154:155], s[16:17], v148, s9, v[140:141]
	v_lshl_add_u64 v[154:155], v[154:155], 0, s[14:15]
	v_cvt_pk_fp8_f32 v156, v54, v55 op_sel:[0,0,1]
	v_cvt_pk_fp8_f32 v157, v46, v47 op_sel:[0,0,1]
	v_lshl_add_u64 v[154:155], v[154:155], 0, s[20:21]
	v_lshl_add_u64 v[154:155], v[154:155], 0, s[4:5]
	v_lshl_add_u64 v[154:155], v[154:155], 0, v[134:135]
	global_store_dwordx2 v[154:155], v[156:157], off offset:-4096
	v_mov_b32_e32 v156, v193
	v_mov_b32_e32 v157, v193
	v_cvt_pk_fp8_f32 v156, v32, v33
	v_cvt_pk_fp8_f32 v157, v24, v25
	v_cvt_pk_fp8_f32 v156, v34, v35 op_sel:[0,0,1]
	v_cvt_pk_fp8_f32 v157, v26, v27 op_sel:[0,0,1]
	global_store_dwordx2 v[154:155], v[156:157], off offset:-3968
	v_mov_b32_e32 v156, v193
	v_mov_b32_e32 v157, v193
	v_cvt_pk_fp8_f32 v156, v36, v37
	v_cvt_pk_fp8_f32 v157, v28, v29
	v_mad_i64_i32 v[154:155], s[16:17], v147, s9, v[140:141]
	v_lshl_add_u64 v[154:155], v[154:155], 0, s[14:15]
	v_cvt_pk_fp8_f32 v156, v38, v39 op_sel:[0,0,1]
	v_cvt_pk_fp8_f32 v157, v30, v31 op_sel:[0,0,1]
	v_lshl_add_u64 v[154:155], v[154:155], 0, s[20:21]
	v_lshl_add_u64 v[154:155], v[154:155], 0, s[4:5]
	v_lshl_add_u64 v[154:155], v[154:155], 0, v[134:135]
	global_store_dwordx2 v[154:155], v[156:157], off offset:-4096
	v_mov_b32_e32 v156, v193
	v_mov_b32_e32 v157, v193
	v_cvt_pk_fp8_f32 v156, v16, v17
	v_cvt_pk_fp8_f32 v157, v8, v9
	v_mad_i64_i32 v[140:141], s[16:17], v146, s9, v[140:141]
	v_cvt_pk_fp8_f32 v156, v18, v19 op_sel:[0,0,1]
	v_cvt_pk_fp8_f32 v157, v10, v11 op_sel:[0,0,1]
	v_lshl_add_u64 v[140:141], v[140:141], 0, s[14:15]
	v_lshl_add_u64 v[140:141], v[140:141], 0, s[20:21]
	v_lshl_add_u64 v[140:141], v[140:141], 0, s[4:5]
	global_store_dwordx2 v[154:155], v[156:157], off offset:-3968
	v_mov_b32_e32 v154, v193
	v_mov_b32_e32 v155, v193
	v_cvt_pk_fp8_f32 v154, v20, v21
	v_cvt_pk_fp8_f32 v155, v12, v13
	v_lshl_add_u64 v[140:141], v[140:141], 0, v[134:135]
	s_mov_b64 s[14:15], 0
	v_cvt_pk_fp8_f32 v154, v22, v23 op_sel:[0,0,1]
	v_cvt_pk_fp8_f32 v155, v14, v15 op_sel:[0,0,1]
	global_store_dwordx2 v[140:141], v[154:155], off offset:-4096
	v_mov_b32_e32 v154, v193
	v_mov_b32_e32 v155, v193
	v_cvt_pk_fp8_f32 v154, v4, v5
	v_cvt_pk_fp8_f32 v155, v0, v1
	v_cvt_pk_fp8_f32 v154, v6, v7 op_sel:[0,0,1]
	v_cvt_pk_fp8_f32 v155, v2, v3 op_sel:[0,0,1]
	global_store_dwordx2 v[140:141], v[154:155], off offset:-3968
